# v50 + nt (streaming) cache policy on the full-line residual f32 Y stores
# baseline (speedup 1.0000x reference)
; __device__ __forceinline__ float xsum16(float v) { const auto r = __builtin_amdgcn_permlane16_swap(__float_as_uint(v), __float_as_uint(v), false, false); return __uint_as_float(r[0]) + __uint_as_float(r[1]); }
; __device__ __forceinline__ float xsum32(float v) { const auto r = __builtin_amdgcn_permlane32_swap(__float_as_uint(v), __float_as_uint(v), false, false); return __uint_as_float(r[0]) + __uint_as_float(r[1]); }
; __device__ __forceinline__ void row_stats4(const float* st, int rowb, int fq, float (&mu)[4], float (&rs)[4]) {
;     f32x4 a[4], b[4];
; #pragma unroll
;     for (int m = 0; m < 4; ++m) { const f32x4* p = (const f32x4*)(st + (size_t)(rowb + m * 16) * 32 + fq * 8); a[m] = p[0]; b[m] = p[1]; }
; #pragma unroll
;     for (int m = 0; m < 4; ++m) { float s1 = (a[m][0] + a[m][2]) + (b[m][0] + b[m][2]), s2 = (a[m][1] + a[m][3]) + (b[m][1] + b[m][3]);
;         s1 = xsum32(xsum16(s1)); s2 = xsum32(xsum16(s2));
;         const float mm = s1 * (1.0f / 1024.0f); mu[m] = mm; rs[m] = rsqrtf(fmaxf(s2 * (1.0f / 1024.0f) - mm * mm, 0.f) + LN_EPS_); }
;     asm volatile("" ::: "memory");
; }
;     __device__ __forceinline__ void operator()(const f32x4 (&acc)[2][2][4][2], const pg8::Unit& u, int wr, int wc, int fr, int fq) const {
;     ...
;             for (int m = 0; m < 4; ++m) { const int row = row0 + ai * 128 + m * 16; const float mu = mu4[m], rs = rs4[m];
;                 f32x4 yv[2][2], gq[2][2], bq_[2][2];
; #pragma unroll
;                 for (int bj = 0; bj < 2; ++bj)
; #pragma unroll
;                     for (int n = 0; n < 2; ++n) { yv[bj][n] = *(const f32x4*)(Yin + (size_t)row * D_ + col0 + bj * 128 + 4 * n); gq[bj][n] = *(const f32x4*)(g + col0 + bj * 128 + 4 * n); bq_[bj][n] = *(const f32x4*)(b + col0 + bj * 128 + 4 * n); }
;                 asm volatile("" ::: "memory");
;                 float s1 = 0.f, s2 = 0.f;
; #pragma unroll
;                 for (int bj = 0; bj < 2; ++bj) { float* yp = Y + (size_t)row * D_ + col0 + bj * 128; f32x4 v[2];
; #pragma unroll
;                     for (int n = 0; n < 2; ++n) { v[n] = (((yv[bj][n] - mu) * rs) * gq[bj][n] + bq_[bj][n]) * ALPHA_ + acc[ai][bj][m][n] * sc;
.LBB0_372:
	s_lshl_b32 s3, s3, 8
	s_add_i32 s3, s3, s53
	v_or_b32_e32 v158, s3, v182
	v_ashrrev_i32_e32 v159, 31, v158
	v_lshlrev_b64 v[130:131], 7, v[158:159]
	v_lshl_add_u64 v[136:137], v[146:147], 0, v[130:131]
	v_or_b32_e32 v180, 16, v158
	global_load_dwordx4 v[132:135], v[136:137], off
	global_load_dwordx4 v[166:169], v[136:137], off offset:16
	v_ashrrev_i32_e32 v181, 31, v180
	v_lshlrev_b64 v[172:173], 7, v[180:181]
	v_lshl_add_u64 v[136:137], v[146:147], 0, v[172:173]
	global_load_dwordx4 v[174:177], v[136:137], off
	global_load_dwordx4 v[186:189], v[136:137], off offset:16
	v_or_b32_e32 v170, 32, v158
	v_ashrrev_i32_e32 v171, 31, v170
	v_lshlrev_b64 v[164:165], 7, v[170:171]
	v_lshl_add_u64 v[136:137], v[146:147], 0, v[164:165]
	global_load_dwordx4 v[190:193], v[136:137], off
	global_load_dwordx4 v[196:199], v[136:137], off offset:16
	v_or_b32_e32 v162, 48, v158
	v_ashrrev_i32_e32 v163, 31, v162
	v_lshlrev_b64 v[160:161], 7, v[162:163]
	v_lshl_add_u64 v[204:205], v[146:147], 0, v[160:161]
	global_load_dwordx4 v[200:203], v[204:205], off
	s_nop 0
	global_load_dwordx4 v[204:207], v[204:205], off offset:16
	s_lshl_b32 s16, s2, 8
	s_lshl_b32 s17, s2, 3
	s_or_b32 s2, s16, s54
	v_or_b32_e32 v152, s2, v183
	v_ashrrev_i32_e32 v153, 31, v152
	v_lshlrev_b64 v[136:137], 12, v[158:159]
	v_lshlrev_b64 v[152:153], 2, v[152:153]
	v_lshl_add_u64 v[178:179], s[12:13], 0, v[136:137]
	v_lshl_add_u64 v[178:179], v[178:179], 0, v[152:153]
	v_lshl_add_u64 v[154:155], s[8:9], 0, v[152:153]
	v_lshl_add_u64 v[156:157], s[10:11], 0, v[152:153]
	global_load_dwordx4 v[208:211], v[178:179], off offset:16
	global_load_dwordx4 v[212:215], v[178:179], off
	global_load_dwordx4 v[216:219], v[154:155], off offset:16
	global_load_dwordx4 v[220:223], v[154:155], off
	global_load_dwordx4 v[234:237], v[156:157], off offset:16
	global_load_dwordx4 v[238:241], v[156:157], off
	s_mov_b32 s16, 0x3a800000
	s_mov_b32 s18, 0x3fd744fd
	s_load_dwordx16 s[60:75], s[34:35], 0x38
	s_or_b32 s24, s17, s57
	v_bitop3_b32 v194, s2, 56, v183 bitop3:0xc8
	s_ashr_i32 s40, s2, 6
	s_ashr_i32 s25, s24, 31
	s_waitcnt lgkmcnt(0)
	v_lshl_add_u64 v[136:137], s[74:75], 0, v[136:137]
	v_lshl_add_u64 v[136:137], v[136:137], 0, v[152:153]
	s_ashr_i32 s41, s40, 31
	s_waitcnt vmcnt(0)
	v_mov_b32_e32 v224, v132
	v_mov_b32_e32 v225, v166
	v_mov_b32_e32 v228, v134
	v_mov_b32_e32 v229, v168
	v_mov_b32_e32 v166, v133
	v_mov_b32_e32 v168, v135
	v_pk_add_f32 v[132:133], v[224:225], v[228:229]
	v_pk_add_f32 v[134:135], v[166:167], v[168:169]
	v_pk_add_f32 v[132:133], v[132:133], v[132:133] op_sel:[0,1] op_sel_hi:[1,0]
	v_pk_add_f32 v[134:135], v[134:135], v[134:135] op_sel:[0,1] op_sel_hi:[1,0]
	v_mov_b32_e32 v166, v174
	v_mov_b32_e32 v167, v186
	v_mov_b32_e32 v168, v176
	v_mov_b32_e32 v169, v188
	v_mov_b32_e32 v0, v132
	v_mov_b32_e32 v133, v134
	v_pk_add_f32 v[166:167], v[166:167], v[168:169]
	v_permlane16_swap_b32_e32 v132, v0
	v_permlane16_swap_b32_e32 v134, v133
	v_mov_b32_e32 v186, v175
	v_mov_b32_e32 v188, v177
	v_pk_add_f32 v[166:167], v[166:167], v[166:167] op_sel:[0,1] op_sel_hi:[1,0]
	v_add_f32_e32 v177, v132, v0
	v_add_f32_e32 v176, v134, v133
	v_pk_add_f32 v[168:169], v[186:187], v[188:189]
	v_mov_b32_e32 v135, v166
	v_mov_b32_e32 v187, v177
	v_mov_b32_e32 v186, v176
	v_permlane16_swap_b32_e32 v166, v135
	v_permlane32_swap_b32_e32 v177, v187
	v_permlane32_swap_b32_e32 v176, v186
	v_add_f32_e32 v133, v166, v135
	v_pk_add_f32 v[166:167], v[176:177], v[186:187]
	v_pk_add_f32 v[168:169], v[168:169], v[168:169] op_sel:[0,1] op_sel_hi:[1,0]
	v_pk_mul_f32 v[224:225], v[166:167], s[16:17] op_sel_hi:[1,0]
	v_mov_b32_e32 v159, v168
	v_fma_f32 v0, -v225, v225, v224
	v_max_f32_e32 v0, 0, v0
	v_permlane16_swap_b32_e32 v168, v159
	v_add_f32_e32 v0, 0x3727c5ac, v0
	s_mov_b32 s16, 0x800000
	v_add_f32_e32 v132, v168, v159
	v_mul_f32_e32 v159, 0x4b800000, v0
	v_cmp_gt_f32_e32 vcc, s16, v0
	v_mov_b32_e32 v174, v190
	v_mov_b32_e32 v175, v196
	v_cndmask_b32_e32 v0, v0, v159, vcc
	v_rsq_f32_e32 v0, v0
	v_mov_b32_e32 v166, v192
	v_mov_b32_e32 v167, v198
	v_pk_add_f32 v[166:167], v[174:175], v[166:167]
	v_mul_f32_e32 v159, 0x45800000, v0
	v_pk_add_f32 v[166:167], v[166:167], v[166:167] op_sel:[0,1] op_sel_hi:[1,0]
	v_mov_b32_e32 v196, v191
	v_mov_b32_e32 v198, v193
	v_cndmask_b32_e32 v0, v0, v159, vcc
	v_pk_add_f32 v[168:169], v[196:197], v[198:199]
	v_mov_b32_e32 v159, v166
	v_pk_add_f32 v[168:169], v[168:169], v[168:169] op_sel:[0,1] op_sel_hi:[1,0]
	s_nop 0
	v_permlane16_swap_b32_e32 v166, v159
	v_add_f32_e32 v175, v166, v159
	v_mov_b32_e32 v159, v168
	s_nop 1
	v_permlane16_swap_b32_e32 v168, v159
	global_load_dwordx4 v[186:189], v[178:179], off offset:528
	global_load_dwordx4 v[190:193], v[178:179], off offset:512
	v_add_f32_e32 v174, v168, v159
	v_mov_b32_e32 v166, v200
	v_mov_b32_e32 v167, v204
	v_mov_b32_e32 v168, v202
	v_mov_b32_e32 v169, v206
	v_mov_b32_e32 v204, v201
	v_mov_b32_e32 v206, v203
	v_pk_add_f32 v[166:167], v[166:167], v[168:169]
	v_pk_add_f32 v[168:169], v[204:205], v[206:207]
	global_load_dwordx4 v[196:199], v[154:155], off offset:528
	global_load_dwordx4 v[200:203], v[154:155], off offset:512
	global_load_dwordx4 v[204:207], v[156:157], off offset:528
	global_load_dwordx4 v[242:245], v[156:157], off offset:512
	v_sub_f32_e32 v179, v215, v225
	v_sub_f32_e32 v178, v214, v225
	v_sub_f32_e32 v213, v213, v225
	v_sub_f32_e32 v212, v212, v225
	v_pk_mul_f32 v[212:213], v[0:1], v[212:213] op_sel_hi:[0,1]
	v_pk_mul_f32 v[178:179], v[0:1], v[178:179] op_sel_hi:[0,1]
	v_pk_fma_f32 v[178:179], v[222:223], v[178:179], v[240:241]
	v_pk_fma_f32 v[212:213], v[220:221], v[212:213], v[238:239]
; __device__ __forceinline__ size_t blk_off(int r, int c, int K) { return (size_t)(r >> 8) * 256 * K + (size_t)(c >> 6) * (256 * 64) + (size_t)((r & 255) * 64 + (c & 63)); }
; __device__ __forceinline__ u32x4 pack8(const f32x4 a, const f32x4 b) { u32x4 w; w.x = cvt_pk_bf16(a[0], a[1]); w.y = cvt_pk_bf16(a[2], a[3]); w.z = cvt_pk_bf16(b[0], b[1]); w.w = cvt_pk_bf16(b[2], b[3]); return w; }
;     __device__ __forceinline__ void operator()(const f32x4 (&acc)[2][2][4][2], const pg8::Unit& u, int wr, int wc, int fr, int fq) const {
;     ...
;                 for (int bj = 0; bj < 2; ++bj) { float* yp = Y + (size_t)row * D_ + col0 + bj * 128; f32x4 v[2];
; #pragma unroll
;                     for (int n = 0; n < 2; ++n) { v[n] = (((yv[bj][n] - mu) * rs) * gq[bj][n] + bq_[bj][n]) * ALPHA_ + acc[ai][bj][m][n] * sc;
;                         *(f32x4*)(yp + 4 * n) = v[n]; s1 += (v[n][0] + v[n][1]) + (v[n][2] + v[n][3]); s2 += (v[n][0] * v[n][0] + v[n][1] * v[n][1]) + (v[n][2] * v[n][2] + v[n][3] * v[n][3]); }
;                     *(u32x4*)(Yb + blk_off(row, col0 + bj * 128, D_)) = pack8(v[0], v[1]); }
	v_pk_mul_f32 v[178:179], v[178:179], s[18:19] op_sel_hi:[1,0]
	v_pk_mul_f32 v[212:213], v[212:213], s[18:19] op_sel_hi:[1,0]
	v_pk_fma_f32 v[128:129], v[128:129], 0.5, v[178:179] op_sel_hi:[1,0,1]
	v_pk_fma_f32 v[126:127], v[126:127], 0.5, v[212:213] op_sel_hi:[1,0,1]
	v_add_f32_e32 v179, v128, v129
	v_add_f32_e32 v178, v126, v127
	v_add_f32_e32 v178, v178, v179
	v_add_f32_e32 v195, 0, v178
	v_mul_f32_e32 v178, v127, v127
	v_mul_f32_e32 v179, v129, v129
	v_fmac_f32_e32 v178, v126, v126
	v_fmac_f32_e32 v179, v128, v128
	v_add_f32_e32 v212, v178, v179
	v_sub_f32_e32 v179, v211, v225
	v_sub_f32_e32 v178, v210, v225
	v_sub_f32_e32 v209, v209, v225
	v_sub_f32_e32 v208, v208, v225
	v_pk_mul_f32 v[208:209], v[0:1], v[208:209] op_sel_hi:[0,1]
	v_pk_mul_f32 v[178:179], v[0:1], v[178:179] op_sel_hi:[0,1]
	v_pk_fma_f32 v[178:179], v[218:219], v[178:179], v[236:237]
	v_pk_fma_f32 v[208:209], v[216:217], v[208:209], v[234:235]
	v_pk_mul_f32 v[178:179], v[178:179], s[18:19] op_sel_hi:[1,0]
	v_pk_mul_f32 v[208:209], v[208:209], s[18:19] op_sel_hi:[1,0]
	v_pk_add_f32 v[166:167], v[166:167], v[166:167] op_sel:[0,1] op_sel_hi:[1,0]
	v_pk_fma_f32 v[124:125], v[124:125], 0.5, v[178:179] op_sel_hi:[1,0,1]
	v_pk_fma_f32 v[122:123], v[122:123], 0.5, v[208:209] op_sel_hi:[1,0,1]
	v_mov_b32_e32 v159, v166
	v_add_f32_e32 v178, v122, v123
	v_add_f32_e32 v179, v124, v125
	v_pk_add_f32 v[168:169], v[168:169], v[168:169] op_sel:[0,1] op_sel_hi:[1,0]
	v_permlane16_swap_b32_e32 v166, v159
	v_add_f32_e32 v178, v178, v179
	v_add_f32_e32 v167, v166, v159
	v_mov_b32_e32 v159, v168
	v_add_f32_e32 v178, v195, v178
	v_mul_f32_e32 v179, v123, v123
	v_mul_f32_e32 v195, v125, v125
	v_permlane16_swap_b32_e32 v168, v159
	s_ashr_i32 s16, s3, 8
	s_nop 0
	s_nop 1
	v_bfe_u32 v135, v227, 4, 2
	v_sub_u32_e32 v134, 0, v135
	v_lshlrev_b32_e32 v134, 4, v134
	v_ashrrev_i32_e32 v135, 31, v134
	v_lshl_add_u64 v[134:135], v[136:137], 0, v[134:135]
	v_permlane16_swap_b32_e32 v126, v122
	v_permlane16_swap_b32_e32 v127, v123
	v_permlane16_swap_b32_e32 v128, v124
	v_permlane16_swap_b32_e32 v129, v125
	v_permlane32_swap_b32_e32 v126, v122
	v_permlane32_swap_b32_e32 v127, v123
	v_permlane32_swap_b32_e32 v128, v124
	v_permlane32_swap_b32_e32 v129, v125
	v_mov_b32_e32 v166, v126
	v_mov_b32_e32 v169, v127
	v_mov_b32_e32 v208, v128
	v_mov_b32_e32 v209, v129
	v_bfe_u32 v176, v227, 3, 1
	v_mul_i32_i24_e32 v176, 0xffff8040, v176
	v_ashrrev_i32_e32 v177, 31, v176
	v_lshl_add_u64 v[134:135], v[134:135], 0, v[176:177]
	v_mov_b32_e32 v176, 0x8000
	v_mov_b32_e32 v177, 0
	v_lshl_add_u64 v[176:177], v[134:135], 0, v[176:177]
	v_mov_b32_dpp v126, v122 row_ror:8 row_mask:0xf bank_mask:0xc
	v_mov_b32_dpp v127, v123 row_ror:8 row_mask:0xf bank_mask:0xc
	v_mov_b32_dpp v128, v124 row_ror:8 row_mask:0xf bank_mask:0xc
	v_mov_b32_dpp v129, v125 row_ror:8 row_mask:0xf bank_mask:0xc
	v_mov_b32_dpp v122, v166 row_ror:8 row_mask:0xf bank_mask:0x3
	v_mov_b32_dpp v123, v169 row_ror:8 row_mask:0xf bank_mask:0x3
	v_mov_b32_dpp v124, v208 row_ror:8 row_mask:0xf bank_mask:0x3
	v_mov_b32_dpp v125, v209 row_ror:8 row_mask:0xf bank_mask:0x3
	global_store_dwordx4 v[134:135], v[126:129], off nt
	global_store_dwordx4 v[176:177], v[122:125], off nt
	s_nop 1
	v_mov_b32_dpp v122, v126 row_ror:8 row_mask:0xf bank_mask:0x3
	v_mov_b32_dpp v123, v127 row_ror:8 row_mask:0xf bank_mask:0x3
	v_mov_b32_dpp v124, v128 row_ror:8 row_mask:0xf bank_mask:0x3
	v_mov_b32_dpp v125, v129 row_ror:8 row_mask:0xf bank_mask:0x3
	v_mov_b32_e32 v126, v166
	v_mov_b32_e32 v127, v169
	v_mov_b32_e32 v128, v208
	v_mov_b32_e32 v129, v209
	s_nop 1
	v_permlane32_swap_b32_e32 v126, v122
	v_permlane32_swap_b32_e32 v127, v123
	v_permlane32_swap_b32_e32 v128, v124
	v_permlane32_swap_b32_e32 v129, v125
	v_permlane16_swap_b32_e32 v126, v122
	v_permlane16_swap_b32_e32 v127, v123
	v_permlane16_swap_b32_e32 v128, v124
	v_permlane16_swap_b32_e32 v129, v125
	v_fmac_f32_e32 v179, v122, v122
	v_fmac_f32_e32 v195, v124, v124
	v_cvt_pk_bf16_f32 v126, v126, v127
	v_cvt_pk_bf16_f32 v127, v128, v129
	v_cvt_pk_bf16_f32 v128, v122, v123
	v_cvt_pk_bf16_f32 v129, v124, v125
	v_add_f32_e32 v166, v168, v159
	s_ashr_i32 s17, s16, 31
	v_lshlrev_b32_e32 v159, 6, v158
	s_movk_i32 s3, 0x33c0
	s_lshl_b64 s[16:17], s[16:17], 19
	v_and_or_b32 v159, v159, s3, v194
	v_readlane_b32 s2, v253, 59
	v_readlane_b32 s3, v253, 60
	s_add_u32 s16, s2, s16
	s_addc_u32 s17, s3, s17
	s_lshl_b64 s[28:29], s[40:41], 15
	s_waitcnt vmcnt(6)
	v_sub_f32_e32 v123, v193, v225
	v_sub_f32_e32 v122, v192, v225
	v_sub_f32_e32 v125, v191, v225
	v_sub_f32_e32 v124, v190, v225
	v_pk_mul_f32 v[124:125], v[0:1], v[124:125] op_sel_hi:[0,1]
	v_pk_mul_f32 v[122:123], v[0:1], v[122:123] op_sel_hi:[0,1]
	s_add_u32 s50, s16, s28
	s_addc_u32 s51, s17, s29
	v_lshlrev_b32_e32 v159, 1, v159
	global_store_dwordx4 v159, v[126:129], s[50:51]
	s_waitcnt vmcnt(3)
; __device__ __forceinline__ float xsum16(float v) { const auto r = __builtin_amdgcn_permlane16_swap(__float_as_uint(v), __float_as_uint(v), false, false); return __uint_as_float(r[0]) + __uint_as_float(r[1]); }
; __device__ __forceinline__ float xsum32(float v) { const auto r = __builtin_amdgcn_permlane32_swap(__float_as_uint(v), __float_as_uint(v), false, false); return __uint_as_float(r[0]) + __uint_as_float(r[1]); }
; __device__ __forceinline__ size_t blk_off(int r, int c, int K) { return (size_t)(r >> 8) * 256 * K + (size_t)(c >> 6) * (256 * 64) + (size_t)((r & 255) * 64 + (c & 63)); }
; __device__ __forceinline__ u32x4 pack8(const f32x4 a, const f32x4 b) { u32x4 w; w.x = cvt_pk_bf16(a[0], a[1]); w.y = cvt_pk_bf16(a[2], a[3]); w.z = cvt_pk_bf16(b[0], b[1]); w.w = cvt_pk_bf16(b[2], b[3]); return w; }
;     __device__ __forceinline__ void operator()(const f32x4 (&acc)[2][2][4][2], const pg8::Unit& u, int wr, int wc, int fr, int fq) const {
;     ...
;                 for (int bj = 0; bj < 2; ++bj) { float* yp = Y + (size_t)row * D_ + col0 + bj * 128; f32x4 v[2];
; #pragma unroll
;                     for (int n = 0; n < 2; ++n) { v[n] = (((yv[bj][n] - mu) * rs) * gq[bj][n] + bq_[bj][n]) * ALPHA_ + acc[ai][bj][m][n] * sc;
;                         *(f32x4*)(yp + 4 * n) = v[n]; s1 += (v[n][0] + v[n][1]) + (v[n][2] + v[n][3]); s2 += (v[n][0] * v[n][0] + v[n][1] * v[n][1]) + (v[n][2] * v[n][2] + v[n][3] * v[n][3]); }
;                     *(u32x4*)(Yb + blk_off(row, col0 + bj * 128, D_)) = pack8(v[0], v[1]); }
;                 s1 = xsum32(xsum16(s1)); s2 = xsum32(xsum16(s2));
;                 if (fq == 0) *(f32x2*)(stn + (size_t)row * 32 + (u.pn * 4 + wc) * 2) = (f32x2){s1, s2}; asm volatile("" ::: "memory"); } }
	v_pk_fma_f32 v[122:123], v[202:203], v[122:123], v[244:245]
	v_pk_fma_f32 v[124:125], v[200:201], v[124:125], v[242:243]
	v_pk_mul_f32 v[122:123], v[122:123], s[18:19] op_sel_hi:[1,0]
	v_pk_mul_f32 v[124:125], v[124:125], s[18:19] op_sel_hi:[1,0]
	v_pk_fma_f32 v[120:121], v[120:121], 0.5, v[122:123] op_sel_hi:[1,0,1]
	v_pk_fma_f32 v[118:119], v[118:119], 0.5, v[124:125] op_sel_hi:[1,0,1]
	v_add_f32_e32 v123, v120, v121
	v_add_f32_e32 v122, v118, v119
	v_add_f32_e32 v122, v122, v123
	v_add_f32_e32 v126, v178, v122
	v_mul_f32_e32 v122, v119, v119
	v_mul_f32_e32 v123, v121, v121
	v_add_f32_e32 v179, v179, v195
	v_fmac_f32_e32 v122, v118, v118
	v_fmac_f32_e32 v123, v120, v120
	v_add_f32_e32 v179, v212, v179
	v_add_f32_e32 v122, v122, v123
	v_add_f32_e32 v127, v179, v122
	v_sub_f32_e32 v123, v189, v225
	v_sub_f32_e32 v122, v188, v225
	v_sub_f32_e32 v125, v187, v225
	v_sub_f32_e32 v124, v186, v225
	v_pk_mul_f32 v[124:125], v[0:1], v[124:125] op_sel_hi:[0,1]
	v_pk_mul_f32 v[122:123], v[0:1], v[122:123] op_sel_hi:[0,1]
	v_pk_fma_f32 v[122:123], v[198:199], v[122:123], v[206:207]
	v_pk_fma_f32 v[124:125], v[196:197], v[124:125], v[204:205]
	v_pk_mul_f32 v[122:123], v[122:123], s[18:19] op_sel_hi:[1,0]
	v_pk_mul_f32 v[124:125], v[124:125], s[18:19] op_sel_hi:[1,0]
	v_pk_fma_f32 v[116:117], v[116:117], 0.5, v[122:123] op_sel_hi:[1,0,1]
	v_pk_fma_f32 v[114:115], v[114:115], 0.5, v[124:125] op_sel_hi:[1,0,1]
	v_add_f32_e32 v122, v116, v117
	v_add_f32_e32 v0, v114, v115
	v_add_f32_e32 v0, v0, v122
	v_mul_f32_e32 v122, v115, v115
	v_mul_f32_e32 v123, v117, v117
	v_add_f32_e32 v0, v126, v0
	v_fmac_f32_e32 v122, v114, v114
	v_fmac_f32_e32 v123, v116, v116
	s_nop 0
	s_nop 1
	v_bfe_u32 v125, v227, 4, 2
	v_sub_u32_e32 v124, 0, v125
	v_lshlrev_b32_e32 v124, 4, v124
	v_ashrrev_i32_e32 v125, 31, v124
	v_lshl_add_u64 v[124:125], v[136:137], 0, v[124:125]
	v_permlane16_swap_b32_e32 v118, v114
	v_permlane16_swap_b32_e32 v119, v115
	v_permlane16_swap_b32_e32 v120, v116
	v_permlane16_swap_b32_e32 v121, v117
	v_permlane32_swap_b32_e32 v118, v114
	v_permlane32_swap_b32_e32 v119, v115
	v_permlane32_swap_b32_e32 v120, v116
	v_permlane32_swap_b32_e32 v121, v117
	v_mov_b32_e32 v134, v118
	v_mov_b32_e32 v135, v119
	v_mov_b32_e32 v168, v120
	v_mov_b32_e32 v169, v121
	v_bfe_u32 v128, v227, 3, 1
	v_mul_i32_i24_e32 v128, 0xffff8040, v128
	v_ashrrev_i32_e32 v129, 31, v128
	v_lshl_add_u64 v[124:125], v[124:125], 0, v[128:129]
	v_mov_b32_e32 v128, 0x8000
	v_mov_b32_e32 v129, 0
	v_lshl_add_u64 v[128:129], v[124:125], 0, v[128:129]
	v_mov_b32_dpp v118, v114 row_ror:8 row_mask:0xf bank_mask:0xc
	v_mov_b32_dpp v119, v115 row_ror:8 row_mask:0xf bank_mask:0xc
	v_mov_b32_dpp v120, v116 row_ror:8 row_mask:0xf bank_mask:0xc
	v_mov_b32_dpp v121, v117 row_ror:8 row_mask:0xf bank_mask:0xc
	v_mov_b32_dpp v114, v134 row_ror:8 row_mask:0xf bank_mask:0x3
	v_mov_b32_dpp v115, v135 row_ror:8 row_mask:0xf bank_mask:0x3
	v_mov_b32_dpp v116, v168 row_ror:8 row_mask:0xf bank_mask:0x3
	v_mov_b32_dpp v117, v169 row_ror:8 row_mask:0xf bank_mask:0x3
	global_store_dwordx4 v[124:125], v[118:121], off offset:512 nt
	global_store_dwordx4 v[128:129], v[114:117], off offset:512 nt
	s_nop 1
	v_mov_b32_dpp v114, v118 row_ror:8 row_mask:0xf bank_mask:0x3
	v_mov_b32_dpp v115, v119 row_ror:8 row_mask:0xf bank_mask:0x3
	v_mov_b32_dpp v116, v120 row_ror:8 row_mask:0xf bank_mask:0x3
	v_mov_b32_dpp v117, v121 row_ror:8 row_mask:0xf bank_mask:0x3
	v_mov_b32_e32 v118, v134
	v_mov_b32_e32 v119, v135
	v_mov_b32_e32 v120, v168
	v_mov_b32_e32 v121, v169
	s_nop 1
	v_permlane32_swap_b32_e32 v118, v114
	v_permlane32_swap_b32_e32 v119, v115
	v_permlane32_swap_b32_e32 v120, v116
	v_permlane32_swap_b32_e32 v121, v117
	v_permlane16_swap_b32_e32 v118, v114
	v_permlane16_swap_b32_e32 v119, v115
	v_permlane16_swap_b32_e32 v120, v116
	v_permlane16_swap_b32_e32 v121, v117
	v_add_f32_e32 v122, v122, v123
	v_cvt_pk_bf16_f32 v118, v118, v119
	v_cvt_pk_bf16_f32 v119, v120, v121
	v_cvt_pk_bf16_f32 v120, v114, v115
	v_mov_b32_e32 v114, v0
	v_add_f32_e32 v122, v127, v122
	s_nop 0
	v_permlane16_swap_b32_e32 v0, v114
	s_or_b32 s2, s40, 2
	v_add_f32_e32 v114, v0, v114
	v_mov_b32_e32 v0, v122
	s_ashr_i32 s3, s2, 31
	s_nop 0
	v_permlane16_swap_b32_e32 v122, v0
	s_lshl_b64 s[40:41], s[2:3], 15
	v_add_f32_e32 v115, v122, v0
	v_mov_b32_e32 v135, v133
	v_mov_b32_e32 v134, v132
	v_mov_b32_e32 v177, v175
	v_mov_b32_e32 v176, v174
	v_mov_b32_e32 v169, v167
	v_mov_b32_e32 v168, v166
	v_cvt_pk_bf16_f32 v121, v116, v117
	s_add_u32 s42, s16, s40
	v_mov_b32_e32 v116, v114
	v_mov_b32_e32 v117, v115
	v_permlane32_swap_b32_e32 v133, v135
	v_permlane32_swap_b32_e32 v132, v134
	v_permlane32_swap_b32_e32 v175, v177
	v_permlane32_swap_b32_e32 v174, v176
	v_permlane32_swap_b32_e32 v167, v169
	v_permlane32_swap_b32_e32 v166, v168
	s_addc_u32 s43, s17, s41
	v_permlane32_swap_b32_e32 v114, v116
	v_permlane32_swap_b32_e32 v115, v117
	global_store_dwordx4 v159, v[118:121], s[42:43]
	s_and_saveexec_b64 s[26:27], s[44:45]
	s_cbranch_execz .LBB0_374
	v_pk_add_f32 v[114:115], v[114:115], v[116:117]
	v_lshl_add_u64 v[116:117], s[30:31], 0, v[130:131]
	v_lshl_add_u64 v[116:117], s[24:25], 2, v[116:117]
	global_store_dwordx2 v[116:117], v[114:115], off
; __device__ __forceinline__ size_t blk_off(int r, int c, int K) { return (size_t)(r >> 8) * 256 * K + (size_t)(c >> 6) * (256 * 64) + (size_t)((r & 255) * 64 + (c & 63)); }
; __device__ __forceinline__ u32x4 pack8(const f32x4 a, const f32x4 b) { u32x4 w; w.x = cvt_pk_bf16(a[0], a[1]); w.y = cvt_pk_bf16(a[2], a[3]); w.z = cvt_pk_bf16(b[0], b[1]); w.w = cvt_pk_bf16(b[2], b[3]); return w; }
;     __device__ __forceinline__ void operator()(const f32x4 (&acc)[2][2][4][2], const pg8::Unit& u, int wr, int wc, int fr, int fq) const {
;     ...
;             for (int m = 0; m < 4; ++m) { const int row = row0 + ai * 128 + m * 16; const float mu = mu4[m], rs = rs4[m];
;                 f32x4 yv[2][2], gq[2][2], bq_[2][2];
; #pragma unroll
;                 for (int bj = 0; bj < 2; ++bj)
; #pragma unroll
;                     for (int n = 0; n < 2; ++n) { yv[bj][n] = *(const f32x4*)(Yin + (size_t)row * D_ + col0 + bj * 128 + 4 * n); gq[bj][n] = *(const f32x4*)(g + col0 + bj * 128 + 4 * n); bq_[bj][n] = *(const f32x4*)(b + col0 + bj * 128 + 4 * n); }
;                 asm volatile("" ::: "memory");
;                 float s1 = 0.f, s2 = 0.f;
; #pragma unroll
;                 for (int bj = 0; bj < 2; ++bj) { float* yp = Y + (size_t)row * D_ + col0 + bj * 128; f32x4 v[2];
; #pragma unroll
;                     for (int n = 0; n < 2; ++n) { v[n] = (((yv[bj][n] - mu) * rs) * gq[bj][n] + bq_[bj][n]) * ALPHA_ + acc[ai][bj][m][n] * sc;
;                         *(f32x4*)(yp + 4 * n) = v[n]; s1 += (v[n][0] + v[n][1]) + (v[n][2] + v[n][3]); s2 += (v[n][0] * v[n][0] + v[n][1] * v[n][1]) + (v[n][2] * v[n][2] + v[n][3] * v[n][3]); }
;                     *(u32x4*)(Yb + blk_off(row, col0 + bj * 128, D_)) = pack8(v[0], v[1]); }
.LBB0_374:
	s_or_b64 exec, exec, s[26:27]
	v_pk_add_f32 v[114:115], v[132:133], v[134:135]
	s_mov_b32 s2, 0x3a800000
	v_pk_mul_f32 v[178:179], v[114:115], s[2:3] op_sel_hi:[1,0]
	s_mov_b32 s2, 0x800000
	v_fma_f32 v0, -v179, v179, v178
	v_max_f32_e32 v0, 0, v0
	v_add_f32_e32 v0, 0x3727c5ac, v0
	v_cmp_gt_f32_e32 vcc, s2, v0
	v_mul_f32_e32 v114, 0x4b800000, v0
	v_lshlrev_b64 v[212:213], 12, v[180:181]
	v_cndmask_b32_e32 v0, v0, v114, vcc
	v_rsq_f32_e32 v0, v0
	v_lshlrev_b32_e32 v159, 6, v180
	s_movk_i32 s2, 0x37c0
	v_mul_f32_e32 v114, 0x45800000, v0
	v_cndmask_b32_e32 v0, v0, v114, vcc
	v_lshl_add_u64 v[114:115], s[12:13], 0, v[212:213]
	v_lshl_add_u64 v[118:119], v[114:115], 0, v[152:153]
	global_load_dwordx4 v[186:189], v[118:119], off offset:16
	global_load_dwordx4 v[190:193], v[118:119], off
	global_load_dwordx4 v[196:199], v[154:155], off offset:16
	global_load_dwordx4 v[200:203], v[154:155], off
	global_load_dwordx4 v[204:207], v[156:157], off offset:16
	global_load_dwordx4 v[208:211], v[156:157], off
	global_load_dwordx4 v[114:117], v[118:119], off offset:528
	global_load_dwordx4 v[134:137], v[118:119], off offset:512
	s_nop 0
	global_load_dwordx4 v[118:121], v[154:155], off offset:528
	global_load_dwordx4 v[126:129], v[154:155], off offset:512
	global_load_dwordx4 v[122:125], v[156:157], off offset:528
	global_load_dwordx4 v[130:133], v[156:157], off offset:512
	v_and_or_b32 v159, v159, s2, v194
	s_load_dwordx16 s[60:75], s[34:35], 0x38
	s_mov_b32 s2, 0x3fd744fd
	v_lshlrev_b32_e32 v159, 1, v159
	s_waitcnt lgkmcnt(0)
	v_lshl_add_u64 v[180:181], s[74:75], 0, v[212:213]
	v_lshl_add_u64 v[180:181], v[180:181], 0, v[152:153]
	s_waitcnt vmcnt(11)
	v_sub_f32_e32 v189, v189, v179
	s_waitcnt vmcnt(10)
	v_sub_f32_e32 v193, v193, v179
	v_sub_f32_e32 v192, v192, v179
	v_sub_f32_e32 v191, v191, v179
	v_sub_f32_e32 v190, v190, v179
	v_pk_mul_f32 v[190:191], v[0:1], v[190:191] op_sel_hi:[0,1]
	v_pk_mul_f32 v[192:193], v[0:1], v[192:193] op_sel_hi:[0,1]
	v_sub_f32_e32 v188, v188, v179
	v_sub_f32_e32 v187, v187, v179
	v_sub_f32_e32 v186, v186, v179
	s_waitcnt vmcnt(6)
	v_pk_fma_f32 v[192:193], v[202:203], v[192:193], v[210:211]
	v_pk_fma_f32 v[190:191], v[200:201], v[190:191], v[208:209]
	v_pk_mul_f32 v[186:187], v[0:1], v[186:187] op_sel_hi:[0,1]
	v_pk_mul_f32 v[188:189], v[0:1], v[188:189] op_sel_hi:[0,1]
	v_pk_mul_f32 v[190:191], v[190:191], s[2:3] op_sel_hi:[1,0]
	v_pk_mul_f32 v[192:193], v[192:193], s[2:3] op_sel_hi:[1,0]
	v_pk_fma_f32 v[188:189], v[198:199], v[188:189], v[206:207]
	v_pk_fma_f32 v[186:187], v[196:197], v[186:187], v[204:205]
	v_pk_fma_f32 v[112:113], v[112:113], 0.5, v[192:193] op_sel_hi:[1,0,1]
	v_pk_fma_f32 v[110:111], v[110:111], 0.5, v[190:191] op_sel_hi:[1,0,1]
	v_pk_mul_f32 v[186:187], v[186:187], s[2:3] op_sel_hi:[1,0]
	v_pk_mul_f32 v[188:189], v[188:189], s[2:3] op_sel_hi:[1,0]
	v_add_f32_e32 v178, v110, v111
	v_add_f32_e32 v190, v112, v113
	v_pk_fma_f32 v[108:109], v[108:109], 0.5, v[188:189] op_sel_hi:[1,0,1]
	v_pk_fma_f32 v[106:107], v[106:107], 0.5, v[186:187] op_sel_hi:[1,0,1]
	v_add_f32_e32 v178, v178, v190
	v_add_f32_e32 v186, v106, v107
	v_add_f32_e32 v187, v108, v109
	v_add_f32_e32 v178, 0, v178
	v_add_f32_e32 v186, v186, v187
	v_mul_f32_e32 v190, v111, v111
	v_mul_f32_e32 v191, v113, v113
	v_add_f32_e32 v178, v178, v186
	v_mul_f32_e32 v186, v107, v107
	v_mul_f32_e32 v187, v109, v109
	s_nop 0
	v_fmac_f32_e32 v190, v110, v110
	v_fmac_f32_e32 v191, v112, v112
	s_nop 1
	v_bfe_u32 v189, v227, 4, 2
	v_sub_u32_e32 v188, 0, v189
	v_lshlrev_b32_e32 v188, 4, v188
	v_ashrrev_i32_e32 v189, 31, v188
	v_lshl_add_u64 v[188:189], v[180:181], 0, v[188:189]
	v_permlane16_swap_b32_e32 v110, v106
	v_permlane16_swap_b32_e32 v111, v107
	v_permlane16_swap_b32_e32 v112, v108
	v_permlane16_swap_b32_e32 v113, v109
	v_permlane32_swap_b32_e32 v110, v106
	v_permlane32_swap_b32_e32 v111, v107
	v_permlane32_swap_b32_e32 v112, v108
	v_permlane32_swap_b32_e32 v113, v109
	v_mov_b32_e32 v195, v110
	v_mov_b32_e32 v196, v111
	v_mov_b32_e32 v197, v112
	v_mov_b32_e32 v198, v113
	v_bfe_u32 v192, v227, 3, 1
	v_mul_i32_i24_e32 v192, 0xffff8040, v192
	v_ashrrev_i32_e32 v193, 31, v192
	v_lshl_add_u64 v[188:189], v[188:189], 0, v[192:193]
	v_mov_b32_e32 v192, 0x8000
	v_mov_b32_e32 v193, 0
	v_lshl_add_u64 v[192:193], v[188:189], 0, v[192:193]
	v_mov_b32_dpp v110, v106 row_ror:8 row_mask:0xf bank_mask:0xc
	v_mov_b32_dpp v111, v107 row_ror:8 row_mask:0xf bank_mask:0xc
	v_mov_b32_dpp v112, v108 row_ror:8 row_mask:0xf bank_mask:0xc
	v_mov_b32_dpp v113, v109 row_ror:8 row_mask:0xf bank_mask:0xc
	v_mov_b32_dpp v106, v195 row_ror:8 row_mask:0xf bank_mask:0x3
	v_mov_b32_dpp v107, v196 row_ror:8 row_mask:0xf bank_mask:0x3
	v_mov_b32_dpp v108, v197 row_ror:8 row_mask:0xf bank_mask:0x3
	v_mov_b32_dpp v109, v198 row_ror:8 row_mask:0xf bank_mask:0x3
	global_store_dwordx4 v[188:189], v[110:113], off nt
	global_store_dwordx4 v[192:193], v[106:109], off nt
	s_nop 1
	v_mov_b32_dpp v106, v110 row_ror:8 row_mask:0xf bank_mask:0x3
	v_mov_b32_dpp v107, v111 row_ror:8 row_mask:0xf bank_mask:0x3
	v_mov_b32_dpp v108, v112 row_ror:8 row_mask:0xf bank_mask:0x3
	v_mov_b32_dpp v109, v113 row_ror:8 row_mask:0xf bank_mask:0x3
	v_mov_b32_e32 v110, v195
	v_mov_b32_e32 v111, v196
	v_mov_b32_e32 v112, v197
	v_mov_b32_e32 v113, v198
	s_nop 1
	v_permlane32_swap_b32_e32 v110, v106
	v_permlane32_swap_b32_e32 v111, v107
	v_permlane32_swap_b32_e32 v112, v108
	v_permlane32_swap_b32_e32 v113, v109
	v_permlane16_swap_b32_e32 v110, v106
	v_permlane16_swap_b32_e32 v111, v107
	v_permlane16_swap_b32_e32 v112, v108
	v_permlane16_swap_b32_e32 v113, v109
	v_fmac_f32_e32 v186, v106, v106
	v_fmac_f32_e32 v187, v108, v108
	v_cvt_pk_bf16_f32 v110, v110, v111
	v_cvt_pk_bf16_f32 v111, v112, v113
	v_cvt_pk_bf16_f32 v112, v106, v107
	v_cvt_pk_bf16_f32 v113, v108, v109
	s_waitcnt vmcnt(6)
; __device__ __forceinline__ float xsum16(float v) { const auto r = __builtin_amdgcn_permlane16_swap(__float_as_uint(v), __float_as_uint(v), false, false); return __uint_as_float(r[0]) + __uint_as_float(r[1]); }
; __device__ __forceinline__ float xsum32(float v) { const auto r = __builtin_amdgcn_permlane32_swap(__float_as_uint(v), __float_as_uint(v), false, false); return __uint_as_float(r[0]) + __uint_as_float(r[1]); }
; __device__ __forceinline__ size_t blk_off(int r, int c, int K) { return (size_t)(r >> 8) * 256 * K + (size_t)(c >> 6) * (256 * 64) + (size_t)((r & 255) * 64 + (c & 63)); }
; __device__ __forceinline__ u32x4 pack8(const f32x4 a, const f32x4 b) { u32x4 w; w.x = cvt_pk_bf16(a[0], a[1]); w.y = cvt_pk_bf16(a[2], a[3]); w.z = cvt_pk_bf16(b[0], b[1]); w.w = cvt_pk_bf16(b[2], b[3]); return w; }
;     __device__ __forceinline__ void operator()(const f32x4 (&acc)[2][2][4][2], const pg8::Unit& u, int wr, int wc, int fr, int fq) const {
;     ...
;                 for (int bj = 0; bj < 2; ++bj) { float* yp = Y + (size_t)row * D_ + col0 + bj * 128; f32x4 v[2];
; #pragma unroll
;                     for (int n = 0; n < 2; ++n) { v[n] = (((yv[bj][n] - mu) * rs) * gq[bj][n] + bq_[bj][n]) * ALPHA_ + acc[ai][bj][m][n] * sc;
;                         *(f32x4*)(yp + 4 * n) = v[n]; s1 += (v[n][0] + v[n][1]) + (v[n][2] + v[n][3]); s2 += (v[n][0] * v[n][0] + v[n][1] * v[n][1]) + (v[n][2] * v[n][2] + v[n][3] * v[n][3]); }
;                     *(u32x4*)(Yb + blk_off(row, col0 + bj * 128, D_)) = pack8(v[0], v[1]); }
;                 s1 = xsum32(xsum16(s1)); s2 = xsum32(xsum16(s2));
;                 if (fq == 0) *(f32x2*)(stn + (size_t)row * 32 + (u.pn * 4 + wc) * 2) = (f32x2){s1, s2}; asm volatile("" ::: "memory"); } }
	v_sub_f32_e32 v107, v137, v179
	v_sub_f32_e32 v106, v136, v179
	v_sub_f32_e32 v109, v135, v179
	v_sub_f32_e32 v108, v134, v179
	v_pk_mul_f32 v[108:109], v[0:1], v[108:109] op_sel_hi:[0,1]
	v_pk_mul_f32 v[106:107], v[0:1], v[106:107] op_sel_hi:[0,1]
	s_waitcnt vmcnt(2)
	v_pk_fma_f32 v[106:107], v[128:129], v[106:107], v[132:133]
	v_pk_fma_f32 v[108:109], v[126:127], v[108:109], v[130:131]
	v_pk_mul_f32 v[106:107], v[106:107], s[2:3] op_sel_hi:[1,0]
	v_pk_mul_f32 v[108:109], v[108:109], s[2:3] op_sel_hi:[1,0]
	v_pk_fma_f32 v[104:105], v[104:105], 0.5, v[106:107] op_sel_hi:[1,0,1]
	v_pk_fma_f32 v[102:103], v[102:103], 0.5, v[108:109] op_sel_hi:[1,0,1]
	v_add_f32_e32 v107, v104, v105
	v_add_f32_e32 v106, v102, v103
	v_add_f32_e32 v106, v106, v107
	global_store_dwordx4 v159, v[110:113], s[50:51]
	v_mul_f32_e32 v107, v105, v105
	v_add_f32_e32 v190, v190, v191
	v_add_f32_e32 v110, v178, v106
	v_mul_f32_e32 v106, v103, v103
	v_add_f32_e32 v186, v186, v187
	v_fmac_f32_e32 v106, v102, v102
	v_fmac_f32_e32 v107, v104, v104
	v_add_f32_e32 v186, v190, v186
	v_add_f32_e32 v106, v106, v107
	v_add_f32_e32 v111, v186, v106
	v_sub_f32_e32 v107, v117, v179
	v_sub_f32_e32 v106, v116, v179
	v_sub_f32_e32 v109, v115, v179
	v_sub_f32_e32 v108, v114, v179
	v_pk_mul_f32 v[108:109], v[0:1], v[108:109] op_sel_hi:[0,1]
	v_pk_mul_f32 v[106:107], v[0:1], v[106:107] op_sel_hi:[0,1]
	v_pk_fma_f32 v[106:107], v[120:121], v[106:107], v[124:125]
	v_pk_fma_f32 v[108:109], v[118:119], v[108:109], v[122:123]
	v_pk_mul_f32 v[106:107], v[106:107], s[2:3] op_sel_hi:[1,0]
	v_pk_mul_f32 v[108:109], v[108:109], s[2:3] op_sel_hi:[1,0]
	v_pk_fma_f32 v[100:101], v[100:101], 0.5, v[106:107] op_sel_hi:[1,0,1]
	v_pk_fma_f32 v[98:99], v[98:99], 0.5, v[108:109] op_sel_hi:[1,0,1]
	v_add_f32_e32 v106, v100, v101
	v_add_f32_e32 v0, v98, v99
	v_add_f32_e32 v0, v0, v106
	v_mul_f32_e32 v106, v99, v99
	v_mul_f32_e32 v107, v101, v101
	v_add_f32_e32 v0, v110, v0
	v_fmac_f32_e32 v106, v98, v98
	v_fmac_f32_e32 v107, v100, v100
	s_nop 0
	s_nop 1
	v_bfe_u32 v109, v227, 4, 2
	v_sub_u32_e32 v108, 0, v109
	v_lshlrev_b32_e32 v108, 4, v108
	v_ashrrev_i32_e32 v109, 31, v108
	v_lshl_add_u64 v[108:109], v[180:181], 0, v[108:109]
	v_permlane16_swap_b32_e32 v102, v98
	v_permlane16_swap_b32_e32 v103, v99
	v_permlane16_swap_b32_e32 v104, v100
	v_permlane16_swap_b32_e32 v105, v101
	v_permlane32_swap_b32_e32 v102, v98
	v_permlane32_swap_b32_e32 v103, v99
	v_permlane32_swap_b32_e32 v104, v100
	v_permlane32_swap_b32_e32 v105, v101
	v_mov_b32_e32 v114, v102
	v_mov_b32_e32 v115, v103
	v_mov_b32_e32 v116, v104
	v_mov_b32_e32 v117, v105
	v_bfe_u32 v112, v227, 3, 1
	v_mul_i32_i24_e32 v112, 0xffff8040, v112
	v_ashrrev_i32_e32 v113, 31, v112
	v_lshl_add_u64 v[108:109], v[108:109], 0, v[112:113]
	v_mov_b32_e32 v112, 0x8000
	v_mov_b32_e32 v113, 0
	v_lshl_add_u64 v[112:113], v[108:109], 0, v[112:113]
	v_mov_b32_dpp v102, v98 row_ror:8 row_mask:0xf bank_mask:0xc
	v_mov_b32_dpp v103, v99 row_ror:8 row_mask:0xf bank_mask:0xc
	v_mov_b32_dpp v104, v100 row_ror:8 row_mask:0xf bank_mask:0xc
	v_mov_b32_dpp v105, v101 row_ror:8 row_mask:0xf bank_mask:0xc
	v_mov_b32_dpp v98, v114 row_ror:8 row_mask:0xf bank_mask:0x3
	v_mov_b32_dpp v99, v115 row_ror:8 row_mask:0xf bank_mask:0x3
	v_mov_b32_dpp v100, v116 row_ror:8 row_mask:0xf bank_mask:0x3
	v_mov_b32_dpp v101, v117 row_ror:8 row_mask:0xf bank_mask:0x3
	global_store_dwordx4 v[108:109], v[102:105], off offset:512 nt
	global_store_dwordx4 v[112:113], v[98:101], off offset:512 nt
	s_nop 1
	v_mov_b32_dpp v98, v102 row_ror:8 row_mask:0xf bank_mask:0x3
	v_mov_b32_dpp v99, v103 row_ror:8 row_mask:0xf bank_mask:0x3
	v_mov_b32_dpp v100, v104 row_ror:8 row_mask:0xf bank_mask:0x3
	v_mov_b32_dpp v101, v105 row_ror:8 row_mask:0xf bank_mask:0x3
	v_mov_b32_e32 v102, v114
	v_mov_b32_e32 v103, v115
	v_mov_b32_e32 v104, v116
	v_mov_b32_e32 v105, v117
	s_nop 1
	v_permlane32_swap_b32_e32 v102, v98
	v_permlane32_swap_b32_e32 v103, v99
	v_permlane32_swap_b32_e32 v104, v100
	v_permlane32_swap_b32_e32 v105, v101
	v_permlane16_swap_b32_e32 v102, v98
	v_permlane16_swap_b32_e32 v103, v99
	v_permlane16_swap_b32_e32 v104, v100
	v_permlane16_swap_b32_e32 v105, v101
	v_add_f32_e32 v106, v106, v107
	v_cvt_pk_bf16_f32 v102, v102, v103
	v_cvt_pk_bf16_f32 v103, v104, v105
	v_cvt_pk_bf16_f32 v104, v98, v99
	v_mov_b32_e32 v98, v0
	v_add_f32_e32 v106, v111, v106
	s_nop 0
	v_permlane16_swap_b32_e32 v0, v98
	v_add_f32_e32 v98, v0, v98
	v_mov_b32_e32 v0, v106
	s_nop 1
	v_permlane16_swap_b32_e32 v106, v0
	v_add_f32_e32 v99, v106, v0
	v_cvt_pk_bf16_f32 v105, v100, v101
	v_mov_b32_e32 v100, v98
	v_mov_b32_e32 v101, v99
	s_nop 0
	v_permlane32_swap_b32_e32 v98, v100
	v_permlane32_swap_b32_e32 v99, v101
	global_store_dwordx4 v159, v[102:105], s[42:43]
	s_and_saveexec_b64 s[26:27], s[44:45]
	s_cbranch_execz .LBB0_376
	v_pk_add_f32 v[98:99], v[98:99], v[100:101]
	v_lshl_add_u64 v[100:101], s[30:31], 0, v[172:173]
	v_lshl_add_u64 v[100:101], s[24:25], 2, v[100:101]
	global_store_dwordx2 v[100:101], v[98:99], off
; __device__ __forceinline__ size_t blk_off(int r, int c, int K) { return (size_t)(r >> 8) * 256 * K + (size_t)(c >> 6) * (256 * 64) + (size_t)((r & 255) * 64 + (c & 63)); }
; __device__ __forceinline__ u32x4 pack8(const f32x4 a, const f32x4 b) { u32x4 w; w.x = cvt_pk_bf16(a[0], a[1]); w.y = cvt_pk_bf16(a[2], a[3]); w.z = cvt_pk_bf16(b[0], b[1]); w.w = cvt_pk_bf16(b[2], b[3]); return w; }
;     __device__ __forceinline__ void operator()(const f32x4 (&acc)[2][2][4][2], const pg8::Unit& u, int wr, int wc, int fr, int fq) const {
;     ...
;             for (int m = 0; m < 4; ++m) { const int row = row0 + ai * 128 + m * 16; const float mu = mu4[m], rs = rs4[m];
;                 f32x4 yv[2][2], gq[2][2], bq_[2][2];
; #pragma unroll
;                 for (int bj = 0; bj < 2; ++bj)
; #pragma unroll
;                     for (int n = 0; n < 2; ++n) { yv[bj][n] = *(const f32x4*)(Yin + (size_t)row * D_ + col0 + bj * 128 + 4 * n); gq[bj][n] = *(const f32x4*)(g + col0 + bj * 128 + 4 * n); bq_[bj][n] = *(const f32x4*)(b + col0 + bj * 128 + 4 * n); }
;                 asm volatile("" ::: "memory");
;                 float s1 = 0.f, s2 = 0.f;
; #pragma unroll
;                 for (int bj = 0; bj < 2; ++bj) { float* yp = Y + (size_t)row * D_ + col0 + bj * 128; f32x4 v[2];
; #pragma unroll
;                     for (int n = 0; n < 2; ++n) { v[n] = (((yv[bj][n] - mu) * rs) * gq[bj][n] + bq_[bj][n]) * ALPHA_ + acc[ai][bj][m][n] * sc;
;                         *(f32x4*)(yp + 4 * n) = v[n]; s1 += (v[n][0] + v[n][1]) + (v[n][2] + v[n][3]); s2 += (v[n][0] * v[n][0] + v[n][1] * v[n][1]) + (v[n][2] * v[n][2] + v[n][3] * v[n][3]); }
;                     *(u32x4*)(Yb + blk_off(row, col0 + bj * 128, D_)) = pack8(v[0], v[1]); }
.LBB0_376:
	s_or_b64 exec, exec, s[26:27]
	v_pk_add_f32 v[98:99], v[174:175], v[176:177]
	s_mov_b32 s2, 0x3a800000
	v_pk_mul_f32 v[122:123], v[98:99], s[2:3] op_sel_hi:[1,0]
	s_mov_b32 s2, 0x800000
	v_fma_f32 v0, -v123, v123, v122
	v_max_f32_e32 v0, 0, v0
	v_add_f32_e32 v0, 0x3727c5ac, v0
	v_cmp_gt_f32_e32 vcc, s2, v0
	v_mul_f32_e32 v98, 0x4b800000, v0
	v_lshlrev_b64 v[124:125], 12, v[170:171]
	v_cndmask_b32_e32 v0, v0, v98, vcc
	v_rsq_f32_e32 v0, v0
	s_load_dwordx16 s[60:75], s[34:35], 0x38
	v_lshlrev_b32_e32 v122, 6, v170
	v_mul_f32_e32 v98, 0x45800000, v0
	v_cndmask_b32_e32 v0, v0, v98, vcc
	v_lshl_add_u64 v[98:99], s[12:13], 0, v[124:125]
	v_lshl_add_u64 v[102:103], v[98:99], 0, v[152:153]
	global_load_dwordx4 v[126:129], v[102:103], off offset:16
	global_load_dwordx4 v[130:133], v[102:103], off
	global_load_dwordx4 v[134:137], v[154:155], off offset:16
	global_load_dwordx4 v[172:175], v[154:155], off
	global_load_dwordx4 v[176:179], v[156:157], off offset:16
	global_load_dwordx4 v[186:189], v[156:157], off
	global_load_dwordx4 v[98:101], v[102:103], off offset:528
	global_load_dwordx4 v[118:121], v[102:103], off offset:512
	s_nop 0
	global_load_dwordx4 v[102:105], v[154:155], off offset:528
	global_load_dwordx4 v[110:113], v[154:155], off offset:512
	global_load_dwordx4 v[106:109], v[156:157], off offset:528
	global_load_dwordx4 v[114:117], v[156:157], off offset:512
	s_movk_i32 s2, 0x3bc0
	v_and_or_b32 v122, v122, s2, v194
	s_mov_b32 s2, 0x3fd744fd
	s_waitcnt lgkmcnt(0)
	v_lshl_add_u64 v[124:125], s[74:75], 0, v[124:125]
	v_lshl_add_u64 v[124:125], v[124:125], 0, v[152:153]
	v_lshlrev_b32_e32 v122, 1, v122
	s_waitcnt vmcnt(11)
	v_sub_f32_e32 v129, v129, v123
	s_waitcnt vmcnt(10)
	v_sub_f32_e32 v133, v133, v123
	v_sub_f32_e32 v132, v132, v123
	v_sub_f32_e32 v131, v131, v123
	v_sub_f32_e32 v130, v130, v123
	v_sub_f32_e32 v128, v128, v123
	v_sub_f32_e32 v127, v127, v123
	v_sub_f32_e32 v126, v126, v123
	v_pk_mul_f32 v[130:131], v[0:1], v[130:131] op_sel_hi:[0,1]
	v_pk_mul_f32 v[132:133], v[0:1], v[132:133] op_sel_hi:[0,1]
	v_pk_mul_f32 v[126:127], v[0:1], v[126:127] op_sel_hi:[0,1]
	v_pk_mul_f32 v[128:129], v[0:1], v[128:129] op_sel_hi:[0,1]
	s_waitcnt vmcnt(6)
	v_pk_fma_f32 v[132:133], v[174:175], v[132:133], v[188:189]
	v_pk_fma_f32 v[130:131], v[172:173], v[130:131], v[186:187]
	v_pk_fma_f32 v[128:129], v[136:137], v[128:129], v[178:179]
	v_pk_fma_f32 v[126:127], v[134:135], v[126:127], v[176:177]
	v_pk_mul_f32 v[130:131], v[130:131], s[2:3] op_sel_hi:[1,0]
	v_pk_mul_f32 v[132:133], v[132:133], s[2:3] op_sel_hi:[1,0]
	v_pk_mul_f32 v[126:127], v[126:127], s[2:3] op_sel_hi:[1,0]
	v_pk_mul_f32 v[128:129], v[128:129], s[2:3] op_sel_hi:[1,0]
	v_pk_fma_f32 v[96:97], v[96:97], 0.5, v[132:133] op_sel_hi:[1,0,1]
	v_pk_fma_f32 v[94:95], v[94:95], 0.5, v[130:131] op_sel_hi:[1,0,1]
	v_pk_fma_f32 v[92:93], v[92:93], 0.5, v[128:129] op_sel_hi:[1,0,1]
	v_pk_fma_f32 v[90:91], v[90:91], 0.5, v[126:127] op_sel_hi:[1,0,1]
	v_add_f32_e32 v130, v94, v95
	v_add_f32_e32 v131, v96, v97
	v_add_f32_e32 v126, v90, v91
	v_add_f32_e32 v127, v92, v93
	v_add_f32_e32 v130, v130, v131
	v_mul_f32_e32 v131, v95, v95
	v_mul_f32_e32 v132, v97, v97
	v_add_f32_e32 v126, v126, v127
	v_mul_f32_e32 v127, v91, v91
	v_mul_f32_e32 v128, v93, v93
	s_nop 0
	v_fmac_f32_e32 v131, v94, v94
	v_fmac_f32_e32 v132, v96, v96
	s_nop 1
	v_bfe_u32 v135, v227, 4, 2
	v_sub_u32_e32 v134, 0, v135
	v_lshlrev_b32_e32 v134, 4, v134
	v_ashrrev_i32_e32 v135, 31, v134
	v_lshl_add_u64 v[134:135], v[124:125], 0, v[134:135]
	v_permlane16_swap_b32_e32 v94, v90
	v_permlane16_swap_b32_e32 v95, v91
	v_permlane16_swap_b32_e32 v96, v92
	v_permlane16_swap_b32_e32 v97, v93
	v_permlane32_swap_b32_e32 v94, v90
	v_permlane32_swap_b32_e32 v95, v91
	v_permlane32_swap_b32_e32 v96, v92
	v_permlane32_swap_b32_e32 v97, v93
	v_mov_b32_e32 v129, v94
	v_mov_b32_e32 v133, v95
	v_mov_b32_e32 v159, v96
	v_mov_b32_e32 v170, v97
	v_bfe_u32 v136, v227, 3, 1
	v_mul_i32_i24_e32 v136, 0xffff8040, v136
	v_ashrrev_i32_e32 v137, 31, v136
	v_lshl_add_u64 v[134:135], v[134:135], 0, v[136:137]
	v_mov_b32_e32 v136, 0x8000
	v_mov_b32_e32 v137, 0
	v_lshl_add_u64 v[136:137], v[134:135], 0, v[136:137]
	v_mov_b32_dpp v94, v90 row_ror:8 row_mask:0xf bank_mask:0xc
	v_mov_b32_dpp v95, v91 row_ror:8 row_mask:0xf bank_mask:0xc
	v_mov_b32_dpp v96, v92 row_ror:8 row_mask:0xf bank_mask:0xc
	v_mov_b32_dpp v97, v93 row_ror:8 row_mask:0xf bank_mask:0xc
	v_mov_b32_dpp v90, v129 row_ror:8 row_mask:0xf bank_mask:0x3
	v_mov_b32_dpp v91, v133 row_ror:8 row_mask:0xf bank_mask:0x3
	v_mov_b32_dpp v92, v159 row_ror:8 row_mask:0xf bank_mask:0x3
	v_mov_b32_dpp v93, v170 row_ror:8 row_mask:0xf bank_mask:0x3
	global_store_dwordx4 v[134:135], v[94:97], off nt
	global_store_dwordx4 v[136:137], v[90:93], off nt
	s_nop 1
	v_mov_b32_dpp v90, v94 row_ror:8 row_mask:0xf bank_mask:0x3
	v_mov_b32_dpp v91, v95 row_ror:8 row_mask:0xf bank_mask:0x3
	v_mov_b32_dpp v92, v96 row_ror:8 row_mask:0xf bank_mask:0x3
	v_mov_b32_dpp v93, v97 row_ror:8 row_mask:0xf bank_mask:0x3
	v_mov_b32_e32 v94, v129
	v_mov_b32_e32 v95, v133
	v_mov_b32_e32 v96, v159
	v_mov_b32_e32 v97, v170
	s_nop 1
	v_permlane32_swap_b32_e32 v94, v90
	v_permlane32_swap_b32_e32 v95, v91
	v_permlane32_swap_b32_e32 v96, v92
	v_permlane32_swap_b32_e32 v97, v93
	v_permlane16_swap_b32_e32 v94, v90
	v_permlane16_swap_b32_e32 v95, v91
	v_permlane16_swap_b32_e32 v96, v92
	v_permlane16_swap_b32_e32 v97, v93
	v_fmac_f32_e32 v127, v90, v90
	v_fmac_f32_e32 v128, v92, v92
	v_cvt_pk_bf16_f32 v94, v94, v95
	v_cvt_pk_bf16_f32 v95, v96, v97
	v_cvt_pk_bf16_f32 v96, v90, v91
	v_cvt_pk_bf16_f32 v97, v92, v93
	s_waitcnt vmcnt(6)
; __device__ __forceinline__ float xsum16(float v) { const auto r = __builtin_amdgcn_permlane16_swap(__float_as_uint(v), __float_as_uint(v), false, false); return __uint_as_float(r[0]) + __uint_as_float(r[1]); }
; __device__ __forceinline__ float xsum32(float v) { const auto r = __builtin_amdgcn_permlane32_swap(__float_as_uint(v), __float_as_uint(v), false, false); return __uint_as_float(r[0]) + __uint_as_float(r[1]); }
; __device__ __forceinline__ size_t blk_off(int r, int c, int K) { return (size_t)(r >> 8) * 256 * K + (size_t)(c >> 6) * (256 * 64) + (size_t)((r & 255) * 64 + (c & 63)); }
; __device__ __forceinline__ u32x4 pack8(const f32x4 a, const f32x4 b) { u32x4 w; w.x = cvt_pk_bf16(a[0], a[1]); w.y = cvt_pk_bf16(a[2], a[3]); w.z = cvt_pk_bf16(b[0], b[1]); w.w = cvt_pk_bf16(b[2], b[3]); return w; }
;     __device__ __forceinline__ void operator()(const f32x4 (&acc)[2][2][4][2], const pg8::Unit& u, int wr, int wc, int fr, int fq) const {
;     ...
;                 for (int bj = 0; bj < 2; ++bj) { float* yp = Y + (size_t)row * D_ + col0 + bj * 128; f32x4 v[2];
; #pragma unroll
;                     for (int n = 0; n < 2; ++n) { v[n] = (((yv[bj][n] - mu) * rs) * gq[bj][n] + bq_[bj][n]) * ALPHA_ + acc[ai][bj][m][n] * sc;
;                         *(f32x4*)(yp + 4 * n) = v[n]; s1 += (v[n][0] + v[n][1]) + (v[n][2] + v[n][3]); s2 += (v[n][0] * v[n][0] + v[n][1] * v[n][1]) + (v[n][2] * v[n][2] + v[n][3] * v[n][3]); }
;                     *(u32x4*)(Yb + blk_off(row, col0 + bj * 128, D_)) = pack8(v[0], v[1]); }
;                 s1 = xsum32(xsum16(s1)); s2 = xsum32(xsum16(s2));
;                 if (fq == 0) *(f32x2*)(stn + (size_t)row * 32 + (u.pn * 4 + wc) * 2) = (f32x2){s1, s2}; asm volatile("" ::: "memory"); } }
	v_sub_f32_e32 v91, v121, v123
	v_sub_f32_e32 v90, v120, v123
	v_sub_f32_e32 v93, v119, v123
	v_sub_f32_e32 v92, v118, v123
	v_pk_mul_f32 v[92:93], v[0:1], v[92:93] op_sel_hi:[0,1]
	v_pk_mul_f32 v[90:91], v[0:1], v[90:91] op_sel_hi:[0,1]
	s_waitcnt vmcnt(2)
	v_pk_fma_f32 v[90:91], v[112:113], v[90:91], v[116:117]
	v_pk_fma_f32 v[92:93], v[110:111], v[92:93], v[114:115]
	v_pk_mul_f32 v[90:91], v[90:91], s[2:3] op_sel_hi:[1,0]
	v_pk_mul_f32 v[92:93], v[92:93], s[2:3] op_sel_hi:[1,0]
	v_pk_fma_f32 v[88:89], v[88:89], 0.5, v[90:91] op_sel_hi:[1,0,1]
	v_pk_fma_f32 v[86:87], v[86:87], 0.5, v[92:93] op_sel_hi:[1,0,1]
	v_add_f32_e32 v130, 0, v130
	v_add_f32_e32 v90, v86, v87
	v_add_f32_e32 v91, v88, v89
	v_add_f32_e32 v126, v130, v126
	v_add_f32_e32 v90, v90, v91
	global_store_dwordx4 v122, v[94:97], s[50:51]
	v_mul_f32_e32 v91, v89, v89
	v_add_f32_e32 v131, v131, v132
	v_add_f32_e32 v94, v126, v90
	v_mul_f32_e32 v90, v87, v87
	v_add_f32_e32 v127, v127, v128
	v_fmac_f32_e32 v90, v86, v86
	v_fmac_f32_e32 v91, v88, v88
	v_add_f32_e32 v127, v131, v127
	v_add_f32_e32 v90, v90, v91
	v_add_f32_e32 v95, v127, v90
	v_sub_f32_e32 v91, v101, v123
	v_sub_f32_e32 v90, v100, v123
	v_sub_f32_e32 v93, v99, v123
	v_sub_f32_e32 v92, v98, v123
	v_pk_mul_f32 v[92:93], v[0:1], v[92:93] op_sel_hi:[0,1]
	v_pk_mul_f32 v[90:91], v[0:1], v[90:91] op_sel_hi:[0,1]
	v_pk_fma_f32 v[90:91], v[104:105], v[90:91], v[108:109]
	v_pk_fma_f32 v[92:93], v[102:103], v[92:93], v[106:107]
	v_pk_mul_f32 v[90:91], v[90:91], s[2:3] op_sel_hi:[1,0]
	v_pk_mul_f32 v[92:93], v[92:93], s[2:3] op_sel_hi:[1,0]
	v_pk_fma_f32 v[84:85], v[84:85], 0.5, v[90:91] op_sel_hi:[1,0,1]
	v_pk_fma_f32 v[82:83], v[82:83], 0.5, v[92:93] op_sel_hi:[1,0,1]
	v_add_f32_e32 v90, v84, v85
	v_add_f32_e32 v0, v82, v83
	v_add_f32_e32 v0, v0, v90
	v_mul_f32_e32 v90, v83, v83
	v_mul_f32_e32 v91, v85, v85
	v_add_f32_e32 v0, v94, v0
	v_fmac_f32_e32 v90, v82, v82
	v_fmac_f32_e32 v91, v84, v84
	s_nop 0
	s_nop 1
	v_bfe_u32 v93, v227, 4, 2
	v_sub_u32_e32 v92, 0, v93
	v_lshlrev_b32_e32 v92, 4, v92
	v_ashrrev_i32_e32 v93, 31, v92
	v_lshl_add_u64 v[92:93], v[124:125], 0, v[92:93]
	v_permlane16_swap_b32_e32 v86, v82
	v_permlane16_swap_b32_e32 v87, v83
	v_permlane16_swap_b32_e32 v88, v84
	v_permlane16_swap_b32_e32 v89, v85
	v_permlane32_swap_b32_e32 v86, v82
	v_permlane32_swap_b32_e32 v87, v83
	v_permlane32_swap_b32_e32 v88, v84
	v_permlane32_swap_b32_e32 v89, v85
	v_mov_b32_e32 v98, v86
	v_mov_b32_e32 v99, v87
	v_mov_b32_e32 v100, v88
	v_mov_b32_e32 v101, v89
	v_bfe_u32 v96, v227, 3, 1
	v_mul_i32_i24_e32 v96, 0xffff8040, v96
	v_ashrrev_i32_e32 v97, 31, v96
	v_lshl_add_u64 v[92:93], v[92:93], 0, v[96:97]
	v_mov_b32_e32 v96, 0x8000
	v_mov_b32_e32 v97, 0
	v_lshl_add_u64 v[96:97], v[92:93], 0, v[96:97]
	v_mov_b32_dpp v86, v82 row_ror:8 row_mask:0xf bank_mask:0xc
	v_mov_b32_dpp v87, v83 row_ror:8 row_mask:0xf bank_mask:0xc
	v_mov_b32_dpp v88, v84 row_ror:8 row_mask:0xf bank_mask:0xc
	v_mov_b32_dpp v89, v85 row_ror:8 row_mask:0xf bank_mask:0xc
	v_mov_b32_dpp v82, v98 row_ror:8 row_mask:0xf bank_mask:0x3
	v_mov_b32_dpp v83, v99 row_ror:8 row_mask:0xf bank_mask:0x3
	v_mov_b32_dpp v84, v100 row_ror:8 row_mask:0xf bank_mask:0x3
	v_mov_b32_dpp v85, v101 row_ror:8 row_mask:0xf bank_mask:0x3
	global_store_dwordx4 v[92:93], v[86:89], off offset:512 nt
	global_store_dwordx4 v[96:97], v[82:85], off offset:512 nt
	s_nop 1
	v_mov_b32_dpp v82, v86 row_ror:8 row_mask:0xf bank_mask:0x3
	v_mov_b32_dpp v83, v87 row_ror:8 row_mask:0xf bank_mask:0x3
	v_mov_b32_dpp v84, v88 row_ror:8 row_mask:0xf bank_mask:0x3
	v_mov_b32_dpp v85, v89 row_ror:8 row_mask:0xf bank_mask:0x3
	v_mov_b32_e32 v86, v98
	v_mov_b32_e32 v87, v99
	v_mov_b32_e32 v88, v100
	v_mov_b32_e32 v89, v101
	s_nop 1
	v_permlane32_swap_b32_e32 v86, v82
	v_permlane32_swap_b32_e32 v87, v83
	v_permlane32_swap_b32_e32 v88, v84
	v_permlane32_swap_b32_e32 v89, v85
	v_permlane16_swap_b32_e32 v86, v82
	v_permlane16_swap_b32_e32 v87, v83
	v_permlane16_swap_b32_e32 v88, v84
	v_permlane16_swap_b32_e32 v89, v85
	v_add_f32_e32 v90, v90, v91
	v_cvt_pk_bf16_f32 v86, v86, v87
	v_cvt_pk_bf16_f32 v87, v88, v89
	v_cvt_pk_bf16_f32 v88, v82, v83
	v_mov_b32_e32 v82, v0
	v_add_f32_e32 v90, v95, v90
	s_nop 0
	v_permlane16_swap_b32_e32 v0, v82
	v_add_f32_e32 v82, v0, v82
	v_mov_b32_e32 v0, v90
	s_nop 1
	v_permlane16_swap_b32_e32 v90, v0
	v_add_f32_e32 v83, v90, v0
	v_cvt_pk_bf16_f32 v89, v84, v85
	v_mov_b32_e32 v84, v82
	v_mov_b32_e32 v85, v83
	s_nop 0
	v_permlane32_swap_b32_e32 v82, v84
	v_permlane32_swap_b32_e32 v83, v85
	global_store_dwordx4 v122, v[86:89], s[42:43]
	s_and_saveexec_b64 s[26:27], s[44:45]
	s_cbranch_execz .LBB0_378
	v_pk_add_f32 v[82:83], v[82:83], v[84:85]
	v_lshl_add_u64 v[84:85], s[30:31], 0, v[164:165]
	v_lshl_add_u64 v[84:85], s[24:25], 2, v[84:85]
	global_store_dwordx2 v[84:85], v[82:83], off
; __device__ __forceinline__ size_t blk_off(int r, int c, int K) { return (size_t)(r >> 8) * 256 * K + (size_t)(c >> 6) * (256 * 64) + (size_t)((r & 255) * 64 + (c & 63)); }
; __device__ __forceinline__ u32x4 pack8(const f32x4 a, const f32x4 b) { u32x4 w; w.x = cvt_pk_bf16(a[0], a[1]); w.y = cvt_pk_bf16(a[2], a[3]); w.z = cvt_pk_bf16(b[0], b[1]); w.w = cvt_pk_bf16(b[2], b[3]); return w; }
;     __device__ __forceinline__ void operator()(const f32x4 (&acc)[2][2][4][2], const pg8::Unit& u, int wr, int wc, int fr, int fq) const {
;     ...
;             for (int m = 0; m < 4; ++m) { const int row = row0 + ai * 128 + m * 16; const float mu = mu4[m], rs = rs4[m];
;                 f32x4 yv[2][2], gq[2][2], bq_[2][2];
; #pragma unroll
;                 for (int bj = 0; bj < 2; ++bj)
; #pragma unroll
;                     for (int n = 0; n < 2; ++n) { yv[bj][n] = *(const f32x4*)(Yin + (size_t)row * D_ + col0 + bj * 128 + 4 * n); gq[bj][n] = *(const f32x4*)(g + col0 + bj * 128 + 4 * n); bq_[bj][n] = *(const f32x4*)(b + col0 + bj * 128 + 4 * n); }
;                 asm volatile("" ::: "memory");
;                 float s1 = 0.f, s2 = 0.f;
; #pragma unroll
;                 for (int bj = 0; bj < 2; ++bj) { float* yp = Y + (size_t)row * D_ + col0 + bj * 128; f32x4 v[2];
; #pragma unroll
;                     for (int n = 0; n < 2; ++n) { v[n] = (((yv[bj][n] - mu) * rs) * gq[bj][n] + bq_[bj][n]) * ALPHA_ + acc[ai][bj][m][n] * sc;
;                         *(f32x4*)(yp + 4 * n) = v[n]; s1 += (v[n][0] + v[n][1]) + (v[n][2] + v[n][3]); s2 += (v[n][0] * v[n][0] + v[n][1] * v[n][1]) + (v[n][2] * v[n][2] + v[n][3] * v[n][3]); }
;                     *(u32x4*)(Yb + blk_off(row, col0 + bj * 128, D_)) = pack8(v[0], v[1]); }
.LBB0_378:
	s_or_b64 exec, exec, s[26:27]
	v_pk_add_f32 v[82:83], v[166:167], v[168:169]
	s_mov_b32 s2, 0x3a800000
	v_pk_mul_f32 v[106:107], v[82:83], s[2:3] op_sel_hi:[1,0]
	s_mov_b32 s2, 0x800000
	v_fma_f32 v0, -v107, v107, v106
	v_max_f32_e32 v0, 0, v0
	v_add_f32_e32 v0, 0x3727c5ac, v0
	v_cmp_gt_f32_e32 vcc, s2, v0
	v_mul_f32_e32 v82, 0x4b800000, v0
	v_lshlrev_b64 v[108:109], 12, v[162:163]
	v_cndmask_b32_e32 v0, v0, v82, vcc
	v_rsq_f32_e32 v0, v0
	s_load_dwordx16 s[60:75], s[34:35], 0x38
	v_lshlrev_b32_e32 v106, 6, v162
	v_mul_f32_e32 v82, 0x45800000, v0
	v_cndmask_b32_e32 v0, v0, v82, vcc
	v_lshl_add_u64 v[82:83], s[12:13], 0, v[108:109]
	v_lshl_add_u64 v[86:87], v[82:83], 0, v[152:153]
	global_load_dwordx4 v[110:113], v[86:87], off offset:16
	global_load_dwordx4 v[114:117], v[86:87], off
	global_load_dwordx4 v[118:121], v[154:155], off offset:16
	global_load_dwordx4 v[122:125], v[154:155], off
	global_load_dwordx4 v[126:129], v[156:157], off offset:16
	global_load_dwordx4 v[130:133], v[156:157], off
	global_load_dwordx4 v[82:85], v[86:87], off offset:528
	global_load_dwordx4 v[102:105], v[86:87], off offset:512
	s_nop 0
	global_load_dwordx4 v[86:89], v[154:155], off offset:528
	global_load_dwordx4 v[94:97], v[154:155], off offset:512
	global_load_dwordx4 v[90:93], v[156:157], off offset:528
	global_load_dwordx4 v[98:101], v[156:157], off offset:512
	s_movk_i32 s2, 0x3fc0
	v_and_or_b32 v106, v106, s2, v194
	s_mov_b32 s2, 0x3fd744fd
	s_waitcnt lgkmcnt(0)
	v_lshl_add_u64 v[108:109], s[74:75], 0, v[108:109]
	v_lshl_add_u64 v[108:109], v[108:109], 0, v[152:153]
	v_lshlrev_b32_e32 v106, 1, v106
	s_waitcnt vmcnt(11)
	v_sub_f32_e32 v113, v113, v107
	s_waitcnt vmcnt(10)
	v_sub_f32_e32 v117, v117, v107
	v_sub_f32_e32 v116, v116, v107
	v_sub_f32_e32 v115, v115, v107
	v_sub_f32_e32 v114, v114, v107
	v_sub_f32_e32 v112, v112, v107
	v_sub_f32_e32 v111, v111, v107
	v_sub_f32_e32 v110, v110, v107
	v_pk_mul_f32 v[114:115], v[0:1], v[114:115] op_sel_hi:[0,1]
	v_pk_mul_f32 v[116:117], v[0:1], v[116:117] op_sel_hi:[0,1]
	v_pk_mul_f32 v[110:111], v[0:1], v[110:111] op_sel_hi:[0,1]
	v_pk_mul_f32 v[112:113], v[0:1], v[112:113] op_sel_hi:[0,1]
	s_waitcnt vmcnt(6)
	v_pk_fma_f32 v[116:117], v[124:125], v[116:117], v[132:133]
	v_pk_fma_f32 v[114:115], v[122:123], v[114:115], v[130:131]
	v_pk_fma_f32 v[112:113], v[120:121], v[112:113], v[128:129]
	v_pk_fma_f32 v[110:111], v[118:119], v[110:111], v[126:127]
	v_pk_mul_f32 v[114:115], v[114:115], s[2:3] op_sel_hi:[1,0]
	v_pk_mul_f32 v[116:117], v[116:117], s[2:3] op_sel_hi:[1,0]
	v_pk_mul_f32 v[110:111], v[110:111], s[2:3] op_sel_hi:[1,0]
	v_pk_mul_f32 v[112:113], v[112:113], s[2:3] op_sel_hi:[1,0]
	v_pk_fma_f32 v[80:81], v[80:81], 0.5, v[116:117] op_sel_hi:[1,0,1]
	v_pk_fma_f32 v[78:79], v[78:79], 0.5, v[114:115] op_sel_hi:[1,0,1]
	v_pk_fma_f32 v[76:77], v[76:77], 0.5, v[112:113] op_sel_hi:[1,0,1]
	v_pk_fma_f32 v[74:75], v[74:75], 0.5, v[110:111] op_sel_hi:[1,0,1]
	v_add_f32_e32 v114, v78, v79
	v_add_f32_e32 v115, v80, v81
	v_add_f32_e32 v110, v74, v75
	v_add_f32_e32 v111, v76, v77
	v_add_f32_e32 v114, v114, v115
	v_mul_f32_e32 v115, v79, v79
	v_mul_f32_e32 v116, v81, v81
	v_add_f32_e32 v110, v110, v111
	v_mul_f32_e32 v111, v75, v75
	v_mul_f32_e32 v112, v77, v77
	s_nop 0
	v_fmac_f32_e32 v115, v78, v78
	v_fmac_f32_e32 v116, v80, v80
	s_nop 1
	v_bfe_u32 v119, v227, 4, 2
	v_sub_u32_e32 v118, 0, v119
	v_lshlrev_b32_e32 v118, 4, v118
	v_ashrrev_i32_e32 v119, 31, v118
	v_lshl_add_u64 v[118:119], v[108:109], 0, v[118:119]
	v_permlane16_swap_b32_e32 v78, v74
	v_permlane16_swap_b32_e32 v79, v75
	v_permlane16_swap_b32_e32 v80, v76
	v_permlane16_swap_b32_e32 v81, v77
	v_permlane32_swap_b32_e32 v78, v74
	v_permlane32_swap_b32_e32 v79, v75
	v_permlane32_swap_b32_e32 v80, v76
	v_permlane32_swap_b32_e32 v81, v77
	v_mov_b32_e32 v113, v78
	v_mov_b32_e32 v117, v79
	v_mov_b32_e32 v122, v80
	v_mov_b32_e32 v123, v81
	v_bfe_u32 v120, v227, 3, 1
	v_mul_i32_i24_e32 v120, 0xffff8040, v120
	v_ashrrev_i32_e32 v121, 31, v120
	v_lshl_add_u64 v[118:119], v[118:119], 0, v[120:121]
	v_mov_b32_e32 v120, 0x8000
	v_mov_b32_e32 v121, 0
	v_lshl_add_u64 v[120:121], v[118:119], 0, v[120:121]
	v_mov_b32_dpp v78, v74 row_ror:8 row_mask:0xf bank_mask:0xc
	v_mov_b32_dpp v79, v75 row_ror:8 row_mask:0xf bank_mask:0xc
	v_mov_b32_dpp v80, v76 row_ror:8 row_mask:0xf bank_mask:0xc
	v_mov_b32_dpp v81, v77 row_ror:8 row_mask:0xf bank_mask:0xc
	v_mov_b32_dpp v74, v113 row_ror:8 row_mask:0xf bank_mask:0x3
	v_mov_b32_dpp v75, v117 row_ror:8 row_mask:0xf bank_mask:0x3
	v_mov_b32_dpp v76, v122 row_ror:8 row_mask:0xf bank_mask:0x3
	v_mov_b32_dpp v77, v123 row_ror:8 row_mask:0xf bank_mask:0x3
	global_store_dwordx4 v[118:119], v[78:81], off nt
	global_store_dwordx4 v[120:121], v[74:77], off nt
	s_nop 1
	v_mov_b32_dpp v74, v78 row_ror:8 row_mask:0xf bank_mask:0x3
	v_mov_b32_dpp v75, v79 row_ror:8 row_mask:0xf bank_mask:0x3
	v_mov_b32_dpp v76, v80 row_ror:8 row_mask:0xf bank_mask:0x3
	v_mov_b32_dpp v77, v81 row_ror:8 row_mask:0xf bank_mask:0x3
	v_mov_b32_e32 v78, v113
	v_mov_b32_e32 v79, v117
	v_mov_b32_e32 v80, v122
	v_mov_b32_e32 v81, v123
	s_nop 1
	v_permlane32_swap_b32_e32 v78, v74
	v_permlane32_swap_b32_e32 v79, v75
	v_permlane32_swap_b32_e32 v80, v76
	v_permlane32_swap_b32_e32 v81, v77
	v_permlane16_swap_b32_e32 v78, v74
	v_permlane16_swap_b32_e32 v79, v75
	v_permlane16_swap_b32_e32 v80, v76
	v_permlane16_swap_b32_e32 v81, v77
	v_fmac_f32_e32 v111, v74, v74
	v_fmac_f32_e32 v112, v76, v76
	v_cvt_pk_bf16_f32 v78, v78, v79
	v_cvt_pk_bf16_f32 v79, v80, v81
	v_cvt_pk_bf16_f32 v80, v74, v75
	v_cvt_pk_bf16_f32 v81, v76, v77
	s_waitcnt vmcnt(6)
; __device__ __forceinline__ float xsum16(float v) { const auto r = __builtin_amdgcn_permlane16_swap(__float_as_uint(v), __float_as_uint(v), false, false); return __uint_as_float(r[0]) + __uint_as_float(r[1]); }
; __device__ __forceinline__ float xsum32(float v) { const auto r = __builtin_amdgcn_permlane32_swap(__float_as_uint(v), __float_as_uint(v), false, false); return __uint_as_float(r[0]) + __uint_as_float(r[1]); }
; __device__ __forceinline__ size_t blk_off(int r, int c, int K) { return (size_t)(r >> 8) * 256 * K + (size_t)(c >> 6) * (256 * 64) + (size_t)((r & 255) * 64 + (c & 63)); }
; __device__ __forceinline__ u32x4 pack8(const f32x4 a, const f32x4 b) { u32x4 w; w.x = cvt_pk_bf16(a[0], a[1]); w.y = cvt_pk_bf16(a[2], a[3]); w.z = cvt_pk_bf16(b[0], b[1]); w.w = cvt_pk_bf16(b[2], b[3]); return w; }
;     __device__ __forceinline__ void operator()(const f32x4 (&acc)[2][2][4][2], const pg8::Unit& u, int wr, int wc, int fr, int fq) const {
;     ...
;                 for (int bj = 0; bj < 2; ++bj) { float* yp = Y + (size_t)row * D_ + col0 + bj * 128; f32x4 v[2];
; #pragma unroll
;                     for (int n = 0; n < 2; ++n) { v[n] = (((yv[bj][n] - mu) * rs) * gq[bj][n] + bq_[bj][n]) * ALPHA_ + acc[ai][bj][m][n] * sc;
;                         *(f32x4*)(yp + 4 * n) = v[n]; s1 += (v[n][0] + v[n][1]) + (v[n][2] + v[n][3]); s2 += (v[n][0] * v[n][0] + v[n][1] * v[n][1]) + (v[n][2] * v[n][2] + v[n][3] * v[n][3]); }
;                     *(u32x4*)(Yb + blk_off(row, col0 + bj * 128, D_)) = pack8(v[0], v[1]); }
;                 s1 = xsum32(xsum16(s1)); s2 = xsum32(xsum16(s2));
;                 if (fq == 0) *(f32x2*)(stn + (size_t)row * 32 + (u.pn * 4 + wc) * 2) = (f32x2){s1, s2}; asm volatile("" ::: "memory"); } }
	v_sub_f32_e32 v75, v105, v107
	v_sub_f32_e32 v74, v104, v107
	v_sub_f32_e32 v77, v103, v107
	v_sub_f32_e32 v76, v102, v107
	v_pk_mul_f32 v[76:77], v[0:1], v[76:77] op_sel_hi:[0,1]
	v_pk_mul_f32 v[74:75], v[0:1], v[74:75] op_sel_hi:[0,1]
	s_waitcnt vmcnt(2)
	v_pk_fma_f32 v[74:75], v[96:97], v[74:75], v[100:101]
	v_pk_fma_f32 v[76:77], v[94:95], v[76:77], v[98:99]
	v_pk_mul_f32 v[74:75], v[74:75], s[2:3] op_sel_hi:[1,0]
	v_pk_mul_f32 v[76:77], v[76:77], s[2:3] op_sel_hi:[1,0]
	v_pk_fma_f32 v[72:73], v[72:73], 0.5, v[74:75] op_sel_hi:[1,0,1]
	v_pk_fma_f32 v[70:71], v[70:71], 0.5, v[76:77] op_sel_hi:[1,0,1]
	v_add_f32_e32 v114, 0, v114
	v_add_f32_e32 v74, v70, v71
	v_add_f32_e32 v75, v72, v73
	v_add_f32_e32 v110, v114, v110
	v_add_f32_e32 v74, v74, v75
	global_store_dwordx4 v106, v[78:81], s[50:51]
	v_mul_f32_e32 v75, v73, v73
	v_add_f32_e32 v115, v115, v116
	v_add_f32_e32 v78, v110, v74
	v_mul_f32_e32 v74, v71, v71
	v_add_f32_e32 v111, v111, v112
	v_fmac_f32_e32 v74, v70, v70
	v_fmac_f32_e32 v75, v72, v72
	v_add_f32_e32 v111, v115, v111
	v_add_f32_e32 v74, v74, v75
	v_add_f32_e32 v79, v111, v74
	v_sub_f32_e32 v75, v85, v107
	v_sub_f32_e32 v74, v84, v107
	v_sub_f32_e32 v77, v83, v107
	v_sub_f32_e32 v76, v82, v107
	v_pk_mul_f32 v[76:77], v[0:1], v[76:77] op_sel_hi:[0,1]
	v_pk_mul_f32 v[74:75], v[0:1], v[74:75] op_sel_hi:[0,1]
	v_pk_fma_f32 v[74:75], v[88:89], v[74:75], v[92:93]
	v_pk_fma_f32 v[76:77], v[86:87], v[76:77], v[90:91]
	v_pk_mul_f32 v[74:75], v[74:75], s[2:3] op_sel_hi:[1,0]
	v_pk_mul_f32 v[76:77], v[76:77], s[2:3] op_sel_hi:[1,0]
	v_pk_fma_f32 v[68:69], v[68:69], 0.5, v[74:75] op_sel_hi:[1,0,1]
	v_pk_fma_f32 v[66:67], v[66:67], 0.5, v[76:77] op_sel_hi:[1,0,1]
	v_add_f32_e32 v74, v68, v69
	v_add_f32_e32 v0, v66, v67
	v_add_f32_e32 v0, v0, v74
	v_mul_f32_e32 v74, v67, v67
	v_mul_f32_e32 v75, v69, v69
	v_add_f32_e32 v0, v78, v0
	v_fmac_f32_e32 v74, v66, v66
	v_fmac_f32_e32 v75, v68, v68
	s_nop 0
	s_nop 1
	v_bfe_u32 v77, v227, 4, 2
	v_sub_u32_e32 v76, 0, v77
	v_lshlrev_b32_e32 v76, 4, v76
	v_ashrrev_i32_e32 v77, 31, v76
	v_lshl_add_u64 v[76:77], v[108:109], 0, v[76:77]
	v_permlane16_swap_b32_e32 v70, v66
	v_permlane16_swap_b32_e32 v71, v67
	v_permlane16_swap_b32_e32 v72, v68
	v_permlane16_swap_b32_e32 v73, v69
	v_permlane32_swap_b32_e32 v70, v66
	v_permlane32_swap_b32_e32 v71, v67
	v_permlane32_swap_b32_e32 v72, v68
	v_permlane32_swap_b32_e32 v73, v69
	v_mov_b32_e32 v82, v70
	v_mov_b32_e32 v83, v71
	v_mov_b32_e32 v84, v72
	v_mov_b32_e32 v85, v73
	v_bfe_u32 v80, v227, 3, 1
	v_mul_i32_i24_e32 v80, 0xffff8040, v80
	v_ashrrev_i32_e32 v81, 31, v80
	v_lshl_add_u64 v[76:77], v[76:77], 0, v[80:81]
	v_mov_b32_e32 v80, 0x8000
	v_mov_b32_e32 v81, 0
	v_lshl_add_u64 v[80:81], v[76:77], 0, v[80:81]
	v_mov_b32_dpp v70, v66 row_ror:8 row_mask:0xf bank_mask:0xc
	v_mov_b32_dpp v71, v67 row_ror:8 row_mask:0xf bank_mask:0xc
	v_mov_b32_dpp v72, v68 row_ror:8 row_mask:0xf bank_mask:0xc
	v_mov_b32_dpp v73, v69 row_ror:8 row_mask:0xf bank_mask:0xc
	v_mov_b32_dpp v66, v82 row_ror:8 row_mask:0xf bank_mask:0x3
	v_mov_b32_dpp v67, v83 row_ror:8 row_mask:0xf bank_mask:0x3
	v_mov_b32_dpp v68, v84 row_ror:8 row_mask:0xf bank_mask:0x3
	v_mov_b32_dpp v69, v85 row_ror:8 row_mask:0xf bank_mask:0x3
	global_store_dwordx4 v[76:77], v[70:73], off offset:512 nt
	global_store_dwordx4 v[80:81], v[66:69], off offset:512 nt
	s_nop 1
	v_mov_b32_dpp v66, v70 row_ror:8 row_mask:0xf bank_mask:0x3
	v_mov_b32_dpp v67, v71 row_ror:8 row_mask:0xf bank_mask:0x3
	v_mov_b32_dpp v68, v72 row_ror:8 row_mask:0xf bank_mask:0x3
	v_mov_b32_dpp v69, v73 row_ror:8 row_mask:0xf bank_mask:0x3
	v_mov_b32_e32 v70, v82
	v_mov_b32_e32 v71, v83
	v_mov_b32_e32 v72, v84
	v_mov_b32_e32 v73, v85
	s_nop 1
	v_permlane32_swap_b32_e32 v70, v66
	v_permlane32_swap_b32_e32 v71, v67
	v_permlane32_swap_b32_e32 v72, v68
	v_permlane32_swap_b32_e32 v73, v69
	v_permlane16_swap_b32_e32 v70, v66
	v_permlane16_swap_b32_e32 v71, v67
	v_permlane16_swap_b32_e32 v72, v68
	v_permlane16_swap_b32_e32 v73, v69
	v_add_f32_e32 v74, v74, v75
	v_cvt_pk_bf16_f32 v70, v70, v71
	v_cvt_pk_bf16_f32 v71, v72, v73
	v_cvt_pk_bf16_f32 v72, v66, v67
	v_mov_b32_e32 v66, v0
	v_add_f32_e32 v74, v79, v74
	s_nop 0
	v_permlane16_swap_b32_e32 v0, v66
	v_add_f32_e32 v66, v0, v66
	v_mov_b32_e32 v0, v74
	s_nop 1
	v_permlane16_swap_b32_e32 v74, v0
	v_add_f32_e32 v67, v74, v0
	v_cvt_pk_bf16_f32 v73, v68, v69
	v_mov_b32_e32 v68, v66
	v_mov_b32_e32 v69, v67
	s_nop 0
	v_permlane32_swap_b32_e32 v66, v68
	v_permlane32_swap_b32_e32 v67, v69
	global_store_dwordx4 v106, v[70:73], s[42:43]
	s_and_saveexec_b64 s[26:27], s[44:45]
	s_cbranch_execz .LBB0_380
	v_pk_add_f32 v[66:67], v[66:67], v[68:69]
	v_lshl_add_u64 v[68:69], s[30:31], 0, v[160:161]
	v_lshl_add_u64 v[68:69], s[24:25], 2, v[68:69]
	global_store_dwordx2 v[68:69], v[66:67], off
; __device__ __forceinline__ float xsum16(float v) { const auto r = __builtin_amdgcn_permlane16_swap(__float_as_uint(v), __float_as_uint(v), false, false); return __uint_as_float(r[0]) + __uint_as_float(r[1]); }
; __device__ __forceinline__ float xsum32(float v) { const auto r = __builtin_amdgcn_permlane32_swap(__float_as_uint(v), __float_as_uint(v), false, false); return __uint_as_float(r[0]) + __uint_as_float(r[1]); }
; __device__ __forceinline__ void row_stats4(const float* st, int rowb, int fq, float (&mu)[4], float (&rs)[4]) {
;     f32x4 a[4], b[4];
; #pragma unroll
;     for (int m = 0; m < 4; ++m) { const f32x4* p = (const f32x4*)(st + (size_t)(rowb + m * 16) * 32 + fq * 8); a[m] = p[0]; b[m] = p[1]; }
; #pragma unroll
;     for (int m = 0; m < 4; ++m) { float s1 = (a[m][0] + a[m][2]) + (b[m][0] + b[m][2]), s2 = (a[m][1] + a[m][3]) + (b[m][1] + b[m][3]);
;         s1 = xsum32(xsum16(s1)); s2 = xsum32(xsum16(s2));
;         const float mm = s1 * (1.0f / 1024.0f); mu[m] = mm; rs[m] = rsqrtf(fmaxf(s2 * (1.0f / 1024.0f) - mm * mm, 0.f) + LN_EPS_); }
;     asm volatile("" ::: "memory");
; }
;     __device__ __forceinline__ void operator()(const f32x4 (&acc)[2][2][4][2], const pg8::Unit& u, int wr, int wc, int fr, int fq) const {
;     ...
;         for (int ai = 0; ai < 2; ++ai) { float mu4[4], rs4[4]; row_stats4(stp, row0 + ai * 128, fq, mu4, rs4);
; #pragma unroll
;             for (int m = 0; m < 4; ++m) { const int row = row0 + ai * 128 + m * 16; const float mu = mu4[m], rs = rs4[m];
;                 f32x4 yv[2][2], gq[2][2], bq_[2][2];
; #pragma unroll
;                 for (int bj = 0; bj < 2; ++bj)
; #pragma unroll
;                     for (int n = 0; n < 2; ++n) { yv[bj][n] = *(const f32x4*)(Yin + (size_t)row * D_ + col0 + bj * 128 + 4 * n); gq[bj][n] = *(const f32x4*)(g + col0 + bj * 128 + 4 * n); bq_[bj][n] = *(const f32x4*)(b + col0 + bj * 128 + 4 * n); }
;                 asm volatile("" ::: "memory");
;                 float s1 = 0.f, s2 = 0.f;
; #pragma unroll
;                 for (int bj = 0; bj < 2; ++bj) { float* yp = Y + (size_t)row * D_ + col0 + bj * 128; f32x4 v[2];
; #pragma unroll
;                     for (int n = 0; n < 2; ++n) { v[n] = (((yv[bj][n] - mu) * rs) * gq[bj][n] + bq_[bj][n]) * ALPHA_ + acc[ai][bj][m][n] * sc;
.LBB0_380:
	s_or_b64 exec, exec, s[26:27]
	v_add_u32_e32 v68, 0x80, v158
	v_ashrrev_i32_e32 v69, 31, v68
	v_add_u32_e32 v94, 0x90, v158
	v_lshlrev_b64 v[66:67], 7, v[68:69]
	v_ashrrev_i32_e32 v95, 31, v94
	v_lshl_add_u64 v[74:75], v[146:147], 0, v[66:67]
	v_lshlrev_b64 v[86:87], 7, v[94:95]
	v_add_u32_e32 v76, 0xa0, v158
	global_load_dwordx4 v[70:73], v[74:75], off
	global_load_dwordx4 v[78:81], v[74:75], off offset:16
	v_lshl_add_u64 v[74:75], v[146:147], 0, v[86:87]
	v_ashrrev_i32_e32 v77, 31, v76
	global_load_dwordx4 v[82:85], v[74:75], off
	global_load_dwordx4 v[88:91], v[74:75], off offset:16
	v_lshlrev_b64 v[74:75], 7, v[76:77]
	v_lshl_add_u64 v[74:75], v[146:147], 0, v[74:75]
	global_load_dwordx4 v[96:99], v[74:75], off
	global_load_dwordx4 v[100:103], v[74:75], off offset:16
	v_add_u32_e32 v74, 0xb0, v158
	v_ashrrev_i32_e32 v75, 31, v74
	v_lshlrev_b64 v[92:93], 7, v[74:75]
	v_lshl_add_u64 v[92:93], v[146:147], 0, v[92:93]
	global_load_dwordx4 v[104:107], v[92:93], off
	global_load_dwordx4 v[108:111], v[92:93], off offset:16
	v_lshlrev_b64 v[136:137], 12, v[68:69]
	v_lshl_add_u64 v[112:113], s[12:13], 0, v[136:137]
	v_lshl_add_u64 v[92:93], v[112:113], 0, v[152:153]
	global_load_dwordx4 v[112:115], v[92:93], off offset:16
	global_load_dwordx4 v[116:119], v[92:93], off
	global_load_dwordx4 v[120:123], v[154:155], off offset:16
	global_load_dwordx4 v[124:127], v[154:155], off
	global_load_dwordx4 v[128:131], v[156:157], off offset:16
	global_load_dwordx4 v[132:135], v[156:157], off
	s_mov_b32 s2, 0x3a800000
	s_mov_b32 s16, 0x3fd744fd
	s_load_dwordx16 s[60:75], s[34:35], 0x38
	s_waitcnt vmcnt(13)
	v_mov_b32_e32 v158, v70
	s_waitcnt vmcnt(12)
	v_mov_b32_e32 v159, v78
	v_mov_b32_e32 v160, v72
	v_mov_b32_e32 v161, v80
	v_mov_b32_e32 v78, v71
	v_mov_b32_e32 v80, v73
	s_waitcnt vmcnt(11)
	v_mov_b32_e32 v70, v82
	s_waitcnt vmcnt(10)
	v_mov_b32_e32 v71, v88
	v_mov_b32_e32 v72, v84
	v_mov_b32_e32 v73, v90
	v_mov_b32_e32 v88, v83
	v_mov_b32_e32 v90, v85
	s_waitcnt vmcnt(9)
	v_mov_b32_e32 v82, v96
	s_waitcnt vmcnt(8)
	v_mov_b32_e32 v83, v100
	v_mov_b32_e32 v84, v98
	v_mov_b32_e32 v85, v102
	v_mov_b32_e32 v100, v97
	v_pk_add_f32 v[96:97], v[158:159], v[160:161]
	v_pk_add_f32 v[78:79], v[78:79], v[80:81]
	v_pk_add_f32 v[80:81], v[82:83], v[84:85]
	v_pk_add_f32 v[84:85], v[96:97], v[96:97] op_sel:[0,1] op_sel_hi:[1,0]
	v_pk_add_f32 v[78:79], v[78:79], v[78:79] op_sel:[0,1] op_sel_hi:[1,0]
	v_mov_b32_e32 v0, v84
	v_mov_b32_e32 v69, v78
	s_nop 0
	v_permlane16_swap_b32_e32 v84, v0
	v_permlane16_swap_b32_e32 v78, v69
	v_add_f32_e32 v79, v84, v0
	v_add_f32_e32 v78, v78, v69
	v_mov_b32_e32 v85, v79
	v_mov_b32_e32 v84, v78
	s_nop 0
	v_permlane32_swap_b32_e32 v79, v85
	v_permlane32_swap_b32_e32 v78, v84
	v_pk_add_f32 v[78:79], v[78:79], v[84:85]
	v_mov_b32_e32 v102, v99
	v_pk_mul_f32 v[78:79], v[78:79], s[2:3] op_sel_hi:[1,0]
	s_mov_b32 s2, 0x800000
	v_fma_f32 v0, -v79, v79, v78
	v_max_f32_e32 v0, 0, v0
	v_add_f32_e32 v0, 0x3727c5ac, v0
	v_mul_f32_e32 v69, 0x4b800000, v0
	v_cmp_gt_f32_e32 vcc, s2, v0
	v_pk_add_f32 v[82:83], v[100:101], v[102:103]
	v_pk_add_f32 v[80:81], v[80:81], v[80:81] op_sel:[0,1] op_sel_hi:[1,0]
	v_cndmask_b32_e32 v0, v0, v69, vcc
	v_rsq_f32_e32 v0, v0
	v_pk_add_f32 v[82:83], v[82:83], v[82:83] op_sel:[0,1] op_sel_hi:[1,0]
	v_mov_b32_e32 v81, v80
	s_nop 1
	v_permlane16_swap_b32_e32 v80, v81
	v_mul_f32_e32 v69, 0x45800000, v0
	v_cndmask_b32_e32 v78, v0, v69, vcc
	v_mov_b32_e32 v0, v82
	s_nop 1
	v_permlane16_swap_b32_e32 v82, v0
	global_load_dwordx4 v[96:99], v[92:93], off offset:528
	global_load_dwordx4 v[100:103], v[92:93], off offset:512
	v_pk_add_f32 v[70:71], v[70:71], v[72:73]
	v_pk_add_f32 v[72:73], v[88:89], v[90:91]
	v_add_f32_e32 v89, v80, v81
	v_add_f32_e32 v88, v82, v0
	s_waitcnt vmcnt(9)
	v_mov_b32_e32 v80, v104
	s_waitcnt vmcnt(8)
	v_mov_b32_e32 v81, v108
	v_mov_b32_e32 v82, v106
	v_mov_b32_e32 v83, v110
	v_mov_b32_e32 v108, v105
	v_mov_b32_e32 v110, v107
	v_pk_add_f32 v[80:81], v[80:81], v[82:83]
	v_pk_add_f32 v[82:83], v[108:109], v[110:111]
	global_load_dwordx4 v[104:107], v[154:155], off offset:528
	global_load_dwordx4 v[108:111], v[154:155], off offset:512
	global_load_dwordx4 v[158:161], v[156:157], off offset:528
	global_load_dwordx4 v[162:165], v[156:157], off offset:512
	s_waitcnt vmcnt(10)
	v_sub_f32_e32 v93, v119, v79
	v_sub_f32_e32 v92, v118, v79
	v_sub_f32_e32 v117, v117, v79
	v_sub_f32_e32 v116, v116, v79
	v_pk_mul_f32 v[116:117], v[78:79], v[116:117] op_sel_hi:[0,1]
	v_pk_mul_f32 v[92:93], v[78:79], v[92:93] op_sel_hi:[0,1]
	s_waitcnt vmcnt(6)
	v_pk_fma_f32 v[92:93], v[126:127], v[92:93], v[134:135]
	v_pk_fma_f32 v[116:117], v[124:125], v[116:117], v[132:133]
	v_pk_mul_f32 v[92:93], v[92:93], s[16:17] op_sel_hi:[1,0]
	v_pk_mul_f32 v[116:117], v[116:117], s[16:17] op_sel_hi:[1,0]
	v_pk_fma_f32 v[64:65], v[64:65], 0.5, v[92:93] op_sel_hi:[1,0,1]
	v_pk_fma_f32 v[62:63], v[62:63], 0.5, v[116:117] op_sel_hi:[1,0,1]
	v_add_f32_e32 v93, v64, v65
	v_add_f32_e32 v92, v62, v63
	v_add_f32_e32 v92, v92, v93
	v_add_f32_e32 v116, 0, v92
	v_mul_f32_e32 v92, v63, v63
	v_mul_f32_e32 v93, v65, v65
	v_pk_add_f32 v[80:81], v[80:81], v[80:81] op_sel:[0,1] op_sel_hi:[1,0]
	v_fmac_f32_e32 v92, v62, v62
	v_fmac_f32_e32 v93, v64, v64
	v_mov_b32_e32 v0, v80
	v_add_f32_e32 v117, v92, v93
	v_sub_f32_e32 v93, v115, v79
	v_sub_f32_e32 v92, v114, v79
	v_sub_f32_e32 v113, v113, v79
	v_sub_f32_e32 v112, v112, v79
	v_pk_add_f32 v[82:83], v[82:83], v[82:83] op_sel:[0,1] op_sel_hi:[1,0]
	v_permlane16_swap_b32_e32 v80, v0
	v_pk_mul_f32 v[112:113], v[78:79], v[112:113] op_sel_hi:[0,1]
	v_pk_mul_f32 v[92:93], v[78:79], v[92:93] op_sel_hi:[0,1]
	v_add_f32_e32 v83, v80, v0
	v_mov_b32_e32 v0, v82
	v_pk_fma_f32 v[92:93], v[122:123], v[92:93], v[130:131]
	v_pk_fma_f32 v[112:113], v[120:121], v[112:113], v[128:129]
	v_permlane16_swap_b32_e32 v82, v0
	v_pk_mul_f32 v[112:113], v[112:113], s[16:17] op_sel_hi:[1,0]
	v_pk_mul_f32 v[92:93], v[92:93], s[16:17] op_sel_hi:[1,0]
	v_add_f32_e32 v82, v82, v0
	v_ashrrev_i32_e32 v80, 8, v68
	v_lshlrev_b32_e32 v0, 6, v68
	s_movk_i32 s2, 0x33c0
	v_pk_fma_f32 v[60:61], v[60:61], 0.5, v[92:93] op_sel_hi:[1,0,1]
	v_pk_fma_f32 v[58:59], v[58:59], 0.5, v[112:113] op_sel_hi:[1,0,1]
	v_ashrrev_i32_e32 v81, 31, v80
	v_and_or_b32 v0, v0, s2, v194
	s_waitcnt lgkmcnt(0)
; __device__ __forceinline__ size_t blk_off(int r, int c, int K) { return (size_t)(r >> 8) * 256 * K + (size_t)(c >> 6) * (256 * 64) + (size_t)((r & 255) * 64 + (c & 63)); }
; __device__ __forceinline__ u32x4 pack8(const f32x4 a, const f32x4 b) { u32x4 w; w.x = cvt_pk_bf16(a[0], a[1]); w.y = cvt_pk_bf16(a[2], a[3]); w.z = cvt_pk_bf16(b[0], b[1]); w.w = cvt_pk_bf16(b[2], b[3]); return w; }
;     __device__ __forceinline__ void operator()(const f32x4 (&acc)[2][2][4][2], const pg8::Unit& u, int wr, int wc, int fr, int fq) const {
;     ...
;                 for (int bj = 0; bj < 2; ++bj) { float* yp = Y + (size_t)row * D_ + col0 + bj * 128; f32x4 v[2];
; #pragma unroll
;                     for (int n = 0; n < 2; ++n) { v[n] = (((yv[bj][n] - mu) * rs) * gq[bj][n] + bq_[bj][n]) * ALPHA_ + acc[ai][bj][m][n] * sc;
;                         *(f32x4*)(yp + 4 * n) = v[n]; s1 += (v[n][0] + v[n][1]) + (v[n][2] + v[n][3]); s2 += (v[n][0] * v[n][0] + v[n][1] * v[n][1]) + (v[n][2] * v[n][2] + v[n][3] * v[n][3]); }
;                     *(u32x4*)(Yb + blk_off(row, col0 + bj * 128, D_)) = pack8(v[0], v[1]); }
	v_lshl_add_u64 v[68:69], s[74:75], 0, v[136:137]
	v_add_f32_e32 v92, v58, v59
	v_add_f32_e32 v93, v60, v61
	v_readlane_b32 s2, v253, 59
	v_lshlrev_b64 v[80:81], 19, v[80:81]
	v_lshl_add_u64 v[68:69], v[68:69], 0, v[152:153]
	v_add_f32_e32 v92, v92, v93
	v_mul_f32_e32 v93, v59, v59
	v_readlane_b32 s3, v253, 60
	s_nop 0
	s_nop 1
	v_bfe_u32 v85, v227, 4, 2
	v_sub_u32_e32 v84, 0, v85
	v_lshlrev_b32_e32 v84, 4, v84
	v_ashrrev_i32_e32 v85, 31, v84
	v_lshl_add_u64 v[84:85], v[68:69], 0, v[84:85]
	v_permlane16_swap_b32_e32 v62, v58
	v_permlane16_swap_b32_e32 v63, v59
	v_permlane16_swap_b32_e32 v64, v60
	v_permlane16_swap_b32_e32 v65, v61
	v_permlane32_swap_b32_e32 v62, v58
	v_permlane32_swap_b32_e32 v63, v59
	v_permlane32_swap_b32_e32 v64, v60
	v_permlane32_swap_b32_e32 v65, v61
	v_mov_b32_e32 v112, v62
	v_mov_b32_e32 v113, v63
	v_mov_b32_e32 v114, v64
	v_mov_b32_e32 v115, v65
	v_bfe_u32 v90, v227, 3, 1
	v_mul_i32_i24_e32 v90, 0xffff8040, v90
	v_ashrrev_i32_e32 v91, 31, v90
	v_lshl_add_u64 v[84:85], v[84:85], 0, v[90:91]
	v_mov_b32_e32 v90, 0x8000
	v_mov_b32_e32 v91, 0
	v_lshl_add_u64 v[90:91], v[84:85], 0, v[90:91]
	v_mov_b32_dpp v62, v58 row_ror:8 row_mask:0xf bank_mask:0xc
	v_mov_b32_dpp v63, v59 row_ror:8 row_mask:0xf bank_mask:0xc
	v_mov_b32_dpp v64, v60 row_ror:8 row_mask:0xf bank_mask:0xc
	v_mov_b32_dpp v65, v61 row_ror:8 row_mask:0xf bank_mask:0xc
	v_mov_b32_dpp v58, v112 row_ror:8 row_mask:0xf bank_mask:0x3
	v_mov_b32_dpp v59, v113 row_ror:8 row_mask:0xf bank_mask:0x3
	v_mov_b32_dpp v60, v114 row_ror:8 row_mask:0xf bank_mask:0x3
	v_mov_b32_dpp v61, v115 row_ror:8 row_mask:0xf bank_mask:0x3
	global_store_dwordx4 v[84:85], v[62:65], off nt
	global_store_dwordx4 v[90:91], v[58:61], off nt
	s_nop 1
	v_mov_b32_dpp v58, v62 row_ror:8 row_mask:0xf bank_mask:0x3
	v_mov_b32_dpp v59, v63 row_ror:8 row_mask:0xf bank_mask:0x3
	v_mov_b32_dpp v60, v64 row_ror:8 row_mask:0xf bank_mask:0x3
	v_mov_b32_dpp v61, v65 row_ror:8 row_mask:0xf bank_mask:0x3
	v_mov_b32_e32 v62, v112
	v_mov_b32_e32 v63, v113
	v_mov_b32_e32 v64, v114
	v_mov_b32_e32 v65, v115
	s_nop 1
	v_permlane32_swap_b32_e32 v62, v58
	v_permlane32_swap_b32_e32 v63, v59
	v_permlane32_swap_b32_e32 v64, v60
	v_permlane32_swap_b32_e32 v65, v61
	v_permlane16_swap_b32_e32 v62, v58
	v_permlane16_swap_b32_e32 v63, v59
	v_permlane16_swap_b32_e32 v64, v60
	v_permlane16_swap_b32_e32 v65, v61
	v_fmac_f32_e32 v93, v58, v58
	v_cvt_pk_bf16_f32 v62, v62, v63
	v_cvt_pk_bf16_f32 v63, v64, v65
	v_cvt_pk_bf16_f32 v64, v58, v59
	v_lshl_add_u64 v[58:59], s[2:3], 0, v[80:81]
	v_mul_f32_e32 v112, v61, v61
	v_lshl_add_u64 v[80:81], v[58:59], 0, s[28:29]
	v_lshlrev_b32_e32 v0, 1, v0
	v_fmac_f32_e32 v112, v60, v60
	v_cvt_pk_bf16_f32 v65, v60, v61
	v_lshl_add_u64 v[60:61], v[80:81], 0, v[0:1]
	global_store_dwordx4 v[60:61], v[62:65], off
	s_waitcnt vmcnt(7)
	v_sub_f32_e32 v61, v103, v79
	v_sub_f32_e32 v60, v102, v79
	v_sub_f32_e32 v63, v101, v79
	v_sub_f32_e32 v62, v100, v79
	v_pk_mul_f32 v[62:63], v[78:79], v[62:63] op_sel_hi:[0,1]
	v_pk_mul_f32 v[60:61], v[78:79], v[60:61] op_sel_hi:[0,1]
	v_add_f32_e32 v92, v116, v92
	s_waitcnt vmcnt(3)
	v_pk_fma_f32 v[60:61], v[110:111], v[60:61], v[164:165]
	v_pk_fma_f32 v[62:63], v[108:109], v[62:63], v[162:163]
	v_pk_mul_f32 v[60:61], v[60:61], s[16:17] op_sel_hi:[1,0]
	v_pk_mul_f32 v[62:63], v[62:63], s[16:17] op_sel_hi:[1,0]
	v_pk_fma_f32 v[56:57], v[56:57], 0.5, v[60:61] op_sel_hi:[1,0,1]
	v_pk_fma_f32 v[54:55], v[54:55], 0.5, v[62:63] op_sel_hi:[1,0,1]
	v_add_f32_e32 v61, v56, v57
	v_add_f32_e32 v60, v54, v55
	v_add_f32_e32 v60, v60, v61
	v_add_f32_e32 v64, v92, v60
	v_mul_f32_e32 v60, v55, v55
	v_mul_f32_e32 v61, v57, v57
	v_add_f32_e32 v93, v93, v112
	v_fmac_f32_e32 v60, v54, v54
	v_fmac_f32_e32 v61, v56, v56
	v_add_f32_e32 v93, v117, v93
	v_add_f32_e32 v60, v60, v61
	v_add_f32_e32 v65, v93, v60
	v_sub_f32_e32 v61, v99, v79
	v_sub_f32_e32 v60, v98, v79
	v_sub_f32_e32 v63, v97, v79
	v_sub_f32_e32 v62, v96, v79
	v_pk_mul_f32 v[62:63], v[78:79], v[62:63] op_sel_hi:[0,1]
	v_pk_mul_f32 v[60:61], v[78:79], v[60:61] op_sel_hi:[0,1]
	v_pk_fma_f32 v[60:61], v[106:107], v[60:61], v[160:161]
	v_pk_fma_f32 v[62:63], v[104:105], v[62:63], v[158:159]
	v_pk_mul_f32 v[60:61], v[60:61], s[16:17] op_sel_hi:[1,0]
	v_pk_mul_f32 v[62:63], v[62:63], s[16:17] op_sel_hi:[1,0]
	v_pk_fma_f32 v[52:53], v[52:53], 0.5, v[60:61] op_sel_hi:[1,0,1]
	v_pk_fma_f32 v[50:51], v[50:51], 0.5, v[62:63] op_sel_hi:[1,0,1]
	v_add_f32_e32 v61, v52, v53
	v_add_f32_e32 v60, v50, v51
	v_add_f32_e32 v60, v60, v61
	v_mul_f32_e32 v61, v51, v51
	v_mul_f32_e32 v62, v53, v53
	v_add_f32_e32 v60, v64, v60
	v_fmac_f32_e32 v61, v50, v50
	v_fmac_f32_e32 v62, v52, v52
	v_lshl_add_u64 v[78:79], v[58:59], 0, s[40:41]
	s_nop 0
	s_nop 1
	v_bfe_u32 v85, v227, 4, 2
	v_sub_u32_e32 v84, 0, v85
	v_lshlrev_b32_e32 v84, 4, v84
	v_ashrrev_i32_e32 v85, 31, v84
	v_lshl_add_u64 v[84:85], v[68:69], 0, v[84:85]
	v_permlane16_swap_b32_e32 v54, v50
	v_permlane16_swap_b32_e32 v55, v51
	v_permlane16_swap_b32_e32 v56, v52
	v_permlane16_swap_b32_e32 v57, v53
	v_permlane32_swap_b32_e32 v54, v50
	v_permlane32_swap_b32_e32 v55, v51
	v_permlane32_swap_b32_e32 v56, v52
	v_permlane32_swap_b32_e32 v57, v53
	v_mov_b32_e32 v63, v54
	v_mov_b32_e32 v64, v55
	v_mov_b32_e32 v92, v56
	v_mov_b32_e32 v93, v57
	v_bfe_u32 v90, v227, 3, 1
	v_mul_i32_i24_e32 v90, 0xffff8040, v90
	v_ashrrev_i32_e32 v91, 31, v90
	v_lshl_add_u64 v[84:85], v[84:85], 0, v[90:91]
	v_mov_b32_e32 v90, 0x8000
	v_mov_b32_e32 v91, 0
	v_lshl_add_u64 v[90:91], v[84:85], 0, v[90:91]
	v_mov_b32_dpp v54, v50 row_ror:8 row_mask:0xf bank_mask:0xc
	v_mov_b32_dpp v55, v51 row_ror:8 row_mask:0xf bank_mask:0xc
; __device__ __forceinline__ float xsum16(float v) { const auto r = __builtin_amdgcn_permlane16_swap(__float_as_uint(v), __float_as_uint(v), false, false); return __uint_as_float(r[0]) + __uint_as_float(r[1]); }
; __device__ __forceinline__ float xsum32(float v) { const auto r = __builtin_amdgcn_permlane32_swap(__float_as_uint(v), __float_as_uint(v), false, false); return __uint_as_float(r[0]) + __uint_as_float(r[1]); }
; __device__ __forceinline__ size_t blk_off(int r, int c, int K) { return (size_t)(r >> 8) * 256 * K + (size_t)(c >> 6) * (256 * 64) + (size_t)((r & 255) * 64 + (c & 63)); }
; __device__ __forceinline__ u32x4 pack8(const f32x4 a, const f32x4 b) { u32x4 w; w.x = cvt_pk_bf16(a[0], a[1]); w.y = cvt_pk_bf16(a[2], a[3]); w.z = cvt_pk_bf16(b[0], b[1]); w.w = cvt_pk_bf16(b[2], b[3]); return w; }
;     __device__ __forceinline__ void operator()(const f32x4 (&acc)[2][2][4][2], const pg8::Unit& u, int wr, int wc, int fr, int fq) const {
;     ...
;             for (int m = 0; m < 4; ++m) { const int row = row0 + ai * 128 + m * 16; const float mu = mu4[m], rs = rs4[m];
;                 f32x4 yv[2][2], gq[2][2], bq_[2][2];
; #pragma unroll
;                 for (int bj = 0; bj < 2; ++bj)
; #pragma unroll
;                     for (int n = 0; n < 2; ++n) { yv[bj][n] = *(const f32x4*)(Yin + (size_t)row * D_ + col0 + bj * 128 + 4 * n); gq[bj][n] = *(const f32x4*)(g + col0 + bj * 128 + 4 * n); bq_[bj][n] = *(const f32x4*)(b + col0 + bj * 128 + 4 * n); }
;     ...
;                 for (int bj = 0; bj < 2; ++bj) { float* yp = Y + (size_t)row * D_ + col0 + bj * 128; f32x4 v[2];
; #pragma unroll
;                     for (int n = 0; n < 2; ++n) { v[n] = (((yv[bj][n] - mu) * rs) * gq[bj][n] + bq_[bj][n]) * ALPHA_ + acc[ai][bj][m][n] * sc;
;                         *(f32x4*)(yp + 4 * n) = v[n]; s1 += (v[n][0] + v[n][1]) + (v[n][2] + v[n][3]); s2 += (v[n][0] * v[n][0] + v[n][1] * v[n][1]) + (v[n][2] * v[n][2] + v[n][3] * v[n][3]); }
;                     *(u32x4*)(Yb + blk_off(row, col0 + bj * 128, D_)) = pack8(v[0], v[1]); }
;                 s1 = xsum32(xsum16(s1)); s2 = xsum32(xsum16(s2));
;                 if (fq == 0) *(f32x2*)(stn + (size_t)row * 32 + (u.pn * 4 + wc) * 2) = (f32x2){s1, s2}; asm volatile("" ::: "memory"); } }
	v_mov_b32_dpp v56, v52 row_ror:8 row_mask:0xf bank_mask:0xc
	v_mov_b32_dpp v57, v53 row_ror:8 row_mask:0xf bank_mask:0xc
	v_mov_b32_dpp v50, v63 row_ror:8 row_mask:0xf bank_mask:0x3
	v_mov_b32_dpp v51, v64 row_ror:8 row_mask:0xf bank_mask:0x3
	v_mov_b32_dpp v52, v92 row_ror:8 row_mask:0xf bank_mask:0x3
	v_mov_b32_dpp v53, v93 row_ror:8 row_mask:0xf bank_mask:0x3
	global_store_dwordx4 v[84:85], v[54:57], off offset:512 nt
	global_store_dwordx4 v[90:91], v[50:53], off offset:512 nt
	s_nop 1
	v_mov_b32_dpp v50, v54 row_ror:8 row_mask:0xf bank_mask:0x3
	v_mov_b32_dpp v51, v55 row_ror:8 row_mask:0xf bank_mask:0x3
	v_mov_b32_dpp v52, v56 row_ror:8 row_mask:0xf bank_mask:0x3
	v_mov_b32_dpp v53, v57 row_ror:8 row_mask:0xf bank_mask:0x3
	v_mov_b32_e32 v54, v63
	v_mov_b32_e32 v55, v64
	v_mov_b32_e32 v56, v92
	v_mov_b32_e32 v57, v93
	s_nop 1
	v_permlane32_swap_b32_e32 v54, v50
	v_permlane32_swap_b32_e32 v55, v51
	v_permlane32_swap_b32_e32 v56, v52
	v_permlane32_swap_b32_e32 v57, v53
	v_permlane16_swap_b32_e32 v54, v50
	v_permlane16_swap_b32_e32 v55, v51
	v_permlane16_swap_b32_e32 v56, v52
	v_permlane16_swap_b32_e32 v57, v53
	v_add_f32_e32 v61, v61, v62
	v_cvt_pk_bf16_f32 v54, v54, v55
	v_cvt_pk_bf16_f32 v55, v56, v57
	v_cvt_pk_bf16_f32 v56, v50, v51
	v_lshl_add_u64 v[50:51], v[78:79], 0, v[0:1]
	v_mov_b32_e32 v0, v60
	v_pk_add_f32 v[70:71], v[70:71], v[70:71] op_sel:[0,1] op_sel_hi:[1,0]
	v_pk_add_f32 v[72:73], v[72:73], v[72:73] op_sel:[0,1] op_sel_hi:[1,0]
	v_add_f32_e32 v61, v65, v61
	v_cvt_pk_bf16_f32 v57, v52, v53
	v_permlane16_swap_b32_e32 v60, v0
	v_mov_b32_e32 v71, v70
	v_mov_b32_e32 v73, v72
	global_store_dwordx4 v[50:51], v[54:57], off
	v_add_f32_e32 v50, v60, v0
	v_mov_b32_e32 v0, v61
	v_permlane16_swap_b32_e32 v70, v71
	v_permlane16_swap_b32_e32 v72, v73
	v_permlane16_swap_b32_e32 v61, v0
	v_add_f32_e32 v71, v70, v71
	v_add_f32_e32 v70, v72, v73
	v_add_f32_e32 v51, v61, v0
	v_mov_b32_e32 v73, v71
	v_mov_b32_e32 v72, v70
	v_mov_b32_e32 v91, v89
	v_mov_b32_e32 v90, v88
	v_mov_b32_e32 v85, v83
	v_mov_b32_e32 v84, v82
	v_mov_b32_e32 v52, v50
	v_mov_b32_e32 v53, v51
	v_permlane32_swap_b32_e32 v71, v73
	v_permlane32_swap_b32_e32 v70, v72
	v_permlane32_swap_b32_e32 v89, v91
	v_permlane32_swap_b32_e32 v88, v90
	v_permlane32_swap_b32_e32 v83, v85
	v_permlane32_swap_b32_e32 v82, v84
	v_permlane32_swap_b32_e32 v50, v52
	v_permlane32_swap_b32_e32 v51, v53
	s_and_saveexec_b64 s[26:27], s[44:45]
	s_cbranch_execz .LBB0_382
	v_pk_add_f32 v[50:51], v[50:51], v[52:53]
	v_lshl_add_u64 v[52:53], s[30:31], 0, v[66:67]
	v_lshl_add_u64 v[52:53], s[24:25], 2, v[52:53]
	global_store_dwordx2 v[52:53], v[50:51], off
.LBB0_382:
	s_or_b64 exec, exec, s[26:27]
	v_pk_add_f32 v[50:51], v[70:71], v[72:73]
	s_mov_b32 s2, 0x3a800000
	v_pk_mul_f32 v[92:93], v[50:51], s[2:3] op_sel_hi:[1,0]
	s_mov_b32 s2, 0x800000
	v_fma_f32 v0, -v93, v93, v92
	v_max_f32_e32 v0, 0, v0
	v_add_f32_e32 v0, 0x3727c5ac, v0
	v_cmp_gt_f32_e32 vcc, s2, v0
	v_mul_f32_e32 v50, 0x4b800000, v0
	v_lshlrev_b64 v[120:121], 12, v[94:95]
	v_cndmask_b32_e32 v0, v0, v50, vcc
	v_rsq_f32_e32 v0, v0
	s_movk_i32 s2, 0x37c0
	s_load_dwordx16 s[60:75], s[34:35], 0x38
	v_mul_f32_e32 v50, 0x45800000, v0
	v_cndmask_b32_e32 v92, v0, v50, vcc
	v_lshl_add_u64 v[50:51], s[12:13], 0, v[120:121]
	v_lshl_add_u64 v[54:55], v[50:51], 0, v[152:153]
	global_load_dwordx4 v[96:99], v[54:55], off offset:16
	global_load_dwordx4 v[100:103], v[54:55], off
	global_load_dwordx4 v[104:107], v[154:155], off offset:16
	global_load_dwordx4 v[108:111], v[154:155], off
	global_load_dwordx4 v[112:115], v[156:157], off offset:16
	global_load_dwordx4 v[116:119], v[156:157], off
	global_load_dwordx4 v[50:53], v[54:55], off offset:528
	global_load_dwordx4 v[70:73], v[54:55], off offset:512
	s_nop 0
	global_load_dwordx4 v[54:57], v[154:155], off offset:528
	global_load_dwordx4 v[62:65], v[154:155], off offset:512
	global_load_dwordx4 v[58:61], v[156:157], off offset:528
	global_load_dwordx4 v[66:69], v[156:157], off offset:512
	v_lshlrev_b32_e32 v0, 6, v94
	v_and_or_b32 v0, v0, s2, v194
	s_mov_b32 s2, 0x3fd744fd
	s_waitcnt lgkmcnt(0)
	v_lshl_add_u64 v[94:95], s[74:75], 0, v[120:121]
	v_lshlrev_b32_e32 v0, 1, v0
	v_lshl_add_u64 v[94:95], v[94:95], 0, v[152:153]
	s_waitcnt vmcnt(10)
	v_sub_f32_e32 v103, v103, v93
	v_sub_f32_e32 v102, v102, v93
	v_sub_f32_e32 v101, v101, v93
	v_sub_f32_e32 v100, v100, v93
	v_pk_mul_f32 v[100:101], v[92:93], v[100:101] op_sel_hi:[0,1]
	v_pk_mul_f32 v[102:103], v[92:93], v[102:103] op_sel_hi:[0,1]
	s_waitcnt vmcnt(6)
; __device__ __forceinline__ size_t blk_off(int r, int c, int K) { return (size_t)(r >> 8) * 256 * K + (size_t)(c >> 6) * (256 * 64) + (size_t)((r & 255) * 64 + (c & 63)); }
; __device__ __forceinline__ u32x4 pack8(const f32x4 a, const f32x4 b) { u32x4 w; w.x = cvt_pk_bf16(a[0], a[1]); w.y = cvt_pk_bf16(a[2], a[3]); w.z = cvt_pk_bf16(b[0], b[1]); w.w = cvt_pk_bf16(b[2], b[3]); return w; }
;     __device__ __forceinline__ void operator()(const f32x4 (&acc)[2][2][4][2], const pg8::Unit& u, int wr, int wc, int fr, int fq) const {
;     ...
;                 for (int bj = 0; bj < 2; ++bj) { float* yp = Y + (size_t)row * D_ + col0 + bj * 128; f32x4 v[2];
; #pragma unroll
;                     for (int n = 0; n < 2; ++n) { v[n] = (((yv[bj][n] - mu) * rs) * gq[bj][n] + bq_[bj][n]) * ALPHA_ + acc[ai][bj][m][n] * sc;
;                         *(f32x4*)(yp + 4 * n) = v[n]; s1 += (v[n][0] + v[n][1]) + (v[n][2] + v[n][3]); s2 += (v[n][0] * v[n][0] + v[n][1] * v[n][1]) + (v[n][2] * v[n][2] + v[n][3] * v[n][3]); }
;                     *(u32x4*)(Yb + blk_off(row, col0 + bj * 128, D_)) = pack8(v[0], v[1]); }
	v_pk_fma_f32 v[102:103], v[110:111], v[102:103], v[118:119]
	v_pk_fma_f32 v[100:101], v[108:109], v[100:101], v[116:117]
	v_pk_mul_f32 v[102:103], v[102:103], s[2:3] op_sel_hi:[1,0]
	v_pk_mul_f32 v[100:101], v[100:101], s[2:3] op_sel_hi:[1,0]
	v_pk_fma_f32 v[102:103], v[48:49], 0.5, v[102:103] op_sel_hi:[1,0,1]
	v_pk_fma_f32 v[100:101], v[46:47], 0.5, v[100:101] op_sel_hi:[1,0,1]
	v_add_f32_e32 v47, v102, v103
	v_add_f32_e32 v46, v100, v101
	v_add_f32_e32 v46, v46, v47
	v_add_f32_e32 v108, 0, v46
	v_mul_f32_e32 v46, v101, v101
	v_mul_f32_e32 v47, v103, v103
	v_fmac_f32_e32 v46, v100, v100
	v_fmac_f32_e32 v47, v102, v102
	v_add_f32_e32 v109, v46, v47
	v_sub_f32_e32 v47, v99, v93
	v_sub_f32_e32 v46, v98, v93
	v_sub_f32_e32 v49, v97, v93
	v_sub_f32_e32 v48, v96, v93
	v_pk_mul_f32 v[48:49], v[92:93], v[48:49] op_sel_hi:[0,1]
	v_pk_mul_f32 v[46:47], v[92:93], v[46:47] op_sel_hi:[0,1]
	v_pk_fma_f32 v[46:47], v[106:107], v[46:47], v[114:115]
	v_pk_fma_f32 v[48:49], v[104:105], v[48:49], v[112:113]
	v_pk_mul_f32 v[46:47], v[46:47], s[2:3] op_sel_hi:[1,0]
	v_pk_mul_f32 v[48:49], v[48:49], s[2:3] op_sel_hi:[1,0]
	v_pk_fma_f32 v[98:99], v[44:45], 0.5, v[46:47] op_sel_hi:[1,0,1]
	v_pk_fma_f32 v[96:97], v[42:43], 0.5, v[48:49] op_sel_hi:[1,0,1]
	v_add_f32_e32 v43, v98, v99
	v_add_f32_e32 v42, v96, v97
	v_add_f32_e32 v42, v42, v43
	v_add_f32_e32 v47, v108, v42
	v_mul_f32_e32 v42, v97, v97
	v_mul_f32_e32 v43, v99, v99
	v_fmac_f32_e32 v42, v96, v96
	v_fmac_f32_e32 v43, v98, v98
	v_add_f32_e32 v42, v42, v43
	v_add_f32_e32 v46, v109, v42
	v_cvt_pk_bf16_f32 v42, v100, v101
	v_cvt_pk_bf16_f32 v43, v102, v103
	v_cvt_pk_bf16_f32 v44, v96, v97
	v_cvt_pk_bf16_f32 v45, v98, v99
	v_lshl_add_u64 v[48:49], v[80:81], 0, v[0:1]
	s_nop 0
	s_nop 1
	v_bfe_u32 v105, v227, 4, 2
	v_sub_u32_e32 v104, 0, v105
	v_lshlrev_b32_e32 v104, 4, v104
	v_ashrrev_i32_e32 v105, 31, v104
	v_lshl_add_u64 v[104:105], v[94:95], 0, v[104:105]
	v_permlane16_swap_b32_e32 v100, v96
	v_permlane16_swap_b32_e32 v101, v97
	v_permlane16_swap_b32_e32 v102, v98
	v_permlane16_swap_b32_e32 v103, v99
	v_permlane32_swap_b32_e32 v100, v96
	v_permlane32_swap_b32_e32 v101, v97
	v_permlane32_swap_b32_e32 v102, v98
	v_permlane32_swap_b32_e32 v103, v99
	v_mov_b32_e32 v108, v100
	v_mov_b32_e32 v109, v101
	v_mov_b32_e32 v110, v102
	v_mov_b32_e32 v111, v103
	v_bfe_u32 v106, v227, 3, 1
	v_mul_i32_i24_e32 v106, 0xffff8040, v106
	v_ashrrev_i32_e32 v107, 31, v106
	v_lshl_add_u64 v[104:105], v[104:105], 0, v[106:107]
	v_mov_b32_e32 v106, 0x8000
	v_mov_b32_e32 v107, 0
	v_lshl_add_u64 v[106:107], v[104:105], 0, v[106:107]
	v_mov_b32_dpp v100, v96 row_ror:8 row_mask:0xf bank_mask:0xc
	v_mov_b32_dpp v101, v97 row_ror:8 row_mask:0xf bank_mask:0xc
	v_mov_b32_dpp v102, v98 row_ror:8 row_mask:0xf bank_mask:0xc
	v_mov_b32_dpp v103, v99 row_ror:8 row_mask:0xf bank_mask:0xc
	v_mov_b32_dpp v96, v108 row_ror:8 row_mask:0xf bank_mask:0x3
	v_mov_b32_dpp v97, v109 row_ror:8 row_mask:0xf bank_mask:0x3
	v_mov_b32_dpp v98, v110 row_ror:8 row_mask:0xf bank_mask:0x3
	v_mov_b32_dpp v99, v111 row_ror:8 row_mask:0xf bank_mask:0x3
	global_store_dwordx4 v[104:105], v[100:103], off nt
	global_store_dwordx4 v[106:107], v[96:99], off nt
	s_nop 1
	global_store_dwordx4 v[48:49], v[42:45], off
	s_waitcnt vmcnt(7)
	s_nop 0
	v_sub_f32_e32 v43, v73, v93
	v_sub_f32_e32 v42, v72, v93
	v_sub_f32_e32 v45, v71, v93
	v_sub_f32_e32 v44, v70, v93
	v_pk_mul_f32 v[44:45], v[92:93], v[44:45] op_sel_hi:[0,1]
	v_pk_mul_f32 v[42:43], v[92:93], v[42:43] op_sel_hi:[0,1]
	s_waitcnt vmcnt(3)
	v_pk_fma_f32 v[42:43], v[64:65], v[42:43], v[68:69]
	v_pk_fma_f32 v[44:45], v[62:63], v[44:45], v[66:67]
	v_pk_mul_f32 v[42:43], v[42:43], s[2:3] op_sel_hi:[1,0]
	v_pk_mul_f32 v[44:45], v[44:45], s[2:3] op_sel_hi:[1,0]
	v_pk_fma_f32 v[40:41], v[40:41], 0.5, v[42:43] op_sel_hi:[1,0,1]
	v_pk_fma_f32 v[38:39], v[38:39], 0.5, v[44:45] op_sel_hi:[1,0,1]
	v_add_f32_e32 v43, v40, v41
	v_add_f32_e32 v42, v38, v39
	v_add_f32_e32 v42, v42, v43
	v_add_f32_e32 v47, v47, v42
	v_mul_f32_e32 v42, v39, v39
	v_mul_f32_e32 v43, v41, v41
	v_fmac_f32_e32 v42, v38, v38
	v_fmac_f32_e32 v43, v40, v40
	v_add_f32_e32 v42, v42, v43
	v_add_f32_e32 v46, v46, v42
	v_sub_f32_e32 v43, v53, v93
	v_sub_f32_e32 v42, v52, v93
	v_sub_f32_e32 v45, v51, v93
	v_sub_f32_e32 v44, v50, v93
	v_pk_mul_f32 v[44:45], v[92:93], v[44:45] op_sel_hi:[0,1]
	v_pk_mul_f32 v[42:43], v[92:93], v[42:43] op_sel_hi:[0,1]
	v_pk_fma_f32 v[42:43], v[56:57], v[42:43], v[60:61]
	v_pk_fma_f32 v[44:45], v[54:55], v[44:45], v[58:59]
	v_pk_mul_f32 v[42:43], v[42:43], s[2:3] op_sel_hi:[1,0]
	v_pk_mul_f32 v[44:45], v[44:45], s[2:3] op_sel_hi:[1,0]
	v_pk_fma_f32 v[36:37], v[36:37], 0.5, v[42:43] op_sel_hi:[1,0,1]
	v_pk_fma_f32 v[34:35], v[34:35], 0.5, v[44:45] op_sel_hi:[1,0,1]
	v_add_f32_e32 v43, v36, v37
	v_add_f32_e32 v42, v34, v35
	v_add_f32_e32 v42, v42, v43
	v_mul_f32_e32 v43, v35, v35
	v_mul_f32_e32 v44, v37, v37
	v_add_f32_e32 v42, v47, v42
	v_fmac_f32_e32 v43, v34, v34
	v_fmac_f32_e32 v44, v36, v36
	s_nop 0
	s_nop 1
	v_bfe_u32 v49, v227, 4, 2
	v_sub_u32_e32 v48, 0, v49
	v_lshlrev_b32_e32 v48, 4, v48
	v_ashrrev_i32_e32 v49, 31, v48
	v_lshl_add_u64 v[48:49], v[94:95], 0, v[48:49]
	v_permlane16_swap_b32_e32 v38, v34
	v_permlane16_swap_b32_e32 v39, v35
	v_permlane16_swap_b32_e32 v40, v36
	v_permlane16_swap_b32_e32 v41, v37
	v_permlane32_swap_b32_e32 v38, v34
	v_permlane32_swap_b32_e32 v39, v35
	v_permlane32_swap_b32_e32 v40, v36
	v_permlane32_swap_b32_e32 v41, v37
	v_mov_b32_e32 v45, v38
	v_mov_b32_e32 v52, v39
	v_mov_b32_e32 v53, v40
	v_mov_b32_e32 v54, v41
	v_bfe_u32 v50, v227, 3, 1
	v_mul_i32_i24_e32 v50, 0xffff8040, v50
	v_ashrrev_i32_e32 v51, 31, v50
; __device__ __forceinline__ float xsum16(float v) { const auto r = __builtin_amdgcn_permlane16_swap(__float_as_uint(v), __float_as_uint(v), false, false); return __uint_as_float(r[0]) + __uint_as_float(r[1]); }
; __device__ __forceinline__ float xsum32(float v) { const auto r = __builtin_amdgcn_permlane32_swap(__float_as_uint(v), __float_as_uint(v), false, false); return __uint_as_float(r[0]) + __uint_as_float(r[1]); }
; __device__ __forceinline__ size_t blk_off(int r, int c, int K) { return (size_t)(r >> 8) * 256 * K + (size_t)(c >> 6) * (256 * 64) + (size_t)((r & 255) * 64 + (c & 63)); }
; __device__ __forceinline__ u32x4 pack8(const f32x4 a, const f32x4 b) { u32x4 w; w.x = cvt_pk_bf16(a[0], a[1]); w.y = cvt_pk_bf16(a[2], a[3]); w.z = cvt_pk_bf16(b[0], b[1]); w.w = cvt_pk_bf16(b[2], b[3]); return w; }
;     __device__ __forceinline__ void operator()(const f32x4 (&acc)[2][2][4][2], const pg8::Unit& u, int wr, int wc, int fr, int fq) const {
;     ...
;             for (int m = 0; m < 4; ++m) { const int row = row0 + ai * 128 + m * 16; const float mu = mu4[m], rs = rs4[m];
;                 f32x4 yv[2][2], gq[2][2], bq_[2][2];
; #pragma unroll
;                 for (int bj = 0; bj < 2; ++bj)
; #pragma unroll
;                     for (int n = 0; n < 2; ++n) { yv[bj][n] = *(const f32x4*)(Yin + (size_t)row * D_ + col0 + bj * 128 + 4 * n); gq[bj][n] = *(const f32x4*)(g + col0 + bj * 128 + 4 * n); bq_[bj][n] = *(const f32x4*)(b + col0 + bj * 128 + 4 * n); }
;                 asm volatile("" ::: "memory");
;                 float s1 = 0.f, s2 = 0.f;
; #pragma unroll
;                 for (int bj = 0; bj < 2; ++bj) { float* yp = Y + (size_t)row * D_ + col0 + bj * 128; f32x4 v[2];
; #pragma unroll
;                     for (int n = 0; n < 2; ++n) { v[n] = (((yv[bj][n] - mu) * rs) * gq[bj][n] + bq_[bj][n]) * ALPHA_ + acc[ai][bj][m][n] * sc;
;                         *(f32x4*)(yp + 4 * n) = v[n]; s1 += (v[n][0] + v[n][1]) + (v[n][2] + v[n][3]); s2 += (v[n][0] * v[n][0] + v[n][1] * v[n][1]) + (v[n][2] * v[n][2] + v[n][3] * v[n][3]); }
;                     *(u32x4*)(Yb + blk_off(row, col0 + bj * 128, D_)) = pack8(v[0], v[1]); }
;                 s1 = xsum32(xsum16(s1)); s2 = xsum32(xsum16(s2));
;                 if (fq == 0) *(f32x2*)(stn + (size_t)row * 32 + (u.pn * 4 + wc) * 2) = (f32x2){s1, s2}; asm volatile("" ::: "memory"); } }
	v_lshl_add_u64 v[48:49], v[48:49], 0, v[50:51]
	v_mov_b32_e32 v50, 0x8000
	v_mov_b32_e32 v51, 0
	v_lshl_add_u64 v[50:51], v[48:49], 0, v[50:51]
	v_mov_b32_dpp v38, v34 row_ror:8 row_mask:0xf bank_mask:0xc
	v_mov_b32_dpp v39, v35 row_ror:8 row_mask:0xf bank_mask:0xc
	v_mov_b32_dpp v40, v36 row_ror:8 row_mask:0xf bank_mask:0xc
	v_mov_b32_dpp v41, v37 row_ror:8 row_mask:0xf bank_mask:0xc
	v_mov_b32_dpp v34, v45 row_ror:8 row_mask:0xf bank_mask:0x3
	v_mov_b32_dpp v35, v52 row_ror:8 row_mask:0xf bank_mask:0x3
	v_mov_b32_dpp v36, v53 row_ror:8 row_mask:0xf bank_mask:0x3
	v_mov_b32_dpp v37, v54 row_ror:8 row_mask:0xf bank_mask:0x3
	global_store_dwordx4 v[48:49], v[38:41], off offset:512 nt
	global_store_dwordx4 v[50:51], v[34:37], off offset:512 nt
	s_nop 1
	v_mov_b32_dpp v34, v38 row_ror:8 row_mask:0xf bank_mask:0x3
	v_mov_b32_dpp v35, v39 row_ror:8 row_mask:0xf bank_mask:0x3
	v_mov_b32_dpp v36, v40 row_ror:8 row_mask:0xf bank_mask:0x3
	v_mov_b32_dpp v37, v41 row_ror:8 row_mask:0xf bank_mask:0x3
	v_mov_b32_e32 v38, v45
	v_mov_b32_e32 v39, v52
	v_mov_b32_e32 v40, v53
	v_mov_b32_e32 v41, v54
	s_nop 1
	v_permlane32_swap_b32_e32 v38, v34
	v_permlane32_swap_b32_e32 v39, v35
	v_permlane32_swap_b32_e32 v40, v36
	v_permlane32_swap_b32_e32 v41, v37
	v_permlane16_swap_b32_e32 v38, v34
	v_permlane16_swap_b32_e32 v39, v35
	v_permlane16_swap_b32_e32 v40, v36
	v_permlane16_swap_b32_e32 v41, v37
	v_add_f32_e32 v43, v43, v44
	v_cvt_pk_bf16_f32 v38, v38, v39
	v_cvt_pk_bf16_f32 v39, v40, v41
	v_cvt_pk_bf16_f32 v40, v34, v35
	v_lshl_add_u64 v[34:35], v[78:79], 0, v[0:1]
	v_mov_b32_e32 v0, v42
	v_add_f32_e32 v43, v46, v43
	v_cvt_pk_bf16_f32 v41, v36, v37
	v_permlane16_swap_b32_e32 v42, v0
	global_store_dwordx4 v[34:35], v[38:41], off
	v_add_f32_e32 v34, v42, v0
	v_mov_b32_e32 v0, v43
	s_nop 1
	v_permlane16_swap_b32_e32 v43, v0
	v_add_f32_e32 v35, v43, v0
	v_mov_b32_e32 v36, v34
	v_mov_b32_e32 v37, v35
	s_nop 0
	v_permlane32_swap_b32_e32 v34, v36
	v_permlane32_swap_b32_e32 v35, v37
	s_and_saveexec_b64 s[26:27], s[44:45]
	s_cbranch_execz .LBB0_384
	v_pk_add_f32 v[34:35], v[34:35], v[36:37]
	v_lshl_add_u64 v[36:37], s[30:31], 0, v[86:87]
	v_lshl_add_u64 v[36:37], s[24:25], 2, v[36:37]
	global_store_dwordx2 v[36:37], v[34:35], off
.LBB0_384:
	s_or_b64 exec, exec, s[26:27]
	v_pk_add_f32 v[34:35], v[88:89], v[90:91]
	s_mov_b32 s2, 0x3a800000
	v_pk_mul_f32 v[58:59], v[34:35], s[2:3] op_sel_hi:[1,0]
	s_mov_b32 s2, 0x800000
	v_fma_f32 v0, -v59, v59, v58
	v_max_f32_e32 v0, 0, v0
	v_add_f32_e32 v0, 0x3727c5ac, v0
	v_cmp_gt_f32_e32 vcc, s2, v0
	v_mul_f32_e32 v34, 0x4b800000, v0
	v_lshlrev_b64 v[60:61], 12, v[76:77]
	v_cndmask_b32_e32 v0, v0, v34, vcc
	v_rsq_f32_e32 v0, v0
	s_movk_i32 s2, 0x3bc0
	s_load_dwordx16 s[60:75], s[34:35], 0x38
	v_mul_f32_e32 v34, 0x45800000, v0
	v_cndmask_b32_e32 v58, v0, v34, vcc
	v_lshl_add_u64 v[34:35], s[12:13], 0, v[60:61]
	v_lshl_add_u64 v[38:39], v[34:35], 0, v[152:153]
	global_load_dwordx4 v[62:65], v[38:39], off offset:16
	global_load_dwordx4 v[66:69], v[38:39], off
	global_load_dwordx4 v[70:73], v[154:155], off offset:16
	global_load_dwordx4 v[86:89], v[154:155], off
	global_load_dwordx4 v[90:93], v[156:157], off offset:16
	global_load_dwordx4 v[94:97], v[156:157], off
	global_load_dwordx4 v[34:37], v[38:39], off offset:528
	global_load_dwordx4 v[54:57], v[38:39], off offset:512
	s_nop 0
	global_load_dwordx4 v[38:41], v[154:155], off offset:528
	global_load_dwordx4 v[46:49], v[154:155], off offset:512
	global_load_dwordx4 v[42:45], v[156:157], off offset:528
	global_load_dwordx4 v[50:53], v[156:157], off offset:512
	v_lshlrev_b32_e32 v0, 6, v76
	v_and_or_b32 v0, v0, s2, v194
	s_mov_b32 s2, 0x3fd744fd
	s_waitcnt lgkmcnt(0)
	v_lshl_add_u64 v[60:61], s[74:75], 0, v[60:61]
	v_lshlrev_b32_e32 v0, 1, v0
	v_lshl_add_u64 v[60:61], v[60:61], 0, v[152:153]
	s_waitcnt vmcnt(10)
	v_sub_f32_e32 v69, v69, v59
	v_sub_f32_e32 v68, v68, v59
	v_sub_f32_e32 v67, v67, v59
	v_sub_f32_e32 v66, v66, v59
	v_pk_mul_f32 v[66:67], v[58:59], v[66:67] op_sel_hi:[0,1]
	v_pk_mul_f32 v[68:69], v[58:59], v[68:69] op_sel_hi:[0,1]
	s_waitcnt vmcnt(6)
	v_pk_fma_f32 v[68:69], v[88:89], v[68:69], v[96:97]
	v_pk_fma_f32 v[66:67], v[86:87], v[66:67], v[94:95]
	v_pk_mul_f32 v[68:69], v[68:69], s[2:3] op_sel_hi:[1,0]
	v_pk_mul_f32 v[66:67], v[66:67], s[2:3] op_sel_hi:[1,0]
	v_pk_fma_f32 v[68:69], v[32:33], 0.5, v[68:69] op_sel_hi:[1,0,1]
	v_pk_fma_f32 v[66:67], v[30:31], 0.5, v[66:67] op_sel_hi:[1,0,1]
	v_add_f32_e32 v31, v68, v69
	v_add_f32_e32 v30, v66, v67
	v_add_f32_e32 v30, v30, v31
	v_add_f32_e32 v86, 0, v30
	v_mul_f32_e32 v30, v67, v67
	v_mul_f32_e32 v31, v69, v69
	v_fmac_f32_e32 v30, v66, v66
	v_fmac_f32_e32 v31, v68, v68
	v_add_f32_e32 v87, v30, v31
	v_sub_f32_e32 v31, v65, v59
	v_sub_f32_e32 v30, v64, v59
	v_sub_f32_e32 v33, v63, v59
	v_sub_f32_e32 v32, v62, v59
	v_pk_mul_f32 v[32:33], v[58:59], v[32:33] op_sel_hi:[0,1]
	v_pk_mul_f32 v[30:31], v[58:59], v[30:31] op_sel_hi:[0,1]
	v_pk_fma_f32 v[30:31], v[72:73], v[30:31], v[92:93]
	v_pk_fma_f32 v[32:33], v[70:71], v[32:33], v[90:91]
	v_pk_mul_f32 v[30:31], v[30:31], s[2:3] op_sel_hi:[1,0]
	v_pk_mul_f32 v[32:33], v[32:33], s[2:3] op_sel_hi:[1,0]
	v_pk_fma_f32 v[64:65], v[28:29], 0.5, v[30:31] op_sel_hi:[1,0,1]
	v_pk_fma_f32 v[62:63], v[26:27], 0.5, v[32:33] op_sel_hi:[1,0,1]
	v_add_f32_e32 v27, v64, v65
	v_add_f32_e32 v26, v62, v63
	v_add_f32_e32 v26, v26, v27
	v_add_f32_e32 v31, v86, v26
	v_mul_f32_e32 v26, v63, v63
	v_mul_f32_e32 v27, v65, v65
	v_fmac_f32_e32 v26, v62, v62
	v_fmac_f32_e32 v27, v64, v64
	v_add_f32_e32 v26, v26, v27
	v_add_f32_e32 v30, v87, v26
	v_cvt_pk_bf16_f32 v26, v66, v67
	v_cvt_pk_bf16_f32 v27, v68, v69
; __device__ __forceinline__ float xsum16(float v) { const auto r = __builtin_amdgcn_permlane16_swap(__float_as_uint(v), __float_as_uint(v), false, false); return __uint_as_float(r[0]) + __uint_as_float(r[1]); }
; __device__ __forceinline__ float xsum32(float v) { const auto r = __builtin_amdgcn_permlane32_swap(__float_as_uint(v), __float_as_uint(v), false, false); return __uint_as_float(r[0]) + __uint_as_float(r[1]); }
; __device__ __forceinline__ size_t blk_off(int r, int c, int K) { return (size_t)(r >> 8) * 256 * K + (size_t)(c >> 6) * (256 * 64) + (size_t)((r & 255) * 64 + (c & 63)); }
; __device__ __forceinline__ u32x4 pack8(const f32x4 a, const f32x4 b) { u32x4 w; w.x = cvt_pk_bf16(a[0], a[1]); w.y = cvt_pk_bf16(a[2], a[3]); w.z = cvt_pk_bf16(b[0], b[1]); w.w = cvt_pk_bf16(b[2], b[3]); return w; }
;     __device__ __forceinline__ void operator()(const f32x4 (&acc)[2][2][4][2], const pg8::Unit& u, int wr, int wc, int fr, int fq) const {
;     ...
;                 for (int bj = 0; bj < 2; ++bj) { float* yp = Y + (size_t)row * D_ + col0 + bj * 128; f32x4 v[2];
; #pragma unroll
;                     for (int n = 0; n < 2; ++n) { v[n] = (((yv[bj][n] - mu) * rs) * gq[bj][n] + bq_[bj][n]) * ALPHA_ + acc[ai][bj][m][n] * sc;
;                         *(f32x4*)(yp + 4 * n) = v[n]; s1 += (v[n][0] + v[n][1]) + (v[n][2] + v[n][3]); s2 += (v[n][0] * v[n][0] + v[n][1] * v[n][1]) + (v[n][2] * v[n][2] + v[n][3] * v[n][3]); }
;                     *(u32x4*)(Yb + blk_off(row, col0 + bj * 128, D_)) = pack8(v[0], v[1]); }
;                 s1 = xsum32(xsum16(s1)); s2 = xsum32(xsum16(s2));
;                 if (fq == 0) *(f32x2*)(stn + (size_t)row * 32 + (u.pn * 4 + wc) * 2) = (f32x2){s1, s2}; asm volatile("" ::: "memory"); } }
	v_cvt_pk_bf16_f32 v28, v62, v63
	v_cvt_pk_bf16_f32 v29, v64, v65
	v_lshl_add_u64 v[32:33], v[80:81], 0, v[0:1]
	s_nop 0
	s_nop 1
	v_bfe_u32 v71, v227, 4, 2
	v_sub_u32_e32 v70, 0, v71
	v_lshlrev_b32_e32 v70, 4, v70
	v_ashrrev_i32_e32 v71, 31, v70
	v_lshl_add_u64 v[70:71], v[60:61], 0, v[70:71]
	v_permlane16_swap_b32_e32 v66, v62
	v_permlane16_swap_b32_e32 v67, v63
	v_permlane16_swap_b32_e32 v68, v64
	v_permlane16_swap_b32_e32 v69, v65
	v_permlane32_swap_b32_e32 v66, v62
	v_permlane32_swap_b32_e32 v67, v63
	v_permlane32_swap_b32_e32 v68, v64
	v_permlane32_swap_b32_e32 v69, v65
	v_mov_b32_e32 v86, v66
	v_mov_b32_e32 v87, v67
	v_mov_b32_e32 v88, v68
	v_mov_b32_e32 v89, v69
	v_bfe_u32 v72, v227, 3, 1
	v_mul_i32_i24_e32 v72, 0xffff8040, v72
	v_ashrrev_i32_e32 v73, 31, v72
	v_lshl_add_u64 v[70:71], v[70:71], 0, v[72:73]
	v_mov_b32_e32 v72, 0x8000
	v_mov_b32_e32 v73, 0
	v_lshl_add_u64 v[72:73], v[70:71], 0, v[72:73]
	v_mov_b32_dpp v66, v62 row_ror:8 row_mask:0xf bank_mask:0xc
	v_mov_b32_dpp v67, v63 row_ror:8 row_mask:0xf bank_mask:0xc
	v_mov_b32_dpp v68, v64 row_ror:8 row_mask:0xf bank_mask:0xc
	v_mov_b32_dpp v69, v65 row_ror:8 row_mask:0xf bank_mask:0xc
	v_mov_b32_dpp v62, v86 row_ror:8 row_mask:0xf bank_mask:0x3
	v_mov_b32_dpp v63, v87 row_ror:8 row_mask:0xf bank_mask:0x3
	v_mov_b32_dpp v64, v88 row_ror:8 row_mask:0xf bank_mask:0x3
	v_mov_b32_dpp v65, v89 row_ror:8 row_mask:0xf bank_mask:0x3
	global_store_dwordx4 v[70:71], v[66:69], off nt
	global_store_dwordx4 v[72:73], v[62:65], off nt
	s_nop 1
	global_store_dwordx4 v[32:33], v[26:29], off
	s_waitcnt vmcnt(7)
	s_nop 0
	v_sub_f32_e32 v27, v57, v59
	v_sub_f32_e32 v26, v56, v59
	v_sub_f32_e32 v29, v55, v59
	v_sub_f32_e32 v28, v54, v59
	v_pk_mul_f32 v[28:29], v[58:59], v[28:29] op_sel_hi:[0,1]
	v_pk_mul_f32 v[26:27], v[58:59], v[26:27] op_sel_hi:[0,1]
	s_waitcnt vmcnt(3)
	v_pk_fma_f32 v[26:27], v[48:49], v[26:27], v[52:53]
	v_pk_fma_f32 v[28:29], v[46:47], v[28:29], v[50:51]
	v_pk_mul_f32 v[26:27], v[26:27], s[2:3] op_sel_hi:[1,0]
	v_pk_mul_f32 v[28:29], v[28:29], s[2:3] op_sel_hi:[1,0]
	v_pk_fma_f32 v[24:25], v[24:25], 0.5, v[26:27] op_sel_hi:[1,0,1]
	v_pk_fma_f32 v[22:23], v[22:23], 0.5, v[28:29] op_sel_hi:[1,0,1]
	v_add_f32_e32 v27, v24, v25
	v_add_f32_e32 v26, v22, v23
	v_add_f32_e32 v26, v26, v27
	v_add_f32_e32 v31, v31, v26
	v_mul_f32_e32 v26, v23, v23
	v_mul_f32_e32 v27, v25, v25
	v_fmac_f32_e32 v26, v22, v22
	v_fmac_f32_e32 v27, v24, v24
	v_add_f32_e32 v26, v26, v27
	v_add_f32_e32 v30, v30, v26
	v_sub_f32_e32 v27, v37, v59
	v_sub_f32_e32 v26, v36, v59
	v_sub_f32_e32 v29, v35, v59
	v_sub_f32_e32 v28, v34, v59
	v_pk_mul_f32 v[28:29], v[58:59], v[28:29] op_sel_hi:[0,1]
	v_pk_mul_f32 v[26:27], v[58:59], v[26:27] op_sel_hi:[0,1]
	v_pk_fma_f32 v[26:27], v[40:41], v[26:27], v[44:45]
	v_pk_fma_f32 v[28:29], v[38:39], v[28:29], v[42:43]
	v_pk_mul_f32 v[26:27], v[26:27], s[2:3] op_sel_hi:[1,0]
	v_pk_mul_f32 v[28:29], v[28:29], s[2:3] op_sel_hi:[1,0]
	v_pk_fma_f32 v[20:21], v[20:21], 0.5, v[26:27] op_sel_hi:[1,0,1]
	v_pk_fma_f32 v[18:19], v[18:19], 0.5, v[28:29] op_sel_hi:[1,0,1]
	v_add_f32_e32 v27, v20, v21
	v_add_f32_e32 v26, v18, v19
	v_add_f32_e32 v26, v26, v27
	v_mul_f32_e32 v27, v19, v19
	v_mul_f32_e32 v28, v21, v21
	v_add_f32_e32 v26, v31, v26
	v_fmac_f32_e32 v27, v18, v18
	v_fmac_f32_e32 v28, v20, v20
	s_nop 0
	s_nop 1
	v_bfe_u32 v33, v227, 4, 2
	v_sub_u32_e32 v32, 0, v33
	v_lshlrev_b32_e32 v32, 4, v32
	v_ashrrev_i32_e32 v33, 31, v32
	v_lshl_add_u64 v[32:33], v[60:61], 0, v[32:33]
	v_permlane16_swap_b32_e32 v22, v18
	v_permlane16_swap_b32_e32 v23, v19
	v_permlane16_swap_b32_e32 v24, v20
	v_permlane16_swap_b32_e32 v25, v21
	v_permlane32_swap_b32_e32 v22, v18
	v_permlane32_swap_b32_e32 v23, v19
	v_permlane32_swap_b32_e32 v24, v20
	v_permlane32_swap_b32_e32 v25, v21
	v_mov_b32_e32 v29, v22
	v_mov_b32_e32 v36, v23
	v_mov_b32_e32 v37, v24
	v_mov_b32_e32 v38, v25
	v_bfe_u32 v34, v227, 3, 1
	v_mul_i32_i24_e32 v34, 0xffff8040, v34
	v_ashrrev_i32_e32 v35, 31, v34
	v_lshl_add_u64 v[32:33], v[32:33], 0, v[34:35]
	v_mov_b32_e32 v34, 0x8000
	v_mov_b32_e32 v35, 0
	v_lshl_add_u64 v[34:35], v[32:33], 0, v[34:35]
	v_mov_b32_dpp v22, v18 row_ror:8 row_mask:0xf bank_mask:0xc
	v_mov_b32_dpp v23, v19 row_ror:8 row_mask:0xf bank_mask:0xc
	v_mov_b32_dpp v24, v20 row_ror:8 row_mask:0xf bank_mask:0xc
	v_mov_b32_dpp v25, v21 row_ror:8 row_mask:0xf bank_mask:0xc
	v_mov_b32_dpp v18, v29 row_ror:8 row_mask:0xf bank_mask:0x3
	v_mov_b32_dpp v19, v36 row_ror:8 row_mask:0xf bank_mask:0x3
	v_mov_b32_dpp v20, v37 row_ror:8 row_mask:0xf bank_mask:0x3
	v_mov_b32_dpp v21, v38 row_ror:8 row_mask:0xf bank_mask:0x3
	global_store_dwordx4 v[32:33], v[22:25], off offset:512 nt
	global_store_dwordx4 v[34:35], v[18:21], off offset:512 nt
	s_nop 1
	v_mov_b32_dpp v18, v22 row_ror:8 row_mask:0xf bank_mask:0x3
	v_mov_b32_dpp v19, v23 row_ror:8 row_mask:0xf bank_mask:0x3
	v_mov_b32_dpp v20, v24 row_ror:8 row_mask:0xf bank_mask:0x3
	v_mov_b32_dpp v21, v25 row_ror:8 row_mask:0xf bank_mask:0x3
	v_mov_b32_e32 v22, v29
	v_mov_b32_e32 v23, v36
	v_mov_b32_e32 v24, v37
	v_mov_b32_e32 v25, v38
	s_nop 1
	v_permlane32_swap_b32_e32 v22, v18
	v_permlane32_swap_b32_e32 v23, v19
	v_permlane32_swap_b32_e32 v24, v20
	v_permlane32_swap_b32_e32 v25, v21
	v_permlane16_swap_b32_e32 v22, v18
	v_permlane16_swap_b32_e32 v23, v19
	v_permlane16_swap_b32_e32 v24, v20
	v_permlane16_swap_b32_e32 v25, v21
	v_add_f32_e32 v27, v27, v28
	v_cvt_pk_bf16_f32 v22, v22, v23
	v_cvt_pk_bf16_f32 v23, v24, v25
	v_cvt_pk_bf16_f32 v24, v18, v19
	v_lshl_add_u64 v[18:19], v[78:79], 0, v[0:1]
	v_mov_b32_e32 v0, v26
	v_add_f32_e32 v27, v30, v27
	v_cvt_pk_bf16_f32 v25, v20, v21
	v_permlane16_swap_b32_e32 v26, v0
	global_store_dwordx4 v[18:19], v[22:25], off
	v_add_f32_e32 v18, v26, v0
	v_mov_b32_e32 v0, v27
	s_nop 1
	v_permlane16_swap_b32_e32 v27, v0
	v_add_f32_e32 v19, v27, v0
	v_mov_b32_e32 v20, v18
	v_mov_b32_e32 v21, v19
	s_nop 0
	v_permlane32_swap_b32_e32 v18, v20
	v_permlane32_swap_b32_e32 v19, v21
	s_and_saveexec_b64 s[26:27], s[44:45]
	s_cbranch_execz .LBB0_386
	v_pk_add_f32 v[18:19], v[18:19], v[20:21]
	v_lshlrev_b64 v[20:21], 7, v[76:77]
	v_lshl_add_u64 v[20:21], s[30:31], 0, v[20:21]
	v_lshl_add_u64 v[20:21], s[24:25], 2, v[20:21]
	global_store_dwordx2 v[20:21], v[18:19], off
; __device__ __forceinline__ size_t blk_off(int r, int c, int K) { return (size_t)(r >> 8) * 256 * K + (size_t)(c >> 6) * (256 * 64) + (size_t)((r & 255) * 64 + (c & 63)); }
; __device__ __forceinline__ u32x4 pack8(const f32x4 a, const f32x4 b) { u32x4 w; w.x = cvt_pk_bf16(a[0], a[1]); w.y = cvt_pk_bf16(a[2], a[3]); w.z = cvt_pk_bf16(b[0], b[1]); w.w = cvt_pk_bf16(b[2], b[3]); return w; }
;     __device__ __forceinline__ void operator()(const f32x4 (&acc)[2][2][4][2], const pg8::Unit& u, int wr, int wc, int fr, int fq) const {
;     ...
;             for (int m = 0; m < 4; ++m) { const int row = row0 + ai * 128 + m * 16; const float mu = mu4[m], rs = rs4[m];
;                 f32x4 yv[2][2], gq[2][2], bq_[2][2];
; #pragma unroll
;                 for (int bj = 0; bj < 2; ++bj)
; #pragma unroll
;                     for (int n = 0; n < 2; ++n) { yv[bj][n] = *(const f32x4*)(Yin + (size_t)row * D_ + col0 + bj * 128 + 4 * n); gq[bj][n] = *(const f32x4*)(g + col0 + bj * 128 + 4 * n); bq_[bj][n] = *(const f32x4*)(b + col0 + bj * 128 + 4 * n); }
;                 asm volatile("" ::: "memory");
;                 float s1 = 0.f, s2 = 0.f;
; #pragma unroll
;                 for (int bj = 0; bj < 2; ++bj) { float* yp = Y + (size_t)row * D_ + col0 + bj * 128; f32x4 v[2];
; #pragma unroll
;                     for (int n = 0; n < 2; ++n) { v[n] = (((yv[bj][n] - mu) * rs) * gq[bj][n] + bq_[bj][n]) * ALPHA_ + acc[ai][bj][m][n] * sc;
;                         *(f32x4*)(yp + 4 * n) = v[n]; s1 += (v[n][0] + v[n][1]) + (v[n][2] + v[n][3]); s2 += (v[n][0] * v[n][0] + v[n][1] * v[n][1]) + (v[n][2] * v[n][2] + v[n][3] * v[n][3]); }
;                     *(u32x4*)(Yb + blk_off(row, col0 + bj * 128, D_)) = pack8(v[0], v[1]); }
.LBB0_386:
	s_or_b64 exec, exec, s[26:27]
	v_lshlrev_b64 v[26:27], 12, v[74:75]
	v_lshl_add_u64 v[18:19], s[12:13], 0, v[26:27]
	v_lshl_add_u64 v[28:29], v[18:19], 0, v[152:153]
	global_load_dwordx4 v[34:37], v[28:29], off
	global_load_dwordx4 v[38:41], v[28:29], off offset:16
	global_load_dwordx4 v[42:45], v[28:29], off offset:512
	global_load_dwordx4 v[46:49], v[156:157], off
	global_load_dwordx4 v[50:53], v[154:155], off
	global_load_dwordx4 v[54:57], v[154:155], off offset:16
	global_load_dwordx4 v[58:61], v[156:157], off offset:16
	global_load_dwordx4 v[62:65], v[154:155], off offset:512
	global_load_dwordx4 v[66:69], v[156:157], off offset:512
	s_load_dwordx16 s[60:75], s[34:35], 0x38
	v_pk_add_f32 v[18:19], v[82:83], v[84:85]
	s_mov_b32 s2, 0x3a800000
	v_pk_mul_f32 v[32:33], v[18:19], s[2:3] op_sel_hi:[1,0]
	global_load_dwordx4 v[18:21], v[154:155], off offset:528
	global_load_dwordx4 v[22:25], v[156:157], off offset:528
	s_waitcnt lgkmcnt(0)
	v_lshl_add_u64 v[26:27], s[74:75], 0, v[26:27]
	v_lshl_add_u64 v[30:31], v[26:27], 0, v[152:153]
	global_load_dwordx4 v[26:29], v[28:29], off offset:528
	v_fma_f32 v32, -v33, v33, v32
	v_lshlrev_b32_e32 v0, 6, v74
	s_movk_i32 s2, 0x3fc0
	v_max_f32_e32 v32, 0, v32
	v_and_or_b32 v0, v0, s2, v194
	v_add_f32_e32 v32, 0x3727c5ac, v32
	s_mov_b32 s2, 0x800000
	v_mul_f32_e32 v70, 0x4b800000, v32
	v_cmp_gt_f32_e32 vcc, s2, v32
	s_mov_b32 s2, 0x3fd744fd
	v_lshlrev_b32_e32 v0, 1, v0
	v_cndmask_b32_e32 v32, v32, v70, vcc
	v_rsq_f32_e32 v32, v32
	v_lshl_add_u64 v[70:71], v[80:81], 0, v[0:1]
	v_mul_f32_e32 v72, 0x45800000, v32
	v_cndmask_b32_e32 v32, v32, v72, vcc
	s_waitcnt vmcnt(11)
	v_sub_f32_e32 v37, v37, v33
	v_sub_f32_e32 v36, v36, v33
	v_sub_f32_e32 v35, v35, v33
	v_sub_f32_e32 v34, v34, v33
	s_waitcnt vmcnt(10)
	v_sub_f32_e32 v41, v41, v33
	v_sub_f32_e32 v40, v40, v33
	v_sub_f32_e32 v39, v39, v33
	v_sub_f32_e32 v38, v38, v33
	v_pk_mul_f32 v[34:35], v[32:33], v[34:35] op_sel_hi:[0,1]
	v_pk_mul_f32 v[36:37], v[32:33], v[36:37] op_sel_hi:[0,1]
	v_pk_mul_f32 v[38:39], v[32:33], v[38:39] op_sel_hi:[0,1]
	v_pk_mul_f32 v[40:41], v[32:33], v[40:41] op_sel_hi:[0,1]
	s_waitcnt vmcnt(7)
	v_pk_fma_f32 v[36:37], v[52:53], v[36:37], v[48:49]
	v_pk_fma_f32 v[34:35], v[50:51], v[34:35], v[46:47]
	s_waitcnt vmcnt(5)
	v_pk_fma_f32 v[40:41], v[56:57], v[40:41], v[60:61]
	v_pk_fma_f32 v[38:39], v[54:55], v[38:39], v[58:59]
	v_pk_mul_f32 v[34:35], v[34:35], s[2:3] op_sel_hi:[1,0]
	v_pk_mul_f32 v[36:37], v[36:37], s[2:3] op_sel_hi:[1,0]
	v_pk_mul_f32 v[38:39], v[38:39], s[2:3] op_sel_hi:[1,0]
	v_pk_mul_f32 v[40:41], v[40:41], s[2:3] op_sel_hi:[1,0]
	v_pk_fma_f32 v[16:17], v[16:17], 0.5, v[36:37] op_sel_hi:[1,0,1]
	v_pk_fma_f32 v[14:15], v[14:15], 0.5, v[34:35] op_sel_hi:[1,0,1]
	v_pk_fma_f32 v[12:13], v[12:13], 0.5, v[40:41] op_sel_hi:[1,0,1]
	v_pk_fma_f32 v[10:11], v[10:11], 0.5, v[38:39] op_sel_hi:[1,0,1]
	v_sub_f32_e32 v45, v45, v33
	v_sub_f32_e32 v44, v44, v33
	v_sub_f32_e32 v43, v43, v33
	v_sub_f32_e32 v42, v42, v33
	v_add_f32_e32 v38, v14, v15
	v_add_f32_e32 v39, v16, v17
	v_mul_f32_e32 v40, v15, v15
	v_mul_f32_e32 v41, v17, v17
	v_mul_f32_e32 v48, v11, v11
	v_mul_f32_e32 v49, v13, v13
	v_pk_mul_f32 v[42:43], v[32:33], v[42:43] op_sel_hi:[0,1]
	v_pk_mul_f32 v[44:45], v[32:33], v[44:45] op_sel_hi:[0,1]
	global_store_dwordx4 v[30:31], v[10:13], off offset:16
	v_add_f32_e32 v46, v10, v11
	v_add_f32_e32 v47, v12, v13
	v_cvt_pk_bf16_f32 v36, v10, v11
	v_add_f32_e32 v11, v38, v39
	v_fmac_f32_e32 v40, v14, v14
	v_fmac_f32_e32 v41, v16, v16
	v_fmac_f32_e32 v48, v10, v10
	v_fmac_f32_e32 v49, v12, v12
	s_waitcnt vmcnt(4)
	v_pk_fma_f32 v[44:45], v[64:65], v[44:45], v[68:69]
	v_pk_fma_f32 v[42:43], v[62:63], v[42:43], v[66:67]
	v_cvt_pk_bf16_f32 v37, v12, v13
	v_add_f32_e32 v13, v46, v47
	v_add_f32_e32 v10, 0, v11
	v_add_f32_e32 v11, v40, v41
	v_add_f32_e32 v12, v48, v49
	global_store_dwordx4 v[30:31], v[14:17], off
	v_cvt_pk_bf16_f32 v34, v14, v15
	v_cvt_pk_bf16_f32 v35, v16, v17
	v_add_f32_e32 v14, v10, v13
	v_add_f32_e32 v15, v11, v12
	v_pk_mul_f32 v[10:11], v[42:43], s[2:3] op_sel_hi:[1,0]
	v_pk_mul_f32 v[12:13], v[44:45], s[2:3] op_sel_hi:[1,0]
	v_pk_fma_f32 v[6:7], v[6:7], 0.5, v[10:11] op_sel_hi:[1,0,1]
	v_pk_fma_f32 v[8:9], v[8:9], 0.5, v[12:13] op_sel_hi:[1,0,1]
	v_add_f32_e32 v10, v6, v7
	v_add_f32_e32 v11, v8, v9
	v_add_f32_e32 v10, v10, v11
	v_add_f32_e32 v14, v14, v10
	v_mul_f32_e32 v10, v7, v7
	v_mul_f32_e32 v11, v9, v9
	v_fmac_f32_e32 v10, v6, v6
	v_fmac_f32_e32 v11, v8, v8
	v_add_f32_e32 v10, v10, v11
	v_add_f32_e32 v15, v15, v10
	s_waitcnt vmcnt(2)
; __device__ __forceinline__ float xsum16(float v) { const auto r = __builtin_amdgcn_permlane16_swap(__float_as_uint(v), __float_as_uint(v), false, false); return __uint_as_float(r[0]) + __uint_as_float(r[1]); }
; __device__ __forceinline__ float xsum32(float v) { const auto r = __builtin_amdgcn_permlane32_swap(__float_as_uint(v), __float_as_uint(v), false, false); return __uint_as_float(r[0]) + __uint_as_float(r[1]); }
; __device__ __forceinline__ size_t blk_off(int r, int c, int K) { return (size_t)(r >> 8) * 256 * K + (size_t)(c >> 6) * (256 * 64) + (size_t)((r & 255) * 64 + (c & 63)); }
; __device__ __forceinline__ u32x4 pack8(const f32x4 a, const f32x4 b) { u32x4 w; w.x = cvt_pk_bf16(a[0], a[1]); w.y = cvt_pk_bf16(a[2], a[3]); w.z = cvt_pk_bf16(b[0], b[1]); w.w = cvt_pk_bf16(b[2], b[3]); return w; }
;     __device__ __forceinline__ void operator()(const f32x4 (&acc)[2][2][4][2], const pg8::Unit& u, int wr, int wc, int fr, int fq) const {
;     ...
;                 for (int bj = 0; bj < 2; ++bj) { float* yp = Y + (size_t)row * D_ + col0 + bj * 128; f32x4 v[2];
; #pragma unroll
;                     for (int n = 0; n < 2; ++n) { v[n] = (((yv[bj][n] - mu) * rs) * gq[bj][n] + bq_[bj][n]) * ALPHA_ + acc[ai][bj][m][n] * sc;
;                         *(f32x4*)(yp + 4 * n) = v[n]; s1 += (v[n][0] + v[n][1]) + (v[n][2] + v[n][3]); s2 += (v[n][0] * v[n][0] + v[n][1] * v[n][1]) + (v[n][2] * v[n][2] + v[n][3] * v[n][3]); }
;                     *(u32x4*)(Yb + blk_off(row, col0 + bj * 128, D_)) = pack8(v[0], v[1]); }
;                 s1 = xsum32(xsum16(s1)); s2 = xsum32(xsum16(s2));
;                 if (fq == 0) *(f32x2*)(stn + (size_t)row * 32 + (u.pn * 4 + wc) * 2) = (f32x2){s1, s2}; asm volatile("" ::: "memory"); } }
	v_sub_f32_e32 v11, v29, v33
	v_sub_f32_e32 v10, v28, v33
	v_sub_f32_e32 v13, v27, v33
	v_sub_f32_e32 v12, v26, v33
	v_pk_mul_f32 v[12:13], v[32:33], v[12:13] op_sel_hi:[0,1]
	v_pk_mul_f32 v[10:11], v[32:33], v[10:11] op_sel_hi:[0,1]
	v_pk_fma_f32 v[10:11], v[20:21], v[10:11], v[24:25]
	v_pk_fma_f32 v[12:13], v[18:19], v[12:13], v[22:23]
	v_pk_mul_f32 v[10:11], v[10:11], s[2:3] op_sel_hi:[1,0]
	v_pk_mul_f32 v[12:13], v[12:13], s[2:3] op_sel_hi:[1,0]
	v_pk_fma_f32 v[4:5], v[4:5], 0.5, v[10:11] op_sel_hi:[1,0,1]
	v_pk_fma_f32 v[2:3], v[2:3], 0.5, v[12:13] op_sel_hi:[1,0,1]
	v_add_f32_e32 v11, v4, v5
	v_add_f32_e32 v10, v2, v3
	v_add_f32_e32 v10, v10, v11
	v_mul_f32_e32 v11, v3, v3
	v_mul_f32_e32 v12, v5, v5
	v_add_f32_e32 v10, v14, v10
	v_fmac_f32_e32 v11, v2, v2
	v_fmac_f32_e32 v12, v4, v4
	global_store_dwordx4 v[70:71], v[34:37], off
	s_nop 0
	s_nop 1
	v_bfe_u32 v17, v227, 4, 2
	v_sub_u32_e32 v16, 0, v17
	v_lshlrev_b32_e32 v16, 4, v16
	v_ashrrev_i32_e32 v17, 31, v16
	v_lshl_add_u64 v[16:17], v[30:31], 0, v[16:17]
	v_permlane16_swap_b32_e32 v6, v2
	v_permlane16_swap_b32_e32 v7, v3
	v_permlane16_swap_b32_e32 v8, v4
	v_permlane16_swap_b32_e32 v9, v5
	v_permlane32_swap_b32_e32 v6, v2
	v_permlane32_swap_b32_e32 v7, v3
	v_permlane32_swap_b32_e32 v8, v4
	v_permlane32_swap_b32_e32 v9, v5
	v_mov_b32_e32 v13, v6
	v_mov_b32_e32 v14, v7
	v_mov_b32_e32 v20, v8
	v_mov_b32_e32 v21, v9
	v_bfe_u32 v18, v227, 3, 1
	v_mul_i32_i24_e32 v18, 0xffff8040, v18
	v_ashrrev_i32_e32 v19, 31, v18
	v_lshl_add_u64 v[16:17], v[16:17], 0, v[18:19]
	v_mov_b32_e32 v18, 0x8000
	v_mov_b32_e32 v19, 0
	v_lshl_add_u64 v[18:19], v[16:17], 0, v[18:19]
	v_mov_b32_dpp v6, v2 row_ror:8 row_mask:0xf bank_mask:0xc
	v_mov_b32_dpp v7, v3 row_ror:8 row_mask:0xf bank_mask:0xc
	v_mov_b32_dpp v8, v4 row_ror:8 row_mask:0xf bank_mask:0xc
	v_mov_b32_dpp v9, v5 row_ror:8 row_mask:0xf bank_mask:0xc
	v_mov_b32_dpp v2, v13 row_ror:8 row_mask:0xf bank_mask:0x3
	v_mov_b32_dpp v3, v14 row_ror:8 row_mask:0xf bank_mask:0x3
	v_mov_b32_dpp v4, v20 row_ror:8 row_mask:0xf bank_mask:0x3
	v_mov_b32_dpp v5, v21 row_ror:8 row_mask:0xf bank_mask:0x3
	global_store_dwordx4 v[16:17], v[6:9], off offset:512 nt
	global_store_dwordx4 v[18:19], v[2:5], off offset:512 nt
	s_nop 1
	v_mov_b32_dpp v2, v6 row_ror:8 row_mask:0xf bank_mask:0x3
	v_mov_b32_dpp v3, v7 row_ror:8 row_mask:0xf bank_mask:0x3
	v_mov_b32_dpp v4, v8 row_ror:8 row_mask:0xf bank_mask:0x3
	v_mov_b32_dpp v5, v9 row_ror:8 row_mask:0xf bank_mask:0x3
	v_mov_b32_e32 v6, v13
	v_mov_b32_e32 v7, v14
	v_mov_b32_e32 v8, v20
	v_mov_b32_e32 v9, v21
	s_nop 1
	v_permlane32_swap_b32_e32 v6, v2
	v_permlane32_swap_b32_e32 v7, v3
	v_permlane32_swap_b32_e32 v8, v4
	v_permlane32_swap_b32_e32 v9, v5
	v_permlane16_swap_b32_e32 v6, v2
	v_permlane16_swap_b32_e32 v7, v3
	v_permlane16_swap_b32_e32 v8, v4
	v_permlane16_swap_b32_e32 v9, v5
	v_add_f32_e32 v11, v11, v12
	v_cvt_pk_bf16_f32 v6, v6, v7
	v_cvt_pk_bf16_f32 v7, v8, v9
	v_cvt_pk_bf16_f32 v8, v2, v3
	v_lshl_add_u64 v[2:3], v[78:79], 0, v[0:1]
	v_mov_b32_e32 v0, v10
	v_add_f32_e32 v11, v15, v11
	v_cvt_pk_bf16_f32 v9, v4, v5
	v_permlane16_swap_b32_e32 v10, v0
	global_store_dwordx4 v[2:3], v[6:9], off
	v_add_f32_e32 v2, v10, v0
	v_mov_b32_e32 v0, v11
	s_nop 1
	v_permlane16_swap_b32_e32 v11, v0
	v_add_f32_e32 v3, v11, v0
	v_mov_b32_e32 v4, v2
	v_mov_b32_e32 v5, v3
	s_nop 0
	v_permlane32_swap_b32_e32 v2, v4
	v_permlane32_swap_b32_e32 v3, v5
	s_and_saveexec_b64 s[26:27], s[44:45]
	s_cbranch_execz .LBB0_388
	v_pk_add_f32 v[2:3], v[2:3], v[4:5]
	v_lshlrev_b64 v[4:5], 7, v[74:75]
	v_lshl_add_u64 v[4:5], s[30:31], 0, v[4:5]
	v_lshl_add_u64 v[4:5], s[24:25], 2, v[4:5]
	global_store_dwordx2 v[4:5], v[2:3], off

; __device__ __forceinline__ float xsum16(float v) { const auto r = __builtin_amdgcn_permlane16_swap(__float_as_uint(v), __float_as_uint(v), false, false); return __uint_as_float(r[0]) + __uint_as_float(r[1]); }
; __device__ __forceinline__ float xsum32(float v) { const auto r = __builtin_amdgcn_permlane32_swap(__float_as_uint(v), __float_as_uint(v), false, false); return __uint_as_float(r[0]) + __uint_as_float(r[1]); }
; __device__ __forceinline__ void row_stats4(const float* st, int rowb, int fq, float (&mu)[4], float (&rs)[4]) {
;     ...
;     for (int m = 0; m < 4; ++m) { const f32x4* p = (const f32x4*)(st + (size_t)(rowb + m * 16) * 32 + fq * 8); a[m] = p[0]; b[m] = p[1]; }
; #pragma unroll
;     for (int m = 0; m < 4; ++m) { float s1 = (a[m][0] + a[m][2]) + (b[m][0] + b[m][2]), s2 = (a[m][1] + a[m][3]) + (b[m][1] + b[m][3]);
;         s1 = xsum32(xsum16(s1)); s2 = xsum32(xsum16(s2));
;         const float mm = s1 * (1.0f / 1024.0f); mu[m] = mm; rs[m] = rsqrtf(fmaxf(s2 * (1.0f / 1024.0f) - mm * mm, 0.f) + LN_EPS_); }
;     __device__ __forceinline__ void operator()(const f32x4 (&acc)[2][2][4][2], const pg8::Unit& u, int wr, int wc, int fr, int fq) const {
;     ...
;         for (int ai = 0; ai < 2; ++ai) { float mu4[4], rs4[4]; row_stats4(stp, row0 + ai * 128, fq, mu4, rs4);
; #pragma unroll
;             for (int m = 0; m < 4; ++m) { const int row = row0 + ai * 128 + m * 16; const float mu = mu4[m], rs = rs4[m];
;                 f32x4 yv[2][2], gq[2][2], bq_[2][2];
; #pragma unroll
;                 for (int bj = 0; bj < 2; ++bj)
; #pragma unroll
;                     for (int n = 0; n < 2; ++n) { yv[bj][n] = *(const f32x4*)(Yin + (size_t)row * D_ + col0 + bj * 128 + 4 * n); gq[bj][n] = *(const f32x4*)(g + col0 + bj * 128 + 4 * n); bq_[bj][n] = *(const f32x4*)(b + col0 + bj * 128 + 4 * n); }
.LBB0_1535:
	s_lshl_b32 s3, s3, 8
	s_add_i32 s3, s3, s0
	v_or_b32_e32 v158, s3, v184
	v_ashrrev_i32_e32 v159, 31, v158
	v_lshlrev_b64 v[130:131], 7, v[158:159]
	v_lshl_add_u64 v[136:137], v[146:147], 0, v[130:131]
	v_or_b32_e32 v180, 16, v158
	global_load_dwordx4 v[132:135], v[136:137], off
	global_load_dwordx4 v[166:169], v[136:137], off offset:16
	v_ashrrev_i32_e32 v181, 31, v180
	v_lshlrev_b64 v[172:173], 7, v[180:181]
	v_lshl_add_u64 v[136:137], v[146:147], 0, v[172:173]
	global_load_dwordx4 v[174:177], v[136:137], off
	global_load_dwordx4 v[186:189], v[136:137], off offset:16
	v_or_b32_e32 v170, 32, v158
	v_ashrrev_i32_e32 v171, 31, v170
	v_lshlrev_b64 v[164:165], 7, v[170:171]
	v_lshl_add_u64 v[136:137], v[146:147], 0, v[164:165]
	global_load_dwordx4 v[190:193], v[136:137], off
	global_load_dwordx4 v[198:201], v[136:137], off offset:16
	v_or_b32_e32 v162, 48, v158
	v_ashrrev_i32_e32 v163, 31, v162
	v_lshlrev_b64 v[160:161], 7, v[162:163]
	v_lshl_add_u64 v[182:183], v[146:147], 0, v[160:161]
	global_load_dwordx4 v[202:205], v[182:183], off
	global_load_dwordx4 v[206:209], v[182:183], off offset:16
	s_load_dwordx16 s[64:79], s[34:35], 0x38
	s_lshl_b32 s1, s2, 8
	s_lshl_b32 s14, s2, 3
	s_or_b32 s2, s1, s57
	v_or_b32_e32 v152, s2, v185
	v_ashrrev_i32_e32 v153, 31, v152
	v_lshlrev_b64 v[136:137], 12, v[158:159]
	v_lshlrev_b64 v[178:179], 2, v[152:153]
	s_waitcnt lgkmcnt(0)
	v_lshl_add_u64 v[136:137], s[78:79], 0, v[136:137]
	v_lshl_add_u64 v[156:157], s[8:9], 0, v[178:179]
	v_lshl_add_u64 v[154:155], s[10:11], 0, v[178:179]
	v_lshl_add_u64 v[136:137], v[136:137], 0, v[178:179]
	s_or_b32 s52, s14, s61
	s_mov_b32 s14, 0x3a800000
	global_load_dwordx4 v[210:213], v[136:137], off offset:16
	global_load_dwordx4 v[214:217], v[136:137], off
	global_load_dwordx4 v[218:221], v[156:157], off offset:16
	global_load_dwordx4 v[222:225], v[156:157], off
	global_load_dwordx4 v[234:237], v[154:155], off offset:16
	global_load_dwordx4 v[238:241], v[154:155], off
	s_mov_b32 s1, 0x800000
	s_mov_b32 s18, 0x3fd744fd
	v_bitop3_b32 v196, s2, 56, v185 bitop3:0xc8
	s_ashr_i32 s2, s2, 6
	s_ashr_i32 s53, s52, 31
	v_readlane_b32 s16, v253, 59
	v_readlane_b32 s17, v253, 60
	s_waitcnt vmcnt(0)
	v_mov_b32_e32 v178, v132
	v_mov_b32_e32 v179, v166
	v_mov_b32_e32 v182, v134
	v_mov_b32_e32 v183, v168
	v_mov_b32_e32 v166, v133
	v_mov_b32_e32 v168, v135
	v_pk_add_f32 v[132:133], v[178:179], v[182:183]
	v_pk_add_f32 v[134:135], v[166:167], v[168:169]
	v_pk_add_f32 v[132:133], v[132:133], v[132:133] op_sel:[0,1] op_sel_hi:[1,0]
	v_pk_add_f32 v[134:135], v[134:135], v[134:135] op_sel:[0,1] op_sel_hi:[1,0]
	v_mov_b32_e32 v166, v174
	v_mov_b32_e32 v167, v186
	v_mov_b32_e32 v168, v176
	v_mov_b32_e32 v169, v188
	v_mov_b32_e32 v0, v132
	v_mov_b32_e32 v133, v134
	v_pk_add_f32 v[166:167], v[166:167], v[168:169]
	v_permlane16_swap_b32_e32 v132, v0
	v_permlane16_swap_b32_e32 v134, v133
	v_mov_b32_e32 v188, v177
	v_pk_add_f32 v[166:167], v[166:167], v[166:167] op_sel:[0,1] op_sel_hi:[1,0]
	v_add_f32_e32 v177, v132, v0
	v_add_f32_e32 v176, v134, v133
	v_mov_b32_e32 v135, v166
	v_mov_b32_e32 v179, v177
	v_mov_b32_e32 v178, v176
	v_permlane16_swap_b32_e32 v166, v135
	v_permlane32_swap_b32_e32 v177, v179
	v_permlane32_swap_b32_e32 v176, v178
	v_mov_b32_e32 v186, v175
	v_add_f32_e32 v133, v166, v135
	v_pk_add_f32 v[166:167], v[176:177], v[178:179]
	v_pk_add_f32 v[168:169], v[186:187], v[188:189]
	v_pk_mul_f32 v[178:179], v[166:167], s[14:15] op_sel_hi:[1,0]
	v_pk_add_f32 v[168:169], v[168:169], v[168:169] op_sel:[0,1] op_sel_hi:[1,0]
	v_fma_f32 v0, -v179, v179, v178
	v_mov_b32_e32 v159, v168
	v_max_f32_e32 v0, 0, v0
	s_nop 0
	v_permlane16_swap_b32_e32 v168, v159
	v_add_f32_e32 v0, 0x3727c5ac, v0
	v_add_f32_e32 v132, v168, v159
	v_mul_f32_e32 v159, 0x4b800000, v0
	v_cmp_gt_f32_e32 vcc, s1, v0
	v_mov_b32_e32 v174, v190
	v_mov_b32_e32 v175, v198
	v_cndmask_b32_e32 v0, v0, v159, vcc
	v_rsq_f32_e32 v0, v0
	v_mov_b32_e32 v166, v192
	v_mov_b32_e32 v167, v200
	v_pk_add_f32 v[166:167], v[174:175], v[166:167]
	v_mul_f32_e32 v159, 0x45800000, v0
	v_pk_add_f32 v[166:167], v[166:167], v[166:167] op_sel:[0,1] op_sel_hi:[1,0]
	v_mov_b32_e32 v198, v191
	v_mov_b32_e32 v200, v193
	v_cndmask_b32_e32 v0, v0, v159, vcc
	v_pk_add_f32 v[168:169], v[198:199], v[200:201]
	v_mov_b32_e32 v159, v166
	v_pk_add_f32 v[168:169], v[168:169], v[168:169] op_sel:[0,1] op_sel_hi:[1,0]
	s_nop 0
	v_permlane16_swap_b32_e32 v166, v159
	v_add_f32_e32 v175, v166, v159
	v_mov_b32_e32 v159, v168
	s_nop 1
	v_permlane16_swap_b32_e32 v168, v159
	global_load_dwordx4 v[186:189], v[136:137], off offset:528
	global_load_dwordx4 v[190:193], v[136:137], off offset:512
	v_add_f32_e32 v174, v168, v159
	v_mov_b32_e32 v166, v202
	v_mov_b32_e32 v167, v206
	v_mov_b32_e32 v168, v204
	v_mov_b32_e32 v169, v208
	v_mov_b32_e32 v206, v203
	v_mov_b32_e32 v208, v205
	v_pk_add_f32 v[166:167], v[166:167], v[168:169]
	v_pk_add_f32 v[168:169], v[206:207], v[208:209]
	global_load_dwordx4 v[198:201], v[156:157], off offset:528
	global_load_dwordx4 v[202:205], v[156:157], off offset:512
	global_load_dwordx4 v[206:209], v[154:155], off offset:528
	global_load_dwordx4 v[242:245], v[154:155], off offset:512
	v_sub_f32_e32 v183, v215, v179
	v_sub_f32_e32 v182, v214, v179
	v_sub_f32_e32 v215, v217, v179
	v_sub_f32_e32 v214, v216, v179
	v_pk_mul_f32 v[214:215], v[0:1], v[214:215] op_sel_hi:[0,1]
	v_pk_mul_f32 v[182:183], v[0:1], v[182:183] op_sel_hi:[0,1]
	v_pk_fma_f32 v[182:183], v[222:223], v[182:183], v[238:239]
	v_pk_fma_f32 v[214:215], v[224:225], v[214:215], v[240:241]
	v_pk_fma_f32 v[126:127], v[182:183], s[18:19], v[126:127] op_sel_hi:[1,0,1]
; __device__ __forceinline__ size_t blk_off(int r, int c, int K) { return (size_t)(r >> 8) * 256 * K + (size_t)(c >> 6) * (256 * 64) + (size_t)((r & 255) * 64 + (c & 63)); }
; __device__ __forceinline__ u32x4 pack8(const f32x4 a, const f32x4 b) { u32x4 w; w.x = cvt_pk_bf16(a[0], a[1]); w.y = cvt_pk_bf16(a[2], a[3]); w.z = cvt_pk_bf16(b[0], b[1]); w.w = cvt_pk_bf16(b[2], b[3]); return w; }
;     __device__ __forceinline__ void operator()(const f32x4 (&acc)[2][2][4][2], const pg8::Unit& u, int wr, int wc, int fr, int fq) const {
;     ...
;                     for (int n = 0; n < 2; ++n) { yv[bj][n] = *(const f32x4*)(Yin + (size_t)row * D_ + col0 + bj * 128 + 4 * n); gq[bj][n] = *(const f32x4*)(g + col0 + bj * 128 + 4 * n); bq_[bj][n] = *(const f32x4*)(b + col0 + bj * 128 + 4 * n); }
;                 asm volatile("" ::: "memory");
;                 float s1 = 0.f, s2 = 0.f;
; #pragma unroll
;                 for (int bj = 0; bj < 2; ++bj) { float* yp = Y + (size_t)row * D_ + col0 + bj * 128; f32x4 v[2];
; #pragma unroll
;                     for (int n = 0; n < 2; ++n) { v[n] = (((yv[bj][n] - mu) * rs) * gq[bj][n] + bq_[bj][n]) * ALPHA_ + acc[ai][bj][m][n] * sc;
;                         *(f32x4*)(yp + 4 * n) = v[n]; s1 += (v[n][0] + v[n][1]) + (v[n][2] + v[n][3]); s2 += (v[n][0] * v[n][0] + v[n][1] * v[n][1]) + (v[n][2] * v[n][2] + v[n][3] * v[n][3]); }
;                     *(u32x4*)(Yb + blk_off(row, col0 + bj * 128, D_)) = pack8(v[0], v[1]); }
	v_pk_fma_f32 v[128:129], v[214:215], s[18:19], v[128:129] op_sel_hi:[1,0,1]
	v_add_f32_e32 v178, v126, v127
	v_add_f32_e32 v182, v128, v129
	v_add_f32_e32 v178, v178, v182
	v_mul_f32_e32 v182, v127, v127
	v_mul_f32_e32 v183, v129, v129
	v_fmac_f32_e32 v182, v126, v126
	v_fmac_f32_e32 v183, v128, v128
	v_add_f32_e32 v197, v182, v183
	v_sub_f32_e32 v183, v211, v179
	v_sub_f32_e32 v182, v210, v179
	v_sub_f32_e32 v211, v213, v179
	v_sub_f32_e32 v210, v212, v179
	v_pk_mul_f32 v[210:211], v[0:1], v[210:211] op_sel_hi:[0,1]
	v_pk_mul_f32 v[182:183], v[0:1], v[182:183] op_sel_hi:[0,1]
	v_pk_fma_f32 v[182:183], v[218:219], v[182:183], v[234:235]
	v_pk_fma_f32 v[210:211], v[220:221], v[210:211], v[236:237]
	v_pk_add_f32 v[166:167], v[166:167], v[166:167] op_sel:[0,1] op_sel_hi:[1,0]
	v_pk_fma_f32 v[124:125], v[210:211], s[18:19], v[124:125] op_sel_hi:[1,0,1]
	v_pk_fma_f32 v[122:123], v[182:183], s[18:19], v[122:123] op_sel_hi:[1,0,1]
	v_mov_b32_e32 v159, v166
	v_add_f32_e32 v182, v122, v123
	v_add_f32_e32 v183, v124, v125
	v_pk_add_f32 v[168:169], v[168:169], v[168:169] op_sel:[0,1] op_sel_hi:[1,0]
	v_permlane16_swap_b32_e32 v166, v159
	v_add_f32_e32 v178, 0, v178
	v_add_f32_e32 v182, v182, v183
	v_add_f32_e32 v167, v166, v159
	v_mov_b32_e32 v159, v168
	s_ashr_i32 s14, s3, 8
	v_add_f32_e32 v178, v178, v182
	v_mul_f32_e32 v182, v123, v123
	v_mul_f32_e32 v183, v125, v125
	v_permlane16_swap_b32_e32 v168, v159
	s_ashr_i32 s15, s14, 31
	s_nop 0
	s_nop 1
	v_bfe_u32 v135, v227, 4, 2
	v_sub_u32_e32 v134, 0, v135
	v_lshlrev_b32_e32 v134, 4, v134
	v_ashrrev_i32_e32 v135, 31, v134
	v_lshl_add_u64 v[134:135], v[136:137], 0, v[134:135]
	v_permlane16_swap_b32_e32 v126, v122
	v_permlane16_swap_b32_e32 v127, v123
	v_permlane16_swap_b32_e32 v128, v124
	v_permlane16_swap_b32_e32 v129, v125
	v_permlane32_swap_b32_e32 v126, v122
	v_permlane32_swap_b32_e32 v127, v123
	v_permlane32_swap_b32_e32 v128, v124
	v_permlane32_swap_b32_e32 v129, v125
	v_mov_b32_e32 v166, v126
	v_mov_b32_e32 v169, v127
	v_mov_b32_e32 v210, v128
	v_mov_b32_e32 v211, v129
	v_bfe_u32 v176, v227, 3, 1
	v_mul_i32_i24_e32 v176, 0xffff8040, v176
	v_ashrrev_i32_e32 v177, 31, v176
	v_lshl_add_u64 v[134:135], v[134:135], 0, v[176:177]
	v_mov_b32_e32 v176, 0x8000
	v_mov_b32_e32 v177, 0
	v_lshl_add_u64 v[176:177], v[134:135], 0, v[176:177]
	v_mov_b32_dpp v126, v122 row_ror:8 row_mask:0xf bank_mask:0xc
	v_mov_b32_dpp v127, v123 row_ror:8 row_mask:0xf bank_mask:0xc
	v_mov_b32_dpp v128, v124 row_ror:8 row_mask:0xf bank_mask:0xc
	v_mov_b32_dpp v129, v125 row_ror:8 row_mask:0xf bank_mask:0xc
	v_mov_b32_dpp v122, v166 row_ror:8 row_mask:0xf bank_mask:0x3
	v_mov_b32_dpp v123, v169 row_ror:8 row_mask:0xf bank_mask:0x3
	v_mov_b32_dpp v124, v210 row_ror:8 row_mask:0xf bank_mask:0x3
	v_mov_b32_dpp v125, v211 row_ror:8 row_mask:0xf bank_mask:0x3
	global_store_dwordx4 v[134:135], v[126:129], off nt
	global_store_dwordx4 v[176:177], v[122:125], off nt
	s_nop 1
	v_mov_b32_dpp v122, v126 row_ror:8 row_mask:0xf bank_mask:0x3
	v_mov_b32_dpp v123, v127 row_ror:8 row_mask:0xf bank_mask:0x3
	v_mov_b32_dpp v124, v128 row_ror:8 row_mask:0xf bank_mask:0x3
	v_mov_b32_dpp v125, v129 row_ror:8 row_mask:0xf bank_mask:0x3
	v_mov_b32_e32 v126, v166
	v_mov_b32_e32 v127, v169
	v_mov_b32_e32 v128, v210
	v_mov_b32_e32 v129, v211
	s_nop 1
	v_permlane32_swap_b32_e32 v126, v122
	v_permlane32_swap_b32_e32 v127, v123
	v_permlane32_swap_b32_e32 v128, v124
	v_permlane32_swap_b32_e32 v129, v125
	v_permlane16_swap_b32_e32 v126, v122
	v_permlane16_swap_b32_e32 v127, v123
	v_permlane16_swap_b32_e32 v128, v124
	v_permlane16_swap_b32_e32 v129, v125
	v_fmac_f32_e32 v182, v122, v122
	v_fmac_f32_e32 v183, v124, v124
	v_cvt_pk_bf16_f32 v126, v126, v127
	v_cvt_pk_bf16_f32 v127, v128, v129
	v_cvt_pk_bf16_f32 v128, v122, v123
	v_cvt_pk_bf16_f32 v129, v124, v125
	v_add_f32_e32 v166, v168, v159
	s_lshl_b64 s[14:15], s[14:15], 19
	v_lshlrev_b32_e32 v159, 6, v158
	s_movk_i32 s1, 0x33c0
	s_ashr_i32 s3, s2, 31
	v_and_or_b32 v159, v159, s1, v196
	s_add_u32 s1, s16, s14
	s_addc_u32 s14, s17, s15
	s_lshl_b64 s[24:25], s[2:3], 15
	s_add_u32 s42, s1, s24
	s_addc_u32 s43, s14, s25
	v_lshlrev_b32_e32 v159, 1, v159
	global_store_dwordx4 v159, v[126:129], s[42:43]
	v_add_f32_e32 v182, v182, v183
	s_waitcnt vmcnt(7)
	v_sub_f32_e32 v123, v191, v179
	v_sub_f32_e32 v122, v190, v179
	v_sub_f32_e32 v125, v193, v179
	v_sub_f32_e32 v124, v192, v179
	v_pk_mul_f32 v[124:125], v[0:1], v[124:125] op_sel_hi:[0,1]
	v_pk_mul_f32 v[122:123], v[0:1], v[122:123] op_sel_hi:[0,1]
	v_add_f32_e32 v182, v197, v182
	s_or_b32 s2, s2, 2
	s_ashr_i32 s3, s2, 31
	s_lshl_b64 s[28:29], s[2:3], 15
	s_waitcnt vmcnt(3)
; __device__ __forceinline__ float xsum16(float v) { const auto r = __builtin_amdgcn_permlane16_swap(__float_as_uint(v), __float_as_uint(v), false, false); return __uint_as_float(r[0]) + __uint_as_float(r[1]); }
; __device__ __forceinline__ float xsum32(float v) { const auto r = __builtin_amdgcn_permlane32_swap(__float_as_uint(v), __float_as_uint(v), false, false); return __uint_as_float(r[0]) + __uint_as_float(r[1]); }
; __device__ __forceinline__ size_t blk_off(int r, int c, int K) { return (size_t)(r >> 8) * 256 * K + (size_t)(c >> 6) * (256 * 64) + (size_t)((r & 255) * 64 + (c & 63)); }
; __device__ __forceinline__ u32x4 pack8(const f32x4 a, const f32x4 b) { u32x4 w; w.x = cvt_pk_bf16(a[0], a[1]); w.y = cvt_pk_bf16(a[2], a[3]); w.z = cvt_pk_bf16(b[0], b[1]); w.w = cvt_pk_bf16(b[2], b[3]); return w; }
;     __device__ __forceinline__ void operator()(const f32x4 (&acc)[2][2][4][2], const pg8::Unit& u, int wr, int wc, int fr, int fq) const {
;     ...
;                 for (int bj = 0; bj < 2; ++bj) { float* yp = Y + (size_t)row * D_ + col0 + bj * 128; f32x4 v[2];
; #pragma unroll
;                     for (int n = 0; n < 2; ++n) { v[n] = (((yv[bj][n] - mu) * rs) * gq[bj][n] + bq_[bj][n]) * ALPHA_ + acc[ai][bj][m][n] * sc;
;                         *(f32x4*)(yp + 4 * n) = v[n]; s1 += (v[n][0] + v[n][1]) + (v[n][2] + v[n][3]); s2 += (v[n][0] * v[n][0] + v[n][1] * v[n][1]) + (v[n][2] * v[n][2] + v[n][3] * v[n][3]); }
;                     *(u32x4*)(Yb + blk_off(row, col0 + bj * 128, D_)) = pack8(v[0], v[1]); }
;                 s1 = xsum32(xsum16(s1)); s2 = xsum32(xsum16(s2));
;                 if (fq == 0) *(f32x2*)(stn + (size_t)row * 32 + (u.pn * 4 + wc) * 2) = (f32x2){s1, s2}; asm volatile("" ::: "memory"); } }
	v_pk_fma_f32 v[122:123], v[202:203], v[122:123], v[242:243]
	v_pk_fma_f32 v[124:125], v[204:205], v[124:125], v[244:245]
	v_pk_fma_f32 v[118:119], v[122:123], s[18:19], v[118:119] op_sel_hi:[1,0,1]
	v_pk_fma_f32 v[120:121], v[124:125], s[18:19], v[120:121] op_sel_hi:[1,0,1]
	v_add_f32_e32 v122, v118, v119
	v_add_f32_e32 v123, v120, v121
	v_add_f32_e32 v122, v122, v123
	v_add_f32_e32 v126, v178, v122
	v_mul_f32_e32 v122, v119, v119
	v_mul_f32_e32 v123, v121, v121
	v_fmac_f32_e32 v122, v118, v118
	v_fmac_f32_e32 v123, v120, v120
	v_add_f32_e32 v122, v122, v123
	v_add_f32_e32 v127, v182, v122
	v_sub_f32_e32 v123, v187, v179
	v_sub_f32_e32 v122, v186, v179
	v_sub_f32_e32 v125, v189, v179
	v_sub_f32_e32 v124, v188, v179
	v_pk_mul_f32 v[124:125], v[0:1], v[124:125] op_sel_hi:[0,1]
	v_pk_mul_f32 v[122:123], v[0:1], v[122:123] op_sel_hi:[0,1]
	v_pk_fma_f32 v[122:123], v[198:199], v[122:123], v[206:207]
	v_pk_fma_f32 v[124:125], v[200:201], v[124:125], v[208:209]
	v_pk_fma_f32 v[114:115], v[122:123], s[18:19], v[114:115] op_sel_hi:[1,0,1]
	v_pk_fma_f32 v[116:117], v[124:125], s[18:19], v[116:117] op_sel_hi:[1,0,1]
	v_add_f32_e32 v0, v114, v115
	v_add_f32_e32 v122, v116, v117
	v_add_f32_e32 v0, v0, v122
	v_mul_f32_e32 v122, v115, v115
	v_mul_f32_e32 v123, v117, v117
	v_add_f32_e32 v0, v126, v0
	v_fmac_f32_e32 v122, v114, v114
	v_fmac_f32_e32 v123, v116, v116
	s_nop 0
	s_nop 1
	v_bfe_u32 v125, v227, 4, 2
	v_sub_u32_e32 v124, 0, v125
	v_lshlrev_b32_e32 v124, 4, v124
	v_ashrrev_i32_e32 v125, 31, v124
	v_lshl_add_u64 v[124:125], v[136:137], 0, v[124:125]
	v_permlane16_swap_b32_e32 v118, v114
	v_permlane16_swap_b32_e32 v119, v115
	v_permlane16_swap_b32_e32 v120, v116
	v_permlane16_swap_b32_e32 v121, v117
	v_permlane32_swap_b32_e32 v118, v114
	v_permlane32_swap_b32_e32 v119, v115
	v_permlane32_swap_b32_e32 v120, v116
	v_permlane32_swap_b32_e32 v121, v117
	v_mov_b32_e32 v134, v118
	v_mov_b32_e32 v135, v119
	v_mov_b32_e32 v168, v120
	v_mov_b32_e32 v169, v121
	v_bfe_u32 v128, v227, 3, 1
	v_mul_i32_i24_e32 v128, 0xffff8040, v128
	v_ashrrev_i32_e32 v129, 31, v128
	v_lshl_add_u64 v[124:125], v[124:125], 0, v[128:129]
	v_mov_b32_e32 v128, 0x8000
	v_mov_b32_e32 v129, 0
	v_lshl_add_u64 v[128:129], v[124:125], 0, v[128:129]
	v_mov_b32_dpp v118, v114 row_ror:8 row_mask:0xf bank_mask:0xc
	v_mov_b32_dpp v119, v115 row_ror:8 row_mask:0xf bank_mask:0xc
	v_mov_b32_dpp v120, v116 row_ror:8 row_mask:0xf bank_mask:0xc
	v_mov_b32_dpp v121, v117 row_ror:8 row_mask:0xf bank_mask:0xc
	v_mov_b32_dpp v114, v134 row_ror:8 row_mask:0xf bank_mask:0x3
	v_mov_b32_dpp v115, v135 row_ror:8 row_mask:0xf bank_mask:0x3
	v_mov_b32_dpp v116, v168 row_ror:8 row_mask:0xf bank_mask:0x3
	v_mov_b32_dpp v117, v169 row_ror:8 row_mask:0xf bank_mask:0x3
	global_store_dwordx4 v[124:125], v[118:121], off offset:512 nt
	global_store_dwordx4 v[128:129], v[114:117], off offset:512 nt
	s_nop 1
	v_mov_b32_dpp v114, v118 row_ror:8 row_mask:0xf bank_mask:0x3
	v_mov_b32_dpp v115, v119 row_ror:8 row_mask:0xf bank_mask:0x3
	v_mov_b32_dpp v116, v120 row_ror:8 row_mask:0xf bank_mask:0x3
	v_mov_b32_dpp v117, v121 row_ror:8 row_mask:0xf bank_mask:0x3
	v_mov_b32_e32 v118, v134
	v_mov_b32_e32 v119, v135
	v_mov_b32_e32 v120, v168
	v_mov_b32_e32 v121, v169
	s_nop 1
	v_permlane32_swap_b32_e32 v118, v114
	v_permlane32_swap_b32_e32 v119, v115
	v_permlane32_swap_b32_e32 v120, v116
	v_permlane32_swap_b32_e32 v121, v117
	v_permlane16_swap_b32_e32 v118, v114
	v_permlane16_swap_b32_e32 v119, v115
	v_permlane16_swap_b32_e32 v120, v116
	v_permlane16_swap_b32_e32 v121, v117
	v_add_f32_e32 v122, v122, v123
	v_cvt_pk_bf16_f32 v118, v118, v119
	v_cvt_pk_bf16_f32 v119, v120, v121
	v_cvt_pk_bf16_f32 v120, v114, v115
	v_mov_b32_e32 v114, v0
	v_add_f32_e32 v122, v127, v122
	s_nop 0
	v_permlane16_swap_b32_e32 v0, v114
	v_add_f32_e32 v114, v0, v114
	v_mov_b32_e32 v0, v122
	s_nop 1
	v_permlane16_swap_b32_e32 v122, v0
	v_add_f32_e32 v115, v122, v0
	v_mov_b32_e32 v135, v133
	v_mov_b32_e32 v134, v132
	v_mov_b32_e32 v177, v175
	v_mov_b32_e32 v176, v174
	v_mov_b32_e32 v169, v167
	v_mov_b32_e32 v168, v166
	v_cvt_pk_bf16_f32 v121, v116, v117
	s_add_u32 s40, s1, s28
	v_mov_b32_e32 v116, v114
	v_mov_b32_e32 v117, v115
	v_permlane32_swap_b32_e32 v133, v135
	v_permlane32_swap_b32_e32 v132, v134
	v_permlane32_swap_b32_e32 v175, v177
	v_permlane32_swap_b32_e32 v174, v176
	v_permlane32_swap_b32_e32 v167, v169
	v_permlane32_swap_b32_e32 v166, v168
	s_addc_u32 s41, s14, s29
	v_permlane32_swap_b32_e32 v114, v116
	v_permlane32_swap_b32_e32 v115, v117
	global_store_dwordx4 v159, v[118:121], s[40:41]
	s_and_saveexec_b64 s[26:27], s[44:45]
	s_cbranch_execz .LBB0_1537
	v_pk_add_f32 v[114:115], v[114:115], v[116:117]
	v_lshl_add_u64 v[116:117], s[6:7], 0, v[130:131]
	v_lshl_add_u64 v[116:117], s[52:53], 2, v[116:117]
	global_store_dwordx2 v[116:117], v[114:115], off
; __device__ __forceinline__ size_t blk_off(int r, int c, int K) { return (size_t)(r >> 8) * 256 * K + (size_t)(c >> 6) * (256 * 64) + (size_t)((r & 255) * 64 + (c & 63)); }
; __device__ __forceinline__ u32x4 pack8(const f32x4 a, const f32x4 b) { u32x4 w; w.x = cvt_pk_bf16(a[0], a[1]); w.y = cvt_pk_bf16(a[2], a[3]); w.z = cvt_pk_bf16(b[0], b[1]); w.w = cvt_pk_bf16(b[2], b[3]); return w; }
;     __device__ __forceinline__ void operator()(const f32x4 (&acc)[2][2][4][2], const pg8::Unit& u, int wr, int wc, int fr, int fq) const {
;     ...
;             for (int m = 0; m < 4; ++m) { const int row = row0 + ai * 128 + m * 16; const float mu = mu4[m], rs = rs4[m];
;                 f32x4 yv[2][2], gq[2][2], bq_[2][2];
; #pragma unroll
;                 for (int bj = 0; bj < 2; ++bj)
; #pragma unroll
;                     for (int n = 0; n < 2; ++n) { yv[bj][n] = *(const f32x4*)(Yin + (size_t)row * D_ + col0 + bj * 128 + 4 * n); gq[bj][n] = *(const f32x4*)(g + col0 + bj * 128 + 4 * n); bq_[bj][n] = *(const f32x4*)(b + col0 + bj * 128 + 4 * n); }
;                 asm volatile("" ::: "memory");
;                 float s1 = 0.f, s2 = 0.f;
; #pragma unroll
;                 for (int bj = 0; bj < 2; ++bj) { float* yp = Y + (size_t)row * D_ + col0 + bj * 128; f32x4 v[2];
; #pragma unroll
;                     for (int n = 0; n < 2; ++n) { v[n] = (((yv[bj][n] - mu) * rs) * gq[bj][n] + bq_[bj][n]) * ALPHA_ + acc[ai][bj][m][n] * sc;
;                         *(f32x4*)(yp + 4 * n) = v[n]; s1 += (v[n][0] + v[n][1]) + (v[n][2] + v[n][3]); s2 += (v[n][0] * v[n][0] + v[n][1] * v[n][1]) + (v[n][2] * v[n][2] + v[n][3] * v[n][3]); }
;                     *(u32x4*)(Yb + blk_off(row, col0 + bj * 128, D_)) = pack8(v[0], v[1]); }
.LBB0_1537:
	s_or_b64 exec, exec, s[26:27]
	v_pk_add_f32 v[114:115], v[132:133], v[134:135]
	s_mov_b32 s2, 0x3a800000
	v_pk_mul_f32 v[178:179], v[114:115], s[2:3] op_sel_hi:[1,0]
	s_mov_b32 s1, 0x800000
	v_fma_f32 v0, -v179, v179, v178
	v_max_f32_e32 v0, 0, v0
	v_add_f32_e32 v0, 0x3727c5ac, v0
	v_cmp_gt_f32_e32 vcc, s1, v0
	v_mul_f32_e32 v114, 0x4b800000, v0
	s_load_dwordx16 s[64:79], s[34:35], 0x38
	v_cndmask_b32_e32 v0, v0, v114, vcc
	v_rsq_f32_e32 v0, v0
	v_lshlrev_b32_e32 v159, 6, v180
	s_mov_b32 s2, 0x3fd744fd
	v_mul_f32_e32 v114, 0x45800000, v0
	v_cndmask_b32_e32 v0, v0, v114, vcc
	v_lshlrev_b64 v[114:115], 12, v[180:181]
	s_waitcnt lgkmcnt(0)
	v_lshl_add_u64 v[114:115], s[78:79], 0, v[114:115]
	v_lshl_add_u64 v[182:183], v[152:153], 2, v[114:115]
	global_load_dwordx4 v[186:189], v[182:183], off offset:16
	global_load_dwordx4 v[190:193], v[182:183], off
	global_load_dwordx4 v[198:201], v[156:157], off offset:16
	global_load_dwordx4 v[202:205], v[156:157], off
	global_load_dwordx4 v[206:209], v[154:155], off offset:16
	global_load_dwordx4 v[210:213], v[154:155], off
	global_load_dwordx4 v[114:117], v[182:183], off offset:528
	global_load_dwordx4 v[134:137], v[182:183], off offset:512
	global_load_dwordx4 v[118:121], v[156:157], off offset:528
	global_load_dwordx4 v[126:129], v[156:157], off offset:512
	global_load_dwordx4 v[122:125], v[154:155], off offset:528
	global_load_dwordx4 v[130:133], v[154:155], off offset:512
	s_movk_i32 s1, 0x37c0
	v_and_or_b32 v159, v159, s1, v196
	v_lshlrev_b32_e32 v159, 1, v159
	s_waitcnt vmcnt(10)
	v_sub_f32_e32 v181, v191, v179
	v_sub_f32_e32 v180, v190, v179
	v_sub_f32_e32 v191, v193, v179
	v_sub_f32_e32 v190, v192, v179
	v_pk_mul_f32 v[190:191], v[0:1], v[190:191] op_sel_hi:[0,1]
	v_pk_mul_f32 v[180:181], v[0:1], v[180:181] op_sel_hi:[0,1]
	s_waitcnt vmcnt(6)
	v_pk_fma_f32 v[180:181], v[202:203], v[180:181], v[210:211]
	v_pk_fma_f32 v[190:191], v[204:205], v[190:191], v[212:213]
	v_pk_fma_f32 v[110:111], v[180:181], s[2:3], v[110:111] op_sel_hi:[1,0,1]
	v_pk_fma_f32 v[112:113], v[190:191], s[2:3], v[112:113] op_sel_hi:[1,0,1]
	v_add_f32_e32 v178, v110, v111
	v_add_f32_e32 v180, v112, v113
	v_add_f32_e32 v178, v178, v180
	v_mul_f32_e32 v180, v111, v111
	v_mul_f32_e32 v181, v113, v113
	v_fmac_f32_e32 v180, v110, v110
	v_fmac_f32_e32 v181, v112, v112
	v_add_f32_e32 v190, v180, v181
	v_sub_f32_e32 v181, v187, v179
	v_sub_f32_e32 v180, v186, v179
	v_sub_f32_e32 v187, v189, v179
	v_sub_f32_e32 v186, v188, v179
	v_pk_mul_f32 v[186:187], v[0:1], v[186:187] op_sel_hi:[0,1]
	v_pk_mul_f32 v[180:181], v[0:1], v[180:181] op_sel_hi:[0,1]
	v_pk_fma_f32 v[180:181], v[198:199], v[180:181], v[206:207]
	v_pk_fma_f32 v[186:187], v[200:201], v[186:187], v[208:209]
	v_pk_fma_f32 v[106:107], v[180:181], s[2:3], v[106:107] op_sel_hi:[1,0,1]
	v_pk_fma_f32 v[108:109], v[186:187], s[2:3], v[108:109] op_sel_hi:[1,0,1]
	v_add_f32_e32 v180, v106, v107
	v_add_f32_e32 v181, v108, v109
	v_add_f32_e32 v178, 0, v178
	v_add_f32_e32 v180, v180, v181
	v_add_f32_e32 v178, v178, v180
	v_mul_f32_e32 v180, v107, v107
	v_mul_f32_e32 v181, v109, v109
	s_nop 0
	s_nop 1
	v_bfe_u32 v187, v227, 4, 2
	v_sub_u32_e32 v186, 0, v187
	v_lshlrev_b32_e32 v186, 4, v186
	v_ashrrev_i32_e32 v187, 31, v186
	v_lshl_add_u64 v[186:187], v[182:183], 0, v[186:187]
	v_permlane16_swap_b32_e32 v110, v106
	v_permlane16_swap_b32_e32 v111, v107
	v_permlane16_swap_b32_e32 v112, v108
	v_permlane16_swap_b32_e32 v113, v109
	v_permlane32_swap_b32_e32 v110, v106
	v_permlane32_swap_b32_e32 v111, v107
	v_permlane32_swap_b32_e32 v112, v108
	v_permlane32_swap_b32_e32 v113, v109
	v_mov_b32_e32 v191, v110
	v_mov_b32_e32 v192, v111
	v_mov_b32_e32 v193, v112
	v_mov_b32_e32 v197, v113
	v_bfe_u32 v188, v227, 3, 1
	v_mul_i32_i24_e32 v188, 0xffff8040, v188
	v_ashrrev_i32_e32 v189, 31, v188
	v_lshl_add_u64 v[186:187], v[186:187], 0, v[188:189]
	v_mov_b32_e32 v188, 0x8000
	v_mov_b32_e32 v189, 0
	v_lshl_add_u64 v[188:189], v[186:187], 0, v[188:189]
	v_mov_b32_dpp v110, v106 row_ror:8 row_mask:0xf bank_mask:0xc
	v_mov_b32_dpp v111, v107 row_ror:8 row_mask:0xf bank_mask:0xc
	v_mov_b32_dpp v112, v108 row_ror:8 row_mask:0xf bank_mask:0xc
	v_mov_b32_dpp v113, v109 row_ror:8 row_mask:0xf bank_mask:0xc
	v_mov_b32_dpp v106, v191 row_ror:8 row_mask:0xf bank_mask:0x3
	v_mov_b32_dpp v107, v192 row_ror:8 row_mask:0xf bank_mask:0x3
	v_mov_b32_dpp v108, v193 row_ror:8 row_mask:0xf bank_mask:0x3
	v_mov_b32_dpp v109, v197 row_ror:8 row_mask:0xf bank_mask:0x3
	global_store_dwordx4 v[186:187], v[110:113], off nt
	global_store_dwordx4 v[188:189], v[106:109], off nt
	s_nop 1
	v_mov_b32_dpp v106, v110 row_ror:8 row_mask:0xf bank_mask:0x3
	v_mov_b32_dpp v107, v111 row_ror:8 row_mask:0xf bank_mask:0x3
	v_mov_b32_dpp v108, v112 row_ror:8 row_mask:0xf bank_mask:0x3
	v_mov_b32_dpp v109, v113 row_ror:8 row_mask:0xf bank_mask:0x3
	v_mov_b32_e32 v110, v191
	v_mov_b32_e32 v111, v192
	v_mov_b32_e32 v112, v193
	v_mov_b32_e32 v113, v197
	s_nop 1
	v_permlane32_swap_b32_e32 v110, v106
	v_permlane32_swap_b32_e32 v111, v107
	v_permlane32_swap_b32_e32 v112, v108
	v_permlane32_swap_b32_e32 v113, v109
	v_permlane16_swap_b32_e32 v110, v106
	v_permlane16_swap_b32_e32 v111, v107
	v_permlane16_swap_b32_e32 v112, v108
	v_permlane16_swap_b32_e32 v113, v109
	v_fmac_f32_e32 v180, v106, v106
	v_fmac_f32_e32 v181, v108, v108
	v_cvt_pk_bf16_f32 v110, v110, v111
	v_cvt_pk_bf16_f32 v111, v112, v113
	v_cvt_pk_bf16_f32 v112, v106, v107
	v_cvt_pk_bf16_f32 v113, v108, v109
	s_waitcnt vmcnt(6)
	v_sub_f32_e32 v107, v135, v179
	v_sub_f32_e32 v106, v134, v179
	v_sub_f32_e32 v109, v137, v179
	v_sub_f32_e32 v108, v136, v179
	v_pk_mul_f32 v[108:109], v[0:1], v[108:109] op_sel_hi:[0,1]
	v_pk_mul_f32 v[106:107], v[0:1], v[106:107] op_sel_hi:[0,1]
	s_waitcnt vmcnt(2)
; __device__ __forceinline__ float xsum16(float v) { const auto r = __builtin_amdgcn_permlane16_swap(__float_as_uint(v), __float_as_uint(v), false, false); return __uint_as_float(r[0]) + __uint_as_float(r[1]); }
; __device__ __forceinline__ float xsum32(float v) { const auto r = __builtin_amdgcn_permlane32_swap(__float_as_uint(v), __float_as_uint(v), false, false); return __uint_as_float(r[0]) + __uint_as_float(r[1]); }
; __device__ __forceinline__ size_t blk_off(int r, int c, int K) { return (size_t)(r >> 8) * 256 * K + (size_t)(c >> 6) * (256 * 64) + (size_t)((r & 255) * 64 + (c & 63)); }
; __device__ __forceinline__ u32x4 pack8(const f32x4 a, const f32x4 b) { u32x4 w; w.x = cvt_pk_bf16(a[0], a[1]); w.y = cvt_pk_bf16(a[2], a[3]); w.z = cvt_pk_bf16(b[0], b[1]); w.w = cvt_pk_bf16(b[2], b[3]); return w; }
;     __device__ __forceinline__ void operator()(const f32x4 (&acc)[2][2][4][2], const pg8::Unit& u, int wr, int wc, int fr, int fq) const {
;     ...
;                 for (int bj = 0; bj < 2; ++bj) { float* yp = Y + (size_t)row * D_ + col0 + bj * 128; f32x4 v[2];
; #pragma unroll
;                     for (int n = 0; n < 2; ++n) { v[n] = (((yv[bj][n] - mu) * rs) * gq[bj][n] + bq_[bj][n]) * ALPHA_ + acc[ai][bj][m][n] * sc;
;                         *(f32x4*)(yp + 4 * n) = v[n]; s1 += (v[n][0] + v[n][1]) + (v[n][2] + v[n][3]); s2 += (v[n][0] * v[n][0] + v[n][1] * v[n][1]) + (v[n][2] * v[n][2] + v[n][3] * v[n][3]); }
;                     *(u32x4*)(Yb + blk_off(row, col0 + bj * 128, D_)) = pack8(v[0], v[1]); }
;                 s1 = xsum32(xsum16(s1)); s2 = xsum32(xsum16(s2));
;                 if (fq == 0) *(f32x2*)(stn + (size_t)row * 32 + (u.pn * 4 + wc) * 2) = (f32x2){s1, s2}; asm volatile("" ::: "memory"); } }
	v_pk_fma_f32 v[106:107], v[126:127], v[106:107], v[130:131]
	v_pk_fma_f32 v[108:109], v[128:129], v[108:109], v[132:133]
	v_pk_fma_f32 v[102:103], v[106:107], s[2:3], v[102:103] op_sel_hi:[1,0,1]
	v_pk_fma_f32 v[104:105], v[108:109], s[2:3], v[104:105] op_sel_hi:[1,0,1]
	v_add_f32_e32 v106, v102, v103
	v_add_f32_e32 v107, v104, v105
	v_add_f32_e32 v106, v106, v107
	global_store_dwordx4 v159, v[110:113], s[42:43]
	v_mul_f32_e32 v107, v105, v105
	v_add_f32_e32 v180, v180, v181
	v_add_f32_e32 v110, v178, v106
	v_mul_f32_e32 v106, v103, v103
	v_fmac_f32_e32 v106, v102, v102
	v_fmac_f32_e32 v107, v104, v104
	v_add_f32_e32 v180, v190, v180
	v_add_f32_e32 v106, v106, v107
	v_add_f32_e32 v111, v180, v106
	v_sub_f32_e32 v107, v115, v179
	v_sub_f32_e32 v106, v114, v179
	v_sub_f32_e32 v109, v117, v179
	v_sub_f32_e32 v108, v116, v179
	v_pk_mul_f32 v[108:109], v[0:1], v[108:109] op_sel_hi:[0,1]
	v_pk_mul_f32 v[106:107], v[0:1], v[106:107] op_sel_hi:[0,1]
	v_pk_fma_f32 v[106:107], v[118:119], v[106:107], v[122:123]
	v_pk_fma_f32 v[108:109], v[120:121], v[108:109], v[124:125]
	v_pk_fma_f32 v[98:99], v[106:107], s[2:3], v[98:99] op_sel_hi:[1,0,1]
	v_pk_fma_f32 v[100:101], v[108:109], s[2:3], v[100:101] op_sel_hi:[1,0,1]
	v_add_f32_e32 v0, v98, v99
	v_add_f32_e32 v106, v100, v101
	v_add_f32_e32 v0, v0, v106
	v_mul_f32_e32 v106, v99, v99
	v_mul_f32_e32 v107, v101, v101
	v_add_f32_e32 v0, v110, v0
	v_fmac_f32_e32 v106, v98, v98
	v_fmac_f32_e32 v107, v100, v100
	s_nop 0
	s_nop 1
	v_bfe_u32 v109, v227, 4, 2
	v_sub_u32_e32 v108, 0, v109
	v_lshlrev_b32_e32 v108, 4, v108
	v_ashrrev_i32_e32 v109, 31, v108
	v_lshl_add_u64 v[108:109], v[182:183], 0, v[108:109]
	v_permlane16_swap_b32_e32 v102, v98
	v_permlane16_swap_b32_e32 v103, v99
	v_permlane16_swap_b32_e32 v104, v100
	v_permlane16_swap_b32_e32 v105, v101
	v_permlane32_swap_b32_e32 v102, v98
	v_permlane32_swap_b32_e32 v103, v99
	v_permlane32_swap_b32_e32 v104, v100
	v_permlane32_swap_b32_e32 v105, v101
	v_mov_b32_e32 v114, v102
	v_mov_b32_e32 v115, v103
	v_mov_b32_e32 v116, v104
	v_mov_b32_e32 v117, v105
	v_bfe_u32 v112, v227, 3, 1
	v_mul_i32_i24_e32 v112, 0xffff8040, v112
	v_ashrrev_i32_e32 v113, 31, v112
	v_lshl_add_u64 v[108:109], v[108:109], 0, v[112:113]
	v_mov_b32_e32 v112, 0x8000
	v_mov_b32_e32 v113, 0
	v_lshl_add_u64 v[112:113], v[108:109], 0, v[112:113]
	v_mov_b32_dpp v102, v98 row_ror:8 row_mask:0xf bank_mask:0xc
	v_mov_b32_dpp v103, v99 row_ror:8 row_mask:0xf bank_mask:0xc
	v_mov_b32_dpp v104, v100 row_ror:8 row_mask:0xf bank_mask:0xc
	v_mov_b32_dpp v105, v101 row_ror:8 row_mask:0xf bank_mask:0xc
	v_mov_b32_dpp v98, v114 row_ror:8 row_mask:0xf bank_mask:0x3
	v_mov_b32_dpp v99, v115 row_ror:8 row_mask:0xf bank_mask:0x3
	v_mov_b32_dpp v100, v116 row_ror:8 row_mask:0xf bank_mask:0x3
	v_mov_b32_dpp v101, v117 row_ror:8 row_mask:0xf bank_mask:0x3
	global_store_dwordx4 v[108:109], v[102:105], off offset:512 nt
	global_store_dwordx4 v[112:113], v[98:101], off offset:512 nt
	s_nop 1
	v_mov_b32_dpp v98, v102 row_ror:8 row_mask:0xf bank_mask:0x3
	v_mov_b32_dpp v99, v103 row_ror:8 row_mask:0xf bank_mask:0x3
	v_mov_b32_dpp v100, v104 row_ror:8 row_mask:0xf bank_mask:0x3
	v_mov_b32_dpp v101, v105 row_ror:8 row_mask:0xf bank_mask:0x3
	v_mov_b32_e32 v102, v114
	v_mov_b32_e32 v103, v115
	v_mov_b32_e32 v104, v116
	v_mov_b32_e32 v105, v117
	s_nop 1
	v_permlane32_swap_b32_e32 v102, v98
	v_permlane32_swap_b32_e32 v103, v99
	v_permlane32_swap_b32_e32 v104, v100
	v_permlane32_swap_b32_e32 v105, v101
	v_permlane16_swap_b32_e32 v102, v98
	v_permlane16_swap_b32_e32 v103, v99
	v_permlane16_swap_b32_e32 v104, v100
	v_permlane16_swap_b32_e32 v105, v101
	v_add_f32_e32 v106, v106, v107
	v_cvt_pk_bf16_f32 v102, v102, v103
	v_cvt_pk_bf16_f32 v103, v104, v105
	v_cvt_pk_bf16_f32 v104, v98, v99
	v_mov_b32_e32 v98, v0
	v_add_f32_e32 v106, v111, v106
	s_nop 0
	v_permlane16_swap_b32_e32 v0, v98
	v_add_f32_e32 v98, v0, v98
	v_mov_b32_e32 v0, v106
	s_nop 1
	v_permlane16_swap_b32_e32 v106, v0
	v_add_f32_e32 v99, v106, v0
	v_cvt_pk_bf16_f32 v105, v100, v101
	v_mov_b32_e32 v100, v98
	v_mov_b32_e32 v101, v99
	s_nop 0
	v_permlane32_swap_b32_e32 v98, v100
	v_permlane32_swap_b32_e32 v99, v101
	global_store_dwordx4 v159, v[102:105], s[40:41]
	s_and_saveexec_b64 s[26:27], s[44:45]
	s_cbranch_execz .LBB0_1539
	v_pk_add_f32 v[98:99], v[98:99], v[100:101]
	v_lshl_add_u64 v[100:101], s[6:7], 0, v[172:173]
	v_lshl_add_u64 v[100:101], s[52:53], 2, v[100:101]
	global_store_dwordx2 v[100:101], v[98:99], off
; __device__ __forceinline__ size_t blk_off(int r, int c, int K) { return (size_t)(r >> 8) * 256 * K + (size_t)(c >> 6) * (256 * 64) + (size_t)((r & 255) * 64 + (c & 63)); }
; __device__ __forceinline__ u32x4 pack8(const f32x4 a, const f32x4 b) { u32x4 w; w.x = cvt_pk_bf16(a[0], a[1]); w.y = cvt_pk_bf16(a[2], a[3]); w.z = cvt_pk_bf16(b[0], b[1]); w.w = cvt_pk_bf16(b[2], b[3]); return w; }
;     __device__ __forceinline__ void operator()(const f32x4 (&acc)[2][2][4][2], const pg8::Unit& u, int wr, int wc, int fr, int fq) const {
;     ...
;             for (int m = 0; m < 4; ++m) { const int row = row0 + ai * 128 + m * 16; const float mu = mu4[m], rs = rs4[m];
;                 f32x4 yv[2][2], gq[2][2], bq_[2][2];
; #pragma unroll
;                 for (int bj = 0; bj < 2; ++bj)
; #pragma unroll
;                     for (int n = 0; n < 2; ++n) { yv[bj][n] = *(const f32x4*)(Yin + (size_t)row * D_ + col0 + bj * 128 + 4 * n); gq[bj][n] = *(const f32x4*)(g + col0 + bj * 128 + 4 * n); bq_[bj][n] = *(const f32x4*)(b + col0 + bj * 128 + 4 * n); }
;                 asm volatile("" ::: "memory");
;                 float s1 = 0.f, s2 = 0.f;
; #pragma unroll
;                 for (int bj = 0; bj < 2; ++bj) { float* yp = Y + (size_t)row * D_ + col0 + bj * 128; f32x4 v[2];
; #pragma unroll
;                     for (int n = 0; n < 2; ++n) { v[n] = (((yv[bj][n] - mu) * rs) * gq[bj][n] + bq_[bj][n]) * ALPHA_ + acc[ai][bj][m][n] * sc;
;                         *(f32x4*)(yp + 4 * n) = v[n]; s1 += (v[n][0] + v[n][1]) + (v[n][2] + v[n][3]); s2 += (v[n][0] * v[n][0] + v[n][1] * v[n][1]) + (v[n][2] * v[n][2] + v[n][3] * v[n][3]); }
;                     *(u32x4*)(Yb + blk_off(row, col0 + bj * 128, D_)) = pack8(v[0], v[1]); }
.LBB0_1539:
	s_or_b64 exec, exec, s[26:27]
	v_pk_add_f32 v[98:99], v[174:175], v[176:177]
	s_mov_b32 s2, 0x3a800000
	v_pk_mul_f32 v[122:123], v[98:99], s[2:3] op_sel_hi:[1,0]
	s_mov_b32 s1, 0x800000
	v_fma_f32 v0, -v123, v123, v122
	v_max_f32_e32 v0, 0, v0
	v_add_f32_e32 v0, 0x3727c5ac, v0
	v_cmp_gt_f32_e32 vcc, s1, v0
	v_mul_f32_e32 v98, 0x4b800000, v0
	s_load_dwordx16 s[64:79], s[34:35], 0x38
	v_cndmask_b32_e32 v0, v0, v98, vcc
	v_rsq_f32_e32 v0, v0
	s_mov_b32 s2, 0x3fd744fd
	v_lshlrev_b32_e32 v122, 6, v170
	v_mul_f32_e32 v98, 0x45800000, v0
	v_cndmask_b32_e32 v0, v0, v98, vcc
	v_lshlrev_b64 v[98:99], 12, v[170:171]
	s_waitcnt lgkmcnt(0)
	v_lshl_add_u64 v[98:99], s[78:79], 0, v[98:99]
	v_lshl_add_u64 v[124:125], v[152:153], 2, v[98:99]
	global_load_dwordx4 v[126:129], v[124:125], off offset:16
	global_load_dwordx4 v[130:133], v[124:125], off
	global_load_dwordx4 v[134:137], v[156:157], off offset:16
	global_load_dwordx4 v[172:175], v[156:157], off
	global_load_dwordx4 v[176:179], v[154:155], off offset:16
	global_load_dwordx4 v[180:183], v[154:155], off
	global_load_dwordx4 v[98:101], v[124:125], off offset:528
	global_load_dwordx4 v[118:121], v[124:125], off offset:512
	global_load_dwordx4 v[102:105], v[156:157], off offset:528
	global_load_dwordx4 v[110:113], v[156:157], off offset:512
	global_load_dwordx4 v[106:109], v[154:155], off offset:528
	global_load_dwordx4 v[114:117], v[154:155], off offset:512
	s_movk_i32 s1, 0x3bc0
	v_and_or_b32 v122, v122, s1, v196
	v_lshlrev_b32_e32 v122, 1, v122
	s_waitcnt vmcnt(11)
	v_sub_f32_e32 v127, v127, v123
	s_waitcnt vmcnt(10)
	v_sub_f32_e32 v131, v131, v123
	v_sub_f32_e32 v130, v130, v123
	v_sub_f32_e32 v133, v133, v123
	v_sub_f32_e32 v132, v132, v123
	v_sub_f32_e32 v126, v126, v123
	v_sub_f32_e32 v129, v129, v123
	v_sub_f32_e32 v128, v128, v123
	v_pk_mul_f32 v[132:133], v[0:1], v[132:133] op_sel_hi:[0,1]
	v_pk_mul_f32 v[130:131], v[0:1], v[130:131] op_sel_hi:[0,1]
	v_pk_mul_f32 v[128:129], v[0:1], v[128:129] op_sel_hi:[0,1]
	v_pk_mul_f32 v[126:127], v[0:1], v[126:127] op_sel_hi:[0,1]
	s_waitcnt vmcnt(6)
	v_pk_fma_f32 v[130:131], v[172:173], v[130:131], v[180:181]
	v_pk_fma_f32 v[132:133], v[174:175], v[132:133], v[182:183]
	v_pk_fma_f32 v[126:127], v[134:135], v[126:127], v[176:177]
	v_pk_fma_f32 v[128:129], v[136:137], v[128:129], v[178:179]
	v_pk_fma_f32 v[96:97], v[132:133], s[2:3], v[96:97] op_sel_hi:[1,0,1]
	v_pk_fma_f32 v[94:95], v[130:131], s[2:3], v[94:95] op_sel_hi:[1,0,1]
	v_pk_fma_f32 v[92:93], v[128:129], s[2:3], v[92:93] op_sel_hi:[1,0,1]
	v_pk_fma_f32 v[90:91], v[126:127], s[2:3], v[90:91] op_sel_hi:[1,0,1]
	v_add_f32_e32 v130, v94, v95
	v_add_f32_e32 v131, v96, v97
	v_add_f32_e32 v126, v90, v91
	v_add_f32_e32 v127, v92, v93
	v_add_f32_e32 v130, v130, v131
	v_mul_f32_e32 v131, v95, v95
	v_mul_f32_e32 v132, v97, v97
	v_add_f32_e32 v126, v126, v127
	v_mul_f32_e32 v127, v91, v91
	v_mul_f32_e32 v128, v93, v93
	s_nop 0
	v_fmac_f32_e32 v131, v94, v94
	v_fmac_f32_e32 v132, v96, v96
	s_nop 1
	v_bfe_u32 v135, v227, 4, 2
	v_sub_u32_e32 v134, 0, v135
	v_lshlrev_b32_e32 v134, 4, v134
	v_ashrrev_i32_e32 v135, 31, v134
	v_lshl_add_u64 v[134:135], v[124:125], 0, v[134:135]
	v_permlane16_swap_b32_e32 v94, v90
	v_permlane16_swap_b32_e32 v95, v91
	v_permlane16_swap_b32_e32 v96, v92
	v_permlane16_swap_b32_e32 v97, v93
	v_permlane32_swap_b32_e32 v94, v90
	v_permlane32_swap_b32_e32 v95, v91
	v_permlane32_swap_b32_e32 v96, v92
	v_permlane32_swap_b32_e32 v97, v93
	v_mov_b32_e32 v129, v94
	v_mov_b32_e32 v133, v95
	v_mov_b32_e32 v159, v96
	v_mov_b32_e32 v170, v97
	v_bfe_u32 v136, v227, 3, 1
	v_mul_i32_i24_e32 v136, 0xffff8040, v136
	v_ashrrev_i32_e32 v137, 31, v136
	v_lshl_add_u64 v[134:135], v[134:135], 0, v[136:137]
	v_mov_b32_e32 v136, 0x8000
	v_mov_b32_e32 v137, 0
	v_lshl_add_u64 v[136:137], v[134:135], 0, v[136:137]
	v_mov_b32_dpp v94, v90 row_ror:8 row_mask:0xf bank_mask:0xc
	v_mov_b32_dpp v95, v91 row_ror:8 row_mask:0xf bank_mask:0xc
	v_mov_b32_dpp v96, v92 row_ror:8 row_mask:0xf bank_mask:0xc
	v_mov_b32_dpp v97, v93 row_ror:8 row_mask:0xf bank_mask:0xc
	v_mov_b32_dpp v90, v129 row_ror:8 row_mask:0xf bank_mask:0x3
	v_mov_b32_dpp v91, v133 row_ror:8 row_mask:0xf bank_mask:0x3
	v_mov_b32_dpp v92, v159 row_ror:8 row_mask:0xf bank_mask:0x3
	v_mov_b32_dpp v93, v170 row_ror:8 row_mask:0xf bank_mask:0x3
	global_store_dwordx4 v[134:135], v[94:97], off nt
	global_store_dwordx4 v[136:137], v[90:93], off nt
	s_nop 1
	v_mov_b32_dpp v90, v94 row_ror:8 row_mask:0xf bank_mask:0x3
	v_mov_b32_dpp v91, v95 row_ror:8 row_mask:0xf bank_mask:0x3
	v_mov_b32_dpp v92, v96 row_ror:8 row_mask:0xf bank_mask:0x3
	v_mov_b32_dpp v93, v97 row_ror:8 row_mask:0xf bank_mask:0x3
	v_mov_b32_e32 v94, v129
	v_mov_b32_e32 v95, v133
	v_mov_b32_e32 v96, v159
	v_mov_b32_e32 v97, v170
	s_nop 1
	v_permlane32_swap_b32_e32 v94, v90
	v_permlane32_swap_b32_e32 v95, v91
	v_permlane32_swap_b32_e32 v96, v92
	v_permlane32_swap_b32_e32 v97, v93
	v_permlane16_swap_b32_e32 v94, v90
	v_permlane16_swap_b32_e32 v95, v91
	v_permlane16_swap_b32_e32 v96, v92
	v_permlane16_swap_b32_e32 v97, v93
	v_fmac_f32_e32 v127, v90, v90
	v_fmac_f32_e32 v128, v92, v92
	v_cvt_pk_bf16_f32 v94, v94, v95
	v_cvt_pk_bf16_f32 v95, v96, v97
	v_cvt_pk_bf16_f32 v96, v90, v91
	v_cvt_pk_bf16_f32 v97, v92, v93
	s_waitcnt vmcnt(6)
	v_sub_f32_e32 v91, v119, v123
	v_sub_f32_e32 v90, v118, v123
	v_sub_f32_e32 v93, v121, v123
	v_sub_f32_e32 v92, v120, v123
	v_pk_mul_f32 v[92:93], v[0:1], v[92:93] op_sel_hi:[0,1]
	v_pk_mul_f32 v[90:91], v[0:1], v[90:91] op_sel_hi:[0,1]
	s_waitcnt vmcnt(2)
; __device__ __forceinline__ float xsum16(float v) { const auto r = __builtin_amdgcn_permlane16_swap(__float_as_uint(v), __float_as_uint(v), false, false); return __uint_as_float(r[0]) + __uint_as_float(r[1]); }
; __device__ __forceinline__ float xsum32(float v) { const auto r = __builtin_amdgcn_permlane32_swap(__float_as_uint(v), __float_as_uint(v), false, false); return __uint_as_float(r[0]) + __uint_as_float(r[1]); }
; __device__ __forceinline__ size_t blk_off(int r, int c, int K) { return (size_t)(r >> 8) * 256 * K + (size_t)(c >> 6) * (256 * 64) + (size_t)((r & 255) * 64 + (c & 63)); }
; __device__ __forceinline__ u32x4 pack8(const f32x4 a, const f32x4 b) { u32x4 w; w.x = cvt_pk_bf16(a[0], a[1]); w.y = cvt_pk_bf16(a[2], a[3]); w.z = cvt_pk_bf16(b[0], b[1]); w.w = cvt_pk_bf16(b[2], b[3]); return w; }
;     __device__ __forceinline__ void operator()(const f32x4 (&acc)[2][2][4][2], const pg8::Unit& u, int wr, int wc, int fr, int fq) const {
;     ...
;                 for (int bj = 0; bj < 2; ++bj) { float* yp = Y + (size_t)row * D_ + col0 + bj * 128; f32x4 v[2];
; #pragma unroll
;                     for (int n = 0; n < 2; ++n) { v[n] = (((yv[bj][n] - mu) * rs) * gq[bj][n] + bq_[bj][n]) * ALPHA_ + acc[ai][bj][m][n] * sc;
;                         *(f32x4*)(yp + 4 * n) = v[n]; s1 += (v[n][0] + v[n][1]) + (v[n][2] + v[n][3]); s2 += (v[n][0] * v[n][0] + v[n][1] * v[n][1]) + (v[n][2] * v[n][2] + v[n][3] * v[n][3]); }
;                     *(u32x4*)(Yb + blk_off(row, col0 + bj * 128, D_)) = pack8(v[0], v[1]); }
;                 s1 = xsum32(xsum16(s1)); s2 = xsum32(xsum16(s2));
;                 if (fq == 0) *(f32x2*)(stn + (size_t)row * 32 + (u.pn * 4 + wc) * 2) = (f32x2){s1, s2}; asm volatile("" ::: "memory"); } }
	v_pk_fma_f32 v[90:91], v[110:111], v[90:91], v[114:115]
	v_pk_fma_f32 v[92:93], v[112:113], v[92:93], v[116:117]
	v_pk_fma_f32 v[86:87], v[90:91], s[2:3], v[86:87] op_sel_hi:[1,0,1]
	v_pk_fma_f32 v[88:89], v[92:93], s[2:3], v[88:89] op_sel_hi:[1,0,1]
	v_add_f32_e32 v130, 0, v130
	v_add_f32_e32 v90, v86, v87
	v_add_f32_e32 v91, v88, v89
	v_add_f32_e32 v126, v130, v126
	v_add_f32_e32 v90, v90, v91
	global_store_dwordx4 v122, v[94:97], s[42:43]
	v_mul_f32_e32 v91, v89, v89
	v_add_f32_e32 v131, v131, v132
	v_add_f32_e32 v94, v126, v90
	v_mul_f32_e32 v90, v87, v87
	v_add_f32_e32 v127, v127, v128
	v_fmac_f32_e32 v90, v86, v86
	v_fmac_f32_e32 v91, v88, v88
	v_add_f32_e32 v127, v131, v127
	v_add_f32_e32 v90, v90, v91
	v_add_f32_e32 v95, v127, v90
	v_sub_f32_e32 v91, v99, v123
	v_sub_f32_e32 v90, v98, v123
	v_sub_f32_e32 v93, v101, v123
	v_sub_f32_e32 v92, v100, v123
	v_pk_mul_f32 v[92:93], v[0:1], v[92:93] op_sel_hi:[0,1]
	v_pk_mul_f32 v[90:91], v[0:1], v[90:91] op_sel_hi:[0,1]
	v_pk_fma_f32 v[90:91], v[102:103], v[90:91], v[106:107]
	v_pk_fma_f32 v[92:93], v[104:105], v[92:93], v[108:109]
	v_pk_fma_f32 v[82:83], v[90:91], s[2:3], v[82:83] op_sel_hi:[1,0,1]
	v_pk_fma_f32 v[84:85], v[92:93], s[2:3], v[84:85] op_sel_hi:[1,0,1]
	v_add_f32_e32 v0, v82, v83
	v_add_f32_e32 v90, v84, v85
	v_add_f32_e32 v0, v0, v90
	v_mul_f32_e32 v90, v83, v83
	v_mul_f32_e32 v91, v85, v85
	v_add_f32_e32 v0, v94, v0
	v_fmac_f32_e32 v90, v82, v82
	v_fmac_f32_e32 v91, v84, v84
	s_nop 0
	s_nop 1
	v_bfe_u32 v93, v227, 4, 2
	v_sub_u32_e32 v92, 0, v93
	v_lshlrev_b32_e32 v92, 4, v92
	v_ashrrev_i32_e32 v93, 31, v92
	v_lshl_add_u64 v[92:93], v[124:125], 0, v[92:93]
	v_permlane16_swap_b32_e32 v86, v82
	v_permlane16_swap_b32_e32 v87, v83
	v_permlane16_swap_b32_e32 v88, v84
	v_permlane16_swap_b32_e32 v89, v85
	v_permlane32_swap_b32_e32 v86, v82
	v_permlane32_swap_b32_e32 v87, v83
	v_permlane32_swap_b32_e32 v88, v84
	v_permlane32_swap_b32_e32 v89, v85
	v_mov_b32_e32 v98, v86
	v_mov_b32_e32 v99, v87
	v_mov_b32_e32 v100, v88
	v_mov_b32_e32 v101, v89
	v_bfe_u32 v96, v227, 3, 1
	v_mul_i32_i24_e32 v96, 0xffff8040, v96
	v_ashrrev_i32_e32 v97, 31, v96
	v_lshl_add_u64 v[92:93], v[92:93], 0, v[96:97]
	v_mov_b32_e32 v96, 0x8000
	v_mov_b32_e32 v97, 0
	v_lshl_add_u64 v[96:97], v[92:93], 0, v[96:97]
	v_mov_b32_dpp v86, v82 row_ror:8 row_mask:0xf bank_mask:0xc
	v_mov_b32_dpp v87, v83 row_ror:8 row_mask:0xf bank_mask:0xc
	v_mov_b32_dpp v88, v84 row_ror:8 row_mask:0xf bank_mask:0xc
	v_mov_b32_dpp v89, v85 row_ror:8 row_mask:0xf bank_mask:0xc
	v_mov_b32_dpp v82, v98 row_ror:8 row_mask:0xf bank_mask:0x3
	v_mov_b32_dpp v83, v99 row_ror:8 row_mask:0xf bank_mask:0x3
	v_mov_b32_dpp v84, v100 row_ror:8 row_mask:0xf bank_mask:0x3
	v_mov_b32_dpp v85, v101 row_ror:8 row_mask:0xf bank_mask:0x3
	global_store_dwordx4 v[92:93], v[86:89], off offset:512 nt
	global_store_dwordx4 v[96:97], v[82:85], off offset:512 nt
	s_nop 1
	v_mov_b32_dpp v82, v86 row_ror:8 row_mask:0xf bank_mask:0x3
	v_mov_b32_dpp v83, v87 row_ror:8 row_mask:0xf bank_mask:0x3
	v_mov_b32_dpp v84, v88 row_ror:8 row_mask:0xf bank_mask:0x3
	v_mov_b32_dpp v85, v89 row_ror:8 row_mask:0xf bank_mask:0x3
	v_mov_b32_e32 v86, v98
	v_mov_b32_e32 v87, v99
	v_mov_b32_e32 v88, v100
	v_mov_b32_e32 v89, v101
	s_nop 1
	v_permlane32_swap_b32_e32 v86, v82
	v_permlane32_swap_b32_e32 v87, v83
	v_permlane32_swap_b32_e32 v88, v84
	v_permlane32_swap_b32_e32 v89, v85
	v_permlane16_swap_b32_e32 v86, v82
	v_permlane16_swap_b32_e32 v87, v83
	v_permlane16_swap_b32_e32 v88, v84
	v_permlane16_swap_b32_e32 v89, v85
	v_add_f32_e32 v90, v90, v91
	v_cvt_pk_bf16_f32 v86, v86, v87
	v_cvt_pk_bf16_f32 v87, v88, v89
	v_cvt_pk_bf16_f32 v88, v82, v83
	v_mov_b32_e32 v82, v0
	v_add_f32_e32 v90, v95, v90
	s_nop 0
	v_permlane16_swap_b32_e32 v0, v82
	v_add_f32_e32 v82, v0, v82
	v_mov_b32_e32 v0, v90
	s_nop 1
	v_permlane16_swap_b32_e32 v90, v0
	v_add_f32_e32 v83, v90, v0
	v_cvt_pk_bf16_f32 v89, v84, v85
	v_mov_b32_e32 v84, v82
	v_mov_b32_e32 v85, v83
	s_nop 0
	v_permlane32_swap_b32_e32 v82, v84
	v_permlane32_swap_b32_e32 v83, v85
	global_store_dwordx4 v122, v[86:89], s[40:41]
	s_and_saveexec_b64 s[26:27], s[44:45]
	s_cbranch_execz .LBB0_1541
	v_pk_add_f32 v[82:83], v[82:83], v[84:85]
	v_lshl_add_u64 v[84:85], s[6:7], 0, v[164:165]
	v_lshl_add_u64 v[84:85], s[52:53], 2, v[84:85]
	global_store_dwordx2 v[84:85], v[82:83], off
; __device__ __forceinline__ size_t blk_off(int r, int c, int K) { return (size_t)(r >> 8) * 256 * K + (size_t)(c >> 6) * (256 * 64) + (size_t)((r & 255) * 64 + (c & 63)); }
; __device__ __forceinline__ u32x4 pack8(const f32x4 a, const f32x4 b) { u32x4 w; w.x = cvt_pk_bf16(a[0], a[1]); w.y = cvt_pk_bf16(a[2], a[3]); w.z = cvt_pk_bf16(b[0], b[1]); w.w = cvt_pk_bf16(b[2], b[3]); return w; }
;     __device__ __forceinline__ void operator()(const f32x4 (&acc)[2][2][4][2], const pg8::Unit& u, int wr, int wc, int fr, int fq) const {
;     ...
;             for (int m = 0; m < 4; ++m) { const int row = row0 + ai * 128 + m * 16; const float mu = mu4[m], rs = rs4[m];
;                 f32x4 yv[2][2], gq[2][2], bq_[2][2];
; #pragma unroll
;                 for (int bj = 0; bj < 2; ++bj)
; #pragma unroll
;                     for (int n = 0; n < 2; ++n) { yv[bj][n] = *(const f32x4*)(Yin + (size_t)row * D_ + col0 + bj * 128 + 4 * n); gq[bj][n] = *(const f32x4*)(g + col0 + bj * 128 + 4 * n); bq_[bj][n] = *(const f32x4*)(b + col0 + bj * 128 + 4 * n); }
;                 asm volatile("" ::: "memory");
;                 float s1 = 0.f, s2 = 0.f;
; #pragma unroll
;                 for (int bj = 0; bj < 2; ++bj) { float* yp = Y + (size_t)row * D_ + col0 + bj * 128; f32x4 v[2];
; #pragma unroll
;                     for (int n = 0; n < 2; ++n) { v[n] = (((yv[bj][n] - mu) * rs) * gq[bj][n] + bq_[bj][n]) * ALPHA_ + acc[ai][bj][m][n] * sc;
;                         *(f32x4*)(yp + 4 * n) = v[n]; s1 += (v[n][0] + v[n][1]) + (v[n][2] + v[n][3]); s2 += (v[n][0] * v[n][0] + v[n][1] * v[n][1]) + (v[n][2] * v[n][2] + v[n][3] * v[n][3]); }
;                     *(u32x4*)(Yb + blk_off(row, col0 + bj * 128, D_)) = pack8(v[0], v[1]); }
.LBB0_1541:
	s_or_b64 exec, exec, s[26:27]
	v_pk_add_f32 v[82:83], v[166:167], v[168:169]
	s_mov_b32 s2, 0x3a800000
	v_pk_mul_f32 v[106:107], v[82:83], s[2:3] op_sel_hi:[1,0]
	s_mov_b32 s1, 0x800000
	v_fma_f32 v0, -v107, v107, v106
	v_max_f32_e32 v0, 0, v0
	v_add_f32_e32 v0, 0x3727c5ac, v0
	v_cmp_gt_f32_e32 vcc, s1, v0
	v_mul_f32_e32 v82, 0x4b800000, v0
	s_load_dwordx16 s[64:79], s[34:35], 0x38
	v_cndmask_b32_e32 v0, v0, v82, vcc
	v_rsq_f32_e32 v0, v0
	s_mov_b32 s2, 0x3fd744fd
	v_lshlrev_b32_e32 v106, 6, v162
	v_mul_f32_e32 v82, 0x45800000, v0
	v_cndmask_b32_e32 v0, v0, v82, vcc
	v_lshlrev_b64 v[82:83], 12, v[162:163]
	s_waitcnt lgkmcnt(0)
	v_lshl_add_u64 v[82:83], s[78:79], 0, v[82:83]
	v_lshl_add_u64 v[108:109], v[152:153], 2, v[82:83]
	global_load_dwordx4 v[110:113], v[108:109], off offset:16
	global_load_dwordx4 v[114:117], v[108:109], off
	global_load_dwordx4 v[118:121], v[156:157], off offset:16
	global_load_dwordx4 v[122:125], v[156:157], off
	global_load_dwordx4 v[126:129], v[154:155], off offset:16
	global_load_dwordx4 v[130:133], v[154:155], off
	global_load_dwordx4 v[82:85], v[108:109], off offset:528
	global_load_dwordx4 v[102:105], v[108:109], off offset:512
	global_load_dwordx4 v[86:89], v[156:157], off offset:528
	global_load_dwordx4 v[94:97], v[156:157], off offset:512
	global_load_dwordx4 v[90:93], v[154:155], off offset:528
	global_load_dwordx4 v[98:101], v[154:155], off offset:512
	s_movk_i32 s1, 0x3fc0
	v_and_or_b32 v106, v106, s1, v196
	v_lshlrev_b32_e32 v106, 1, v106
	s_waitcnt vmcnt(11)
	v_sub_f32_e32 v111, v111, v107
	s_waitcnt vmcnt(10)
	v_sub_f32_e32 v115, v115, v107
	v_sub_f32_e32 v114, v114, v107
	v_sub_f32_e32 v117, v117, v107
	v_sub_f32_e32 v116, v116, v107
	v_sub_f32_e32 v110, v110, v107
	v_sub_f32_e32 v113, v113, v107
	v_sub_f32_e32 v112, v112, v107
	v_pk_mul_f32 v[116:117], v[0:1], v[116:117] op_sel_hi:[0,1]
	v_pk_mul_f32 v[114:115], v[0:1], v[114:115] op_sel_hi:[0,1]
	v_pk_mul_f32 v[112:113], v[0:1], v[112:113] op_sel_hi:[0,1]
	v_pk_mul_f32 v[110:111], v[0:1], v[110:111] op_sel_hi:[0,1]
	s_waitcnt vmcnt(6)
	v_pk_fma_f32 v[114:115], v[122:123], v[114:115], v[130:131]
	v_pk_fma_f32 v[116:117], v[124:125], v[116:117], v[132:133]
	v_pk_fma_f32 v[110:111], v[118:119], v[110:111], v[126:127]
	v_pk_fma_f32 v[112:113], v[120:121], v[112:113], v[128:129]
	v_pk_fma_f32 v[80:81], v[116:117], s[2:3], v[80:81] op_sel_hi:[1,0,1]
	v_pk_fma_f32 v[78:79], v[114:115], s[2:3], v[78:79] op_sel_hi:[1,0,1]
	v_pk_fma_f32 v[76:77], v[112:113], s[2:3], v[76:77] op_sel_hi:[1,0,1]
	v_pk_fma_f32 v[74:75], v[110:111], s[2:3], v[74:75] op_sel_hi:[1,0,1]
	v_add_f32_e32 v114, v78, v79
	v_add_f32_e32 v115, v80, v81
	v_add_f32_e32 v110, v74, v75
	v_add_f32_e32 v111, v76, v77
	v_add_f32_e32 v114, v114, v115
	v_mul_f32_e32 v115, v79, v79
	v_mul_f32_e32 v116, v81, v81
	v_add_f32_e32 v110, v110, v111
	v_mul_f32_e32 v111, v75, v75
	v_mul_f32_e32 v112, v77, v77
	s_nop 0
	v_fmac_f32_e32 v115, v78, v78
	v_fmac_f32_e32 v116, v80, v80
	s_nop 1
	v_bfe_u32 v119, v227, 4, 2
	v_sub_u32_e32 v118, 0, v119
	v_lshlrev_b32_e32 v118, 4, v118
	v_ashrrev_i32_e32 v119, 31, v118
	v_lshl_add_u64 v[118:119], v[108:109], 0, v[118:119]
	v_permlane16_swap_b32_e32 v78, v74
	v_permlane16_swap_b32_e32 v79, v75
	v_permlane16_swap_b32_e32 v80, v76
	v_permlane16_swap_b32_e32 v81, v77
	v_permlane32_swap_b32_e32 v78, v74
	v_permlane32_swap_b32_e32 v79, v75
	v_permlane32_swap_b32_e32 v80, v76
	v_permlane32_swap_b32_e32 v81, v77
	v_mov_b32_e32 v113, v78
	v_mov_b32_e32 v117, v79
	v_mov_b32_e32 v122, v80
	v_mov_b32_e32 v123, v81
	v_bfe_u32 v120, v227, 3, 1
	v_mul_i32_i24_e32 v120, 0xffff8040, v120
	v_ashrrev_i32_e32 v121, 31, v120
	v_lshl_add_u64 v[118:119], v[118:119], 0, v[120:121]
	v_mov_b32_e32 v120, 0x8000
	v_mov_b32_e32 v121, 0
	v_lshl_add_u64 v[120:121], v[118:119], 0, v[120:121]
	v_mov_b32_dpp v78, v74 row_ror:8 row_mask:0xf bank_mask:0xc
	v_mov_b32_dpp v79, v75 row_ror:8 row_mask:0xf bank_mask:0xc
	v_mov_b32_dpp v80, v76 row_ror:8 row_mask:0xf bank_mask:0xc
	v_mov_b32_dpp v81, v77 row_ror:8 row_mask:0xf bank_mask:0xc
	v_mov_b32_dpp v74, v113 row_ror:8 row_mask:0xf bank_mask:0x3
	v_mov_b32_dpp v75, v117 row_ror:8 row_mask:0xf bank_mask:0x3
	v_mov_b32_dpp v76, v122 row_ror:8 row_mask:0xf bank_mask:0x3
	v_mov_b32_dpp v77, v123 row_ror:8 row_mask:0xf bank_mask:0x3
	global_store_dwordx4 v[118:119], v[78:81], off nt
	global_store_dwordx4 v[120:121], v[74:77], off nt
	s_nop 1
	v_mov_b32_dpp v74, v78 row_ror:8 row_mask:0xf bank_mask:0x3
	v_mov_b32_dpp v75, v79 row_ror:8 row_mask:0xf bank_mask:0x3
	v_mov_b32_dpp v76, v80 row_ror:8 row_mask:0xf bank_mask:0x3
	v_mov_b32_dpp v77, v81 row_ror:8 row_mask:0xf bank_mask:0x3
	v_mov_b32_e32 v78, v113
	v_mov_b32_e32 v79, v117
	v_mov_b32_e32 v80, v122
	v_mov_b32_e32 v81, v123
	s_nop 1
	v_permlane32_swap_b32_e32 v78, v74
	v_permlane32_swap_b32_e32 v79, v75
	v_permlane32_swap_b32_e32 v80, v76
	v_permlane32_swap_b32_e32 v81, v77
	v_permlane16_swap_b32_e32 v78, v74
	v_permlane16_swap_b32_e32 v79, v75
	v_permlane16_swap_b32_e32 v80, v76
	v_permlane16_swap_b32_e32 v81, v77
	v_fmac_f32_e32 v111, v74, v74
	v_fmac_f32_e32 v112, v76, v76
	v_cvt_pk_bf16_f32 v78, v78, v79
	v_cvt_pk_bf16_f32 v79, v80, v81
	v_cvt_pk_bf16_f32 v80, v74, v75
	v_cvt_pk_bf16_f32 v81, v76, v77
	s_waitcnt vmcnt(6)
	v_sub_f32_e32 v75, v103, v107
	v_sub_f32_e32 v74, v102, v107
	v_sub_f32_e32 v77, v105, v107
	v_sub_f32_e32 v76, v104, v107
	v_pk_mul_f32 v[76:77], v[0:1], v[76:77] op_sel_hi:[0,1]
	v_pk_mul_f32 v[74:75], v[0:1], v[74:75] op_sel_hi:[0,1]
	s_waitcnt vmcnt(2)
; __device__ __forceinline__ float xsum16(float v) { const auto r = __builtin_amdgcn_permlane16_swap(__float_as_uint(v), __float_as_uint(v), false, false); return __uint_as_float(r[0]) + __uint_as_float(r[1]); }
; __device__ __forceinline__ float xsum32(float v) { const auto r = __builtin_amdgcn_permlane32_swap(__float_as_uint(v), __float_as_uint(v), false, false); return __uint_as_float(r[0]) + __uint_as_float(r[1]); }
; __device__ __forceinline__ size_t blk_off(int r, int c, int K) { return (size_t)(r >> 8) * 256 * K + (size_t)(c >> 6) * (256 * 64) + (size_t)((r & 255) * 64 + (c & 63)); }
; __device__ __forceinline__ u32x4 pack8(const f32x4 a, const f32x4 b) { u32x4 w; w.x = cvt_pk_bf16(a[0], a[1]); w.y = cvt_pk_bf16(a[2], a[3]); w.z = cvt_pk_bf16(b[0], b[1]); w.w = cvt_pk_bf16(b[2], b[3]); return w; }
;     __device__ __forceinline__ void operator()(const f32x4 (&acc)[2][2][4][2], const pg8::Unit& u, int wr, int wc, int fr, int fq) const {
;     ...
;                 for (int bj = 0; bj < 2; ++bj) { float* yp = Y + (size_t)row * D_ + col0 + bj * 128; f32x4 v[2];
; #pragma unroll
;                     for (int n = 0; n < 2; ++n) { v[n] = (((yv[bj][n] - mu) * rs) * gq[bj][n] + bq_[bj][n]) * ALPHA_ + acc[ai][bj][m][n] * sc;
;                         *(f32x4*)(yp + 4 * n) = v[n]; s1 += (v[n][0] + v[n][1]) + (v[n][2] + v[n][3]); s2 += (v[n][0] * v[n][0] + v[n][1] * v[n][1]) + (v[n][2] * v[n][2] + v[n][3] * v[n][3]); }
;                     *(u32x4*)(Yb + blk_off(row, col0 + bj * 128, D_)) = pack8(v[0], v[1]); }
;                 s1 = xsum32(xsum16(s1)); s2 = xsum32(xsum16(s2));
;                 if (fq == 0) *(f32x2*)(stn + (size_t)row * 32 + (u.pn * 4 + wc) * 2) = (f32x2){s1, s2}; asm volatile("" ::: "memory"); } }
	v_pk_fma_f32 v[74:75], v[94:95], v[74:75], v[98:99]
	v_pk_fma_f32 v[76:77], v[96:97], v[76:77], v[100:101]
	v_pk_fma_f32 v[70:71], v[74:75], s[2:3], v[70:71] op_sel_hi:[1,0,1]
	v_pk_fma_f32 v[72:73], v[76:77], s[2:3], v[72:73] op_sel_hi:[1,0,1]
	v_add_f32_e32 v114, 0, v114
	v_add_f32_e32 v74, v70, v71
	v_add_f32_e32 v75, v72, v73
	v_add_f32_e32 v110, v114, v110
	v_add_f32_e32 v74, v74, v75
	global_store_dwordx4 v106, v[78:81], s[42:43]
	v_mul_f32_e32 v75, v73, v73
	v_add_f32_e32 v115, v115, v116
	v_add_f32_e32 v78, v110, v74
	v_mul_f32_e32 v74, v71, v71
	v_add_f32_e32 v111, v111, v112
	v_fmac_f32_e32 v74, v70, v70
	v_fmac_f32_e32 v75, v72, v72
	v_add_f32_e32 v111, v115, v111
	v_add_f32_e32 v74, v74, v75
	v_add_f32_e32 v79, v111, v74
	v_sub_f32_e32 v75, v83, v107
	v_sub_f32_e32 v74, v82, v107
	v_sub_f32_e32 v77, v85, v107
	v_sub_f32_e32 v76, v84, v107
	v_pk_mul_f32 v[76:77], v[0:1], v[76:77] op_sel_hi:[0,1]
	v_pk_mul_f32 v[74:75], v[0:1], v[74:75] op_sel_hi:[0,1]
	v_pk_fma_f32 v[74:75], v[86:87], v[74:75], v[90:91]
	v_pk_fma_f32 v[76:77], v[88:89], v[76:77], v[92:93]
	v_pk_fma_f32 v[66:67], v[74:75], s[2:3], v[66:67] op_sel_hi:[1,0,1]
	v_pk_fma_f32 v[68:69], v[76:77], s[2:3], v[68:69] op_sel_hi:[1,0,1]
	v_add_f32_e32 v0, v66, v67
	v_add_f32_e32 v74, v68, v69
	v_add_f32_e32 v0, v0, v74
	v_mul_f32_e32 v74, v67, v67
	v_mul_f32_e32 v75, v69, v69
	v_add_f32_e32 v0, v78, v0
	v_fmac_f32_e32 v74, v66, v66
	v_fmac_f32_e32 v75, v68, v68
	s_nop 0
	s_nop 1
	v_bfe_u32 v77, v227, 4, 2
	v_sub_u32_e32 v76, 0, v77
	v_lshlrev_b32_e32 v76, 4, v76
	v_ashrrev_i32_e32 v77, 31, v76
	v_lshl_add_u64 v[76:77], v[108:109], 0, v[76:77]
	v_permlane16_swap_b32_e32 v70, v66
	v_permlane16_swap_b32_e32 v71, v67
	v_permlane16_swap_b32_e32 v72, v68
	v_permlane16_swap_b32_e32 v73, v69
	v_permlane32_swap_b32_e32 v70, v66
	v_permlane32_swap_b32_e32 v71, v67
	v_permlane32_swap_b32_e32 v72, v68
	v_permlane32_swap_b32_e32 v73, v69
	v_mov_b32_e32 v82, v70
	v_mov_b32_e32 v83, v71
	v_mov_b32_e32 v84, v72
	v_mov_b32_e32 v85, v73
	v_bfe_u32 v80, v227, 3, 1
	v_mul_i32_i24_e32 v80, 0xffff8040, v80
	v_ashrrev_i32_e32 v81, 31, v80
	v_lshl_add_u64 v[76:77], v[76:77], 0, v[80:81]
	v_mov_b32_e32 v80, 0x8000
	v_mov_b32_e32 v81, 0
	v_lshl_add_u64 v[80:81], v[76:77], 0, v[80:81]
	v_mov_b32_dpp v70, v66 row_ror:8 row_mask:0xf bank_mask:0xc
	v_mov_b32_dpp v71, v67 row_ror:8 row_mask:0xf bank_mask:0xc
	v_mov_b32_dpp v72, v68 row_ror:8 row_mask:0xf bank_mask:0xc
	v_mov_b32_dpp v73, v69 row_ror:8 row_mask:0xf bank_mask:0xc
	v_mov_b32_dpp v66, v82 row_ror:8 row_mask:0xf bank_mask:0x3
	v_mov_b32_dpp v67, v83 row_ror:8 row_mask:0xf bank_mask:0x3
	v_mov_b32_dpp v68, v84 row_ror:8 row_mask:0xf bank_mask:0x3
	v_mov_b32_dpp v69, v85 row_ror:8 row_mask:0xf bank_mask:0x3
	global_store_dwordx4 v[76:77], v[70:73], off offset:512 nt
	global_store_dwordx4 v[80:81], v[66:69], off offset:512 nt
	s_nop 1
	v_mov_b32_dpp v66, v70 row_ror:8 row_mask:0xf bank_mask:0x3
	v_mov_b32_dpp v67, v71 row_ror:8 row_mask:0xf bank_mask:0x3
	v_mov_b32_dpp v68, v72 row_ror:8 row_mask:0xf bank_mask:0x3
	v_mov_b32_dpp v69, v73 row_ror:8 row_mask:0xf bank_mask:0x3
	v_mov_b32_e32 v70, v82
	v_mov_b32_e32 v71, v83
	v_mov_b32_e32 v72, v84
	v_mov_b32_e32 v73, v85
	s_nop 1
	v_permlane32_swap_b32_e32 v70, v66
	v_permlane32_swap_b32_e32 v71, v67
	v_permlane32_swap_b32_e32 v72, v68
	v_permlane32_swap_b32_e32 v73, v69
	v_permlane16_swap_b32_e32 v70, v66
	v_permlane16_swap_b32_e32 v71, v67
	v_permlane16_swap_b32_e32 v72, v68
	v_permlane16_swap_b32_e32 v73, v69
	v_add_f32_e32 v74, v74, v75
	v_cvt_pk_bf16_f32 v70, v70, v71
	v_cvt_pk_bf16_f32 v71, v72, v73
	v_cvt_pk_bf16_f32 v72, v66, v67
	v_mov_b32_e32 v66, v0
	v_add_f32_e32 v74, v79, v74
	s_nop 0
	v_permlane16_swap_b32_e32 v0, v66
	v_add_f32_e32 v66, v0, v66
	v_mov_b32_e32 v0, v74
	s_nop 1
	v_permlane16_swap_b32_e32 v74, v0
	v_add_f32_e32 v67, v74, v0
	v_cvt_pk_bf16_f32 v73, v68, v69
	v_mov_b32_e32 v68, v66
	v_mov_b32_e32 v69, v67
	s_nop 0
	v_permlane32_swap_b32_e32 v66, v68
	v_permlane32_swap_b32_e32 v67, v69
	global_store_dwordx4 v106, v[70:73], s[40:41]
	s_and_saveexec_b64 s[26:27], s[44:45]
	s_cbranch_execz .LBB0_1543
	v_pk_add_f32 v[66:67], v[66:67], v[68:69]
	v_lshl_add_u64 v[68:69], s[6:7], 0, v[160:161]
	v_lshl_add_u64 v[68:69], s[52:53], 2, v[68:69]
	global_store_dwordx2 v[68:69], v[66:67], off
; __device__ __forceinline__ float xsum16(float v) { const auto r = __builtin_amdgcn_permlane16_swap(__float_as_uint(v), __float_as_uint(v), false, false); return __uint_as_float(r[0]) + __uint_as_float(r[1]); }
; __device__ __forceinline__ float xsum32(float v) { const auto r = __builtin_amdgcn_permlane32_swap(__float_as_uint(v), __float_as_uint(v), false, false); return __uint_as_float(r[0]) + __uint_as_float(r[1]); }
; __device__ __forceinline__ void row_stats4(const float* st, int rowb, int fq, float (&mu)[4], float (&rs)[4]) {
;     ...
;     for (int m = 0; m < 4; ++m) { const f32x4* p = (const f32x4*)(st + (size_t)(rowb + m * 16) * 32 + fq * 8); a[m] = p[0]; b[m] = p[1]; }
; #pragma unroll
;     for (int m = 0; m < 4; ++m) { float s1 = (a[m][0] + a[m][2]) + (b[m][0] + b[m][2]), s2 = (a[m][1] + a[m][3]) + (b[m][1] + b[m][3]);
;         s1 = xsum32(xsum16(s1)); s2 = xsum32(xsum16(s2));
;         const float mm = s1 * (1.0f / 1024.0f); mu[m] = mm; rs[m] = rsqrtf(fmaxf(s2 * (1.0f / 1024.0f) - mm * mm, 0.f) + LN_EPS_); }
;     __device__ __forceinline__ void operator()(const f32x4 (&acc)[2][2][4][2], const pg8::Unit& u, int wr, int wc, int fr, int fq) const {
;     ...
;         for (int ai = 0; ai < 2; ++ai) { float mu4[4], rs4[4]; row_stats4(stp, row0 + ai * 128, fq, mu4, rs4);
; #pragma unroll
;             for (int m = 0; m < 4; ++m) { const int row = row0 + ai * 128 + m * 16; const float mu = mu4[m], rs = rs4[m];
;                 f32x4 yv[2][2], gq[2][2], bq_[2][2];
; #pragma unroll
;                 for (int bj = 0; bj < 2; ++bj)
; #pragma unroll
;                     for (int n = 0; n < 2; ++n) { yv[bj][n] = *(const f32x4*)(Yin + (size_t)row * D_ + col0 + bj * 128 + 4 * n); gq[bj][n] = *(const f32x4*)(g + col0 + bj * 128 + 4 * n); bq_[bj][n] = *(const f32x4*)(b + col0 + bj * 128 + 4 * n); }
.LBB0_1543:
	s_or_b64 exec, exec, s[26:27]
	v_add_u32_e32 v118, 0x80, v158
	v_ashrrev_i32_e32 v119, 31, v118
	v_lshlrev_b64 v[110:111], 7, v[118:119]
	v_lshl_add_u64 v[70:71], v[146:147], 0, v[110:111]
	global_load_dwordx4 v[66:69], v[70:71], off
	s_nop 0
	global_load_dwordx4 v[70:73], v[70:71], off offset:16
	v_add_u32_e32 v108, 0x90, v158
	v_ashrrev_i32_e32 v109, 31, v108
	v_lshlrev_b64 v[102:103], 7, v[108:109]
	v_lshl_add_u64 v[78:79], v[146:147], 0, v[102:103]
	global_load_dwordx4 v[74:77], v[78:79], off
	s_nop 0
	global_load_dwordx4 v[78:81], v[78:79], off offset:16
	v_add_u32_e32 v96, 0xa0, v158
	v_ashrrev_i32_e32 v97, 31, v96
	v_lshlrev_b64 v[82:83], 7, v[96:97]
	v_lshl_add_u64 v[86:87], v[146:147], 0, v[82:83]
	global_load_dwordx4 v[82:85], v[86:87], off
	s_nop 0
	global_load_dwordx4 v[86:89], v[86:87], off offset:16
	v_add_u32_e32 v94, 0xb0, v158
	v_ashrrev_i32_e32 v95, 31, v94
	v_lshlrev_b64 v[90:91], 7, v[94:95]
	v_lshl_add_u64 v[98:99], v[146:147], 0, v[90:91]
	global_load_dwordx4 v[90:93], v[98:99], off
	s_nop 0
	global_load_dwordx4 v[98:101], v[98:99], off offset:16
	s_mov_b32 s2, 0x3a800000
	s_mov_b32 s1, 0x800000
	s_load_dwordx16 s[64:79], s[34:35], 0x38
	s_mov_b32 s14, 0x3fd744fd
	s_waitcnt vmcnt(7)
	v_mov_b32_e32 v104, v66
	s_waitcnt vmcnt(6)
	v_mov_b32_e32 v105, v70
	v_mov_b32_e32 v106, v68
	v_mov_b32_e32 v107, v72
	v_pk_add_f32 v[104:105], v[104:105], v[106:107]
	v_mov_b32_e32 v70, v67
	v_pk_add_f32 v[104:105], v[104:105], v[104:105] op_sel:[0,1] op_sel_hi:[1,0]
	v_mov_b32_e32 v72, v69
	v_pk_add_f32 v[66:67], v[70:71], v[72:73]
	v_mov_b32_e32 v0, v104
	v_pk_add_f32 v[66:67], v[66:67], v[66:67] op_sel:[0,1] op_sel_hi:[1,0]
	s_nop 0
	v_permlane16_swap_b32_e32 v104, v0
	v_add_f32_e32 v67, v104, v0
	v_mov_b32_e32 v0, v66
	s_nop 1
	v_permlane16_swap_b32_e32 v66, v0
	v_add_f32_e32 v66, v66, v0
	v_mov_b32_e32 v69, v67
	v_mov_b32_e32 v68, v66
	s_nop 0
	v_permlane32_swap_b32_e32 v67, v69
	v_permlane32_swap_b32_e32 v66, v68
	v_pk_add_f32 v[66:67], v[66:67], v[68:69]
	s_waitcnt vmcnt(5)
	v_mov_b32_e32 v68, v76
	v_pk_mul_f32 v[116:117], v[66:67], s[2:3] op_sel_hi:[1,0]
	s_waitcnt vmcnt(4)
	v_mov_b32_e32 v67, v78
	v_fma_f32 v0, -v117, v117, v116
	v_max_f32_e32 v0, 0, v0
	v_add_f32_e32 v0, 0x3727c5ac, v0
	v_cmp_gt_f32_e32 vcc, s1, v0
	v_mul_f32_e32 v66, 0x4b800000, v0
	v_mov_b32_e32 v69, v80
	v_cndmask_b32_e32 v0, v0, v66, vcc
	v_rsq_f32_e32 v0, v0
	v_mov_b32_e32 v78, v75
	v_mov_b32_e32 v80, v77
	v_readlane_b32 s2, v253, 59
	v_mul_f32_e32 v66, 0x45800000, v0
	v_cndmask_b32_e32 v116, v0, v66, vcc
	v_mov_b32_e32 v66, v74
	v_pk_add_f32 v[66:67], v[66:67], v[68:69]
	v_pk_add_f32 v[68:69], v[78:79], v[80:81]
	v_pk_add_f32 v[66:67], v[66:67], v[66:67] op_sel:[0,1] op_sel_hi:[1,0]
	v_pk_add_f32 v[68:69], v[68:69], v[68:69] op_sel:[0,1] op_sel_hi:[1,0]
	v_mov_b32_e32 v0, v66
	s_nop 1
	v_permlane16_swap_b32_e32 v66, v0
	v_add_f32_e32 v113, v66, v0
	v_mov_b32_e32 v0, v68
	s_nop 1
	v_permlane16_swap_b32_e32 v68, v0
	v_add_f32_e32 v112, v68, v0
	s_waitcnt vmcnt(3)
	v_mov_b32_e32 v66, v82
	s_waitcnt vmcnt(2)
	v_mov_b32_e32 v67, v86
	v_mov_b32_e32 v68, v84
	v_mov_b32_e32 v69, v88
	v_pk_add_f32 v[66:67], v[66:67], v[68:69]
	v_mov_b32_e32 v86, v83
	v_pk_add_f32 v[66:67], v[66:67], v[66:67] op_sel:[0,1] op_sel_hi:[1,0]
	v_mov_b32_e32 v88, v85
	v_pk_add_f32 v[68:69], v[86:87], v[88:89]
	v_mov_b32_e32 v0, v66
	v_pk_add_f32 v[68:69], v[68:69], v[68:69] op_sel:[0,1] op_sel_hi:[1,0]
	s_nop 0
	v_permlane16_swap_b32_e32 v66, v0
	v_add_f32_e32 v105, v66, v0
	v_mov_b32_e32 v0, v68
	s_nop 1
	v_permlane16_swap_b32_e32 v68, v0
	v_add_f32_e32 v104, v68, v0
	s_waitcnt vmcnt(1)
	v_mov_b32_e32 v66, v90
	s_waitcnt vmcnt(0)
	v_mov_b32_e32 v67, v98
	v_mov_b32_e32 v68, v92
	v_mov_b32_e32 v69, v100
	v_pk_add_f32 v[66:67], v[66:67], v[68:69]
	v_mov_b32_e32 v98, v91
	v_pk_add_f32 v[66:67], v[66:67], v[66:67] op_sel:[0,1] op_sel_hi:[1,0]
	v_mov_b32_e32 v100, v93
	v_mov_b32_e32 v0, v66
	s_nop 1
	v_permlane16_swap_b32_e32 v66, v0
	v_pk_add_f32 v[68:69], v[98:99], v[100:101]
	v_add_f32_e32 v99, v66, v0
	v_ashrrev_i32_e32 v66, 8, v118
	v_ashrrev_i32_e32 v67, 31, v66
	v_pk_add_f32 v[68:69], v[68:69], v[68:69] op_sel:[0,1] op_sel_hi:[1,0]
	v_lshlrev_b64 v[120:121], 19, v[66:67]
	v_lshlrev_b64 v[66:67], 12, v[118:119]
	v_mov_b32_e32 v0, v68
	s_waitcnt lgkmcnt(0)
	v_lshl_add_u64 v[66:67], s[78:79], 0, v[66:67]
	v_permlane16_swap_b32_e32 v68, v0
	v_lshl_add_u64 v[122:123], v[152:153], 2, v[66:67]
	v_add_f32_e32 v98, v68, v0
	global_load_dwordx4 v[74:77], v[122:123], off offset:16
	global_load_dwordx4 v[86:89], v[122:123], off
	global_load_dwordx4 v[66:69], v[156:157], off offset:16
	global_load_dwordx4 v[78:81], v[156:157], off
	global_load_dwordx4 v[70:73], v[154:155], off offset:16
	global_load_dwordx4 v[82:85], v[154:155], off
	global_load_dwordx4 v[90:93], v[122:123], off offset:528
	global_load_dwordx4 v[124:127], v[122:123], off offset:512
	global_load_dwordx4 v[128:131], v[156:157], off offset:528
	global_load_dwordx4 v[132:135], v[156:157], off offset:512
	global_load_dwordx4 v[158:161], v[154:155], off offset:528
	global_load_dwordx4 v[162:165], v[154:155], off offset:512
	v_lshlrev_b32_e32 v0, 6, v118
	s_movk_i32 s1, 0x33c0
	v_readlane_b32 s3, v253, 60
	v_and_or_b32 v0, v0, s1, v196
	v_lshlrev_b32_e32 v0, 1, v0
	v_mov_b32_e32 v115, v113
	v_mov_b32_e32 v114, v112
	v_mov_b32_e32 v107, v105
	v_mov_b32_e32 v106, v104
	v_mov_b32_e32 v101, v99
	v_mov_b32_e32 v100, v98
	v_permlane32_swap_b32_e32 v113, v115
	v_permlane32_swap_b32_e32 v112, v114
	v_permlane32_swap_b32_e32 v105, v107
	v_permlane32_swap_b32_e32 v104, v106
	v_permlane32_swap_b32_e32 v99, v101
	v_permlane32_swap_b32_e32 v98, v100
	s_waitcnt vmcnt(11)
; __device__ __forceinline__ size_t blk_off(int r, int c, int K) { return (size_t)(r >> 8) * 256 * K + (size_t)(c >> 6) * (256 * 64) + (size_t)((r & 255) * 64 + (c & 63)); }
; __device__ __forceinline__ u32x4 pack8(const f32x4 a, const f32x4 b) { u32x4 w; w.x = cvt_pk_bf16(a[0], a[1]); w.y = cvt_pk_bf16(a[2], a[3]); w.z = cvt_pk_bf16(b[0], b[1]); w.w = cvt_pk_bf16(b[2], b[3]); return w; }
;     __device__ __forceinline__ void operator()(const f32x4 (&acc)[2][2][4][2], const pg8::Unit& u, int wr, int wc, int fr, int fq) const {
;     ...
;                     for (int n = 0; n < 2; ++n) { yv[bj][n] = *(const f32x4*)(Yin + (size_t)row * D_ + col0 + bj * 128 + 4 * n); gq[bj][n] = *(const f32x4*)(g + col0 + bj * 128 + 4 * n); bq_[bj][n] = *(const f32x4*)(b + col0 + bj * 128 + 4 * n); }
;                 asm volatile("" ::: "memory");
;                 float s1 = 0.f, s2 = 0.f;
; #pragma unroll
;                 for (int bj = 0; bj < 2; ++bj) { float* yp = Y + (size_t)row * D_ + col0 + bj * 128; f32x4 v[2];
; #pragma unroll
;                     for (int n = 0; n < 2; ++n) { v[n] = (((yv[bj][n] - mu) * rs) * gq[bj][n] + bq_[bj][n]) * ALPHA_ + acc[ai][bj][m][n] * sc;
;                         *(f32x4*)(yp + 4 * n) = v[n]; s1 += (v[n][0] + v[n][1]) + (v[n][2] + v[n][3]); s2 += (v[n][0] * v[n][0] + v[n][1] * v[n][1]) + (v[n][2] * v[n][2] + v[n][3] * v[n][3]); }
;                     *(u32x4*)(Yb + blk_off(row, col0 + bj * 128, D_)) = pack8(v[0], v[1]); }
	v_sub_f32_e32 v75, v75, v117
	s_waitcnt vmcnt(10)
	v_sub_f32_e32 v87, v87, v117
	v_sub_f32_e32 v86, v86, v117
	v_sub_f32_e32 v89, v89, v117
	v_sub_f32_e32 v88, v88, v117
	v_sub_f32_e32 v74, v74, v117
	v_sub_f32_e32 v77, v77, v117
	v_sub_f32_e32 v76, v76, v117
	v_pk_mul_f32 v[88:89], v[116:117], v[88:89] op_sel_hi:[0,1]
	v_pk_mul_f32 v[86:87], v[116:117], v[86:87] op_sel_hi:[0,1]
	v_pk_mul_f32 v[76:77], v[116:117], v[76:77] op_sel_hi:[0,1]
	v_pk_mul_f32 v[74:75], v[116:117], v[74:75] op_sel_hi:[0,1]
	s_waitcnt vmcnt(6)
	v_pk_fma_f32 v[78:79], v[78:79], v[86:87], v[82:83]
	v_pk_fma_f32 v[80:81], v[80:81], v[88:89], v[84:85]
	v_pk_fma_f32 v[66:67], v[66:67], v[74:75], v[70:71]
	v_pk_fma_f32 v[68:69], v[68:69], v[76:77], v[72:73]
	v_pk_fma_f32 v[64:65], v[80:81], s[14:15], v[64:65] op_sel_hi:[1,0,1]
	v_pk_fma_f32 v[62:63], v[78:79], s[14:15], v[62:63] op_sel_hi:[1,0,1]
	v_pk_fma_f32 v[60:61], v[68:69], s[14:15], v[60:61] op_sel_hi:[1,0,1]
	v_pk_fma_f32 v[58:59], v[66:67], s[14:15], v[58:59] op_sel_hi:[1,0,1]
	v_add_f32_e32 v78, v62, v63
	v_add_f32_e32 v79, v64, v65
	v_add_f32_e32 v66, v58, v59
	v_add_f32_e32 v67, v60, v61
	v_add_f32_e32 v78, v78, v79
	v_mul_f32_e32 v79, v63, v63
	v_mul_f32_e32 v80, v65, v65
	v_add_f32_e32 v66, v66, v67
	v_mul_f32_e32 v67, v59, v59
	s_nop 0
	v_fmac_f32_e32 v79, v62, v62
	v_fmac_f32_e32 v80, v64, v64
	s_nop 1
	v_bfe_u32 v69, v227, 4, 2
	v_sub_u32_e32 v68, 0, v69
	v_lshlrev_b32_e32 v68, 4, v68
	v_ashrrev_i32_e32 v69, 31, v68
	v_lshl_add_u64 v[68:69], v[122:123], 0, v[68:69]
	v_permlane16_swap_b32_e32 v62, v58
	v_permlane16_swap_b32_e32 v63, v59
	v_permlane16_swap_b32_e32 v64, v60
	v_permlane16_swap_b32_e32 v65, v61
	v_permlane32_swap_b32_e32 v62, v58
	v_permlane32_swap_b32_e32 v63, v59
	v_permlane32_swap_b32_e32 v64, v60
	v_permlane32_swap_b32_e32 v65, v61
	v_mov_b32_e32 v72, v62
	v_mov_b32_e32 v73, v63
	v_mov_b32_e32 v74, v64
	v_mov_b32_e32 v75, v65
	v_bfe_u32 v70, v227, 3, 1
	v_mul_i32_i24_e32 v70, 0xffff8040, v70
	v_ashrrev_i32_e32 v71, 31, v70
	v_lshl_add_u64 v[68:69], v[68:69], 0, v[70:71]
	v_mov_b32_e32 v70, 0x8000
	v_mov_b32_e32 v71, 0
	v_lshl_add_u64 v[70:71], v[68:69], 0, v[70:71]
	v_mov_b32_dpp v62, v58 row_ror:8 row_mask:0xf bank_mask:0xc
	v_mov_b32_dpp v63, v59 row_ror:8 row_mask:0xf bank_mask:0xc
	v_mov_b32_dpp v64, v60 row_ror:8 row_mask:0xf bank_mask:0xc
	v_mov_b32_dpp v65, v61 row_ror:8 row_mask:0xf bank_mask:0xc
	v_mov_b32_dpp v58, v72 row_ror:8 row_mask:0xf bank_mask:0x3
	v_mov_b32_dpp v59, v73 row_ror:8 row_mask:0xf bank_mask:0x3
	v_mov_b32_dpp v60, v74 row_ror:8 row_mask:0xf bank_mask:0x3
	v_mov_b32_dpp v61, v75 row_ror:8 row_mask:0xf bank_mask:0x3
	global_store_dwordx4 v[68:69], v[62:65], off nt
	global_store_dwordx4 v[70:71], v[58:61], off nt
	s_nop 1
	v_mov_b32_dpp v58, v62 row_ror:8 row_mask:0xf bank_mask:0x3
	v_mov_b32_dpp v59, v63 row_ror:8 row_mask:0xf bank_mask:0x3
	v_mov_b32_dpp v60, v64 row_ror:8 row_mask:0xf bank_mask:0x3
	v_mov_b32_dpp v61, v65 row_ror:8 row_mask:0xf bank_mask:0x3
	v_mov_b32_e32 v62, v72
	v_mov_b32_e32 v63, v73
	v_mov_b32_e32 v64, v74
	v_mov_b32_e32 v65, v75
	s_nop 1
	v_permlane32_swap_b32_e32 v62, v58
	v_permlane32_swap_b32_e32 v63, v59
	v_permlane32_swap_b32_e32 v64, v60
	v_permlane32_swap_b32_e32 v65, v61
	v_permlane16_swap_b32_e32 v62, v58
	v_permlane16_swap_b32_e32 v63, v59
	v_permlane16_swap_b32_e32 v64, v60
	v_permlane16_swap_b32_e32 v65, v61
	v_fmac_f32_e32 v67, v58, v58
	v_cvt_pk_bf16_f32 v62, v62, v63
	v_cvt_pk_bf16_f32 v63, v64, v65
	v_cvt_pk_bf16_f32 v64, v58, v59
	v_lshl_add_u64 v[58:59], s[2:3], 0, v[120:121]
	v_mul_f32_e32 v68, v61, v61
	v_lshl_add_u64 v[76:77], v[58:59], 0, s[24:25]
	v_fmac_f32_e32 v68, v60, v60
	v_cvt_pk_bf16_f32 v65, v60, v61
	v_lshl_add_u64 v[60:61], v[76:77], 0, v[0:1]
	global_store_dwordx4 v[60:61], v[62:65], off
	s_waitcnt vmcnt(7)
	v_sub_f32_e32 v61, v125, v117
	v_sub_f32_e32 v60, v124, v117
	v_sub_f32_e32 v63, v127, v117
	v_sub_f32_e32 v62, v126, v117
	v_pk_mul_f32 v[62:63], v[116:117], v[62:63] op_sel_hi:[0,1]
	v_pk_mul_f32 v[60:61], v[116:117], v[60:61] op_sel_hi:[0,1]
	s_waitcnt vmcnt(3)
	v_pk_fma_f32 v[60:61], v[132:133], v[60:61], v[162:163]
	v_pk_fma_f32 v[62:63], v[134:135], v[62:63], v[164:165]
	v_pk_fma_f32 v[54:55], v[60:61], s[14:15], v[54:55] op_sel_hi:[1,0,1]
	v_pk_fma_f32 v[56:57], v[62:63], s[14:15], v[56:57] op_sel_hi:[1,0,1]
	v_add_f32_e32 v78, 0, v78
	v_add_f32_e32 v60, v54, v55
	v_add_f32_e32 v61, v56, v57
	v_add_f32_e32 v66, v78, v66
	v_add_f32_e32 v60, v60, v61
	v_add_f32_e32 v64, v66, v60
	v_mul_f32_e32 v60, v55, v55
	v_mul_f32_e32 v61, v57, v57
	v_add_f32_e32 v79, v79, v80
	v_add_f32_e32 v67, v67, v68
	v_fmac_f32_e32 v60, v54, v54
	v_fmac_f32_e32 v61, v56, v56
	v_add_f32_e32 v67, v79, v67
	v_add_f32_e32 v60, v60, v61
	v_add_f32_e32 v65, v67, v60
	v_sub_f32_e32 v61, v91, v117
	v_sub_f32_e32 v60, v90, v117
	v_sub_f32_e32 v63, v93, v117
	v_sub_f32_e32 v62, v92, v117
	v_pk_mul_f32 v[62:63], v[116:117], v[62:63] op_sel_hi:[0,1]
	v_pk_mul_f32 v[60:61], v[116:117], v[60:61] op_sel_hi:[0,1]
	v_pk_fma_f32 v[60:61], v[128:129], v[60:61], v[158:159]
	v_pk_fma_f32 v[62:63], v[130:131], v[62:63], v[160:161]
	v_pk_fma_f32 v[50:51], v[60:61], s[14:15], v[50:51] op_sel_hi:[1,0,1]
	v_pk_fma_f32 v[52:53], v[62:63], s[14:15], v[52:53] op_sel_hi:[1,0,1]
	v_add_f32_e32 v60, v50, v51
	v_add_f32_e32 v61, v52, v53
	v_add_f32_e32 v60, v60, v61
	v_mul_f32_e32 v61, v51, v51
	v_mul_f32_e32 v62, v53, v53
	v_add_f32_e32 v60, v64, v60
	v_fmac_f32_e32 v61, v50, v50
	v_fmac_f32_e32 v62, v52, v52
	v_lshl_add_u64 v[74:75], v[58:59], 0, s[28:29]
	s_nop 0
	s_nop 1
	v_bfe_u32 v67, v227, 4, 2
	v_sub_u32_e32 v66, 0, v67
; __device__ __forceinline__ float xsum16(float v) { const auto r = __builtin_amdgcn_permlane16_swap(__float_as_uint(v), __float_as_uint(v), false, false); return __uint_as_float(r[0]) + __uint_as_float(r[1]); }
; __device__ __forceinline__ float xsum32(float v) { const auto r = __builtin_amdgcn_permlane32_swap(__float_as_uint(v), __float_as_uint(v), false, false); return __uint_as_float(r[0]) + __uint_as_float(r[1]); }
; __device__ __forceinline__ size_t blk_off(int r, int c, int K) { return (size_t)(r >> 8) * 256 * K + (size_t)(c >> 6) * (256 * 64) + (size_t)((r & 255) * 64 + (c & 63)); }
; __device__ __forceinline__ u32x4 pack8(const f32x4 a, const f32x4 b) { u32x4 w; w.x = cvt_pk_bf16(a[0], a[1]); w.y = cvt_pk_bf16(a[2], a[3]); w.z = cvt_pk_bf16(b[0], b[1]); w.w = cvt_pk_bf16(b[2], b[3]); return w; }
;     __device__ __forceinline__ void operator()(const f32x4 (&acc)[2][2][4][2], const pg8::Unit& u, int wr, int wc, int fr, int fq) const {
;     ...
;             for (int m = 0; m < 4; ++m) { const int row = row0 + ai * 128 + m * 16; const float mu = mu4[m], rs = rs4[m];
;                 f32x4 yv[2][2], gq[2][2], bq_[2][2];
; #pragma unroll
;                 for (int bj = 0; bj < 2; ++bj)
; #pragma unroll
;                     for (int n = 0; n < 2; ++n) { yv[bj][n] = *(const f32x4*)(Yin + (size_t)row * D_ + col0 + bj * 128 + 4 * n); gq[bj][n] = *(const f32x4*)(g + col0 + bj * 128 + 4 * n); bq_[bj][n] = *(const f32x4*)(b + col0 + bj * 128 + 4 * n); }
;     ...
;                 for (int bj = 0; bj < 2; ++bj) { float* yp = Y + (size_t)row * D_ + col0 + bj * 128; f32x4 v[2];
; #pragma unroll
;                     for (int n = 0; n < 2; ++n) { v[n] = (((yv[bj][n] - mu) * rs) * gq[bj][n] + bq_[bj][n]) * ALPHA_ + acc[ai][bj][m][n] * sc;
;                         *(f32x4*)(yp + 4 * n) = v[n]; s1 += (v[n][0] + v[n][1]) + (v[n][2] + v[n][3]); s2 += (v[n][0] * v[n][0] + v[n][1] * v[n][1]) + (v[n][2] * v[n][2] + v[n][3] * v[n][3]); }
;                     *(u32x4*)(Yb + blk_off(row, col0 + bj * 128, D_)) = pack8(v[0], v[1]); }
;                 s1 = xsum32(xsum16(s1)); s2 = xsum32(xsum16(s2));
;                 if (fq == 0) *(f32x2*)(stn + (size_t)row * 32 + (u.pn * 4 + wc) * 2) = (f32x2){s1, s2}; asm volatile("" ::: "memory"); } }
	v_lshlrev_b32_e32 v66, 4, v66
	v_ashrrev_i32_e32 v67, 31, v66
	v_lshl_add_u64 v[66:67], v[122:123], 0, v[66:67]
	v_permlane16_swap_b32_e32 v54, v50
	v_permlane16_swap_b32_e32 v55, v51
	v_permlane16_swap_b32_e32 v56, v52
	v_permlane16_swap_b32_e32 v57, v53
	v_permlane32_swap_b32_e32 v54, v50
	v_permlane32_swap_b32_e32 v55, v51
	v_permlane32_swap_b32_e32 v56, v52
	v_permlane32_swap_b32_e32 v57, v53
	v_mov_b32_e32 v63, v54
	v_mov_b32_e32 v64, v55
	v_mov_b32_e32 v70, v56
	v_mov_b32_e32 v71, v57
	v_bfe_u32 v68, v227, 3, 1
	v_mul_i32_i24_e32 v68, 0xffff8040, v68
	v_ashrrev_i32_e32 v69, 31, v68
	v_lshl_add_u64 v[66:67], v[66:67], 0, v[68:69]
	v_mov_b32_e32 v68, 0x8000
	v_mov_b32_e32 v69, 0
	v_lshl_add_u64 v[68:69], v[66:67], 0, v[68:69]
	v_mov_b32_dpp v54, v50 row_ror:8 row_mask:0xf bank_mask:0xc
	v_mov_b32_dpp v55, v51 row_ror:8 row_mask:0xf bank_mask:0xc
	v_mov_b32_dpp v56, v52 row_ror:8 row_mask:0xf bank_mask:0xc
	v_mov_b32_dpp v57, v53 row_ror:8 row_mask:0xf bank_mask:0xc
	v_mov_b32_dpp v50, v63 row_ror:8 row_mask:0xf bank_mask:0x3
	v_mov_b32_dpp v51, v64 row_ror:8 row_mask:0xf bank_mask:0x3
	v_mov_b32_dpp v52, v70 row_ror:8 row_mask:0xf bank_mask:0x3
	v_mov_b32_dpp v53, v71 row_ror:8 row_mask:0xf bank_mask:0x3
	global_store_dwordx4 v[66:67], v[54:57], off offset:512 nt
	global_store_dwordx4 v[68:69], v[50:53], off offset:512 nt
	s_nop 1
	v_mov_b32_dpp v50, v54 row_ror:8 row_mask:0xf bank_mask:0x3
	v_mov_b32_dpp v51, v55 row_ror:8 row_mask:0xf bank_mask:0x3
	v_mov_b32_dpp v52, v56 row_ror:8 row_mask:0xf bank_mask:0x3
	v_mov_b32_dpp v53, v57 row_ror:8 row_mask:0xf bank_mask:0x3
	v_mov_b32_e32 v54, v63
	v_mov_b32_e32 v55, v64
	v_mov_b32_e32 v56, v70
	v_mov_b32_e32 v57, v71
	s_nop 1
	v_permlane32_swap_b32_e32 v54, v50
	v_permlane32_swap_b32_e32 v55, v51
	v_permlane32_swap_b32_e32 v56, v52
	v_permlane32_swap_b32_e32 v57, v53
	v_permlane16_swap_b32_e32 v54, v50
	v_permlane16_swap_b32_e32 v55, v51
	v_permlane16_swap_b32_e32 v56, v52
	v_permlane16_swap_b32_e32 v57, v53
	v_add_f32_e32 v61, v61, v62
	v_cvt_pk_bf16_f32 v54, v54, v55
	v_cvt_pk_bf16_f32 v55, v56, v57
	v_cvt_pk_bf16_f32 v56, v50, v51
	v_lshl_add_u64 v[50:51], v[74:75], 0, v[0:1]
	v_mov_b32_e32 v0, v60
	v_add_f32_e32 v61, v65, v61
	v_cvt_pk_bf16_f32 v57, v52, v53
	v_permlane16_swap_b32_e32 v60, v0
	global_store_dwordx4 v[50:51], v[54:57], off
	v_add_f32_e32 v50, v60, v0
	v_mov_b32_e32 v0, v61
	s_nop 1
	v_permlane16_swap_b32_e32 v61, v0
	v_add_f32_e32 v51, v61, v0
	v_mov_b32_e32 v52, v50
	v_mov_b32_e32 v53, v51
	s_nop 0
	v_permlane32_swap_b32_e32 v50, v52
	v_permlane32_swap_b32_e32 v51, v53
	s_and_saveexec_b64 s[24:25], s[44:45]
	s_cbranch_execz .LBB0_1545
	v_pk_add_f32 v[50:51], v[50:51], v[52:53]
	v_lshl_add_u64 v[52:53], s[6:7], 0, v[110:111]
	v_lshl_add_u64 v[52:53], s[52:53], 2, v[52:53]
	global_store_dwordx2 v[52:53], v[50:51], off
.LBB0_1545:
	s_or_b64 exec, exec, s[24:25]
	v_pk_add_f32 v[50:51], v[112:113], v[114:115]
	s_mov_b32 s2, 0x3a800000
	v_pk_mul_f32 v[78:79], v[50:51], s[2:3] op_sel_hi:[1,0]
	s_mov_b32 s1, 0x800000
	v_fma_f32 v0, -v79, v79, v78
	v_max_f32_e32 v0, 0, v0
	v_add_f32_e32 v0, 0x3727c5ac, v0
	v_cmp_gt_f32_e32 vcc, s1, v0
	v_mul_f32_e32 v50, 0x4b800000, v0
	s_load_dwordx16 s[64:79], s[34:35], 0x38
	v_cndmask_b32_e32 v0, v0, v50, vcc
	v_rsq_f32_e32 v0, v0
	s_mov_b32 s2, 0x3fd744fd
	s_movk_i32 s1, 0x37c0
	v_mul_f32_e32 v50, 0x45800000, v0
	v_cndmask_b32_e32 v78, v0, v50, vcc
	v_lshlrev_b64 v[50:51], 12, v[108:109]
	s_waitcnt lgkmcnt(0)
	v_lshl_add_u64 v[50:51], s[78:79], 0, v[50:51]
	v_lshl_add_u64 v[80:81], v[152:153], 2, v[50:51]
	global_load_dwordx4 v[82:85], v[80:81], off offset:16
	global_load_dwordx4 v[86:89], v[80:81], off
	global_load_dwordx4 v[90:93], v[156:157], off offset:16
	global_load_dwordx4 v[110:113], v[156:157], off
	global_load_dwordx4 v[114:117], v[154:155], off offset:16
	global_load_dwordx4 v[118:121], v[154:155], off
	global_load_dwordx4 v[50:53], v[80:81], off offset:528
	global_load_dwordx4 v[70:73], v[80:81], off offset:512
	global_load_dwordx4 v[54:57], v[156:157], off offset:528
	global_load_dwordx4 v[62:65], v[156:157], off offset:512
	global_load_dwordx4 v[58:61], v[154:155], off offset:528
	global_load_dwordx4 v[66:69], v[154:155], off offset:512
	v_lshlrev_b32_e32 v0, 6, v108
	v_and_or_b32 v0, v0, s1, v196
	v_lshlrev_b32_e32 v0, 1, v0
	s_waitcnt vmcnt(10)
	v_sub_f32_e32 v87, v87, v79
	v_sub_f32_e32 v86, v86, v79
	v_sub_f32_e32 v89, v89, v79
	v_sub_f32_e32 v88, v88, v79
	v_pk_mul_f32 v[88:89], v[78:79], v[88:89] op_sel_hi:[0,1]
	v_pk_mul_f32 v[86:87], v[78:79], v[86:87] op_sel_hi:[0,1]
	s_waitcnt vmcnt(6)
; __device__ __forceinline__ size_t blk_off(int r, int c, int K) { return (size_t)(r >> 8) * 256 * K + (size_t)(c >> 6) * (256 * 64) + (size_t)((r & 255) * 64 + (c & 63)); }
; __device__ __forceinline__ u32x4 pack8(const f32x4 a, const f32x4 b) { u32x4 w; w.x = cvt_pk_bf16(a[0], a[1]); w.y = cvt_pk_bf16(a[2], a[3]); w.z = cvt_pk_bf16(b[0], b[1]); w.w = cvt_pk_bf16(b[2], b[3]); return w; }
;     __device__ __forceinline__ void operator()(const f32x4 (&acc)[2][2][4][2], const pg8::Unit& u, int wr, int wc, int fr, int fq) const {
;     ...
;                     for (int n = 0; n < 2; ++n) { yv[bj][n] = *(const f32x4*)(Yin + (size_t)row * D_ + col0 + bj * 128 + 4 * n); gq[bj][n] = *(const f32x4*)(g + col0 + bj * 128 + 4 * n); bq_[bj][n] = *(const f32x4*)(b + col0 + bj * 128 + 4 * n); }
;                 asm volatile("" ::: "memory");
;                 float s1 = 0.f, s2 = 0.f;
; #pragma unroll
;                 for (int bj = 0; bj < 2; ++bj) { float* yp = Y + (size_t)row * D_ + col0 + bj * 128; f32x4 v[2];
; #pragma unroll
;                     for (int n = 0; n < 2; ++n) { v[n] = (((yv[bj][n] - mu) * rs) * gq[bj][n] + bq_[bj][n]) * ALPHA_ + acc[ai][bj][m][n] * sc;
;                         *(f32x4*)(yp + 4 * n) = v[n]; s1 += (v[n][0] + v[n][1]) + (v[n][2] + v[n][3]); s2 += (v[n][0] * v[n][0] + v[n][1] * v[n][1]) + (v[n][2] * v[n][2] + v[n][3] * v[n][3]); }
;                     *(u32x4*)(Yb + blk_off(row, col0 + bj * 128, D_)) = pack8(v[0], v[1]); }
	v_pk_fma_f32 v[86:87], v[110:111], v[86:87], v[118:119]
	v_pk_fma_f32 v[88:89], v[112:113], v[88:89], v[120:121]
	v_pk_fma_f32 v[86:87], v[86:87], s[2:3], v[46:47] op_sel_hi:[1,0,1]
	v_pk_fma_f32 v[88:89], v[88:89], s[2:3], v[48:49] op_sel_hi:[1,0,1]
	v_add_f32_e32 v46, v86, v87
	v_add_f32_e32 v47, v88, v89
	v_add_f32_e32 v46, v46, v47
	v_add_f32_e32 v108, 0, v46
	v_mul_f32_e32 v46, v87, v87
	v_mul_f32_e32 v47, v89, v89
	v_fmac_f32_e32 v46, v86, v86
	v_fmac_f32_e32 v47, v88, v88
	v_add_f32_e32 v109, v46, v47
	v_sub_f32_e32 v47, v83, v79
	v_sub_f32_e32 v46, v82, v79
	v_sub_f32_e32 v49, v85, v79
	v_sub_f32_e32 v48, v84, v79
	v_pk_mul_f32 v[48:49], v[78:79], v[48:49] op_sel_hi:[0,1]
	v_pk_mul_f32 v[46:47], v[78:79], v[46:47] op_sel_hi:[0,1]
	v_pk_fma_f32 v[46:47], v[90:91], v[46:47], v[114:115]
	v_pk_fma_f32 v[48:49], v[92:93], v[48:49], v[116:117]
	v_pk_fma_f32 v[82:83], v[46:47], s[2:3], v[42:43] op_sel_hi:[1,0,1]
	v_pk_fma_f32 v[84:85], v[48:49], s[2:3], v[44:45] op_sel_hi:[1,0,1]
	v_add_f32_e32 v42, v82, v83
	v_add_f32_e32 v43, v84, v85
	v_add_f32_e32 v42, v42, v43
	v_add_f32_e32 v47, v108, v42
	v_mul_f32_e32 v42, v83, v83
	v_mul_f32_e32 v43, v85, v85
	v_fmac_f32_e32 v42, v82, v82
	v_fmac_f32_e32 v43, v84, v84
	v_add_f32_e32 v42, v42, v43
	v_add_f32_e32 v46, v109, v42
	v_cvt_pk_bf16_f32 v42, v86, v87
	v_cvt_pk_bf16_f32 v43, v88, v89
	v_cvt_pk_bf16_f32 v44, v82, v83
	v_cvt_pk_bf16_f32 v45, v84, v85
	v_lshl_add_u64 v[48:49], v[76:77], 0, v[0:1]
	s_nop 0
	s_nop 1
	v_bfe_u32 v91, v227, 4, 2
	v_sub_u32_e32 v90, 0, v91
	v_lshlrev_b32_e32 v90, 4, v90
	v_ashrrev_i32_e32 v91, 31, v90
	v_lshl_add_u64 v[90:91], v[80:81], 0, v[90:91]
	v_permlane16_swap_b32_e32 v86, v82
	v_permlane16_swap_b32_e32 v87, v83
	v_permlane16_swap_b32_e32 v88, v84
	v_permlane16_swap_b32_e32 v89, v85
	v_permlane32_swap_b32_e32 v86, v82
	v_permlane32_swap_b32_e32 v87, v83
	v_permlane32_swap_b32_e32 v88, v84
	v_permlane32_swap_b32_e32 v89, v85
	v_mov_b32_e32 v108, v86
	v_mov_b32_e32 v109, v87
	v_mov_b32_e32 v110, v88
	v_mov_b32_e32 v111, v89
	v_bfe_u32 v92, v227, 3, 1
	v_mul_i32_i24_e32 v92, 0xffff8040, v92
	v_ashrrev_i32_e32 v93, 31, v92
	v_lshl_add_u64 v[90:91], v[90:91], 0, v[92:93]
	v_mov_b32_e32 v92, 0x8000
	v_mov_b32_e32 v93, 0
	v_lshl_add_u64 v[92:93], v[90:91], 0, v[92:93]
	v_mov_b32_dpp v86, v82 row_ror:8 row_mask:0xf bank_mask:0xc
	v_mov_b32_dpp v87, v83 row_ror:8 row_mask:0xf bank_mask:0xc
	v_mov_b32_dpp v88, v84 row_ror:8 row_mask:0xf bank_mask:0xc
	v_mov_b32_dpp v89, v85 row_ror:8 row_mask:0xf bank_mask:0xc
	v_mov_b32_dpp v82, v108 row_ror:8 row_mask:0xf bank_mask:0x3
	v_mov_b32_dpp v83, v109 row_ror:8 row_mask:0xf bank_mask:0x3
	v_mov_b32_dpp v84, v110 row_ror:8 row_mask:0xf bank_mask:0x3
	v_mov_b32_dpp v85, v111 row_ror:8 row_mask:0xf bank_mask:0x3
	global_store_dwordx4 v[90:91], v[86:89], off nt
	global_store_dwordx4 v[92:93], v[82:85], off nt
	s_nop 1
	global_store_dwordx4 v[48:49], v[42:45], off
	s_waitcnt vmcnt(7)
	s_nop 0
	v_sub_f32_e32 v43, v71, v79
	v_sub_f32_e32 v42, v70, v79
	v_sub_f32_e32 v45, v73, v79
	v_sub_f32_e32 v44, v72, v79
	v_pk_mul_f32 v[44:45], v[78:79], v[44:45] op_sel_hi:[0,1]
	v_pk_mul_f32 v[42:43], v[78:79], v[42:43] op_sel_hi:[0,1]
	s_waitcnt vmcnt(3)
	v_pk_fma_f32 v[42:43], v[62:63], v[42:43], v[66:67]
	v_pk_fma_f32 v[44:45], v[64:65], v[44:45], v[68:69]
	v_pk_fma_f32 v[38:39], v[42:43], s[2:3], v[38:39] op_sel_hi:[1,0,1]
	v_pk_fma_f32 v[40:41], v[44:45], s[2:3], v[40:41] op_sel_hi:[1,0,1]
	v_add_f32_e32 v42, v38, v39
	v_add_f32_e32 v43, v40, v41
	v_add_f32_e32 v42, v42, v43
	v_add_f32_e32 v47, v47, v42
	v_mul_f32_e32 v42, v39, v39
	v_mul_f32_e32 v43, v41, v41
	v_fmac_f32_e32 v42, v38, v38
	v_fmac_f32_e32 v43, v40, v40
	v_add_f32_e32 v42, v42, v43
	v_add_f32_e32 v46, v46, v42
	v_sub_f32_e32 v43, v51, v79
	v_sub_f32_e32 v42, v50, v79
	v_sub_f32_e32 v45, v53, v79
	v_sub_f32_e32 v44, v52, v79
	v_pk_mul_f32 v[44:45], v[78:79], v[44:45] op_sel_hi:[0,1]
	v_pk_mul_f32 v[42:43], v[78:79], v[42:43] op_sel_hi:[0,1]
	v_pk_fma_f32 v[42:43], v[54:55], v[42:43], v[58:59]
	v_pk_fma_f32 v[44:45], v[56:57], v[44:45], v[60:61]
	v_pk_fma_f32 v[34:35], v[42:43], s[2:3], v[34:35] op_sel_hi:[1,0,1]
	v_pk_fma_f32 v[36:37], v[44:45], s[2:3], v[36:37] op_sel_hi:[1,0,1]
	v_add_f32_e32 v42, v34, v35
	v_add_f32_e32 v43, v36, v37
	v_add_f32_e32 v42, v42, v43
	v_mul_f32_e32 v43, v35, v35
	v_mul_f32_e32 v44, v37, v37
	v_add_f32_e32 v42, v47, v42
	v_fmac_f32_e32 v43, v34, v34
	v_fmac_f32_e32 v44, v36, v36
	s_nop 0
	s_nop 1
	v_bfe_u32 v49, v227, 4, 2
	v_sub_u32_e32 v48, 0, v49
	v_lshlrev_b32_e32 v48, 4, v48
	v_ashrrev_i32_e32 v49, 31, v48
	v_lshl_add_u64 v[48:49], v[80:81], 0, v[48:49]
	v_permlane16_swap_b32_e32 v38, v34
	v_permlane16_swap_b32_e32 v39, v35
	v_permlane16_swap_b32_e32 v40, v36
	v_permlane16_swap_b32_e32 v41, v37
	v_permlane32_swap_b32_e32 v38, v34
	v_permlane32_swap_b32_e32 v39, v35
	v_permlane32_swap_b32_e32 v40, v36
	v_permlane32_swap_b32_e32 v41, v37
	v_mov_b32_e32 v45, v38
	v_mov_b32_e32 v52, v39
	v_mov_b32_e32 v53, v40
	v_mov_b32_e32 v54, v41
	v_bfe_u32 v50, v227, 3, 1
	v_mul_i32_i24_e32 v50, 0xffff8040, v50
	v_ashrrev_i32_e32 v51, 31, v50
	v_lshl_add_u64 v[48:49], v[48:49], 0, v[50:51]
	v_mov_b32_e32 v50, 0x8000
	v_mov_b32_e32 v51, 0
	v_lshl_add_u64 v[50:51], v[48:49], 0, v[50:51]
	v_mov_b32_dpp v38, v34 row_ror:8 row_mask:0xf bank_mask:0xc
	v_mov_b32_dpp v39, v35 row_ror:8 row_mask:0xf bank_mask:0xc
	v_mov_b32_dpp v40, v36 row_ror:8 row_mask:0xf bank_mask:0xc
	v_mov_b32_dpp v41, v37 row_ror:8 row_mask:0xf bank_mask:0xc
	v_mov_b32_dpp v34, v45 row_ror:8 row_mask:0xf bank_mask:0x3
	v_mov_b32_dpp v35, v52 row_ror:8 row_mask:0xf bank_mask:0x3
; __device__ __forceinline__ float xsum16(float v) { const auto r = __builtin_amdgcn_permlane16_swap(__float_as_uint(v), __float_as_uint(v), false, false); return __uint_as_float(r[0]) + __uint_as_float(r[1]); }
; __device__ __forceinline__ float xsum32(float v) { const auto r = __builtin_amdgcn_permlane32_swap(__float_as_uint(v), __float_as_uint(v), false, false); return __uint_as_float(r[0]) + __uint_as_float(r[1]); }
; __device__ __forceinline__ size_t blk_off(int r, int c, int K) { return (size_t)(r >> 8) * 256 * K + (size_t)(c >> 6) * (256 * 64) + (size_t)((r & 255) * 64 + (c & 63)); }
; __device__ __forceinline__ u32x4 pack8(const f32x4 a, const f32x4 b) { u32x4 w; w.x = cvt_pk_bf16(a[0], a[1]); w.y = cvt_pk_bf16(a[2], a[3]); w.z = cvt_pk_bf16(b[0], b[1]); w.w = cvt_pk_bf16(b[2], b[3]); return w; }
;     __device__ __forceinline__ void operator()(const f32x4 (&acc)[2][2][4][2], const pg8::Unit& u, int wr, int wc, int fr, int fq) const {
;     ...
;             for (int m = 0; m < 4; ++m) { const int row = row0 + ai * 128 + m * 16; const float mu = mu4[m], rs = rs4[m];
;                 f32x4 yv[2][2], gq[2][2], bq_[2][2];
; #pragma unroll
;                 for (int bj = 0; bj < 2; ++bj)
; #pragma unroll
;                     for (int n = 0; n < 2; ++n) { yv[bj][n] = *(const f32x4*)(Yin + (size_t)row * D_ + col0 + bj * 128 + 4 * n); gq[bj][n] = *(const f32x4*)(g + col0 + bj * 128 + 4 * n); bq_[bj][n] = *(const f32x4*)(b + col0 + bj * 128 + 4 * n); }
;                 asm volatile("" ::: "memory");
;                 float s1 = 0.f, s2 = 0.f;
; #pragma unroll
;                 for (int bj = 0; bj < 2; ++bj) { float* yp = Y + (size_t)row * D_ + col0 + bj * 128; f32x4 v[2];
; #pragma unroll
;                     for (int n = 0; n < 2; ++n) { v[n] = (((yv[bj][n] - mu) * rs) * gq[bj][n] + bq_[bj][n]) * ALPHA_ + acc[ai][bj][m][n] * sc;
;                         *(f32x4*)(yp + 4 * n) = v[n]; s1 += (v[n][0] + v[n][1]) + (v[n][2] + v[n][3]); s2 += (v[n][0] * v[n][0] + v[n][1] * v[n][1]) + (v[n][2] * v[n][2] + v[n][3] * v[n][3]); }
;                     *(u32x4*)(Yb + blk_off(row, col0 + bj * 128, D_)) = pack8(v[0], v[1]); }
;                 s1 = xsum32(xsum16(s1)); s2 = xsum32(xsum16(s2));
;                 if (fq == 0) *(f32x2*)(stn + (size_t)row * 32 + (u.pn * 4 + wc) * 2) = (f32x2){s1, s2}; asm volatile("" ::: "memory"); } }
	v_mov_b32_dpp v36, v53 row_ror:8 row_mask:0xf bank_mask:0x3
	v_mov_b32_dpp v37, v54 row_ror:8 row_mask:0xf bank_mask:0x3
	global_store_dwordx4 v[48:49], v[38:41], off offset:512 nt
	global_store_dwordx4 v[50:51], v[34:37], off offset:512 nt
	s_nop 1
	v_mov_b32_dpp v34, v38 row_ror:8 row_mask:0xf bank_mask:0x3
	v_mov_b32_dpp v35, v39 row_ror:8 row_mask:0xf bank_mask:0x3
	v_mov_b32_dpp v36, v40 row_ror:8 row_mask:0xf bank_mask:0x3
	v_mov_b32_dpp v37, v41 row_ror:8 row_mask:0xf bank_mask:0x3
	v_mov_b32_e32 v38, v45
	v_mov_b32_e32 v39, v52
	v_mov_b32_e32 v40, v53
	v_mov_b32_e32 v41, v54
	s_nop 1
	v_permlane32_swap_b32_e32 v38, v34
	v_permlane32_swap_b32_e32 v39, v35
	v_permlane32_swap_b32_e32 v40, v36
	v_permlane32_swap_b32_e32 v41, v37
	v_permlane16_swap_b32_e32 v38, v34
	v_permlane16_swap_b32_e32 v39, v35
	v_permlane16_swap_b32_e32 v40, v36
	v_permlane16_swap_b32_e32 v41, v37
	v_add_f32_e32 v43, v43, v44
	v_cvt_pk_bf16_f32 v38, v38, v39
	v_cvt_pk_bf16_f32 v39, v40, v41
	v_cvt_pk_bf16_f32 v40, v34, v35
	v_lshl_add_u64 v[34:35], v[74:75], 0, v[0:1]
	v_mov_b32_e32 v0, v42
	v_add_f32_e32 v43, v46, v43
	v_cvt_pk_bf16_f32 v41, v36, v37
	v_permlane16_swap_b32_e32 v42, v0
	global_store_dwordx4 v[34:35], v[38:41], off
	v_add_f32_e32 v34, v42, v0
	v_mov_b32_e32 v0, v43
	s_nop 1
	v_permlane16_swap_b32_e32 v43, v0
	v_add_f32_e32 v35, v43, v0
	v_mov_b32_e32 v36, v34
	v_mov_b32_e32 v37, v35
	s_nop 0
	v_permlane32_swap_b32_e32 v34, v36
	v_permlane32_swap_b32_e32 v35, v37
	s_and_saveexec_b64 s[24:25], s[44:45]
	s_cbranch_execz .LBB0_1547
	v_pk_add_f32 v[34:35], v[34:35], v[36:37]
	v_lshl_add_u64 v[36:37], s[6:7], 0, v[102:103]
	v_lshl_add_u64 v[36:37], s[52:53], 2, v[36:37]
	global_store_dwordx2 v[36:37], v[34:35], off
.LBB0_1547:
	s_or_b64 exec, exec, s[24:25]
	v_pk_add_f32 v[34:35], v[104:105], v[106:107]
	s_mov_b32 s2, 0x3a800000
	v_pk_mul_f32 v[58:59], v[34:35], s[2:3] op_sel_hi:[1,0]
	s_mov_b32 s1, 0x800000
	v_fma_f32 v0, -v59, v59, v58
	v_max_f32_e32 v0, 0, v0
	v_add_f32_e32 v0, 0x3727c5ac, v0
	v_cmp_gt_f32_e32 vcc, s1, v0
	v_mul_f32_e32 v34, 0x4b800000, v0
	s_load_dwordx16 s[64:79], s[34:35], 0x38
	v_cndmask_b32_e32 v0, v0, v34, vcc
	v_rsq_f32_e32 v0, v0
	s_mov_b32 s2, 0x3fd744fd
	s_movk_i32 s1, 0x3bc0
	v_mul_f32_e32 v34, 0x45800000, v0
	v_cndmask_b32_e32 v58, v0, v34, vcc
	v_lshlrev_b64 v[34:35], 12, v[96:97]
	s_waitcnt lgkmcnt(0)
	v_lshl_add_u64 v[34:35], s[78:79], 0, v[34:35]
	v_lshl_add_u64 v[60:61], v[152:153], 2, v[34:35]
	global_load_dwordx4 v[62:65], v[60:61], off offset:16
	global_load_dwordx4 v[66:69], v[60:61], off
	global_load_dwordx4 v[70:73], v[156:157], off offset:16
	global_load_dwordx4 v[78:81], v[156:157], off
	global_load_dwordx4 v[82:85], v[154:155], off offset:16
	global_load_dwordx4 v[86:89], v[154:155], off
	global_load_dwordx4 v[34:37], v[60:61], off offset:528
	global_load_dwordx4 v[54:57], v[60:61], off offset:512
	global_load_dwordx4 v[38:41], v[156:157], off offset:528
	global_load_dwordx4 v[46:49], v[156:157], off offset:512
	global_load_dwordx4 v[42:45], v[154:155], off offset:528
	global_load_dwordx4 v[50:53], v[154:155], off offset:512
	v_lshlrev_b32_e32 v0, 6, v96
	v_and_or_b32 v0, v0, s1, v196
	v_lshlrev_b32_e32 v0, 1, v0
	s_waitcnt vmcnt(10)
	v_sub_f32_e32 v67, v67, v59
	v_sub_f32_e32 v66, v66, v59
	v_sub_f32_e32 v69, v69, v59
	v_sub_f32_e32 v68, v68, v59
	v_pk_mul_f32 v[68:69], v[58:59], v[68:69] op_sel_hi:[0,1]
	v_pk_mul_f32 v[66:67], v[58:59], v[66:67] op_sel_hi:[0,1]
	s_waitcnt vmcnt(6)
	v_pk_fma_f32 v[66:67], v[78:79], v[66:67], v[86:87]
	v_pk_fma_f32 v[68:69], v[80:81], v[68:69], v[88:89]
	v_pk_fma_f32 v[66:67], v[66:67], s[2:3], v[30:31] op_sel_hi:[1,0,1]
	v_pk_fma_f32 v[68:69], v[68:69], s[2:3], v[32:33] op_sel_hi:[1,0,1]
	v_add_f32_e32 v30, v66, v67
	v_add_f32_e32 v31, v68, v69
	v_add_f32_e32 v30, v30, v31
	v_add_f32_e32 v78, 0, v30
	v_mul_f32_e32 v30, v67, v67
	v_mul_f32_e32 v31, v69, v69
	v_fmac_f32_e32 v30, v66, v66
	v_fmac_f32_e32 v31, v68, v68
	v_add_f32_e32 v79, v30, v31
	v_sub_f32_e32 v31, v63, v59
	v_sub_f32_e32 v30, v62, v59
	v_sub_f32_e32 v33, v65, v59
	v_sub_f32_e32 v32, v64, v59
	v_pk_mul_f32 v[32:33], v[58:59], v[32:33] op_sel_hi:[0,1]
	v_pk_mul_f32 v[30:31], v[58:59], v[30:31] op_sel_hi:[0,1]
	v_pk_fma_f32 v[30:31], v[70:71], v[30:31], v[82:83]
	v_pk_fma_f32 v[32:33], v[72:73], v[32:33], v[84:85]
	v_pk_fma_f32 v[62:63], v[30:31], s[2:3], v[26:27] op_sel_hi:[1,0,1]
	v_pk_fma_f32 v[64:65], v[32:33], s[2:3], v[28:29] op_sel_hi:[1,0,1]
	v_add_f32_e32 v26, v62, v63
	v_add_f32_e32 v27, v64, v65
	v_add_f32_e32 v26, v26, v27
	v_add_f32_e32 v31, v78, v26
	v_mul_f32_e32 v26, v63, v63
	v_mul_f32_e32 v27, v65, v65
	v_fmac_f32_e32 v26, v62, v62
	v_fmac_f32_e32 v27, v64, v64
	v_add_f32_e32 v26, v26, v27
	v_add_f32_e32 v30, v79, v26
	v_cvt_pk_bf16_f32 v26, v66, v67
	v_cvt_pk_bf16_f32 v27, v68, v69
	v_cvt_pk_bf16_f32 v28, v62, v63
	v_cvt_pk_bf16_f32 v29, v64, v65
	v_lshl_add_u64 v[32:33], v[76:77], 0, v[0:1]
	s_nop 0
	s_nop 1
	v_bfe_u32 v71, v227, 4, 2
	v_sub_u32_e32 v70, 0, v71
	v_lshlrev_b32_e32 v70, 4, v70
	v_ashrrev_i32_e32 v71, 31, v70
	v_lshl_add_u64 v[70:71], v[60:61], 0, v[70:71]
	v_permlane16_swap_b32_e32 v66, v62
	v_permlane16_swap_b32_e32 v67, v63
	v_permlane16_swap_b32_e32 v68, v64
	v_permlane16_swap_b32_e32 v69, v65
	v_permlane32_swap_b32_e32 v66, v62
	v_permlane32_swap_b32_e32 v67, v63
	v_permlane32_swap_b32_e32 v68, v64
	v_permlane32_swap_b32_e32 v69, v65
	v_mov_b32_e32 v78, v66
	v_mov_b32_e32 v79, v67
	v_mov_b32_e32 v80, v68
	v_mov_b32_e32 v81, v69
	v_bfe_u32 v72, v227, 3, 1
	v_mul_i32_i24_e32 v72, 0xffff8040, v72
	v_ashrrev_i32_e32 v73, 31, v72
	v_lshl_add_u64 v[70:71], v[70:71], 0, v[72:73]
	v_mov_b32_e32 v72, 0x8000
	v_mov_b32_e32 v73, 0
	v_lshl_add_u64 v[72:73], v[70:71], 0, v[72:73]
	v_mov_b32_dpp v66, v62 row_ror:8 row_mask:0xf bank_mask:0xc
	v_mov_b32_dpp v67, v63 row_ror:8 row_mask:0xf bank_mask:0xc
	v_mov_b32_dpp v68, v64 row_ror:8 row_mask:0xf bank_mask:0xc
	v_mov_b32_dpp v69, v65 row_ror:8 row_mask:0xf bank_mask:0xc
	v_mov_b32_dpp v62, v78 row_ror:8 row_mask:0xf bank_mask:0x3
	v_mov_b32_dpp v63, v79 row_ror:8 row_mask:0xf bank_mask:0x3
	v_mov_b32_dpp v64, v80 row_ror:8 row_mask:0xf bank_mask:0x3
	v_mov_b32_dpp v65, v81 row_ror:8 row_mask:0xf bank_mask:0x3
	global_store_dwordx4 v[70:71], v[66:69], off nt
	global_store_dwordx4 v[72:73], v[62:65], off nt
	s_nop 1
	global_store_dwordx4 v[32:33], v[26:29], off
	s_waitcnt vmcnt(7)
; __device__ __forceinline__ float xsum16(float v) { const auto r = __builtin_amdgcn_permlane16_swap(__float_as_uint(v), __float_as_uint(v), false, false); return __uint_as_float(r[0]) + __uint_as_float(r[1]); }
; __device__ __forceinline__ float xsum32(float v) { const auto r = __builtin_amdgcn_permlane32_swap(__float_as_uint(v), __float_as_uint(v), false, false); return __uint_as_float(r[0]) + __uint_as_float(r[1]); }
; __device__ __forceinline__ size_t blk_off(int r, int c, int K) { return (size_t)(r >> 8) * 256 * K + (size_t)(c >> 6) * (256 * 64) + (size_t)((r & 255) * 64 + (c & 63)); }
; __device__ __forceinline__ u32x4 pack8(const f32x4 a, const f32x4 b) { u32x4 w; w.x = cvt_pk_bf16(a[0], a[1]); w.y = cvt_pk_bf16(a[2], a[3]); w.z = cvt_pk_bf16(b[0], b[1]); w.w = cvt_pk_bf16(b[2], b[3]); return w; }
;     __device__ __forceinline__ void operator()(const f32x4 (&acc)[2][2][4][2], const pg8::Unit& u, int wr, int wc, int fr, int fq) const {
;     ...
;                 for (int bj = 0; bj < 2; ++bj) { float* yp = Y + (size_t)row * D_ + col0 + bj * 128; f32x4 v[2];
; #pragma unroll
;                     for (int n = 0; n < 2; ++n) { v[n] = (((yv[bj][n] - mu) * rs) * gq[bj][n] + bq_[bj][n]) * ALPHA_ + acc[ai][bj][m][n] * sc;
;                         *(f32x4*)(yp + 4 * n) = v[n]; s1 += (v[n][0] + v[n][1]) + (v[n][2] + v[n][3]); s2 += (v[n][0] * v[n][0] + v[n][1] * v[n][1]) + (v[n][2] * v[n][2] + v[n][3] * v[n][3]); }
;                     *(u32x4*)(Yb + blk_off(row, col0 + bj * 128, D_)) = pack8(v[0], v[1]); }
;                 s1 = xsum32(xsum16(s1)); s2 = xsum32(xsum16(s2));
;                 if (fq == 0) *(f32x2*)(stn + (size_t)row * 32 + (u.pn * 4 + wc) * 2) = (f32x2){s1, s2}; asm volatile("" ::: "memory"); } }
	s_nop 0
	v_sub_f32_e32 v27, v55, v59
	v_sub_f32_e32 v26, v54, v59
	v_sub_f32_e32 v29, v57, v59
	v_sub_f32_e32 v28, v56, v59
	v_pk_mul_f32 v[28:29], v[58:59], v[28:29] op_sel_hi:[0,1]
	v_pk_mul_f32 v[26:27], v[58:59], v[26:27] op_sel_hi:[0,1]
	s_waitcnt vmcnt(3)
	v_pk_fma_f32 v[26:27], v[46:47], v[26:27], v[50:51]
	v_pk_fma_f32 v[28:29], v[48:49], v[28:29], v[52:53]
	v_pk_fma_f32 v[22:23], v[26:27], s[2:3], v[22:23] op_sel_hi:[1,0,1]
	v_pk_fma_f32 v[24:25], v[28:29], s[2:3], v[24:25] op_sel_hi:[1,0,1]
	v_add_f32_e32 v26, v22, v23
	v_add_f32_e32 v27, v24, v25
	v_add_f32_e32 v26, v26, v27
	v_add_f32_e32 v31, v31, v26
	v_mul_f32_e32 v26, v23, v23
	v_mul_f32_e32 v27, v25, v25
	v_fmac_f32_e32 v26, v22, v22
	v_fmac_f32_e32 v27, v24, v24
	v_add_f32_e32 v26, v26, v27
	v_add_f32_e32 v30, v30, v26
	v_sub_f32_e32 v27, v35, v59
	v_sub_f32_e32 v26, v34, v59
	v_sub_f32_e32 v29, v37, v59
	v_sub_f32_e32 v28, v36, v59
	v_pk_mul_f32 v[28:29], v[58:59], v[28:29] op_sel_hi:[0,1]
	v_pk_mul_f32 v[26:27], v[58:59], v[26:27] op_sel_hi:[0,1]
	v_pk_fma_f32 v[26:27], v[38:39], v[26:27], v[42:43]
	v_pk_fma_f32 v[28:29], v[40:41], v[28:29], v[44:45]
	v_pk_fma_f32 v[18:19], v[26:27], s[2:3], v[18:19] op_sel_hi:[1,0,1]
	v_pk_fma_f32 v[20:21], v[28:29], s[2:3], v[20:21] op_sel_hi:[1,0,1]
	v_add_f32_e32 v26, v18, v19
	v_add_f32_e32 v27, v20, v21
	v_add_f32_e32 v26, v26, v27
	v_mul_f32_e32 v27, v19, v19
	v_mul_f32_e32 v28, v21, v21
	v_add_f32_e32 v26, v31, v26
	v_fmac_f32_e32 v27, v18, v18
	v_fmac_f32_e32 v28, v20, v20
	s_nop 0
	s_nop 1
	v_bfe_u32 v33, v227, 4, 2
	v_sub_u32_e32 v32, 0, v33
	v_lshlrev_b32_e32 v32, 4, v32
	v_ashrrev_i32_e32 v33, 31, v32
	v_lshl_add_u64 v[32:33], v[60:61], 0, v[32:33]
	v_permlane16_swap_b32_e32 v22, v18
	v_permlane16_swap_b32_e32 v23, v19
	v_permlane16_swap_b32_e32 v24, v20
	v_permlane16_swap_b32_e32 v25, v21
	v_permlane32_swap_b32_e32 v22, v18
	v_permlane32_swap_b32_e32 v23, v19
	v_permlane32_swap_b32_e32 v24, v20
	v_permlane32_swap_b32_e32 v25, v21
	v_mov_b32_e32 v29, v22
	v_mov_b32_e32 v36, v23
	v_mov_b32_e32 v37, v24
	v_mov_b32_e32 v38, v25
	v_bfe_u32 v34, v227, 3, 1
	v_mul_i32_i24_e32 v34, 0xffff8040, v34
	v_ashrrev_i32_e32 v35, 31, v34
	v_lshl_add_u64 v[32:33], v[32:33], 0, v[34:35]
	v_mov_b32_e32 v34, 0x8000
	v_mov_b32_e32 v35, 0
	v_lshl_add_u64 v[34:35], v[32:33], 0, v[34:35]
	v_mov_b32_dpp v22, v18 row_ror:8 row_mask:0xf bank_mask:0xc
	v_mov_b32_dpp v23, v19 row_ror:8 row_mask:0xf bank_mask:0xc
	v_mov_b32_dpp v24, v20 row_ror:8 row_mask:0xf bank_mask:0xc
	v_mov_b32_dpp v25, v21 row_ror:8 row_mask:0xf bank_mask:0xc
	v_mov_b32_dpp v18, v29 row_ror:8 row_mask:0xf bank_mask:0x3
	v_mov_b32_dpp v19, v36 row_ror:8 row_mask:0xf bank_mask:0x3
	v_mov_b32_dpp v20, v37 row_ror:8 row_mask:0xf bank_mask:0x3
	v_mov_b32_dpp v21, v38 row_ror:8 row_mask:0xf bank_mask:0x3
	global_store_dwordx4 v[32:33], v[22:25], off offset:512 nt
	global_store_dwordx4 v[34:35], v[18:21], off offset:512 nt
	s_nop 1
	v_mov_b32_dpp v18, v22 row_ror:8 row_mask:0xf bank_mask:0x3
	v_mov_b32_dpp v19, v23 row_ror:8 row_mask:0xf bank_mask:0x3
	v_mov_b32_dpp v20, v24 row_ror:8 row_mask:0xf bank_mask:0x3
	v_mov_b32_dpp v21, v25 row_ror:8 row_mask:0xf bank_mask:0x3
	v_mov_b32_e32 v22, v29
	v_mov_b32_e32 v23, v36
	v_mov_b32_e32 v24, v37
	v_mov_b32_e32 v25, v38
	s_nop 1
	v_permlane32_swap_b32_e32 v22, v18
	v_permlane32_swap_b32_e32 v23, v19
	v_permlane32_swap_b32_e32 v24, v20
	v_permlane32_swap_b32_e32 v25, v21
	v_permlane16_swap_b32_e32 v22, v18
	v_permlane16_swap_b32_e32 v23, v19
	v_permlane16_swap_b32_e32 v24, v20
	v_permlane16_swap_b32_e32 v25, v21
	v_add_f32_e32 v27, v27, v28
	v_cvt_pk_bf16_f32 v22, v22, v23
	v_cvt_pk_bf16_f32 v23, v24, v25
	v_cvt_pk_bf16_f32 v24, v18, v19
	v_lshl_add_u64 v[18:19], v[74:75], 0, v[0:1]
	v_mov_b32_e32 v0, v26
	v_add_f32_e32 v27, v30, v27
	v_cvt_pk_bf16_f32 v25, v20, v21
	v_permlane16_swap_b32_e32 v26, v0
	global_store_dwordx4 v[18:19], v[22:25], off
	v_add_f32_e32 v18, v26, v0
	v_mov_b32_e32 v0, v27
	s_nop 1
	v_permlane16_swap_b32_e32 v27, v0
	v_add_f32_e32 v19, v27, v0
	v_mov_b32_e32 v20, v18
	v_mov_b32_e32 v21, v19
	s_nop 0
	v_permlane32_swap_b32_e32 v18, v20
	v_permlane32_swap_b32_e32 v19, v21
	s_and_saveexec_b64 s[24:25], s[44:45]
	s_cbranch_execz .LBB0_1549
	v_pk_add_f32 v[18:19], v[18:19], v[20:21]
	v_lshlrev_b64 v[20:21], 7, v[96:97]
	v_lshl_add_u64 v[20:21], s[6:7], 0, v[20:21]
	v_lshl_add_u64 v[20:21], s[52:53], 2, v[20:21]
	global_store_dwordx2 v[20:21], v[18:19], off
; __device__ __forceinline__ size_t blk_off(int r, int c, int K) { return (size_t)(r >> 8) * 256 * K + (size_t)(c >> 6) * (256 * 64) + (size_t)((r & 255) * 64 + (c & 63)); }
; __device__ __forceinline__ u32x4 pack8(const f32x4 a, const f32x4 b) { u32x4 w; w.x = cvt_pk_bf16(a[0], a[1]); w.y = cvt_pk_bf16(a[2], a[3]); w.z = cvt_pk_bf16(b[0], b[1]); w.w = cvt_pk_bf16(b[2], b[3]); return w; }
;     __device__ __forceinline__ void operator()(const f32x4 (&acc)[2][2][4][2], const pg8::Unit& u, int wr, int wc, int fr, int fq) const {
;     ...
;             for (int m = 0; m < 4; ++m) { const int row = row0 + ai * 128 + m * 16; const float mu = mu4[m], rs = rs4[m];
;                 f32x4 yv[2][2], gq[2][2], bq_[2][2];
; #pragma unroll
;                 for (int bj = 0; bj < 2; ++bj)
; #pragma unroll
;                     for (int n = 0; n < 2; ++n) { yv[bj][n] = *(const f32x4*)(Yin + (size_t)row * D_ + col0 + bj * 128 + 4 * n); gq[bj][n] = *(const f32x4*)(g + col0 + bj * 128 + 4 * n); bq_[bj][n] = *(const f32x4*)(b + col0 + bj * 128 + 4 * n); }
;                 asm volatile("" ::: "memory");
;                 float s1 = 0.f, s2 = 0.f;
; #pragma unroll
;                 for (int bj = 0; bj < 2; ++bj) { float* yp = Y + (size_t)row * D_ + col0 + bj * 128; f32x4 v[2];
; #pragma unroll
;                     for (int n = 0; n < 2; ++n) { v[n] = (((yv[bj][n] - mu) * rs) * gq[bj][n] + bq_[bj][n]) * ALPHA_ + acc[ai][bj][m][n] * sc;
;                         *(f32x4*)(yp + 4 * n) = v[n]; s1 += (v[n][0] + v[n][1]) + (v[n][2] + v[n][3]); s2 += (v[n][0] * v[n][0] + v[n][1] * v[n][1]) + (v[n][2] * v[n][2] + v[n][3] * v[n][3]); }
;                     *(u32x4*)(Yb + blk_off(row, col0 + bj * 128, D_)) = pack8(v[0], v[1]); }
.LBB0_1549:
	s_or_b64 exec, exec, s[24:25]
	v_pk_add_f32 v[18:19], v[98:99], v[100:101]
	s_mov_b32 s2, 0x3a800000
	v_pk_mul_f32 v[42:43], v[18:19], s[2:3] op_sel_hi:[1,0]
	s_mov_b32 s1, 0x800000
	v_fma_f32 v0, -v43, v43, v42
	v_max_f32_e32 v0, 0, v0
	v_add_f32_e32 v0, 0x3727c5ac, v0
	v_cmp_gt_f32_e32 vcc, s1, v0
	v_mul_f32_e32 v18, 0x4b800000, v0
	s_load_dwordx16 s[64:79], s[34:35], 0x38
	v_cndmask_b32_e32 v0, v0, v18, vcc
	v_rsq_f32_e32 v0, v0
	s_mov_b32 s2, 0x3fd744fd
	s_movk_i32 s1, 0x3fc0
	v_mul_f32_e32 v18, 0x45800000, v0
	v_cndmask_b32_e32 v42, v0, v18, vcc
	v_lshlrev_b64 v[18:19], 12, v[94:95]
	s_waitcnt lgkmcnt(0)
	v_lshl_add_u64 v[18:19], s[78:79], 0, v[18:19]
	v_lshl_add_u64 v[44:45], v[152:153], 2, v[18:19]
	global_load_dwordx4 v[46:49], v[44:45], off offset:16
	global_load_dwordx4 v[50:53], v[44:45], off
	global_load_dwordx4 v[54:57], v[156:157], off offset:16
	global_load_dwordx4 v[58:61], v[156:157], off
	global_load_dwordx4 v[62:65], v[154:155], off offset:16
	global_load_dwordx4 v[66:69], v[154:155], off
	global_load_dwordx4 v[18:21], v[44:45], off offset:528
	global_load_dwordx4 v[38:41], v[44:45], off offset:512
	global_load_dwordx4 v[22:25], v[156:157], off offset:528
	global_load_dwordx4 v[30:33], v[156:157], off offset:512
	global_load_dwordx4 v[26:29], v[154:155], off offset:528
	global_load_dwordx4 v[34:37], v[154:155], off offset:512
	v_lshlrev_b32_e32 v0, 6, v94
	v_and_or_b32 v0, v0, s1, v196
	v_lshlrev_b32_e32 v0, 1, v0
	s_waitcnt vmcnt(10)
	v_sub_f32_e32 v51, v51, v43
	v_sub_f32_e32 v50, v50, v43
	v_sub_f32_e32 v53, v53, v43
	v_sub_f32_e32 v52, v52, v43
	v_pk_mul_f32 v[52:53], v[42:43], v[52:53] op_sel_hi:[0,1]
	v_pk_mul_f32 v[50:51], v[42:43], v[50:51] op_sel_hi:[0,1]
	s_waitcnt vmcnt(6)
	v_pk_fma_f32 v[50:51], v[58:59], v[50:51], v[66:67]
	v_pk_fma_f32 v[52:53], v[60:61], v[52:53], v[68:69]
	v_pk_fma_f32 v[50:51], v[50:51], s[2:3], v[14:15] op_sel_hi:[1,0,1]
	v_pk_fma_f32 v[52:53], v[52:53], s[2:3], v[16:17] op_sel_hi:[1,0,1]
	v_add_f32_e32 v14, v50, v51
	v_add_f32_e32 v15, v52, v53
	v_add_f32_e32 v14, v14, v15
	v_add_f32_e32 v58, 0, v14
	v_mul_f32_e32 v14, v51, v51
	v_mul_f32_e32 v15, v53, v53
	v_fmac_f32_e32 v14, v50, v50
	v_fmac_f32_e32 v15, v52, v52
	v_add_f32_e32 v59, v14, v15
	v_sub_f32_e32 v15, v47, v43
	v_sub_f32_e32 v14, v46, v43
	v_sub_f32_e32 v17, v49, v43
	v_sub_f32_e32 v16, v48, v43
	v_pk_mul_f32 v[16:17], v[42:43], v[16:17] op_sel_hi:[0,1]
	v_pk_mul_f32 v[14:15], v[42:43], v[14:15] op_sel_hi:[0,1]
	v_pk_fma_f32 v[14:15], v[54:55], v[14:15], v[62:63]
	v_pk_fma_f32 v[16:17], v[56:57], v[16:17], v[64:65]
	v_pk_fma_f32 v[46:47], v[14:15], s[2:3], v[10:11] op_sel_hi:[1,0,1]
	v_pk_fma_f32 v[48:49], v[16:17], s[2:3], v[12:13] op_sel_hi:[1,0,1]
	v_add_f32_e32 v10, v46, v47
	v_add_f32_e32 v11, v48, v49
	v_add_f32_e32 v10, v10, v11
	v_add_f32_e32 v15, v58, v10
	v_mul_f32_e32 v10, v47, v47
	v_mul_f32_e32 v11, v49, v49
	v_fmac_f32_e32 v10, v46, v46
	v_fmac_f32_e32 v11, v48, v48
	v_add_f32_e32 v10, v10, v11
	v_add_f32_e32 v14, v59, v10
	v_cvt_pk_bf16_f32 v10, v50, v51
	v_cvt_pk_bf16_f32 v11, v52, v53
	v_cvt_pk_bf16_f32 v12, v46, v47
	v_cvt_pk_bf16_f32 v13, v48, v49
	v_lshl_add_u64 v[16:17], v[76:77], 0, v[0:1]
	s_nop 0
	s_nop 1
	v_bfe_u32 v55, v227, 4, 2
	v_sub_u32_e32 v54, 0, v55
	v_lshlrev_b32_e32 v54, 4, v54
	v_ashrrev_i32_e32 v55, 31, v54
	v_lshl_add_u64 v[54:55], v[44:45], 0, v[54:55]
	v_permlane16_swap_b32_e32 v50, v46
	v_permlane16_swap_b32_e32 v51, v47
	v_permlane16_swap_b32_e32 v52, v48
	v_permlane16_swap_b32_e32 v53, v49
	v_permlane32_swap_b32_e32 v50, v46
	v_permlane32_swap_b32_e32 v51, v47
	v_permlane32_swap_b32_e32 v52, v48
	v_permlane32_swap_b32_e32 v53, v49
	v_mov_b32_e32 v58, v50
	v_mov_b32_e32 v59, v51
	v_mov_b32_e32 v60, v52
	v_mov_b32_e32 v61, v53
	v_bfe_u32 v56, v227, 3, 1
	v_mul_i32_i24_e32 v56, 0xffff8040, v56
	v_ashrrev_i32_e32 v57, 31, v56
	v_lshl_add_u64 v[54:55], v[54:55], 0, v[56:57]
	v_mov_b32_e32 v56, 0x8000
	v_mov_b32_e32 v57, 0
	v_lshl_add_u64 v[56:57], v[54:55], 0, v[56:57]
	v_mov_b32_dpp v50, v46 row_ror:8 row_mask:0xf bank_mask:0xc
	v_mov_b32_dpp v51, v47 row_ror:8 row_mask:0xf bank_mask:0xc
	v_mov_b32_dpp v52, v48 row_ror:8 row_mask:0xf bank_mask:0xc
	v_mov_b32_dpp v53, v49 row_ror:8 row_mask:0xf bank_mask:0xc
	v_mov_b32_dpp v46, v58 row_ror:8 row_mask:0xf bank_mask:0x3
	v_mov_b32_dpp v47, v59 row_ror:8 row_mask:0xf bank_mask:0x3
	v_mov_b32_dpp v48, v60 row_ror:8 row_mask:0xf bank_mask:0x3
	v_mov_b32_dpp v49, v61 row_ror:8 row_mask:0xf bank_mask:0x3
	global_store_dwordx4 v[54:55], v[50:53], off nt
	global_store_dwordx4 v[56:57], v[46:49], off nt
	s_nop 1
	global_store_dwordx4 v[16:17], v[10:13], off
	s_waitcnt vmcnt(7)
; __device__ __forceinline__ float xsum16(float v) { const auto r = __builtin_amdgcn_permlane16_swap(__float_as_uint(v), __float_as_uint(v), false, false); return __uint_as_float(r[0]) + __uint_as_float(r[1]); }
; __device__ __forceinline__ float xsum32(float v) { const auto r = __builtin_amdgcn_permlane32_swap(__float_as_uint(v), __float_as_uint(v), false, false); return __uint_as_float(r[0]) + __uint_as_float(r[1]); }
; __device__ __forceinline__ size_t blk_off(int r, int c, int K) { return (size_t)(r >> 8) * 256 * K + (size_t)(c >> 6) * (256 * 64) + (size_t)((r & 255) * 64 + (c & 63)); }
; __device__ __forceinline__ u32x4 pack8(const f32x4 a, const f32x4 b) { u32x4 w; w.x = cvt_pk_bf16(a[0], a[1]); w.y = cvt_pk_bf16(a[2], a[3]); w.z = cvt_pk_bf16(b[0], b[1]); w.w = cvt_pk_bf16(b[2], b[3]); return w; }
;     __device__ __forceinline__ void operator()(const f32x4 (&acc)[2][2][4][2], const pg8::Unit& u, int wr, int wc, int fr, int fq) const {
;     ...
;                 for (int bj = 0; bj < 2; ++bj) { float* yp = Y + (size_t)row * D_ + col0 + bj * 128; f32x4 v[2];
; #pragma unroll
;                     for (int n = 0; n < 2; ++n) { v[n] = (((yv[bj][n] - mu) * rs) * gq[bj][n] + bq_[bj][n]) * ALPHA_ + acc[ai][bj][m][n] * sc;
;                         *(f32x4*)(yp + 4 * n) = v[n]; s1 += (v[n][0] + v[n][1]) + (v[n][2] + v[n][3]); s2 += (v[n][0] * v[n][0] + v[n][1] * v[n][1]) + (v[n][2] * v[n][2] + v[n][3] * v[n][3]); }
;                     *(u32x4*)(Yb + blk_off(row, col0 + bj * 128, D_)) = pack8(v[0], v[1]); }
;                 s1 = xsum32(xsum16(s1)); s2 = xsum32(xsum16(s2));
;                 if (fq == 0) *(f32x2*)(stn + (size_t)row * 32 + (u.pn * 4 + wc) * 2) = (f32x2){s1, s2}; asm volatile("" ::: "memory"); } }
	s_nop 0
	v_sub_f32_e32 v11, v39, v43
	v_sub_f32_e32 v10, v38, v43
	v_sub_f32_e32 v13, v41, v43
	v_sub_f32_e32 v12, v40, v43
	v_pk_mul_f32 v[12:13], v[42:43], v[12:13] op_sel_hi:[0,1]
	v_pk_mul_f32 v[10:11], v[42:43], v[10:11] op_sel_hi:[0,1]
	s_waitcnt vmcnt(3)
	v_pk_fma_f32 v[10:11], v[30:31], v[10:11], v[34:35]
	v_pk_fma_f32 v[12:13], v[32:33], v[12:13], v[36:37]
	v_pk_fma_f32 v[6:7], v[10:11], s[2:3], v[6:7] op_sel_hi:[1,0,1]
	v_pk_fma_f32 v[8:9], v[12:13], s[2:3], v[8:9] op_sel_hi:[1,0,1]
	v_add_f32_e32 v10, v6, v7
	v_add_f32_e32 v11, v8, v9
	v_add_f32_e32 v10, v10, v11
	v_add_f32_e32 v15, v15, v10
	v_mul_f32_e32 v10, v7, v7
	v_mul_f32_e32 v11, v9, v9
	v_fmac_f32_e32 v10, v6, v6
	v_fmac_f32_e32 v11, v8, v8
	v_add_f32_e32 v10, v10, v11
	v_add_f32_e32 v14, v14, v10
	v_sub_f32_e32 v11, v19, v43
	v_sub_f32_e32 v10, v18, v43
	v_sub_f32_e32 v13, v21, v43
	v_sub_f32_e32 v12, v20, v43
	v_pk_mul_f32 v[12:13], v[42:43], v[12:13] op_sel_hi:[0,1]
	v_pk_mul_f32 v[10:11], v[42:43], v[10:11] op_sel_hi:[0,1]
	v_pk_fma_f32 v[10:11], v[22:23], v[10:11], v[26:27]
	v_pk_fma_f32 v[12:13], v[24:25], v[12:13], v[28:29]
	v_pk_fma_f32 v[2:3], v[10:11], s[2:3], v[2:3] op_sel_hi:[1,0,1]
	v_pk_fma_f32 v[4:5], v[12:13], s[2:3], v[4:5] op_sel_hi:[1,0,1]
	v_add_f32_e32 v10, v2, v3
	v_add_f32_e32 v11, v4, v5
	v_add_f32_e32 v10, v10, v11
	v_mul_f32_e32 v11, v3, v3
	v_mul_f32_e32 v12, v5, v5
	v_add_f32_e32 v10, v15, v10
	v_fmac_f32_e32 v11, v2, v2
	v_fmac_f32_e32 v12, v4, v4
	s_nop 0
	s_nop 1
	v_bfe_u32 v17, v227, 4, 2
	v_sub_u32_e32 v16, 0, v17
	v_lshlrev_b32_e32 v16, 4, v16
	v_ashrrev_i32_e32 v17, 31, v16
	v_lshl_add_u64 v[16:17], v[44:45], 0, v[16:17]
	v_permlane16_swap_b32_e32 v6, v2
	v_permlane16_swap_b32_e32 v7, v3
	v_permlane16_swap_b32_e32 v8, v4
	v_permlane16_swap_b32_e32 v9, v5
	v_permlane32_swap_b32_e32 v6, v2
	v_permlane32_swap_b32_e32 v7, v3
	v_permlane32_swap_b32_e32 v8, v4
	v_permlane32_swap_b32_e32 v9, v5
	v_mov_b32_e32 v13, v6
	v_mov_b32_e32 v20, v7
	v_mov_b32_e32 v21, v8
	v_mov_b32_e32 v22, v9
	v_bfe_u32 v18, v227, 3, 1
	v_mul_i32_i24_e32 v18, 0xffff8040, v18
	v_ashrrev_i32_e32 v19, 31, v18
	v_lshl_add_u64 v[16:17], v[16:17], 0, v[18:19]
	v_mov_b32_e32 v18, 0x8000
	v_mov_b32_e32 v19, 0
	v_lshl_add_u64 v[18:19], v[16:17], 0, v[18:19]
	v_mov_b32_dpp v6, v2 row_ror:8 row_mask:0xf bank_mask:0xc
	v_mov_b32_dpp v7, v3 row_ror:8 row_mask:0xf bank_mask:0xc
	v_mov_b32_dpp v8, v4 row_ror:8 row_mask:0xf bank_mask:0xc
	v_mov_b32_dpp v9, v5 row_ror:8 row_mask:0xf bank_mask:0xc
	v_mov_b32_dpp v2, v13 row_ror:8 row_mask:0xf bank_mask:0x3
	v_mov_b32_dpp v3, v20 row_ror:8 row_mask:0xf bank_mask:0x3
	v_mov_b32_dpp v4, v21 row_ror:8 row_mask:0xf bank_mask:0x3
	v_mov_b32_dpp v5, v22 row_ror:8 row_mask:0xf bank_mask:0x3
	global_store_dwordx4 v[16:17], v[6:9], off offset:512 nt
	global_store_dwordx4 v[18:19], v[2:5], off offset:512 nt
	s_nop 1
	v_mov_b32_dpp v2, v6 row_ror:8 row_mask:0xf bank_mask:0x3
	v_mov_b32_dpp v3, v7 row_ror:8 row_mask:0xf bank_mask:0x3
	v_mov_b32_dpp v4, v8 row_ror:8 row_mask:0xf bank_mask:0x3
	v_mov_b32_dpp v5, v9 row_ror:8 row_mask:0xf bank_mask:0x3
	v_mov_b32_e32 v6, v13
	v_mov_b32_e32 v7, v20
	v_mov_b32_e32 v8, v21
	v_mov_b32_e32 v9, v22
	s_nop 1
	v_permlane32_swap_b32_e32 v6, v2
	v_permlane32_swap_b32_e32 v7, v3
	v_permlane32_swap_b32_e32 v8, v4
	v_permlane32_swap_b32_e32 v9, v5
	v_permlane16_swap_b32_e32 v6, v2
	v_permlane16_swap_b32_e32 v7, v3
	v_permlane16_swap_b32_e32 v8, v4
	v_permlane16_swap_b32_e32 v9, v5
	v_add_f32_e32 v11, v11, v12
	v_cvt_pk_bf16_f32 v6, v6, v7
	v_cvt_pk_bf16_f32 v7, v8, v9
	v_cvt_pk_bf16_f32 v8, v2, v3
	v_lshl_add_u64 v[2:3], v[74:75], 0, v[0:1]
	v_mov_b32_e32 v0, v10
	v_add_f32_e32 v11, v14, v11
	v_cvt_pk_bf16_f32 v9, v4, v5
	v_permlane16_swap_b32_e32 v10, v0
	global_store_dwordx4 v[2:3], v[6:9], off
	v_add_f32_e32 v2, v10, v0
	v_mov_b32_e32 v0, v11
	s_nop 1
	v_permlane16_swap_b32_e32 v11, v0
	v_add_f32_e32 v3, v11, v0
	v_mov_b32_e32 v4, v2
	v_mov_b32_e32 v5, v3
	s_nop 0
	v_permlane32_swap_b32_e32 v2, v4
	v_permlane32_swap_b32_e32 v3, v5
	s_and_saveexec_b64 s[24:25], s[44:45]
	s_cbranch_execz .LBB0_1551
	v_pk_add_f32 v[2:3], v[2:3], v[4:5]
	v_lshlrev_b64 v[4:5], 7, v[94:95]
	v_lshl_add_u64 v[4:5], s[6:7], 0, v[4:5]
	v_lshl_add_u64 v[4:5], s[52:53], 2, v[4:5]
	global_store_dwordx2 v[4:5], v[2:3], off

; __device__ __forceinline__ float xsum16(float v) { const auto r = __builtin_amdgcn_permlane16_swap(__float_as_uint(v), __float_as_uint(v), false, false); return __uint_as_float(r[0]) + __uint_as_float(r[1]); }
; __device__ __forceinline__ float xsum32(float v) { const auto r = __builtin_amdgcn_permlane32_swap(__float_as_uint(v), __float_as_uint(v), false, false); return __uint_as_float(r[0]) + __uint_as_float(r[1]); }
; __device__ __forceinline__ void row_stats4(const float* st, int rowb, int fq, float (&mu)[4], float (&rs)[4]) {
;     ...
;     for (int m = 0; m < 4; ++m) { const f32x4* p = (const f32x4*)(st + (size_t)(rowb + m * 16) * 32 + fq * 8); a[m] = p[0]; b[m] = p[1]; }
; #pragma unroll
;     for (int m = 0; m < 4; ++m) { float s1 = (a[m][0] + a[m][2]) + (b[m][0] + b[m][2]), s2 = (a[m][1] + a[m][3]) + (b[m][1] + b[m][3]);
;         s1 = xsum32(xsum16(s1)); s2 = xsum32(xsum16(s2));
;         const float mm = s1 * (1.0f / 1024.0f); mu[m] = mm; rs[m] = rsqrtf(fmaxf(s2 * (1.0f / 1024.0f) - mm * mm, 0.f) + LN_EPS_); }
;     __device__ __forceinline__ void operator()(const f32x4 (&acc)[2][2][4][2], const pg8::Unit& u, int wr, int wc, int fr, int fq) const {
;     ...
;         for (int ai = 0; ai < 2; ++ai) { float mu4[4], rs4[4]; row_stats4(stp, row0 + ai * 128, fq, mu4, rs4);
; #pragma unroll
;             for (int m = 0; m < 4; ++m) { const int row = row0 + ai * 128 + m * 16; const float mu = mu4[m], rs = rs4[m];
;                 f32x4 yv[2][2], gq[2][2], bq_[2][2];
; #pragma unroll
;                 for (int bj = 0; bj < 2; ++bj)
; #pragma unroll
;                     for (int n = 0; n < 2; ++n) { yv[bj][n] = *(const f32x4*)(Yin + (size_t)row * D_ + col0 + bj * 128 + 4 * n); gq[bj][n] = *(const f32x4*)(g + col0 + bj * 128 + 4 * n); bq_[bj][n] = *(const f32x4*)(b + col0 + bj * 128 + 4 * n); }
.LBB0_1703:
	s_lshl_b32 s3, s3, 8
	s_add_i32 s3, s3, s0
	v_or_b32_e32 v158, s3, v184
	v_ashrrev_i32_e32 v159, 31, v158
	v_lshlrev_b64 v[130:131], 7, v[158:159]
	v_lshl_add_u64 v[136:137], v[146:147], 0, v[130:131]
	v_or_b32_e32 v182, 16, v158
	global_load_dwordx4 v[132:135], v[136:137], off
	global_load_dwordx4 v[166:169], v[136:137], off offset:16
	v_ashrrev_i32_e32 v183, 31, v182
	v_lshlrev_b64 v[172:173], 7, v[182:183]
	v_lshl_add_u64 v[136:137], v[146:147], 0, v[172:173]
	global_load_dwordx4 v[174:177], v[136:137], off
	global_load_dwordx4 v[178:181], v[136:137], off offset:16
	v_or_b32_e32 v170, 32, v158
	v_ashrrev_i32_e32 v171, 31, v170
	v_lshlrev_b64 v[164:165], 7, v[170:171]
	v_lshl_add_u64 v[136:137], v[146:147], 0, v[164:165]
	global_load_dwordx4 v[186:189], v[136:137], off
	global_load_dwordx4 v[190:193], v[136:137], off offset:16
	s_load_dwordx16 s[60:75], s[34:35], 0x38
	s_lshl_b32 s1, s2, 8
	s_lshl_b32 s16, s2, 3
	s_or_b32 s2, s1, s53
	v_or_b32_e32 v162, 48, v158
	v_or_b32_e32 v152, s2, v185
	v_ashrrev_i32_e32 v163, 31, v162
	v_ashrrev_i32_e32 v153, 31, v152
	v_lshlrev_b64 v[136:137], 12, v[158:159]
	v_lshlrev_b64 v[160:161], 7, v[162:163]
	v_lshlrev_b64 v[198:199], 2, v[152:153]
	s_waitcnt lgkmcnt(0)
	v_lshl_add_u64 v[136:137], s[74:75], 0, v[136:137]
	v_lshl_add_u64 v[202:203], v[146:147], 0, v[160:161]
	v_lshl_add_u64 v[156:157], s[10:11], 0, v[198:199]
	v_lshl_add_u64 v[154:155], s[12:13], 0, v[198:199]
	v_lshl_add_u64 v[136:137], v[136:137], 0, v[198:199]
	global_load_dwordx4 v[198:201], v[202:203], off
	s_nop 0
	global_load_dwordx4 v[202:205], v[202:203], off offset:16
	s_or_b32 s38, s16, s15
	s_mov_b32 s16, 0x3a800000
	s_mov_b32 s1, 0x800000
	global_load_dwordx4 v[206:209], v[136:137], off offset:16
	global_load_dwordx4 v[210:213], v[136:137], off
	global_load_dwordx4 v[214:217], v[156:157], off offset:16
	global_load_dwordx4 v[218:221], v[156:157], off
	global_load_dwordx4 v[222:225], v[154:155], off offset:16
	global_load_dwordx4 v[234:237], v[154:155], off
	s_mov_b32 s18, 0x3fd744fd
	s_ashr_i32 s44, s2, 6
	v_bitop3_b32 v196, s2, 56, v185 bitop3:0xc8
	s_ashr_i32 s39, s38, 31
	s_ashr_i32 s45, s44, 31
	s_waitcnt vmcnt(0)
	v_mov_b32_e32 v228, v132
	v_mov_b32_e32 v229, v166
	v_mov_b32_e32 v238, v134
	v_mov_b32_e32 v239, v168
	v_mov_b32_e32 v166, v133
	v_mov_b32_e32 v168, v135
	v_pk_add_f32 v[132:133], v[228:229], v[238:239]
	v_pk_add_f32 v[134:135], v[166:167], v[168:169]
	v_pk_add_f32 v[132:133], v[132:133], v[132:133] op_sel:[0,1] op_sel_hi:[1,0]
	v_pk_add_f32 v[134:135], v[134:135], v[134:135] op_sel:[0,1] op_sel_hi:[1,0]
	v_mov_b32_e32 v166, v174
	v_mov_b32_e32 v167, v178
	v_mov_b32_e32 v168, v176
	v_mov_b32_e32 v169, v180
	v_mov_b32_e32 v0, v132
	v_mov_b32_e32 v133, v134
	v_pk_add_f32 v[166:167], v[166:167], v[168:169]
	v_permlane16_swap_b32_e32 v132, v0
	v_permlane16_swap_b32_e32 v134, v133
	v_mov_b32_e32 v178, v175
	v_mov_b32_e32 v180, v177
	v_pk_add_f32 v[166:167], v[166:167], v[166:167] op_sel:[0,1] op_sel_hi:[1,0]
	v_add_f32_e32 v177, v132, v0
	v_add_f32_e32 v176, v134, v133
	v_pk_add_f32 v[168:169], v[178:179], v[180:181]
	v_mov_b32_e32 v135, v166
	v_mov_b32_e32 v179, v177
	v_mov_b32_e32 v178, v176
	v_permlane16_swap_b32_e32 v166, v135
	v_permlane32_swap_b32_e32 v177, v179
	v_permlane32_swap_b32_e32 v176, v178
	v_add_f32_e32 v133, v166, v135
	v_pk_add_f32 v[166:167], v[176:177], v[178:179]
	v_pk_add_f32 v[168:169], v[168:169], v[168:169] op_sel:[0,1] op_sel_hi:[1,0]
	v_pk_mul_f32 v[228:229], v[166:167], s[16:17] op_sel_hi:[1,0]
	v_mov_b32_e32 v159, v168
	v_fma_f32 v0, -v229, v229, v228
	v_max_f32_e32 v0, 0, v0
	v_permlane16_swap_b32_e32 v168, v159
	v_add_f32_e32 v0, 0x3727c5ac, v0
	v_add_f32_e32 v132, v168, v159
	v_mul_f32_e32 v159, 0x4b800000, v0
	v_cmp_gt_f32_e32 vcc, s1, v0
	v_mov_b32_e32 v174, v186
	v_mov_b32_e32 v175, v190
	v_cndmask_b32_e32 v0, v0, v159, vcc
	v_rsq_f32_e32 v0, v0
	v_mov_b32_e32 v166, v188
	v_mov_b32_e32 v167, v192
	v_pk_add_f32 v[166:167], v[174:175], v[166:167]
	v_mul_f32_e32 v159, 0x45800000, v0
	v_pk_add_f32 v[166:167], v[166:167], v[166:167] op_sel:[0,1] op_sel_hi:[1,0]
	v_mov_b32_e32 v190, v187
	v_mov_b32_e32 v192, v189
	v_cndmask_b32_e32 v0, v0, v159, vcc
	v_pk_add_f32 v[168:169], v[190:191], v[192:193]
	v_mov_b32_e32 v159, v166
	v_pk_add_f32 v[168:169], v[168:169], v[168:169] op_sel:[0,1] op_sel_hi:[1,0]
	s_nop 0
	v_permlane16_swap_b32_e32 v166, v159
	v_add_f32_e32 v175, v166, v159
	v_mov_b32_e32 v159, v168
	s_nop 1
	v_permlane16_swap_b32_e32 v168, v159
	global_load_dwordx4 v[178:181], v[136:137], off offset:528
	global_load_dwordx4 v[186:189], v[136:137], off offset:512
	v_add_f32_e32 v174, v168, v159
	v_mov_b32_e32 v166, v198
	v_mov_b32_e32 v167, v202
	v_mov_b32_e32 v168, v200
	v_mov_b32_e32 v169, v204
	v_mov_b32_e32 v202, v199
	v_mov_b32_e32 v204, v201
	v_pk_add_f32 v[166:167], v[166:167], v[168:169]
	v_pk_add_f32 v[168:169], v[202:203], v[204:205]
	global_load_dwordx4 v[190:193], v[156:157], off offset:528
	global_load_dwordx4 v[198:201], v[156:157], off offset:512
	global_load_dwordx4 v[202:205], v[154:155], off offset:528
	global_load_dwordx4 v[238:241], v[154:155], off offset:512
	v_sub_f32_e32 v213, v213, v229
	v_sub_f32_e32 v212, v212, v229
	v_sub_f32_e32 v211, v211, v229
	v_sub_f32_e32 v210, v210, v229
	v_pk_mul_f32 v[210:211], v[0:1], v[210:211] op_sel_hi:[0,1]
	v_pk_mul_f32 v[212:213], v[0:1], v[212:213] op_sel_hi:[0,1]
	v_sub_f32_e32 v209, v209, v229
	v_sub_f32_e32 v208, v208, v229
	v_sub_f32_e32 v207, v207, v229
	v_sub_f32_e32 v206, v206, v229
	v_pk_fma_f32 v[212:213], v[220:221], v[212:213], v[236:237]
	v_pk_fma_f32 v[210:211], v[218:219], v[210:211], v[234:235]
; __device__ __forceinline__ size_t blk_off(int r, int c, int K) { return (size_t)(r >> 8) * 256 * K + (size_t)(c >> 6) * (256 * 64) + (size_t)((r & 255) * 64 + (c & 63)); }
; __device__ __forceinline__ u32x4 pack8(const f32x4 a, const f32x4 b) { u32x4 w; w.x = cvt_pk_bf16(a[0], a[1]); w.y = cvt_pk_bf16(a[2], a[3]); w.z = cvt_pk_bf16(b[0], b[1]); w.w = cvt_pk_bf16(b[2], b[3]); return w; }
;     __device__ __forceinline__ void operator()(const f32x4 (&acc)[2][2][4][2], const pg8::Unit& u, int wr, int wc, int fr, int fq) const {
;     ...
;                     for (int n = 0; n < 2; ++n) { yv[bj][n] = *(const f32x4*)(Yin + (size_t)row * D_ + col0 + bj * 128 + 4 * n); gq[bj][n] = *(const f32x4*)(g + col0 + bj * 128 + 4 * n); bq_[bj][n] = *(const f32x4*)(b + col0 + bj * 128 + 4 * n); }
;                 asm volatile("" ::: "memory");
;                 float s1 = 0.f, s2 = 0.f;
; #pragma unroll
;                 for (int bj = 0; bj < 2; ++bj) { float* yp = Y + (size_t)row * D_ + col0 + bj * 128; f32x4 v[2];
; #pragma unroll
;                     for (int n = 0; n < 2; ++n) { v[n] = (((yv[bj][n] - mu) * rs) * gq[bj][n] + bq_[bj][n]) * ALPHA_ + acc[ai][bj][m][n] * sc;
;                         *(f32x4*)(yp + 4 * n) = v[n]; s1 += (v[n][0] + v[n][1]) + (v[n][2] + v[n][3]); s2 += (v[n][0] * v[n][0] + v[n][1] * v[n][1]) + (v[n][2] * v[n][2] + v[n][3] * v[n][3]); }
;                     *(u32x4*)(Yb + blk_off(row, col0 + bj * 128, D_)) = pack8(v[0], v[1]); }
	v_pk_mul_f32 v[206:207], v[0:1], v[206:207] op_sel_hi:[0,1]
	v_pk_mul_f32 v[208:209], v[0:1], v[208:209] op_sel_hi:[0,1]
	v_pk_mul_f32 v[210:211], v[210:211], s[18:19] op_sel_hi:[1,0]
	v_pk_mul_f32 v[212:213], v[212:213], s[18:19] op_sel_hi:[1,0]
	v_pk_fma_f32 v[208:209], v[216:217], v[208:209], v[224:225]
	v_pk_fma_f32 v[206:207], v[214:215], v[206:207], v[222:223]
	v_pk_fma_f32 v[128:129], v[128:129], 0.5, v[212:213] op_sel_hi:[1,0,1]
	v_pk_fma_f32 v[126:127], v[126:127], 0.5, v[210:211] op_sel_hi:[1,0,1]
	v_pk_mul_f32 v[206:207], v[206:207], s[18:19] op_sel_hi:[1,0]
	v_pk_mul_f32 v[208:209], v[208:209], s[18:19] op_sel_hi:[1,0]
	v_add_f32_e32 v197, v126, v127
	v_add_f32_e32 v210, v128, v129
	v_pk_fma_f32 v[124:125], v[124:125], 0.5, v[208:209] op_sel_hi:[1,0,1]
	v_pk_fma_f32 v[122:123], v[122:123], 0.5, v[206:207] op_sel_hi:[1,0,1]
	v_pk_add_f32 v[166:167], v[166:167], v[166:167] op_sel:[0,1] op_sel_hi:[1,0]
	v_add_f32_e32 v197, v197, v210
	v_add_f32_e32 v206, v122, v123
	v_add_f32_e32 v207, v124, v125
	v_mov_b32_e32 v159, v166
	v_add_f32_e32 v197, 0, v197
	v_add_f32_e32 v206, v206, v207
	v_pk_add_f32 v[168:169], v[168:169], v[168:169] op_sel:[0,1] op_sel_hi:[1,0]
	v_permlane16_swap_b32_e32 v166, v159
	v_mul_f32_e32 v210, v127, v127
	v_mul_f32_e32 v211, v129, v129
	v_add_f32_e32 v197, v197, v206
	v_mul_f32_e32 v206, v123, v123
	v_mul_f32_e32 v207, v125, v125
	v_add_f32_e32 v167, v166, v159
	v_mov_b32_e32 v159, v168
	s_ashr_i32 s16, s3, 8
	s_nop 0
	v_fmac_f32_e32 v210, v126, v126
	v_fmac_f32_e32 v211, v128, v128
	s_nop 1
	v_bfe_u32 v135, v227, 4, 2
	v_sub_u32_e32 v134, 0, v135
	v_lshlrev_b32_e32 v134, 4, v134
	v_ashrrev_i32_e32 v135, 31, v134
	v_lshl_add_u64 v[134:135], v[136:137], 0, v[134:135]
	v_permlane16_swap_b32_e32 v126, v122
	v_permlane16_swap_b32_e32 v127, v123
	v_permlane16_swap_b32_e32 v128, v124
	v_permlane16_swap_b32_e32 v129, v125
	v_permlane32_swap_b32_e32 v126, v122
	v_permlane32_swap_b32_e32 v127, v123
	v_permlane32_swap_b32_e32 v128, v124
	v_permlane32_swap_b32_e32 v129, v125
	v_mov_b32_e32 v166, v126
	v_mov_b32_e32 v169, v127
	v_mov_b32_e32 v208, v128
	v_mov_b32_e32 v209, v129
	v_bfe_u32 v176, v227, 3, 1
	v_mul_i32_i24_e32 v176, 0xffff8040, v176
	v_ashrrev_i32_e32 v177, 31, v176
	v_lshl_add_u64 v[134:135], v[134:135], 0, v[176:177]
	v_mov_b32_e32 v176, 0x8000
	v_mov_b32_e32 v177, 0
	v_lshl_add_u64 v[176:177], v[134:135], 0, v[176:177]
	v_mov_b32_dpp v126, v122 row_ror:8 row_mask:0xf bank_mask:0xc
	v_mov_b32_dpp v127, v123 row_ror:8 row_mask:0xf bank_mask:0xc
	v_mov_b32_dpp v128, v124 row_ror:8 row_mask:0xf bank_mask:0xc
	v_mov_b32_dpp v129, v125 row_ror:8 row_mask:0xf bank_mask:0xc
	v_mov_b32_dpp v122, v166 row_ror:8 row_mask:0xf bank_mask:0x3
	v_mov_b32_dpp v123, v169 row_ror:8 row_mask:0xf bank_mask:0x3
	v_mov_b32_dpp v124, v208 row_ror:8 row_mask:0xf bank_mask:0x3
	v_mov_b32_dpp v125, v209 row_ror:8 row_mask:0xf bank_mask:0x3
	global_store_dwordx4 v[134:135], v[126:129], off nt
	global_store_dwordx4 v[176:177], v[122:125], off nt
	s_nop 1
	v_mov_b32_dpp v122, v126 row_ror:8 row_mask:0xf bank_mask:0x3
	v_mov_b32_dpp v123, v127 row_ror:8 row_mask:0xf bank_mask:0x3
	v_mov_b32_dpp v124, v128 row_ror:8 row_mask:0xf bank_mask:0x3
	v_mov_b32_dpp v125, v129 row_ror:8 row_mask:0xf bank_mask:0x3
	v_mov_b32_e32 v126, v166
	v_mov_b32_e32 v127, v169
	v_mov_b32_e32 v128, v208
	v_mov_b32_e32 v129, v209
	s_nop 1
	v_permlane32_swap_b32_e32 v126, v122
	v_permlane32_swap_b32_e32 v127, v123
	v_permlane32_swap_b32_e32 v128, v124
	v_permlane32_swap_b32_e32 v129, v125
	v_permlane16_swap_b32_e32 v126, v122
	v_permlane16_swap_b32_e32 v127, v123
	v_permlane16_swap_b32_e32 v128, v124
	v_permlane16_swap_b32_e32 v129, v125
	v_fmac_f32_e32 v206, v122, v122
	v_fmac_f32_e32 v207, v124, v124
	v_cvt_pk_bf16_f32 v126, v126, v127
	v_cvt_pk_bf16_f32 v127, v128, v129
	v_cvt_pk_bf16_f32 v128, v122, v123
	v_cvt_pk_bf16_f32 v129, v124, v125
	v_permlane16_swap_b32_e32 v168, v159
	s_ashr_i32 s17, s16, 31
	v_add_f32_e32 v166, v168, v159
	s_lshl_b64 s[16:17], s[16:17], 19
	v_lshlrev_b32_e32 v159, 6, v158
	s_movk_i32 s1, 0x33c0
	v_readlane_b32 s2, v253, 59
	v_and_or_b32 v159, v159, s1, v196
	v_readlane_b32 s3, v253, 60
	s_add_u32 s1, s2, s16
	s_addc_u32 s16, s3, s17
	s_lshl_b64 s[24:25], s[44:45], 15
	s_add_u32 s48, s1, s24
	s_waitcnt vmcnt(6)
	v_sub_f32_e32 v123, v189, v229
	v_sub_f32_e32 v122, v188, v229
	v_sub_f32_e32 v125, v187, v229
	v_sub_f32_e32 v124, v186, v229
	v_pk_mul_f32 v[124:125], v[0:1], v[124:125] op_sel_hi:[0,1]
	v_pk_mul_f32 v[122:123], v[0:1], v[122:123] op_sel_hi:[0,1]
	s_addc_u32 s49, s16, s25
	v_lshlrev_b32_e32 v159, 1, v159
	global_store_dwordx4 v159, v[126:129], s[48:49]
	v_add_f32_e32 v210, v210, v211
	s_waitcnt vmcnt(3)
; __device__ __forceinline__ float xsum16(float v) { const auto r = __builtin_amdgcn_permlane16_swap(__float_as_uint(v), __float_as_uint(v), false, false); return __uint_as_float(r[0]) + __uint_as_float(r[1]); }
; __device__ __forceinline__ float xsum32(float v) { const auto r = __builtin_amdgcn_permlane32_swap(__float_as_uint(v), __float_as_uint(v), false, false); return __uint_as_float(r[0]) + __uint_as_float(r[1]); }
; __device__ __forceinline__ size_t blk_off(int r, int c, int K) { return (size_t)(r >> 8) * 256 * K + (size_t)(c >> 6) * (256 * 64) + (size_t)((r & 255) * 64 + (c & 63)); }
; __device__ __forceinline__ u32x4 pack8(const f32x4 a, const f32x4 b) { u32x4 w; w.x = cvt_pk_bf16(a[0], a[1]); w.y = cvt_pk_bf16(a[2], a[3]); w.z = cvt_pk_bf16(b[0], b[1]); w.w = cvt_pk_bf16(b[2], b[3]); return w; }
;     __device__ __forceinline__ void operator()(const f32x4 (&acc)[2][2][4][2], const pg8::Unit& u, int wr, int wc, int fr, int fq) const {
;     ...
;                 for (int bj = 0; bj < 2; ++bj) { float* yp = Y + (size_t)row * D_ + col0 + bj * 128; f32x4 v[2];
; #pragma unroll
;                     for (int n = 0; n < 2; ++n) { v[n] = (((yv[bj][n] - mu) * rs) * gq[bj][n] + bq_[bj][n]) * ALPHA_ + acc[ai][bj][m][n] * sc;
;                         *(f32x4*)(yp + 4 * n) = v[n]; s1 += (v[n][0] + v[n][1]) + (v[n][2] + v[n][3]); s2 += (v[n][0] * v[n][0] + v[n][1] * v[n][1]) + (v[n][2] * v[n][2] + v[n][3] * v[n][3]); }
;                     *(u32x4*)(Yb + blk_off(row, col0 + bj * 128, D_)) = pack8(v[0], v[1]); }
;                 s1 = xsum32(xsum16(s1)); s2 = xsum32(xsum16(s2));
;                 if (fq == 0) *(f32x2*)(stn + (size_t)row * 32 + (u.pn * 4 + wc) * 2) = (f32x2){s1, s2}; asm volatile("" ::: "memory"); } }
	v_pk_fma_f32 v[122:123], v[200:201], v[122:123], v[240:241]
	v_pk_fma_f32 v[124:125], v[198:199], v[124:125], v[238:239]
	v_pk_mul_f32 v[122:123], v[122:123], s[18:19] op_sel_hi:[1,0]
	v_pk_mul_f32 v[124:125], v[124:125], s[18:19] op_sel_hi:[1,0]
	v_pk_fma_f32 v[120:121], v[120:121], 0.5, v[122:123] op_sel_hi:[1,0,1]
	v_pk_fma_f32 v[118:119], v[118:119], 0.5, v[124:125] op_sel_hi:[1,0,1]
	v_add_f32_e32 v123, v120, v121
	v_add_f32_e32 v122, v118, v119
	v_add_f32_e32 v122, v122, v123
	v_add_f32_e32 v126, v197, v122
	v_mul_f32_e32 v122, v119, v119
	v_mul_f32_e32 v123, v121, v121
	v_add_f32_e32 v206, v206, v207
	v_fmac_f32_e32 v122, v118, v118
	v_fmac_f32_e32 v123, v120, v120
	v_add_f32_e32 v206, v210, v206
	v_add_f32_e32 v122, v122, v123
	v_add_f32_e32 v127, v206, v122
	v_sub_f32_e32 v123, v181, v229
	v_sub_f32_e32 v122, v180, v229
	v_sub_f32_e32 v125, v179, v229
	v_sub_f32_e32 v124, v178, v229
	v_pk_mul_f32 v[124:125], v[0:1], v[124:125] op_sel_hi:[0,1]
	v_pk_mul_f32 v[122:123], v[0:1], v[122:123] op_sel_hi:[0,1]
	v_pk_fma_f32 v[122:123], v[192:193], v[122:123], v[204:205]
	v_pk_fma_f32 v[124:125], v[190:191], v[124:125], v[202:203]
	v_pk_mul_f32 v[122:123], v[122:123], s[18:19] op_sel_hi:[1,0]
	v_pk_mul_f32 v[124:125], v[124:125], s[18:19] op_sel_hi:[1,0]
	v_pk_fma_f32 v[116:117], v[116:117], 0.5, v[122:123] op_sel_hi:[1,0,1]
	v_pk_fma_f32 v[114:115], v[114:115], 0.5, v[124:125] op_sel_hi:[1,0,1]
	v_add_f32_e32 v122, v116, v117
	v_add_f32_e32 v0, v114, v115
	v_add_f32_e32 v0, v0, v122
	v_mul_f32_e32 v122, v115, v115
	v_mul_f32_e32 v123, v117, v117
	v_add_f32_e32 v0, v126, v0
	v_fmac_f32_e32 v122, v114, v114
	v_fmac_f32_e32 v123, v116, v116
	s_nop 0
	s_nop 1
	v_bfe_u32 v125, v227, 4, 2
	v_sub_u32_e32 v124, 0, v125
	v_lshlrev_b32_e32 v124, 4, v124
	v_ashrrev_i32_e32 v125, 31, v124
	v_lshl_add_u64 v[124:125], v[136:137], 0, v[124:125]
	v_permlane16_swap_b32_e32 v118, v114
	v_permlane16_swap_b32_e32 v119, v115
	v_permlane16_swap_b32_e32 v120, v116
	v_permlane16_swap_b32_e32 v121, v117
	v_permlane32_swap_b32_e32 v118, v114
	v_permlane32_swap_b32_e32 v119, v115
	v_permlane32_swap_b32_e32 v120, v116
	v_permlane32_swap_b32_e32 v121, v117
	v_mov_b32_e32 v134, v118
	v_mov_b32_e32 v135, v119
	v_mov_b32_e32 v168, v120
	v_mov_b32_e32 v169, v121
	v_bfe_u32 v128, v227, 3, 1
	v_mul_i32_i24_e32 v128, 0xffff8040, v128
	v_ashrrev_i32_e32 v129, 31, v128
	v_lshl_add_u64 v[124:125], v[124:125], 0, v[128:129]
	v_mov_b32_e32 v128, 0x8000
	v_mov_b32_e32 v129, 0
	v_lshl_add_u64 v[128:129], v[124:125], 0, v[128:129]
	v_mov_b32_dpp v118, v114 row_ror:8 row_mask:0xf bank_mask:0xc
	v_mov_b32_dpp v119, v115 row_ror:8 row_mask:0xf bank_mask:0xc
	v_mov_b32_dpp v120, v116 row_ror:8 row_mask:0xf bank_mask:0xc
	v_mov_b32_dpp v121, v117 row_ror:8 row_mask:0xf bank_mask:0xc
	v_mov_b32_dpp v114, v134 row_ror:8 row_mask:0xf bank_mask:0x3
	v_mov_b32_dpp v115, v135 row_ror:8 row_mask:0xf bank_mask:0x3
	v_mov_b32_dpp v116, v168 row_ror:8 row_mask:0xf bank_mask:0x3
	v_mov_b32_dpp v117, v169 row_ror:8 row_mask:0xf bank_mask:0x3
	global_store_dwordx4 v[124:125], v[118:121], off offset:512 nt
	global_store_dwordx4 v[128:129], v[114:117], off offset:512 nt
	s_nop 1
	v_mov_b32_dpp v114, v118 row_ror:8 row_mask:0xf bank_mask:0x3
	v_mov_b32_dpp v115, v119 row_ror:8 row_mask:0xf bank_mask:0x3
	v_mov_b32_dpp v116, v120 row_ror:8 row_mask:0xf bank_mask:0x3
	v_mov_b32_dpp v117, v121 row_ror:8 row_mask:0xf bank_mask:0x3
	v_mov_b32_e32 v118, v134
	v_mov_b32_e32 v119, v135
	v_mov_b32_e32 v120, v168
	v_mov_b32_e32 v121, v169
	s_nop 1
	v_permlane32_swap_b32_e32 v118, v114
	v_permlane32_swap_b32_e32 v119, v115
	v_permlane32_swap_b32_e32 v120, v116
	v_permlane32_swap_b32_e32 v121, v117
	v_permlane16_swap_b32_e32 v118, v114
	v_permlane16_swap_b32_e32 v119, v115
	v_permlane16_swap_b32_e32 v120, v116
	v_permlane16_swap_b32_e32 v121, v117
	v_add_f32_e32 v122, v122, v123
	v_cvt_pk_bf16_f32 v118, v118, v119
	v_cvt_pk_bf16_f32 v119, v120, v121
	v_cvt_pk_bf16_f32 v120, v114, v115
	v_mov_b32_e32 v114, v0
	v_add_f32_e32 v122, v127, v122
	s_nop 0
	v_permlane16_swap_b32_e32 v0, v114
	s_or_b32 s2, s44, 2
	v_add_f32_e32 v114, v0, v114
	v_mov_b32_e32 v0, v122
	s_ashr_i32 s3, s2, 31
	s_nop 0
	v_permlane16_swap_b32_e32 v122, v0
	s_lshl_b64 s[44:45], s[2:3], 15
	v_add_f32_e32 v115, v122, v0
	v_mov_b32_e32 v135, v133
	v_mov_b32_e32 v134, v132
	v_mov_b32_e32 v177, v175
	v_mov_b32_e32 v176, v174
	v_mov_b32_e32 v169, v167
	v_mov_b32_e32 v168, v166
	v_cvt_pk_bf16_f32 v121, v116, v117
	s_add_u32 s46, s1, s44
	v_mov_b32_e32 v116, v114
	v_mov_b32_e32 v117, v115
	v_permlane32_swap_b32_e32 v133, v135
	v_permlane32_swap_b32_e32 v132, v134
	v_permlane32_swap_b32_e32 v175, v177
	v_permlane32_swap_b32_e32 v174, v176
	v_permlane32_swap_b32_e32 v167, v169
	v_permlane32_swap_b32_e32 v166, v168
	s_addc_u32 s47, s16, s45
	v_permlane32_swap_b32_e32 v114, v116
	v_permlane32_swap_b32_e32 v115, v117
	global_store_dwordx4 v159, v[118:121], s[46:47]
	s_and_saveexec_b64 s[26:27], s[40:41]
	s_cbranch_execz .LBB0_1705
	v_pk_add_f32 v[114:115], v[114:115], v[116:117]
	v_lshl_add_u64 v[116:117], s[8:9], 0, v[130:131]
	v_lshl_add_u64 v[116:117], s[38:39], 2, v[116:117]
	global_store_dwordx2 v[116:117], v[114:115], off
; __device__ __forceinline__ size_t blk_off(int r, int c, int K) { return (size_t)(r >> 8) * 256 * K + (size_t)(c >> 6) * (256 * 64) + (size_t)((r & 255) * 64 + (c & 63)); }
; __device__ __forceinline__ u32x4 pack8(const f32x4 a, const f32x4 b) { u32x4 w; w.x = cvt_pk_bf16(a[0], a[1]); w.y = cvt_pk_bf16(a[2], a[3]); w.z = cvt_pk_bf16(b[0], b[1]); w.w = cvt_pk_bf16(b[2], b[3]); return w; }
;     __device__ __forceinline__ void operator()(const f32x4 (&acc)[2][2][4][2], const pg8::Unit& u, int wr, int wc, int fr, int fq) const {
;     ...
;             for (int m = 0; m < 4; ++m) { const int row = row0 + ai * 128 + m * 16; const float mu = mu4[m], rs = rs4[m];
;                 f32x4 yv[2][2], gq[2][2], bq_[2][2];
; #pragma unroll
;                 for (int bj = 0; bj < 2; ++bj)
; #pragma unroll
;                     for (int n = 0; n < 2; ++n) { yv[bj][n] = *(const f32x4*)(Yin + (size_t)row * D_ + col0 + bj * 128 + 4 * n); gq[bj][n] = *(const f32x4*)(g + col0 + bj * 128 + 4 * n); bq_[bj][n] = *(const f32x4*)(b + col0 + bj * 128 + 4 * n); }
;                 asm volatile("" ::: "memory");
;                 float s1 = 0.f, s2 = 0.f;
; #pragma unroll
;                 for (int bj = 0; bj < 2; ++bj) { float* yp = Y + (size_t)row * D_ + col0 + bj * 128; f32x4 v[2];
; #pragma unroll
;                     for (int n = 0; n < 2; ++n) { v[n] = (((yv[bj][n] - mu) * rs) * gq[bj][n] + bq_[bj][n]) * ALPHA_ + acc[ai][bj][m][n] * sc;
;                         *(f32x4*)(yp + 4 * n) = v[n]; s1 += (v[n][0] + v[n][1]) + (v[n][2] + v[n][3]); s2 += (v[n][0] * v[n][0] + v[n][1] * v[n][1]) + (v[n][2] * v[n][2] + v[n][3] * v[n][3]); }
;                     *(u32x4*)(Yb + blk_off(row, col0 + bj * 128, D_)) = pack8(v[0], v[1]); }
.LBB0_1705:
	s_or_b64 exec, exec, s[26:27]
	v_pk_add_f32 v[114:115], v[132:133], v[134:135]
	s_mov_b32 s2, 0x3a800000
	v_pk_mul_f32 v[178:179], v[114:115], s[2:3] op_sel_hi:[1,0]
	s_mov_b32 s1, 0x800000
	v_fma_f32 v0, -v179, v179, v178
	v_max_f32_e32 v0, 0, v0
	v_add_f32_e32 v0, 0x3727c5ac, v0
	v_cmp_gt_f32_e32 vcc, s1, v0
	v_mul_f32_e32 v114, 0x4b800000, v0
	s_load_dwordx16 s[60:75], s[34:35], 0x38
	v_cndmask_b32_e32 v0, v0, v114, vcc
	v_rsq_f32_e32 v0, v0
	v_lshlrev_b32_e32 v159, 6, v182
	s_mov_b32 s2, 0x3fd744fd
	v_mul_f32_e32 v114, 0x45800000, v0
	v_cndmask_b32_e32 v0, v0, v114, vcc
	v_lshlrev_b64 v[114:115], 12, v[182:183]
	s_waitcnt lgkmcnt(0)
	v_lshl_add_u64 v[114:115], s[74:75], 0, v[114:115]
	v_lshl_add_u64 v[180:181], v[152:153], 2, v[114:115]
	global_load_dwordx4 v[186:189], v[180:181], off offset:16
	global_load_dwordx4 v[190:193], v[180:181], off
	global_load_dwordx4 v[198:201], v[156:157], off offset:16
	global_load_dwordx4 v[202:205], v[156:157], off
	global_load_dwordx4 v[206:209], v[154:155], off offset:16
	global_load_dwordx4 v[210:213], v[154:155], off
	global_load_dwordx4 v[114:117], v[180:181], off offset:528
	global_load_dwordx4 v[134:137], v[180:181], off offset:512
	global_load_dwordx4 v[118:121], v[156:157], off offset:528
	global_load_dwordx4 v[126:129], v[156:157], off offset:512
	global_load_dwordx4 v[122:125], v[154:155], off offset:528
	global_load_dwordx4 v[130:133], v[154:155], off offset:512
	s_movk_i32 s1, 0x37c0
	v_and_or_b32 v159, v159, s1, v196
	v_lshlrev_b32_e32 v159, 1, v159
	s_waitcnt vmcnt(11)
	v_sub_f32_e32 v187, v187, v179
	s_waitcnt vmcnt(10)
	v_sub_f32_e32 v183, v193, v179
	v_sub_f32_e32 v182, v192, v179
	v_sub_f32_e32 v191, v191, v179
	v_sub_f32_e32 v190, v190, v179
	v_pk_mul_f32 v[190:191], v[0:1], v[190:191] op_sel_hi:[0,1]
	v_pk_mul_f32 v[182:183], v[0:1], v[182:183] op_sel_hi:[0,1]
	s_waitcnt vmcnt(6)
	v_pk_fma_f32 v[182:183], v[204:205], v[182:183], v[212:213]
	v_pk_fma_f32 v[190:191], v[202:203], v[190:191], v[210:211]
	v_pk_mul_f32 v[182:183], v[182:183], s[2:3] op_sel_hi:[1,0]
	v_pk_mul_f32 v[190:191], v[190:191], s[2:3] op_sel_hi:[1,0]
	v_pk_fma_f32 v[112:113], v[112:113], 0.5, v[182:183] op_sel_hi:[1,0,1]
	v_pk_fma_f32 v[110:111], v[110:111], 0.5, v[190:191] op_sel_hi:[1,0,1]
	v_add_f32_e32 v182, v112, v113
	v_add_f32_e32 v178, v110, v111
	v_add_f32_e32 v178, v178, v182
	v_mul_f32_e32 v182, v111, v111
	v_mul_f32_e32 v183, v113, v113
	v_fmac_f32_e32 v182, v110, v110
	v_fmac_f32_e32 v183, v112, v112
	v_add_f32_e32 v190, v182, v183
	v_sub_f32_e32 v183, v189, v179
	v_sub_f32_e32 v182, v188, v179
	v_sub_f32_e32 v186, v186, v179
	v_pk_mul_f32 v[186:187], v[0:1], v[186:187] op_sel_hi:[0,1]
	v_pk_mul_f32 v[182:183], v[0:1], v[182:183] op_sel_hi:[0,1]
	v_pk_fma_f32 v[182:183], v[200:201], v[182:183], v[208:209]
	v_pk_fma_f32 v[186:187], v[198:199], v[186:187], v[206:207]
	v_pk_mul_f32 v[182:183], v[182:183], s[2:3] op_sel_hi:[1,0]
	v_pk_mul_f32 v[186:187], v[186:187], s[2:3] op_sel_hi:[1,0]
	v_pk_fma_f32 v[108:109], v[108:109], 0.5, v[182:183] op_sel_hi:[1,0,1]
	v_pk_fma_f32 v[106:107], v[106:107], 0.5, v[186:187] op_sel_hi:[1,0,1]
	v_add_f32_e32 v183, v108, v109
	v_add_f32_e32 v182, v106, v107
	v_add_f32_e32 v178, 0, v178
	v_add_f32_e32 v182, v182, v183
	v_add_f32_e32 v178, v178, v182
	v_mul_f32_e32 v182, v107, v107
	v_mul_f32_e32 v183, v109, v109
	s_nop 0
	s_nop 1
	v_bfe_u32 v187, v227, 4, 2
	v_sub_u32_e32 v186, 0, v187
	v_lshlrev_b32_e32 v186, 4, v186
	v_ashrrev_i32_e32 v187, 31, v186
	v_lshl_add_u64 v[186:187], v[180:181], 0, v[186:187]
	v_permlane16_swap_b32_e32 v110, v106
	v_permlane16_swap_b32_e32 v111, v107
	v_permlane16_swap_b32_e32 v112, v108
	v_permlane16_swap_b32_e32 v113, v109
	v_permlane32_swap_b32_e32 v110, v106
	v_permlane32_swap_b32_e32 v111, v107
	v_permlane32_swap_b32_e32 v112, v108
	v_permlane32_swap_b32_e32 v113, v109
	v_mov_b32_e32 v191, v110
	v_mov_b32_e32 v192, v111
	v_mov_b32_e32 v193, v112
	v_mov_b32_e32 v197, v113
	v_bfe_u32 v188, v227, 3, 1
	v_mul_i32_i24_e32 v188, 0xffff8040, v188
	v_ashrrev_i32_e32 v189, 31, v188
	v_lshl_add_u64 v[186:187], v[186:187], 0, v[188:189]
	v_mov_b32_e32 v188, 0x8000
	v_mov_b32_e32 v189, 0
	v_lshl_add_u64 v[188:189], v[186:187], 0, v[188:189]
	v_mov_b32_dpp v110, v106 row_ror:8 row_mask:0xf bank_mask:0xc
	v_mov_b32_dpp v111, v107 row_ror:8 row_mask:0xf bank_mask:0xc
	v_mov_b32_dpp v112, v108 row_ror:8 row_mask:0xf bank_mask:0xc
	v_mov_b32_dpp v113, v109 row_ror:8 row_mask:0xf bank_mask:0xc
	v_mov_b32_dpp v106, v191 row_ror:8 row_mask:0xf bank_mask:0x3
	v_mov_b32_dpp v107, v192 row_ror:8 row_mask:0xf bank_mask:0x3
	v_mov_b32_dpp v108, v193 row_ror:8 row_mask:0xf bank_mask:0x3
	v_mov_b32_dpp v109, v197 row_ror:8 row_mask:0xf bank_mask:0x3
	global_store_dwordx4 v[186:187], v[110:113], off nt
	global_store_dwordx4 v[188:189], v[106:109], off nt
	s_nop 1
	v_mov_b32_dpp v106, v110 row_ror:8 row_mask:0xf bank_mask:0x3
	v_mov_b32_dpp v107, v111 row_ror:8 row_mask:0xf bank_mask:0x3
	v_mov_b32_dpp v108, v112 row_ror:8 row_mask:0xf bank_mask:0x3
	v_mov_b32_dpp v109, v113 row_ror:8 row_mask:0xf bank_mask:0x3
	v_mov_b32_e32 v110, v191
	v_mov_b32_e32 v111, v192
	v_mov_b32_e32 v112, v193
	v_mov_b32_e32 v113, v197
	s_nop 1
	v_permlane32_swap_b32_e32 v110, v106
	v_permlane32_swap_b32_e32 v111, v107
	v_permlane32_swap_b32_e32 v112, v108
	v_permlane32_swap_b32_e32 v113, v109
	v_permlane16_swap_b32_e32 v110, v106
	v_permlane16_swap_b32_e32 v111, v107
	v_permlane16_swap_b32_e32 v112, v108
	v_permlane16_swap_b32_e32 v113, v109
	v_fmac_f32_e32 v182, v106, v106
	v_fmac_f32_e32 v183, v108, v108
	v_cvt_pk_bf16_f32 v110, v110, v111
	v_cvt_pk_bf16_f32 v111, v112, v113
	v_cvt_pk_bf16_f32 v112, v106, v107
	v_cvt_pk_bf16_f32 v113, v108, v109
	s_waitcnt vmcnt(6)
; __device__ __forceinline__ float xsum16(float v) { const auto r = __builtin_amdgcn_permlane16_swap(__float_as_uint(v), __float_as_uint(v), false, false); return __uint_as_float(r[0]) + __uint_as_float(r[1]); }
; __device__ __forceinline__ float xsum32(float v) { const auto r = __builtin_amdgcn_permlane32_swap(__float_as_uint(v), __float_as_uint(v), false, false); return __uint_as_float(r[0]) + __uint_as_float(r[1]); }
; __device__ __forceinline__ size_t blk_off(int r, int c, int K) { return (size_t)(r >> 8) * 256 * K + (size_t)(c >> 6) * (256 * 64) + (size_t)((r & 255) * 64 + (c & 63)); }
; __device__ __forceinline__ u32x4 pack8(const f32x4 a, const f32x4 b) { u32x4 w; w.x = cvt_pk_bf16(a[0], a[1]); w.y = cvt_pk_bf16(a[2], a[3]); w.z = cvt_pk_bf16(b[0], b[1]); w.w = cvt_pk_bf16(b[2], b[3]); return w; }
;     __device__ __forceinline__ void operator()(const f32x4 (&acc)[2][2][4][2], const pg8::Unit& u, int wr, int wc, int fr, int fq) const {
;     ...
;                 for (int bj = 0; bj < 2; ++bj) { float* yp = Y + (size_t)row * D_ + col0 + bj * 128; f32x4 v[2];
; #pragma unroll
;                     for (int n = 0; n < 2; ++n) { v[n] = (((yv[bj][n] - mu) * rs) * gq[bj][n] + bq_[bj][n]) * ALPHA_ + acc[ai][bj][m][n] * sc;
;                         *(f32x4*)(yp + 4 * n) = v[n]; s1 += (v[n][0] + v[n][1]) + (v[n][2] + v[n][3]); s2 += (v[n][0] * v[n][0] + v[n][1] * v[n][1]) + (v[n][2] * v[n][2] + v[n][3] * v[n][3]); }
;                     *(u32x4*)(Yb + blk_off(row, col0 + bj * 128, D_)) = pack8(v[0], v[1]); }
;                 s1 = xsum32(xsum16(s1)); s2 = xsum32(xsum16(s2));
;                 if (fq == 0) *(f32x2*)(stn + (size_t)row * 32 + (u.pn * 4 + wc) * 2) = (f32x2){s1, s2}; asm volatile("" ::: "memory"); } }
	v_sub_f32_e32 v107, v137, v179
	v_sub_f32_e32 v106, v136, v179
	v_sub_f32_e32 v109, v135, v179
	v_sub_f32_e32 v108, v134, v179
	v_pk_mul_f32 v[108:109], v[0:1], v[108:109] op_sel_hi:[0,1]
	v_pk_mul_f32 v[106:107], v[0:1], v[106:107] op_sel_hi:[0,1]
	s_waitcnt vmcnt(2)
	v_pk_fma_f32 v[106:107], v[128:129], v[106:107], v[132:133]
	v_pk_fma_f32 v[108:109], v[126:127], v[108:109], v[130:131]
	v_pk_mul_f32 v[106:107], v[106:107], s[2:3] op_sel_hi:[1,0]
	v_pk_mul_f32 v[108:109], v[108:109], s[2:3] op_sel_hi:[1,0]
	v_pk_fma_f32 v[104:105], v[104:105], 0.5, v[106:107] op_sel_hi:[1,0,1]
	v_pk_fma_f32 v[102:103], v[102:103], 0.5, v[108:109] op_sel_hi:[1,0,1]
	v_add_f32_e32 v107, v104, v105
	v_add_f32_e32 v106, v102, v103
	v_add_f32_e32 v106, v106, v107
	global_store_dwordx4 v159, v[110:113], s[48:49]
	v_mul_f32_e32 v107, v105, v105
	v_add_f32_e32 v182, v182, v183
	v_add_f32_e32 v110, v178, v106
	v_mul_f32_e32 v106, v103, v103
	v_fmac_f32_e32 v106, v102, v102
	v_fmac_f32_e32 v107, v104, v104
	v_add_f32_e32 v182, v190, v182
	v_add_f32_e32 v106, v106, v107
	v_add_f32_e32 v111, v182, v106
	v_sub_f32_e32 v107, v117, v179
	v_sub_f32_e32 v106, v116, v179
	v_sub_f32_e32 v109, v115, v179
	v_sub_f32_e32 v108, v114, v179
	v_pk_mul_f32 v[108:109], v[0:1], v[108:109] op_sel_hi:[0,1]
	v_pk_mul_f32 v[106:107], v[0:1], v[106:107] op_sel_hi:[0,1]
	v_pk_fma_f32 v[106:107], v[120:121], v[106:107], v[124:125]
	v_pk_fma_f32 v[108:109], v[118:119], v[108:109], v[122:123]
	v_pk_mul_f32 v[106:107], v[106:107], s[2:3] op_sel_hi:[1,0]
	v_pk_mul_f32 v[108:109], v[108:109], s[2:3] op_sel_hi:[1,0]
	v_pk_fma_f32 v[100:101], v[100:101], 0.5, v[106:107] op_sel_hi:[1,0,1]
	v_pk_fma_f32 v[98:99], v[98:99], 0.5, v[108:109] op_sel_hi:[1,0,1]
	v_add_f32_e32 v106, v100, v101
	v_add_f32_e32 v0, v98, v99
	v_add_f32_e32 v0, v0, v106
	v_mul_f32_e32 v106, v99, v99
	v_mul_f32_e32 v107, v101, v101
	v_add_f32_e32 v0, v110, v0
	v_fmac_f32_e32 v106, v98, v98
	v_fmac_f32_e32 v107, v100, v100
	s_nop 0
	s_nop 1
	v_bfe_u32 v109, v227, 4, 2
	v_sub_u32_e32 v108, 0, v109
	v_lshlrev_b32_e32 v108, 4, v108
	v_ashrrev_i32_e32 v109, 31, v108
	v_lshl_add_u64 v[108:109], v[180:181], 0, v[108:109]
	v_permlane16_swap_b32_e32 v102, v98
	v_permlane16_swap_b32_e32 v103, v99
	v_permlane16_swap_b32_e32 v104, v100
	v_permlane16_swap_b32_e32 v105, v101
	v_permlane32_swap_b32_e32 v102, v98
	v_permlane32_swap_b32_e32 v103, v99
	v_permlane32_swap_b32_e32 v104, v100
	v_permlane32_swap_b32_e32 v105, v101
	v_mov_b32_e32 v114, v102
	v_mov_b32_e32 v115, v103
	v_mov_b32_e32 v116, v104
	v_mov_b32_e32 v117, v105
	v_bfe_u32 v112, v227, 3, 1
	v_mul_i32_i24_e32 v112, 0xffff8040, v112
	v_ashrrev_i32_e32 v113, 31, v112
	v_lshl_add_u64 v[108:109], v[108:109], 0, v[112:113]
	v_mov_b32_e32 v112, 0x8000
	v_mov_b32_e32 v113, 0
	v_lshl_add_u64 v[112:113], v[108:109], 0, v[112:113]
	v_mov_b32_dpp v102, v98 row_ror:8 row_mask:0xf bank_mask:0xc
	v_mov_b32_dpp v103, v99 row_ror:8 row_mask:0xf bank_mask:0xc
	v_mov_b32_dpp v104, v100 row_ror:8 row_mask:0xf bank_mask:0xc
	v_mov_b32_dpp v105, v101 row_ror:8 row_mask:0xf bank_mask:0xc
	v_mov_b32_dpp v98, v114 row_ror:8 row_mask:0xf bank_mask:0x3
	v_mov_b32_dpp v99, v115 row_ror:8 row_mask:0xf bank_mask:0x3
	v_mov_b32_dpp v100, v116 row_ror:8 row_mask:0xf bank_mask:0x3
	v_mov_b32_dpp v101, v117 row_ror:8 row_mask:0xf bank_mask:0x3
	global_store_dwordx4 v[108:109], v[102:105], off offset:512 nt
	global_store_dwordx4 v[112:113], v[98:101], off offset:512 nt
	s_nop 1
	v_mov_b32_dpp v98, v102 row_ror:8 row_mask:0xf bank_mask:0x3
	v_mov_b32_dpp v99, v103 row_ror:8 row_mask:0xf bank_mask:0x3
	v_mov_b32_dpp v100, v104 row_ror:8 row_mask:0xf bank_mask:0x3
	v_mov_b32_dpp v101, v105 row_ror:8 row_mask:0xf bank_mask:0x3
	v_mov_b32_e32 v102, v114
	v_mov_b32_e32 v103, v115
	v_mov_b32_e32 v104, v116
	v_mov_b32_e32 v105, v117
	s_nop 1
	v_permlane32_swap_b32_e32 v102, v98
	v_permlane32_swap_b32_e32 v103, v99
	v_permlane32_swap_b32_e32 v104, v100
	v_permlane32_swap_b32_e32 v105, v101
	v_permlane16_swap_b32_e32 v102, v98
	v_permlane16_swap_b32_e32 v103, v99
	v_permlane16_swap_b32_e32 v104, v100
	v_permlane16_swap_b32_e32 v105, v101
	v_add_f32_e32 v106, v106, v107
	v_cvt_pk_bf16_f32 v102, v102, v103
	v_cvt_pk_bf16_f32 v103, v104, v105
	v_cvt_pk_bf16_f32 v104, v98, v99
	v_mov_b32_e32 v98, v0
	v_add_f32_e32 v106, v111, v106
	s_nop 0
	v_permlane16_swap_b32_e32 v0, v98
	v_add_f32_e32 v98, v0, v98
	v_mov_b32_e32 v0, v106
	s_nop 1
	v_permlane16_swap_b32_e32 v106, v0
	v_add_f32_e32 v99, v106, v0
	v_cvt_pk_bf16_f32 v105, v100, v101
	v_mov_b32_e32 v100, v98
	v_mov_b32_e32 v101, v99
	s_nop 0
	v_permlane32_swap_b32_e32 v98, v100
	v_permlane32_swap_b32_e32 v99, v101
	global_store_dwordx4 v159, v[102:105], s[46:47]
	s_and_saveexec_b64 s[26:27], s[40:41]
	s_cbranch_execz .LBB0_1707
	v_pk_add_f32 v[98:99], v[98:99], v[100:101]
	v_lshl_add_u64 v[100:101], s[8:9], 0, v[172:173]
	v_lshl_add_u64 v[100:101], s[38:39], 2, v[100:101]
	global_store_dwordx2 v[100:101], v[98:99], off
; __device__ __forceinline__ size_t blk_off(int r, int c, int K) { return (size_t)(r >> 8) * 256 * K + (size_t)(c >> 6) * (256 * 64) + (size_t)((r & 255) * 64 + (c & 63)); }
; __device__ __forceinline__ u32x4 pack8(const f32x4 a, const f32x4 b) { u32x4 w; w.x = cvt_pk_bf16(a[0], a[1]); w.y = cvt_pk_bf16(a[2], a[3]); w.z = cvt_pk_bf16(b[0], b[1]); w.w = cvt_pk_bf16(b[2], b[3]); return w; }
;     __device__ __forceinline__ void operator()(const f32x4 (&acc)[2][2][4][2], const pg8::Unit& u, int wr, int wc, int fr, int fq) const {
;     ...
;             for (int m = 0; m < 4; ++m) { const int row = row0 + ai * 128 + m * 16; const float mu = mu4[m], rs = rs4[m];
;                 f32x4 yv[2][2], gq[2][2], bq_[2][2];
; #pragma unroll
;                 for (int bj = 0; bj < 2; ++bj)
; #pragma unroll
;                     for (int n = 0; n < 2; ++n) { yv[bj][n] = *(const f32x4*)(Yin + (size_t)row * D_ + col0 + bj * 128 + 4 * n); gq[bj][n] = *(const f32x4*)(g + col0 + bj * 128 + 4 * n); bq_[bj][n] = *(const f32x4*)(b + col0 + bj * 128 + 4 * n); }
;                 asm volatile("" ::: "memory");
;                 float s1 = 0.f, s2 = 0.f;
; #pragma unroll
;                 for (int bj = 0; bj < 2; ++bj) { float* yp = Y + (size_t)row * D_ + col0 + bj * 128; f32x4 v[2];
; #pragma unroll
;                     for (int n = 0; n < 2; ++n) { v[n] = (((yv[bj][n] - mu) * rs) * gq[bj][n] + bq_[bj][n]) * ALPHA_ + acc[ai][bj][m][n] * sc;
;                         *(f32x4*)(yp + 4 * n) = v[n]; s1 += (v[n][0] + v[n][1]) + (v[n][2] + v[n][3]); s2 += (v[n][0] * v[n][0] + v[n][1] * v[n][1]) + (v[n][2] * v[n][2] + v[n][3] * v[n][3]); }
;                     *(u32x4*)(Yb + blk_off(row, col0 + bj * 128, D_)) = pack8(v[0], v[1]); }
.LBB0_1707:
	s_or_b64 exec, exec, s[26:27]
	v_pk_add_f32 v[98:99], v[174:175], v[176:177]
	s_mov_b32 s2, 0x3a800000
	v_pk_mul_f32 v[122:123], v[98:99], s[2:3] op_sel_hi:[1,0]
	s_mov_b32 s1, 0x800000
	v_fma_f32 v0, -v123, v123, v122
	v_max_f32_e32 v0, 0, v0
	v_add_f32_e32 v0, 0x3727c5ac, v0
	v_cmp_gt_f32_e32 vcc, s1, v0
	v_mul_f32_e32 v98, 0x4b800000, v0
	s_load_dwordx16 s[60:75], s[34:35], 0x38
	v_cndmask_b32_e32 v0, v0, v98, vcc
	v_rsq_f32_e32 v0, v0
	s_mov_b32 s2, 0x3fd744fd
	v_lshlrev_b32_e32 v122, 6, v170
	v_mul_f32_e32 v98, 0x45800000, v0
	v_cndmask_b32_e32 v0, v0, v98, vcc
	v_lshlrev_b64 v[98:99], 12, v[170:171]
	s_waitcnt lgkmcnt(0)
	v_lshl_add_u64 v[98:99], s[74:75], 0, v[98:99]
	v_lshl_add_u64 v[124:125], v[152:153], 2, v[98:99]
	global_load_dwordx4 v[126:129], v[124:125], off offset:16
	global_load_dwordx4 v[130:133], v[124:125], off
	global_load_dwordx4 v[134:137], v[156:157], off offset:16
	global_load_dwordx4 v[172:175], v[156:157], off
	global_load_dwordx4 v[176:179], v[154:155], off offset:16
	global_load_dwordx4 v[180:183], v[154:155], off
	global_load_dwordx4 v[98:101], v[124:125], off offset:528
	global_load_dwordx4 v[118:121], v[124:125], off offset:512
	global_load_dwordx4 v[102:105], v[156:157], off offset:528
	global_load_dwordx4 v[110:113], v[156:157], off offset:512
	global_load_dwordx4 v[106:109], v[154:155], off offset:528
	global_load_dwordx4 v[114:117], v[154:155], off offset:512
	s_movk_i32 s1, 0x3bc0
	v_and_or_b32 v122, v122, s1, v196
	v_lshlrev_b32_e32 v122, 1, v122
	s_waitcnt vmcnt(11)
	v_sub_f32_e32 v129, v129, v123
	s_waitcnt vmcnt(10)
	v_sub_f32_e32 v133, v133, v123
	v_sub_f32_e32 v132, v132, v123
	v_sub_f32_e32 v131, v131, v123
	v_sub_f32_e32 v130, v130, v123
	v_sub_f32_e32 v128, v128, v123
	v_sub_f32_e32 v127, v127, v123
	v_sub_f32_e32 v126, v126, v123
	v_pk_mul_f32 v[130:131], v[0:1], v[130:131] op_sel_hi:[0,1]
	v_pk_mul_f32 v[132:133], v[0:1], v[132:133] op_sel_hi:[0,1]
	v_pk_mul_f32 v[126:127], v[0:1], v[126:127] op_sel_hi:[0,1]
	v_pk_mul_f32 v[128:129], v[0:1], v[128:129] op_sel_hi:[0,1]
	s_waitcnt vmcnt(6)
	v_pk_fma_f32 v[132:133], v[174:175], v[132:133], v[182:183]
	v_pk_fma_f32 v[130:131], v[172:173], v[130:131], v[180:181]
	v_pk_fma_f32 v[128:129], v[136:137], v[128:129], v[178:179]
	v_pk_fma_f32 v[126:127], v[134:135], v[126:127], v[176:177]
	v_pk_mul_f32 v[130:131], v[130:131], s[2:3] op_sel_hi:[1,0]
	v_pk_mul_f32 v[132:133], v[132:133], s[2:3] op_sel_hi:[1,0]
	v_pk_mul_f32 v[126:127], v[126:127], s[2:3] op_sel_hi:[1,0]
	v_pk_mul_f32 v[128:129], v[128:129], s[2:3] op_sel_hi:[1,0]
	v_pk_fma_f32 v[96:97], v[96:97], 0.5, v[132:133] op_sel_hi:[1,0,1]
	v_pk_fma_f32 v[94:95], v[94:95], 0.5, v[130:131] op_sel_hi:[1,0,1]
	v_pk_fma_f32 v[92:93], v[92:93], 0.5, v[128:129] op_sel_hi:[1,0,1]
	v_pk_fma_f32 v[90:91], v[90:91], 0.5, v[126:127] op_sel_hi:[1,0,1]
	v_add_f32_e32 v130, v94, v95
	v_add_f32_e32 v131, v96, v97
	v_add_f32_e32 v126, v90, v91
	v_add_f32_e32 v127, v92, v93
	v_add_f32_e32 v130, v130, v131
	v_mul_f32_e32 v131, v95, v95
	v_mul_f32_e32 v132, v97, v97
	v_add_f32_e32 v126, v126, v127
	v_mul_f32_e32 v127, v91, v91
	v_mul_f32_e32 v128, v93, v93
	s_nop 0
	v_fmac_f32_e32 v131, v94, v94
	v_fmac_f32_e32 v132, v96, v96
	s_nop 1
	v_bfe_u32 v135, v227, 4, 2
	v_sub_u32_e32 v134, 0, v135
	v_lshlrev_b32_e32 v134, 4, v134
	v_ashrrev_i32_e32 v135, 31, v134
	v_lshl_add_u64 v[134:135], v[124:125], 0, v[134:135]
	v_permlane16_swap_b32_e32 v94, v90
	v_permlane16_swap_b32_e32 v95, v91
	v_permlane16_swap_b32_e32 v96, v92
	v_permlane16_swap_b32_e32 v97, v93
	v_permlane32_swap_b32_e32 v94, v90
	v_permlane32_swap_b32_e32 v95, v91
	v_permlane32_swap_b32_e32 v96, v92
	v_permlane32_swap_b32_e32 v97, v93
	v_mov_b32_e32 v129, v94
	v_mov_b32_e32 v133, v95
	v_mov_b32_e32 v159, v96
	v_mov_b32_e32 v170, v97
	v_bfe_u32 v136, v227, 3, 1
	v_mul_i32_i24_e32 v136, 0xffff8040, v136
	v_ashrrev_i32_e32 v137, 31, v136
	v_lshl_add_u64 v[134:135], v[134:135], 0, v[136:137]
	v_mov_b32_e32 v136, 0x8000
	v_mov_b32_e32 v137, 0
	v_lshl_add_u64 v[136:137], v[134:135], 0, v[136:137]
	v_mov_b32_dpp v94, v90 row_ror:8 row_mask:0xf bank_mask:0xc
	v_mov_b32_dpp v95, v91 row_ror:8 row_mask:0xf bank_mask:0xc
	v_mov_b32_dpp v96, v92 row_ror:8 row_mask:0xf bank_mask:0xc
	v_mov_b32_dpp v97, v93 row_ror:8 row_mask:0xf bank_mask:0xc
	v_mov_b32_dpp v90, v129 row_ror:8 row_mask:0xf bank_mask:0x3
	v_mov_b32_dpp v91, v133 row_ror:8 row_mask:0xf bank_mask:0x3
	v_mov_b32_dpp v92, v159 row_ror:8 row_mask:0xf bank_mask:0x3
	v_mov_b32_dpp v93, v170 row_ror:8 row_mask:0xf bank_mask:0x3
	global_store_dwordx4 v[134:135], v[94:97], off nt
	global_store_dwordx4 v[136:137], v[90:93], off nt
	s_nop 1
	v_mov_b32_dpp v90, v94 row_ror:8 row_mask:0xf bank_mask:0x3
	v_mov_b32_dpp v91, v95 row_ror:8 row_mask:0xf bank_mask:0x3
	v_mov_b32_dpp v92, v96 row_ror:8 row_mask:0xf bank_mask:0x3
	v_mov_b32_dpp v93, v97 row_ror:8 row_mask:0xf bank_mask:0x3
	v_mov_b32_e32 v94, v129
	v_mov_b32_e32 v95, v133
	v_mov_b32_e32 v96, v159
	v_mov_b32_e32 v97, v170
	s_nop 1
	v_permlane32_swap_b32_e32 v94, v90
	v_permlane32_swap_b32_e32 v95, v91
	v_permlane32_swap_b32_e32 v96, v92
	v_permlane32_swap_b32_e32 v97, v93
	v_permlane16_swap_b32_e32 v94, v90
	v_permlane16_swap_b32_e32 v95, v91
	v_permlane16_swap_b32_e32 v96, v92
	v_permlane16_swap_b32_e32 v97, v93
	v_fmac_f32_e32 v127, v90, v90
	v_fmac_f32_e32 v128, v92, v92
	v_cvt_pk_bf16_f32 v94, v94, v95
	v_cvt_pk_bf16_f32 v95, v96, v97
	v_cvt_pk_bf16_f32 v96, v90, v91
	v_cvt_pk_bf16_f32 v97, v92, v93
	s_waitcnt vmcnt(6)
; __device__ __forceinline__ float xsum16(float v) { const auto r = __builtin_amdgcn_permlane16_swap(__float_as_uint(v), __float_as_uint(v), false, false); return __uint_as_float(r[0]) + __uint_as_float(r[1]); }
; __device__ __forceinline__ float xsum32(float v) { const auto r = __builtin_amdgcn_permlane32_swap(__float_as_uint(v), __float_as_uint(v), false, false); return __uint_as_float(r[0]) + __uint_as_float(r[1]); }
; __device__ __forceinline__ size_t blk_off(int r, int c, int K) { return (size_t)(r >> 8) * 256 * K + (size_t)(c >> 6) * (256 * 64) + (size_t)((r & 255) * 64 + (c & 63)); }
; __device__ __forceinline__ u32x4 pack8(const f32x4 a, const f32x4 b) { u32x4 w; w.x = cvt_pk_bf16(a[0], a[1]); w.y = cvt_pk_bf16(a[2], a[3]); w.z = cvt_pk_bf16(b[0], b[1]); w.w = cvt_pk_bf16(b[2], b[3]); return w; }
;     __device__ __forceinline__ void operator()(const f32x4 (&acc)[2][2][4][2], const pg8::Unit& u, int wr, int wc, int fr, int fq) const {
;     ...
;                 for (int bj = 0; bj < 2; ++bj) { float* yp = Y + (size_t)row * D_ + col0 + bj * 128; f32x4 v[2];
; #pragma unroll
;                     for (int n = 0; n < 2; ++n) { v[n] = (((yv[bj][n] - mu) * rs) * gq[bj][n] + bq_[bj][n]) * ALPHA_ + acc[ai][bj][m][n] * sc;
;                         *(f32x4*)(yp + 4 * n) = v[n]; s1 += (v[n][0] + v[n][1]) + (v[n][2] + v[n][3]); s2 += (v[n][0] * v[n][0] + v[n][1] * v[n][1]) + (v[n][2] * v[n][2] + v[n][3] * v[n][3]); }
;                     *(u32x4*)(Yb + blk_off(row, col0 + bj * 128, D_)) = pack8(v[0], v[1]); }
;                 s1 = xsum32(xsum16(s1)); s2 = xsum32(xsum16(s2));
;                 if (fq == 0) *(f32x2*)(stn + (size_t)row * 32 + (u.pn * 4 + wc) * 2) = (f32x2){s1, s2}; asm volatile("" ::: "memory"); } }
	v_sub_f32_e32 v91, v121, v123
	v_sub_f32_e32 v90, v120, v123
	v_sub_f32_e32 v93, v119, v123
	v_sub_f32_e32 v92, v118, v123
	v_pk_mul_f32 v[92:93], v[0:1], v[92:93] op_sel_hi:[0,1]
	v_pk_mul_f32 v[90:91], v[0:1], v[90:91] op_sel_hi:[0,1]
	s_waitcnt vmcnt(2)
	v_pk_fma_f32 v[90:91], v[112:113], v[90:91], v[116:117]
	v_pk_fma_f32 v[92:93], v[110:111], v[92:93], v[114:115]
	v_pk_mul_f32 v[90:91], v[90:91], s[2:3] op_sel_hi:[1,0]
	v_pk_mul_f32 v[92:93], v[92:93], s[2:3] op_sel_hi:[1,0]
	v_pk_fma_f32 v[88:89], v[88:89], 0.5, v[90:91] op_sel_hi:[1,0,1]
	v_pk_fma_f32 v[86:87], v[86:87], 0.5, v[92:93] op_sel_hi:[1,0,1]
	v_add_f32_e32 v130, 0, v130
	v_add_f32_e32 v90, v86, v87
	v_add_f32_e32 v91, v88, v89
	v_add_f32_e32 v126, v130, v126
	v_add_f32_e32 v90, v90, v91
	global_store_dwordx4 v122, v[94:97], s[48:49]
	v_mul_f32_e32 v91, v89, v89
	v_add_f32_e32 v131, v131, v132
	v_add_f32_e32 v94, v126, v90
	v_mul_f32_e32 v90, v87, v87
	v_add_f32_e32 v127, v127, v128
	v_fmac_f32_e32 v90, v86, v86
	v_fmac_f32_e32 v91, v88, v88
	v_add_f32_e32 v127, v131, v127
	v_add_f32_e32 v90, v90, v91
	v_add_f32_e32 v95, v127, v90
	v_sub_f32_e32 v91, v101, v123
	v_sub_f32_e32 v90, v100, v123
	v_sub_f32_e32 v93, v99, v123
	v_sub_f32_e32 v92, v98, v123
	v_pk_mul_f32 v[92:93], v[0:1], v[92:93] op_sel_hi:[0,1]
	v_pk_mul_f32 v[90:91], v[0:1], v[90:91] op_sel_hi:[0,1]
	v_pk_fma_f32 v[90:91], v[104:105], v[90:91], v[108:109]
	v_pk_fma_f32 v[92:93], v[102:103], v[92:93], v[106:107]
	v_pk_mul_f32 v[90:91], v[90:91], s[2:3] op_sel_hi:[1,0]
	v_pk_mul_f32 v[92:93], v[92:93], s[2:3] op_sel_hi:[1,0]
	v_pk_fma_f32 v[84:85], v[84:85], 0.5, v[90:91] op_sel_hi:[1,0,1]
	v_pk_fma_f32 v[82:83], v[82:83], 0.5, v[92:93] op_sel_hi:[1,0,1]
	v_add_f32_e32 v90, v84, v85
	v_add_f32_e32 v0, v82, v83
	v_add_f32_e32 v0, v0, v90
	v_mul_f32_e32 v90, v83, v83
	v_mul_f32_e32 v91, v85, v85
	v_add_f32_e32 v0, v94, v0
	v_fmac_f32_e32 v90, v82, v82
	v_fmac_f32_e32 v91, v84, v84
	s_nop 0
	s_nop 1
	v_bfe_u32 v93, v227, 4, 2
	v_sub_u32_e32 v92, 0, v93
	v_lshlrev_b32_e32 v92, 4, v92
	v_ashrrev_i32_e32 v93, 31, v92
	v_lshl_add_u64 v[92:93], v[124:125], 0, v[92:93]
	v_permlane16_swap_b32_e32 v86, v82
	v_permlane16_swap_b32_e32 v87, v83
	v_permlane16_swap_b32_e32 v88, v84
	v_permlane16_swap_b32_e32 v89, v85
	v_permlane32_swap_b32_e32 v86, v82
	v_permlane32_swap_b32_e32 v87, v83
	v_permlane32_swap_b32_e32 v88, v84
	v_permlane32_swap_b32_e32 v89, v85
	v_mov_b32_e32 v98, v86
	v_mov_b32_e32 v99, v87
	v_mov_b32_e32 v100, v88
	v_mov_b32_e32 v101, v89
	v_bfe_u32 v96, v227, 3, 1
	v_mul_i32_i24_e32 v96, 0xffff8040, v96
	v_ashrrev_i32_e32 v97, 31, v96
	v_lshl_add_u64 v[92:93], v[92:93], 0, v[96:97]
	v_mov_b32_e32 v96, 0x8000
	v_mov_b32_e32 v97, 0
	v_lshl_add_u64 v[96:97], v[92:93], 0, v[96:97]
	v_mov_b32_dpp v86, v82 row_ror:8 row_mask:0xf bank_mask:0xc
	v_mov_b32_dpp v87, v83 row_ror:8 row_mask:0xf bank_mask:0xc
	v_mov_b32_dpp v88, v84 row_ror:8 row_mask:0xf bank_mask:0xc
	v_mov_b32_dpp v89, v85 row_ror:8 row_mask:0xf bank_mask:0xc
	v_mov_b32_dpp v82, v98 row_ror:8 row_mask:0xf bank_mask:0x3
	v_mov_b32_dpp v83, v99 row_ror:8 row_mask:0xf bank_mask:0x3
	v_mov_b32_dpp v84, v100 row_ror:8 row_mask:0xf bank_mask:0x3
	v_mov_b32_dpp v85, v101 row_ror:8 row_mask:0xf bank_mask:0x3
	global_store_dwordx4 v[92:93], v[86:89], off offset:512 nt
	global_store_dwordx4 v[96:97], v[82:85], off offset:512 nt
	s_nop 1
	v_mov_b32_dpp v82, v86 row_ror:8 row_mask:0xf bank_mask:0x3
	v_mov_b32_dpp v83, v87 row_ror:8 row_mask:0xf bank_mask:0x3
	v_mov_b32_dpp v84, v88 row_ror:8 row_mask:0xf bank_mask:0x3
	v_mov_b32_dpp v85, v89 row_ror:8 row_mask:0xf bank_mask:0x3
	v_mov_b32_e32 v86, v98
	v_mov_b32_e32 v87, v99
	v_mov_b32_e32 v88, v100
	v_mov_b32_e32 v89, v101
	s_nop 1
	v_permlane32_swap_b32_e32 v86, v82
	v_permlane32_swap_b32_e32 v87, v83
	v_permlane32_swap_b32_e32 v88, v84
	v_permlane32_swap_b32_e32 v89, v85
	v_permlane16_swap_b32_e32 v86, v82
	v_permlane16_swap_b32_e32 v87, v83
	v_permlane16_swap_b32_e32 v88, v84
	v_permlane16_swap_b32_e32 v89, v85
	v_add_f32_e32 v90, v90, v91
	v_cvt_pk_bf16_f32 v86, v86, v87
	v_cvt_pk_bf16_f32 v87, v88, v89
	v_cvt_pk_bf16_f32 v88, v82, v83
	v_mov_b32_e32 v82, v0
	v_add_f32_e32 v90, v95, v90
	s_nop 0
	v_permlane16_swap_b32_e32 v0, v82
	v_add_f32_e32 v82, v0, v82
	v_mov_b32_e32 v0, v90
	s_nop 1
	v_permlane16_swap_b32_e32 v90, v0
	v_add_f32_e32 v83, v90, v0
	v_cvt_pk_bf16_f32 v89, v84, v85
	v_mov_b32_e32 v84, v82
	v_mov_b32_e32 v85, v83
	s_nop 0
	v_permlane32_swap_b32_e32 v82, v84
	v_permlane32_swap_b32_e32 v83, v85
	global_store_dwordx4 v122, v[86:89], s[46:47]
	s_and_saveexec_b64 s[26:27], s[40:41]
	s_cbranch_execz .LBB0_1709
	v_pk_add_f32 v[82:83], v[82:83], v[84:85]
	v_lshl_add_u64 v[84:85], s[8:9], 0, v[164:165]
	v_lshl_add_u64 v[84:85], s[38:39], 2, v[84:85]
	global_store_dwordx2 v[84:85], v[82:83], off
; __device__ __forceinline__ size_t blk_off(int r, int c, int K) { return (size_t)(r >> 8) * 256 * K + (size_t)(c >> 6) * (256 * 64) + (size_t)((r & 255) * 64 + (c & 63)); }
; __device__ __forceinline__ u32x4 pack8(const f32x4 a, const f32x4 b) { u32x4 w; w.x = cvt_pk_bf16(a[0], a[1]); w.y = cvt_pk_bf16(a[2], a[3]); w.z = cvt_pk_bf16(b[0], b[1]); w.w = cvt_pk_bf16(b[2], b[3]); return w; }
;     __device__ __forceinline__ void operator()(const f32x4 (&acc)[2][2][4][2], const pg8::Unit& u, int wr, int wc, int fr, int fq) const {
;     ...
;             for (int m = 0; m < 4; ++m) { const int row = row0 + ai * 128 + m * 16; const float mu = mu4[m], rs = rs4[m];
;                 f32x4 yv[2][2], gq[2][2], bq_[2][2];
; #pragma unroll
;                 for (int bj = 0; bj < 2; ++bj)
; #pragma unroll
;                     for (int n = 0; n < 2; ++n) { yv[bj][n] = *(const f32x4*)(Yin + (size_t)row * D_ + col0 + bj * 128 + 4 * n); gq[bj][n] = *(const f32x4*)(g + col0 + bj * 128 + 4 * n); bq_[bj][n] = *(const f32x4*)(b + col0 + bj * 128 + 4 * n); }
;                 asm volatile("" ::: "memory");
;                 float s1 = 0.f, s2 = 0.f;
; #pragma unroll
;                 for (int bj = 0; bj < 2; ++bj) { float* yp = Y + (size_t)row * D_ + col0 + bj * 128; f32x4 v[2];
; #pragma unroll
;                     for (int n = 0; n < 2; ++n) { v[n] = (((yv[bj][n] - mu) * rs) * gq[bj][n] + bq_[bj][n]) * ALPHA_ + acc[ai][bj][m][n] * sc;
;                         *(f32x4*)(yp + 4 * n) = v[n]; s1 += (v[n][0] + v[n][1]) + (v[n][2] + v[n][3]); s2 += (v[n][0] * v[n][0] + v[n][1] * v[n][1]) + (v[n][2] * v[n][2] + v[n][3] * v[n][3]); }
;                     *(u32x4*)(Yb + blk_off(row, col0 + bj * 128, D_)) = pack8(v[0], v[1]); }
.LBB0_1709:
	s_or_b64 exec, exec, s[26:27]
	v_pk_add_f32 v[82:83], v[166:167], v[168:169]
	s_mov_b32 s2, 0x3a800000
	v_pk_mul_f32 v[106:107], v[82:83], s[2:3] op_sel_hi:[1,0]
	s_mov_b32 s1, 0x800000
	v_fma_f32 v0, -v107, v107, v106
	v_max_f32_e32 v0, 0, v0
	v_add_f32_e32 v0, 0x3727c5ac, v0
	v_cmp_gt_f32_e32 vcc, s1, v0
	v_mul_f32_e32 v82, 0x4b800000, v0
	s_load_dwordx16 s[60:75], s[34:35], 0x38
	v_cndmask_b32_e32 v0, v0, v82, vcc
	v_rsq_f32_e32 v0, v0
	s_mov_b32 s2, 0x3fd744fd
	v_lshlrev_b32_e32 v106, 6, v162
	v_mul_f32_e32 v82, 0x45800000, v0
	v_cndmask_b32_e32 v0, v0, v82, vcc
	v_lshlrev_b64 v[82:83], 12, v[162:163]
	s_waitcnt lgkmcnt(0)
	v_lshl_add_u64 v[82:83], s[74:75], 0, v[82:83]
	v_lshl_add_u64 v[108:109], v[152:153], 2, v[82:83]
	global_load_dwordx4 v[110:113], v[108:109], off offset:16
	global_load_dwordx4 v[114:117], v[108:109], off
	global_load_dwordx4 v[118:121], v[156:157], off offset:16
	global_load_dwordx4 v[122:125], v[156:157], off
	global_load_dwordx4 v[126:129], v[154:155], off offset:16
	global_load_dwordx4 v[130:133], v[154:155], off
	global_load_dwordx4 v[82:85], v[108:109], off offset:528
	global_load_dwordx4 v[102:105], v[108:109], off offset:512
	global_load_dwordx4 v[86:89], v[156:157], off offset:528
	global_load_dwordx4 v[94:97], v[156:157], off offset:512
	global_load_dwordx4 v[90:93], v[154:155], off offset:528
	global_load_dwordx4 v[98:101], v[154:155], off offset:512
	s_movk_i32 s1, 0x3fc0
	v_and_or_b32 v106, v106, s1, v196
	v_lshlrev_b32_e32 v106, 1, v106
	s_waitcnt vmcnt(11)
	v_sub_f32_e32 v113, v113, v107
	s_waitcnt vmcnt(10)
	v_sub_f32_e32 v117, v117, v107
	v_sub_f32_e32 v116, v116, v107
	v_sub_f32_e32 v115, v115, v107
	v_sub_f32_e32 v114, v114, v107
	v_sub_f32_e32 v112, v112, v107
	v_sub_f32_e32 v111, v111, v107
	v_sub_f32_e32 v110, v110, v107
	v_pk_mul_f32 v[114:115], v[0:1], v[114:115] op_sel_hi:[0,1]
	v_pk_mul_f32 v[116:117], v[0:1], v[116:117] op_sel_hi:[0,1]
	v_pk_mul_f32 v[110:111], v[0:1], v[110:111] op_sel_hi:[0,1]
	v_pk_mul_f32 v[112:113], v[0:1], v[112:113] op_sel_hi:[0,1]
	s_waitcnt vmcnt(6)
	v_pk_fma_f32 v[116:117], v[124:125], v[116:117], v[132:133]
	v_pk_fma_f32 v[114:115], v[122:123], v[114:115], v[130:131]
	v_pk_fma_f32 v[112:113], v[120:121], v[112:113], v[128:129]
	v_pk_fma_f32 v[110:111], v[118:119], v[110:111], v[126:127]
	v_pk_mul_f32 v[114:115], v[114:115], s[2:3] op_sel_hi:[1,0]
	v_pk_mul_f32 v[116:117], v[116:117], s[2:3] op_sel_hi:[1,0]
	v_pk_mul_f32 v[110:111], v[110:111], s[2:3] op_sel_hi:[1,0]
	v_pk_mul_f32 v[112:113], v[112:113], s[2:3] op_sel_hi:[1,0]
	v_pk_fma_f32 v[80:81], v[80:81], 0.5, v[116:117] op_sel_hi:[1,0,1]
	v_pk_fma_f32 v[78:79], v[78:79], 0.5, v[114:115] op_sel_hi:[1,0,1]
	v_pk_fma_f32 v[76:77], v[76:77], 0.5, v[112:113] op_sel_hi:[1,0,1]
	v_pk_fma_f32 v[74:75], v[74:75], 0.5, v[110:111] op_sel_hi:[1,0,1]
	v_add_f32_e32 v114, v78, v79
	v_add_f32_e32 v115, v80, v81
	v_add_f32_e32 v110, v74, v75
	v_add_f32_e32 v111, v76, v77
	v_add_f32_e32 v114, v114, v115
	v_mul_f32_e32 v115, v79, v79
	v_mul_f32_e32 v116, v81, v81
	v_add_f32_e32 v110, v110, v111
	v_mul_f32_e32 v111, v75, v75
	v_mul_f32_e32 v112, v77, v77
	s_nop 0
	v_fmac_f32_e32 v115, v78, v78
	v_fmac_f32_e32 v116, v80, v80
	s_nop 1
	v_bfe_u32 v119, v227, 4, 2
	v_sub_u32_e32 v118, 0, v119
	v_lshlrev_b32_e32 v118, 4, v118
	v_ashrrev_i32_e32 v119, 31, v118
	v_lshl_add_u64 v[118:119], v[108:109], 0, v[118:119]
	v_permlane16_swap_b32_e32 v78, v74
	v_permlane16_swap_b32_e32 v79, v75
	v_permlane16_swap_b32_e32 v80, v76
	v_permlane16_swap_b32_e32 v81, v77
	v_permlane32_swap_b32_e32 v78, v74
	v_permlane32_swap_b32_e32 v79, v75
	v_permlane32_swap_b32_e32 v80, v76
	v_permlane32_swap_b32_e32 v81, v77
	v_mov_b32_e32 v113, v78
	v_mov_b32_e32 v117, v79
	v_mov_b32_e32 v122, v80
	v_mov_b32_e32 v123, v81
	v_bfe_u32 v120, v227, 3, 1
	v_mul_i32_i24_e32 v120, 0xffff8040, v120
	v_ashrrev_i32_e32 v121, 31, v120
	v_lshl_add_u64 v[118:119], v[118:119], 0, v[120:121]
	v_mov_b32_e32 v120, 0x8000
	v_mov_b32_e32 v121, 0
	v_lshl_add_u64 v[120:121], v[118:119], 0, v[120:121]
	v_mov_b32_dpp v78, v74 row_ror:8 row_mask:0xf bank_mask:0xc
	v_mov_b32_dpp v79, v75 row_ror:8 row_mask:0xf bank_mask:0xc
	v_mov_b32_dpp v80, v76 row_ror:8 row_mask:0xf bank_mask:0xc
	v_mov_b32_dpp v81, v77 row_ror:8 row_mask:0xf bank_mask:0xc
	v_mov_b32_dpp v74, v113 row_ror:8 row_mask:0xf bank_mask:0x3
	v_mov_b32_dpp v75, v117 row_ror:8 row_mask:0xf bank_mask:0x3
	v_mov_b32_dpp v76, v122 row_ror:8 row_mask:0xf bank_mask:0x3
	v_mov_b32_dpp v77, v123 row_ror:8 row_mask:0xf bank_mask:0x3
	global_store_dwordx4 v[118:119], v[78:81], off nt
	global_store_dwordx4 v[120:121], v[74:77], off nt
	s_nop 1
	v_mov_b32_dpp v74, v78 row_ror:8 row_mask:0xf bank_mask:0x3
	v_mov_b32_dpp v75, v79 row_ror:8 row_mask:0xf bank_mask:0x3
	v_mov_b32_dpp v76, v80 row_ror:8 row_mask:0xf bank_mask:0x3
	v_mov_b32_dpp v77, v81 row_ror:8 row_mask:0xf bank_mask:0x3
	v_mov_b32_e32 v78, v113
	v_mov_b32_e32 v79, v117
	v_mov_b32_e32 v80, v122
	v_mov_b32_e32 v81, v123
	s_nop 1
	v_permlane32_swap_b32_e32 v78, v74
	v_permlane32_swap_b32_e32 v79, v75
	v_permlane32_swap_b32_e32 v80, v76
	v_permlane32_swap_b32_e32 v81, v77
	v_permlane16_swap_b32_e32 v78, v74
	v_permlane16_swap_b32_e32 v79, v75
	v_permlane16_swap_b32_e32 v80, v76
	v_permlane16_swap_b32_e32 v81, v77
	v_fmac_f32_e32 v111, v74, v74
	v_fmac_f32_e32 v112, v76, v76
	v_cvt_pk_bf16_f32 v78, v78, v79
	v_cvt_pk_bf16_f32 v79, v80, v81
	v_cvt_pk_bf16_f32 v80, v74, v75
	v_cvt_pk_bf16_f32 v81, v76, v77
	s_waitcnt vmcnt(6)
	v_sub_f32_e32 v75, v105, v107
	v_sub_f32_e32 v74, v104, v107
	v_sub_f32_e32 v77, v103, v107
	v_sub_f32_e32 v76, v102, v107
	v_pk_mul_f32 v[76:77], v[0:1], v[76:77] op_sel_hi:[0,1]
	v_pk_mul_f32 v[74:75], v[0:1], v[74:75] op_sel_hi:[0,1]
	s_waitcnt vmcnt(2)
; __device__ __forceinline__ float xsum16(float v) { const auto r = __builtin_amdgcn_permlane16_swap(__float_as_uint(v), __float_as_uint(v), false, false); return __uint_as_float(r[0]) + __uint_as_float(r[1]); }
; __device__ __forceinline__ float xsum32(float v) { const auto r = __builtin_amdgcn_permlane32_swap(__float_as_uint(v), __float_as_uint(v), false, false); return __uint_as_float(r[0]) + __uint_as_float(r[1]); }
; __device__ __forceinline__ size_t blk_off(int r, int c, int K) { return (size_t)(r >> 8) * 256 * K + (size_t)(c >> 6) * (256 * 64) + (size_t)((r & 255) * 64 + (c & 63)); }
; __device__ __forceinline__ u32x4 pack8(const f32x4 a, const f32x4 b) { u32x4 w; w.x = cvt_pk_bf16(a[0], a[1]); w.y = cvt_pk_bf16(a[2], a[3]); w.z = cvt_pk_bf16(b[0], b[1]); w.w = cvt_pk_bf16(b[2], b[3]); return w; }
;     __device__ __forceinline__ void operator()(const f32x4 (&acc)[2][2][4][2], const pg8::Unit& u, int wr, int wc, int fr, int fq) const {
;     ...
;                 for (int bj = 0; bj < 2; ++bj) { float* yp = Y + (size_t)row * D_ + col0 + bj * 128; f32x4 v[2];
; #pragma unroll
;                     for (int n = 0; n < 2; ++n) { v[n] = (((yv[bj][n] - mu) * rs) * gq[bj][n] + bq_[bj][n]) * ALPHA_ + acc[ai][bj][m][n] * sc;
;                         *(f32x4*)(yp + 4 * n) = v[n]; s1 += (v[n][0] + v[n][1]) + (v[n][2] + v[n][3]); s2 += (v[n][0] * v[n][0] + v[n][1] * v[n][1]) + (v[n][2] * v[n][2] + v[n][3] * v[n][3]); }
;                     *(u32x4*)(Yb + blk_off(row, col0 + bj * 128, D_)) = pack8(v[0], v[1]); }
;                 s1 = xsum32(xsum16(s1)); s2 = xsum32(xsum16(s2));
;                 if (fq == 0) *(f32x2*)(stn + (size_t)row * 32 + (u.pn * 4 + wc) * 2) = (f32x2){s1, s2}; asm volatile("" ::: "memory"); } }
	v_pk_fma_f32 v[74:75], v[96:97], v[74:75], v[100:101]
	v_pk_fma_f32 v[76:77], v[94:95], v[76:77], v[98:99]
	v_pk_mul_f32 v[74:75], v[74:75], s[2:3] op_sel_hi:[1,0]
	v_pk_mul_f32 v[76:77], v[76:77], s[2:3] op_sel_hi:[1,0]
	v_pk_fma_f32 v[72:73], v[72:73], 0.5, v[74:75] op_sel_hi:[1,0,1]
	v_pk_fma_f32 v[70:71], v[70:71], 0.5, v[76:77] op_sel_hi:[1,0,1]
	v_add_f32_e32 v114, 0, v114
	v_add_f32_e32 v74, v70, v71
	v_add_f32_e32 v75, v72, v73
	v_add_f32_e32 v110, v114, v110
	v_add_f32_e32 v74, v74, v75
	global_store_dwordx4 v106, v[78:81], s[48:49]
	v_mul_f32_e32 v75, v73, v73
	v_add_f32_e32 v115, v115, v116
	v_add_f32_e32 v78, v110, v74
	v_mul_f32_e32 v74, v71, v71
	v_add_f32_e32 v111, v111, v112
	v_fmac_f32_e32 v74, v70, v70
	v_fmac_f32_e32 v75, v72, v72
	v_add_f32_e32 v111, v115, v111
	v_add_f32_e32 v74, v74, v75
	v_add_f32_e32 v79, v111, v74
	v_sub_f32_e32 v75, v85, v107
	v_sub_f32_e32 v74, v84, v107
	v_sub_f32_e32 v77, v83, v107
	v_sub_f32_e32 v76, v82, v107
	v_pk_mul_f32 v[76:77], v[0:1], v[76:77] op_sel_hi:[0,1]
	v_pk_mul_f32 v[74:75], v[0:1], v[74:75] op_sel_hi:[0,1]
	v_pk_fma_f32 v[74:75], v[88:89], v[74:75], v[92:93]
	v_pk_fma_f32 v[76:77], v[86:87], v[76:77], v[90:91]
	v_pk_mul_f32 v[74:75], v[74:75], s[2:3] op_sel_hi:[1,0]
	v_pk_mul_f32 v[76:77], v[76:77], s[2:3] op_sel_hi:[1,0]
	v_pk_fma_f32 v[68:69], v[68:69], 0.5, v[74:75] op_sel_hi:[1,0,1]
	v_pk_fma_f32 v[66:67], v[66:67], 0.5, v[76:77] op_sel_hi:[1,0,1]
	v_add_f32_e32 v74, v68, v69
	v_add_f32_e32 v0, v66, v67
	v_add_f32_e32 v0, v0, v74
	v_mul_f32_e32 v74, v67, v67
	v_mul_f32_e32 v75, v69, v69
	v_add_f32_e32 v0, v78, v0
	v_fmac_f32_e32 v74, v66, v66
	v_fmac_f32_e32 v75, v68, v68
	s_nop 0
	s_nop 1
	v_bfe_u32 v77, v227, 4, 2
	v_sub_u32_e32 v76, 0, v77
	v_lshlrev_b32_e32 v76, 4, v76
	v_ashrrev_i32_e32 v77, 31, v76
	v_lshl_add_u64 v[76:77], v[108:109], 0, v[76:77]
	v_permlane16_swap_b32_e32 v70, v66
	v_permlane16_swap_b32_e32 v71, v67
	v_permlane16_swap_b32_e32 v72, v68
	v_permlane16_swap_b32_e32 v73, v69
	v_permlane32_swap_b32_e32 v70, v66
	v_permlane32_swap_b32_e32 v71, v67
	v_permlane32_swap_b32_e32 v72, v68
	v_permlane32_swap_b32_e32 v73, v69
	v_mov_b32_e32 v82, v70
	v_mov_b32_e32 v83, v71
	v_mov_b32_e32 v84, v72
	v_mov_b32_e32 v85, v73
	v_bfe_u32 v80, v227, 3, 1
	v_mul_i32_i24_e32 v80, 0xffff8040, v80
	v_ashrrev_i32_e32 v81, 31, v80
	v_lshl_add_u64 v[76:77], v[76:77], 0, v[80:81]
	v_mov_b32_e32 v80, 0x8000
	v_mov_b32_e32 v81, 0
	v_lshl_add_u64 v[80:81], v[76:77], 0, v[80:81]
	v_mov_b32_dpp v70, v66 row_ror:8 row_mask:0xf bank_mask:0xc
	v_mov_b32_dpp v71, v67 row_ror:8 row_mask:0xf bank_mask:0xc
	v_mov_b32_dpp v72, v68 row_ror:8 row_mask:0xf bank_mask:0xc
	v_mov_b32_dpp v73, v69 row_ror:8 row_mask:0xf bank_mask:0xc
	v_mov_b32_dpp v66, v82 row_ror:8 row_mask:0xf bank_mask:0x3
	v_mov_b32_dpp v67, v83 row_ror:8 row_mask:0xf bank_mask:0x3
	v_mov_b32_dpp v68, v84 row_ror:8 row_mask:0xf bank_mask:0x3
	v_mov_b32_dpp v69, v85 row_ror:8 row_mask:0xf bank_mask:0x3
	global_store_dwordx4 v[76:77], v[70:73], off offset:512 nt
	global_store_dwordx4 v[80:81], v[66:69], off offset:512 nt
	s_nop 1
	v_mov_b32_dpp v66, v70 row_ror:8 row_mask:0xf bank_mask:0x3
	v_mov_b32_dpp v67, v71 row_ror:8 row_mask:0xf bank_mask:0x3
	v_mov_b32_dpp v68, v72 row_ror:8 row_mask:0xf bank_mask:0x3
	v_mov_b32_dpp v69, v73 row_ror:8 row_mask:0xf bank_mask:0x3
	v_mov_b32_e32 v70, v82
	v_mov_b32_e32 v71, v83
	v_mov_b32_e32 v72, v84
	v_mov_b32_e32 v73, v85
	s_nop 1
	v_permlane32_swap_b32_e32 v70, v66
	v_permlane32_swap_b32_e32 v71, v67
	v_permlane32_swap_b32_e32 v72, v68
	v_permlane32_swap_b32_e32 v73, v69
	v_permlane16_swap_b32_e32 v70, v66
	v_permlane16_swap_b32_e32 v71, v67
	v_permlane16_swap_b32_e32 v72, v68
	v_permlane16_swap_b32_e32 v73, v69
	v_add_f32_e32 v74, v74, v75
	v_cvt_pk_bf16_f32 v70, v70, v71
	v_cvt_pk_bf16_f32 v71, v72, v73
	v_cvt_pk_bf16_f32 v72, v66, v67
	v_mov_b32_e32 v66, v0
	v_add_f32_e32 v74, v79, v74
	s_nop 0
	v_permlane16_swap_b32_e32 v0, v66
	v_add_f32_e32 v66, v0, v66
	v_mov_b32_e32 v0, v74
	s_nop 1
	v_permlane16_swap_b32_e32 v74, v0
	v_add_f32_e32 v67, v74, v0
	v_cvt_pk_bf16_f32 v73, v68, v69
	v_mov_b32_e32 v68, v66
	v_mov_b32_e32 v69, v67
	s_nop 0
	v_permlane32_swap_b32_e32 v66, v68
	v_permlane32_swap_b32_e32 v67, v69
	global_store_dwordx4 v106, v[70:73], s[46:47]
	s_and_saveexec_b64 s[26:27], s[40:41]
	s_cbranch_execz .LBB0_1711
	v_pk_add_f32 v[66:67], v[66:67], v[68:69]
	v_lshl_add_u64 v[68:69], s[8:9], 0, v[160:161]
	v_lshl_add_u64 v[68:69], s[38:39], 2, v[68:69]
	global_store_dwordx2 v[68:69], v[66:67], off
; __device__ __forceinline__ float xsum16(float v) { const auto r = __builtin_amdgcn_permlane16_swap(__float_as_uint(v), __float_as_uint(v), false, false); return __uint_as_float(r[0]) + __uint_as_float(r[1]); }
; __device__ __forceinline__ float xsum32(float v) { const auto r = __builtin_amdgcn_permlane32_swap(__float_as_uint(v), __float_as_uint(v), false, false); return __uint_as_float(r[0]) + __uint_as_float(r[1]); }
; __device__ __forceinline__ void row_stats4(const float* st, int rowb, int fq, float (&mu)[4], float (&rs)[4]) {
;     f32x4 a[4], b[4];
; #pragma unroll
;     for (int m = 0; m < 4; ++m) { const f32x4* p = (const f32x4*)(st + (size_t)(rowb + m * 16) * 32 + fq * 8); a[m] = p[0]; b[m] = p[1]; }
; #pragma unroll
;     for (int m = 0; m < 4; ++m) { float s1 = (a[m][0] + a[m][2]) + (b[m][0] + b[m][2]), s2 = (a[m][1] + a[m][3]) + (b[m][1] + b[m][3]);
;         s1 = xsum32(xsum16(s1)); s2 = xsum32(xsum16(s2));
;         const float mm = s1 * (1.0f / 1024.0f); mu[m] = mm; rs[m] = rsqrtf(fmaxf(s2 * (1.0f / 1024.0f) - mm * mm, 0.f) + LN_EPS_); }
;     __device__ __forceinline__ void operator()(const f32x4 (&acc)[2][2][4][2], const pg8::Unit& u, int wr, int wc, int fr, int fq) const {
;     ...
;             for (int m = 0; m < 4; ++m) { const int row = row0 + ai * 128 + m * 16; const float mu = mu4[m], rs = rs4[m];
;                 f32x4 yv[2][2], gq[2][2], bq_[2][2];
; #pragma unroll
;                 for (int bj = 0; bj < 2; ++bj)
; #pragma unroll
;                     for (int n = 0; n < 2; ++n) { yv[bj][n] = *(const f32x4*)(Yin + (size_t)row * D_ + col0 + bj * 128 + 4 * n); gq[bj][n] = *(const f32x4*)(g + col0 + bj * 128 + 4 * n); bq_[bj][n] = *(const f32x4*)(b + col0 + bj * 128 + 4 * n); }
;                 asm volatile("" ::: "memory");
;                 float s1 = 0.f, s2 = 0.f;
; #pragma unroll
;                 for (int bj = 0; bj < 2; ++bj) { float* yp = Y + (size_t)row * D_ + col0 + bj * 128; f32x4 v[2];
; #pragma unroll
;                     for (int n = 0; n < 2; ++n) { v[n] = (((yv[bj][n] - mu) * rs) * gq[bj][n] + bq_[bj][n]) * ALPHA_ + acc[ai][bj][m][n] * sc;
;                         *(f32x4*)(yp + 4 * n) = v[n]; s1 += (v[n][0] + v[n][1]) + (v[n][2] + v[n][3]); s2 += (v[n][0] * v[n][0] + v[n][1] * v[n][1]) + (v[n][2] * v[n][2] + v[n][3] * v[n][3]); }
.LBB0_1711:
	s_or_b64 exec, exec, s[26:27]
	v_add_u32_e32 v68, 0x80, v158
	v_ashrrev_i32_e32 v69, 31, v68
	v_lshlrev_b64 v[66:67], 7, v[68:69]
	v_lshl_add_u64 v[74:75], v[146:147], 0, v[66:67]
	v_add_u32_e32 v96, 0x90, v158
	global_load_dwordx4 v[70:73], v[74:75], off
	global_load_dwordx4 v[82:85], v[74:75], off offset:16
	v_ashrrev_i32_e32 v97, 31, v96
	v_lshlrev_b64 v[86:87], 7, v[96:97]
	v_add_u32_e32 v80, 0xa0, v158
	v_lshl_add_u64 v[74:75], v[146:147], 0, v[86:87]
	v_ashrrev_i32_e32 v81, 31, v80
	global_load_dwordx4 v[88:91], v[74:75], off
	global_load_dwordx4 v[92:95], v[74:75], off offset:16
	v_lshlrev_b64 v[74:75], 7, v[80:81]
	v_lshl_add_u64 v[74:75], v[146:147], 0, v[74:75]
	global_load_dwordx4 v[98:101], v[74:75], off
	global_load_dwordx4 v[102:105], v[74:75], off offset:16
	v_add_u32_e32 v74, 0xb0, v158
	v_ashrrev_i32_e32 v75, 31, v74
	v_lshlrev_b64 v[76:77], 7, v[74:75]
	v_lshl_add_u64 v[76:77], v[146:147], 0, v[76:77]
	global_load_dwordx4 v[106:109], v[76:77], off
	global_load_dwordx4 v[110:113], v[76:77], off offset:16
	s_load_dwordx16 s[60:75], s[34:35], 0x38
	v_lshlrev_b64 v[78:79], 12, v[68:69]
	s_mov_b32 s2, 0x3a800000
	s_mov_b32 s1, 0x800000
	s_waitcnt lgkmcnt(0)
	v_lshl_add_u64 v[78:79], s[74:75], 0, v[78:79]
	v_lshl_add_u64 v[76:77], v[152:153], 2, v[78:79]
	global_load_dwordx4 v[114:117], v[76:77], off offset:16
	global_load_dwordx4 v[118:121], v[76:77], off
	global_load_dwordx4 v[122:125], v[156:157], off offset:16
	global_load_dwordx4 v[126:129], v[156:157], off
	global_load_dwordx4 v[130:133], v[154:155], off offset:16
	global_load_dwordx4 v[134:137], v[154:155], off
	s_mov_b32 s16, 0x3fd744fd
	s_waitcnt vmcnt(13)
	v_mov_b32_e32 v78, v70
	s_waitcnt vmcnt(12)
	v_mov_b32_e32 v79, v82
	v_mov_b32_e32 v158, v72
	v_mov_b32_e32 v159, v84
	v_mov_b32_e32 v82, v71
	v_mov_b32_e32 v84, v73
	v_pk_add_f32 v[78:79], v[78:79], v[158:159]
	v_pk_add_f32 v[82:83], v[82:83], v[84:85]
	v_pk_add_f32 v[78:79], v[78:79], v[78:79] op_sel:[0,1] op_sel_hi:[1,0]
	v_pk_add_f32 v[82:83], v[82:83], v[82:83] op_sel:[0,1] op_sel_hi:[1,0]
	v_mov_b32_e32 v0, v78
	v_mov_b32_e32 v69, v82
	s_nop 0
	v_permlane16_swap_b32_e32 v78, v0
	v_permlane16_swap_b32_e32 v82, v69
	v_add_f32_e32 v79, v78, v0
	v_add_f32_e32 v78, v82, v69
	v_mov_b32_e32 v83, v79
	v_mov_b32_e32 v82, v78
	s_waitcnt vmcnt(11)
	v_mov_b32_e32 v70, v88
	s_waitcnt vmcnt(10)
	v_mov_b32_e32 v71, v92
	v_mov_b32_e32 v72, v90
	v_mov_b32_e32 v73, v94
	v_mov_b32_e32 v92, v89
	v_mov_b32_e32 v94, v91
	v_permlane32_swap_b32_e32 v79, v83
	v_permlane32_swap_b32_e32 v78, v82
	s_waitcnt vmcnt(9)
	v_mov_b32_e32 v88, v98
	s_waitcnt vmcnt(8)
	v_mov_b32_e32 v89, v102
	v_mov_b32_e32 v90, v100
	v_mov_b32_e32 v91, v104
	v_mov_b32_e32 v102, v99
	v_mov_b32_e32 v104, v101
	v_pk_add_f32 v[70:71], v[70:71], v[72:73]
	v_pk_add_f32 v[72:73], v[92:93], v[94:95]
	v_pk_add_f32 v[78:79], v[78:79], v[82:83]
	global_load_dwordx4 v[92:95], v[76:77], off offset:528
	global_load_dwordx4 v[98:101], v[76:77], off offset:512
	v_pk_mul_f32 v[162:163], v[78:79], s[2:3] op_sel_hi:[1,0]
	s_waitcnt vmcnt(9)
	v_mov_b32_e32 v78, v106
	s_waitcnt vmcnt(8)
	v_mov_b32_e32 v79, v110
	v_mov_b32_e32 v82, v108
	v_mov_b32_e32 v83, v112
	v_mov_b32_e32 v110, v107
	v_mov_b32_e32 v112, v109
	v_pk_add_f32 v[84:85], v[88:89], v[90:91]
	v_pk_add_f32 v[88:89], v[102:103], v[104:105]
	v_pk_add_f32 v[78:79], v[78:79], v[82:83]
	v_pk_add_f32 v[82:83], v[110:111], v[112:113]
	global_load_dwordx4 v[102:105], v[156:157], off offset:528
	global_load_dwordx4 v[106:109], v[156:157], off offset:512
	global_load_dwordx4 v[110:113], v[154:155], off offset:528
	global_load_dwordx4 v[158:161], v[154:155], off offset:512
	v_fma_f32 v0, -v163, v163, v162
	v_max_f32_e32 v0, 0, v0
	v_add_f32_e32 v0, 0x3727c5ac, v0
	v_mul_f32_e32 v69, 0x4b800000, v0
	v_cmp_gt_f32_e32 vcc, s1, v0
	v_pk_add_f32 v[88:89], v[88:89], v[88:89] op_sel:[0,1] op_sel_hi:[1,0]
	v_pk_add_f32 v[78:79], v[78:79], v[78:79] op_sel:[0,1] op_sel_hi:[1,0]
	v_cndmask_b32_e32 v0, v0, v69, vcc
	v_rsq_f32_e32 v0, v0
	v_pk_add_f32 v[82:83], v[82:83], v[82:83] op_sel:[0,1] op_sel_hi:[1,0]
	s_waitcnt vmcnt(10)
	v_sub_f32_e32 v119, v119, v163
	v_sub_f32_e32 v118, v118, v163
	v_mul_f32_e32 v69, 0x45800000, v0
	v_cndmask_b32_e32 v162, v0, v69, vcc
	v_mov_b32_e32 v0, v88
	s_nop 1
	v_permlane16_swap_b32_e32 v88, v0
	v_add_f32_e32 v88, v88, v0
	v_mov_b32_e32 v0, v78
	s_nop 1
	v_permlane16_swap_b32_e32 v78, v0
	v_add_f32_e32 v83, v78, v0
	v_mov_b32_e32 v0, v82
	s_nop 1
	v_permlane16_swap_b32_e32 v82, v0
	v_add_f32_e32 v82, v82, v0
	v_ashrrev_i32_e32 v78, 8, v68
	v_lshlrev_b32_e32 v0, 6, v68
	v_sub_f32_e32 v69, v121, v163
	v_sub_f32_e32 v68, v120, v163
	v_pk_mul_f32 v[118:119], v[162:163], v[118:119] op_sel_hi:[0,1]
	v_pk_mul_f32 v[68:69], v[162:163], v[68:69] op_sel_hi:[0,1]
	s_waitcnt vmcnt(6)
; __device__ __forceinline__ size_t blk_off(int r, int c, int K) { return (size_t)(r >> 8) * 256 * K + (size_t)(c >> 6) * (256 * 64) + (size_t)((r & 255) * 64 + (c & 63)); }
; __device__ __forceinline__ u32x4 pack8(const f32x4 a, const f32x4 b) { u32x4 w; w.x = cvt_pk_bf16(a[0], a[1]); w.y = cvt_pk_bf16(a[2], a[3]); w.z = cvt_pk_bf16(b[0], b[1]); w.w = cvt_pk_bf16(b[2], b[3]); return w; }
;     __device__ __forceinline__ void operator()(const f32x4 (&acc)[2][2][4][2], const pg8::Unit& u, int wr, int wc, int fr, int fq) const {
;     ...
;                 for (int bj = 0; bj < 2; ++bj) { float* yp = Y + (size_t)row * D_ + col0 + bj * 128; f32x4 v[2];
; #pragma unroll
;                     for (int n = 0; n < 2; ++n) { v[n] = (((yv[bj][n] - mu) * rs) * gq[bj][n] + bq_[bj][n]) * ALPHA_ + acc[ai][bj][m][n] * sc;
;                         *(f32x4*)(yp + 4 * n) = v[n]; s1 += (v[n][0] + v[n][1]) + (v[n][2] + v[n][3]); s2 += (v[n][0] * v[n][0] + v[n][1] * v[n][1]) + (v[n][2] * v[n][2] + v[n][3] * v[n][3]); }
;                     *(u32x4*)(Yb + blk_off(row, col0 + bj * 128, D_)) = pack8(v[0], v[1]); }
	v_pk_fma_f32 v[68:69], v[128:129], v[68:69], v[136:137]
	v_pk_fma_f32 v[118:119], v[126:127], v[118:119], v[134:135]
	v_pk_mul_f32 v[68:69], v[68:69], s[16:17] op_sel_hi:[1,0]
	v_pk_mul_f32 v[118:119], v[118:119], s[16:17] op_sel_hi:[1,0]
	v_pk_fma_f32 v[64:65], v[64:65], 0.5, v[68:69] op_sel_hi:[1,0,1]
	v_pk_fma_f32 v[62:63], v[62:63], 0.5, v[118:119] op_sel_hi:[1,0,1]
	v_add_f32_e32 v69, v64, v65
	v_add_f32_e32 v68, v62, v63
	v_add_f32_e32 v68, v68, v69
	v_add_f32_e32 v118, 0, v68
	v_mul_f32_e32 v68, v63, v63
	v_mul_f32_e32 v69, v65, v65
	v_fmac_f32_e32 v68, v62, v62
	v_fmac_f32_e32 v69, v64, v64
	v_add_f32_e32 v119, v68, v69
	v_sub_f32_e32 v69, v117, v163
	v_sub_f32_e32 v68, v116, v163
	v_sub_f32_e32 v115, v115, v163
	v_sub_f32_e32 v114, v114, v163
	v_pk_mul_f32 v[114:115], v[162:163], v[114:115] op_sel_hi:[0,1]
	v_pk_mul_f32 v[68:69], v[162:163], v[68:69] op_sel_hi:[0,1]
	v_pk_fma_f32 v[68:69], v[124:125], v[68:69], v[132:133]
	v_pk_fma_f32 v[114:115], v[122:123], v[114:115], v[130:131]
	v_pk_mul_f32 v[68:69], v[68:69], s[16:17] op_sel_hi:[1,0]
	v_pk_mul_f32 v[114:115], v[114:115], s[16:17] op_sel_hi:[1,0]
	v_pk_fma_f32 v[60:61], v[60:61], 0.5, v[68:69] op_sel_hi:[1,0,1]
	v_pk_fma_f32 v[58:59], v[58:59], 0.5, v[114:115] op_sel_hi:[1,0,1]
	v_ashrrev_i32_e32 v79, 31, v78
	v_add_f32_e32 v68, v58, v59
	v_add_f32_e32 v69, v60, v61
	v_readlane_b32 s2, v253, 59
	v_lshlrev_b64 v[78:79], 19, v[78:79]
	s_movk_i32 s1, 0x33c0
	v_add_f32_e32 v68, v68, v69
	v_mul_f32_e32 v69, v59, v59
	v_readlane_b32 s3, v253, 60
	v_and_or_b32 v0, v0, s1, v196
	s_nop 0
	s_nop 1
	v_bfe_u32 v91, v227, 4, 2
	v_sub_u32_e32 v90, 0, v91
	v_lshlrev_b32_e32 v90, 4, v90
	v_ashrrev_i32_e32 v91, 31, v90
	v_lshl_add_u64 v[90:91], v[76:77], 0, v[90:91]
	v_permlane16_swap_b32_e32 v62, v58
	v_permlane16_swap_b32_e32 v63, v59
	v_permlane16_swap_b32_e32 v64, v60
	v_permlane16_swap_b32_e32 v65, v61
	v_permlane32_swap_b32_e32 v62, v58
	v_permlane32_swap_b32_e32 v63, v59
	v_permlane32_swap_b32_e32 v64, v60
	v_permlane32_swap_b32_e32 v65, v61
	v_mov_b32_e32 v89, v62
	v_mov_b32_e32 v116, v63
	v_mov_b32_e32 v117, v64
	v_mov_b32_e32 v120, v65
	v_bfe_u32 v114, v227, 3, 1
	v_mul_i32_i24_e32 v114, 0xffff8040, v114
	v_ashrrev_i32_e32 v115, 31, v114
	v_lshl_add_u64 v[90:91], v[90:91], 0, v[114:115]
	v_mov_b32_e32 v114, 0x8000
	v_mov_b32_e32 v115, 0
	v_lshl_add_u64 v[114:115], v[90:91], 0, v[114:115]
	v_mov_b32_dpp v62, v58 row_ror:8 row_mask:0xf bank_mask:0xc
	v_mov_b32_dpp v63, v59 row_ror:8 row_mask:0xf bank_mask:0xc
	v_mov_b32_dpp v64, v60 row_ror:8 row_mask:0xf bank_mask:0xc
	v_mov_b32_dpp v65, v61 row_ror:8 row_mask:0xf bank_mask:0xc
	v_mov_b32_dpp v58, v89 row_ror:8 row_mask:0xf bank_mask:0x3
	v_mov_b32_dpp v59, v116 row_ror:8 row_mask:0xf bank_mask:0x3
	v_mov_b32_dpp v60, v117 row_ror:8 row_mask:0xf bank_mask:0x3
	v_mov_b32_dpp v61, v120 row_ror:8 row_mask:0xf bank_mask:0x3
	global_store_dwordx4 v[90:91], v[62:65], off nt
	global_store_dwordx4 v[114:115], v[58:61], off nt
	s_nop 1
	v_mov_b32_dpp v58, v62 row_ror:8 row_mask:0xf bank_mask:0x3
	v_mov_b32_dpp v59, v63 row_ror:8 row_mask:0xf bank_mask:0x3
	v_mov_b32_dpp v60, v64 row_ror:8 row_mask:0xf bank_mask:0x3
	v_mov_b32_dpp v61, v65 row_ror:8 row_mask:0xf bank_mask:0x3
	v_mov_b32_e32 v62, v89
	v_mov_b32_e32 v63, v116
	v_mov_b32_e32 v64, v117
	v_mov_b32_e32 v65, v120
	s_nop 1
	v_permlane32_swap_b32_e32 v62, v58
	v_permlane32_swap_b32_e32 v63, v59
	v_permlane32_swap_b32_e32 v64, v60
	v_permlane32_swap_b32_e32 v65, v61
	v_permlane16_swap_b32_e32 v62, v58
	v_permlane16_swap_b32_e32 v63, v59
	v_permlane16_swap_b32_e32 v64, v60
	v_permlane16_swap_b32_e32 v65, v61
	v_fmac_f32_e32 v69, v58, v58
	v_cvt_pk_bf16_f32 v62, v62, v63
	v_cvt_pk_bf16_f32 v63, v64, v65
	v_cvt_pk_bf16_f32 v64, v58, v59
	v_lshl_add_u64 v[58:59], s[2:3], 0, v[78:79]
	v_mul_f32_e32 v114, v61, v61
	v_lshl_add_u64 v[78:79], v[58:59], 0, s[24:25]
	v_lshlrev_b32_e32 v0, 1, v0
	v_fmac_f32_e32 v114, v60, v60
	v_cvt_pk_bf16_f32 v65, v60, v61
	v_lshl_add_u64 v[60:61], v[78:79], 0, v[0:1]
	global_store_dwordx4 v[60:61], v[62:65], off
	s_waitcnt vmcnt(7)
	v_sub_f32_e32 v61, v101, v163
	v_sub_f32_e32 v60, v100, v163
	v_sub_f32_e32 v63, v99, v163
	v_sub_f32_e32 v62, v98, v163
	v_pk_mul_f32 v[62:63], v[162:163], v[62:63] op_sel_hi:[0,1]
	v_pk_mul_f32 v[60:61], v[162:163], v[60:61] op_sel_hi:[0,1]
	s_waitcnt vmcnt(3)
; __device__ __forceinline__ float xsum16(float v) { const auto r = __builtin_amdgcn_permlane16_swap(__float_as_uint(v), __float_as_uint(v), false, false); return __uint_as_float(r[0]) + __uint_as_float(r[1]); }
; __device__ __forceinline__ float xsum32(float v) { const auto r = __builtin_amdgcn_permlane32_swap(__float_as_uint(v), __float_as_uint(v), false, false); return __uint_as_float(r[0]) + __uint_as_float(r[1]); }
; __device__ __forceinline__ size_t blk_off(int r, int c, int K) { return (size_t)(r >> 8) * 256 * K + (size_t)(c >> 6) * (256 * 64) + (size_t)((r & 255) * 64 + (c & 63)); }
; __device__ __forceinline__ u32x4 pack8(const f32x4 a, const f32x4 b) { u32x4 w; w.x = cvt_pk_bf16(a[0], a[1]); w.y = cvt_pk_bf16(a[2], a[3]); w.z = cvt_pk_bf16(b[0], b[1]); w.w = cvt_pk_bf16(b[2], b[3]); return w; }
;     __device__ __forceinline__ void operator()(const f32x4 (&acc)[2][2][4][2], const pg8::Unit& u, int wr, int wc, int fr, int fq) const {
;     ...
;                 for (int bj = 0; bj < 2; ++bj) { float* yp = Y + (size_t)row * D_ + col0 + bj * 128; f32x4 v[2];
; #pragma unroll
;                     for (int n = 0; n < 2; ++n) { v[n] = (((yv[bj][n] - mu) * rs) * gq[bj][n] + bq_[bj][n]) * ALPHA_ + acc[ai][bj][m][n] * sc;
;                         *(f32x4*)(yp + 4 * n) = v[n]; s1 += (v[n][0] + v[n][1]) + (v[n][2] + v[n][3]); s2 += (v[n][0] * v[n][0] + v[n][1] * v[n][1]) + (v[n][2] * v[n][2] + v[n][3] * v[n][3]); }
;                     *(u32x4*)(Yb + blk_off(row, col0 + bj * 128, D_)) = pack8(v[0], v[1]); }
;                 s1 = xsum32(xsum16(s1)); s2 = xsum32(xsum16(s2));
;                 if (fq == 0) *(f32x2*)(stn + (size_t)row * 32 + (u.pn * 4 + wc) * 2) = (f32x2){s1, s2}; asm volatile("" ::: "memory"); } }
	v_pk_fma_f32 v[60:61], v[108:109], v[60:61], v[160:161]
	v_pk_fma_f32 v[62:63], v[106:107], v[62:63], v[158:159]
	v_pk_mul_f32 v[60:61], v[60:61], s[16:17] op_sel_hi:[1,0]
	v_pk_mul_f32 v[62:63], v[62:63], s[16:17] op_sel_hi:[1,0]
	v_pk_fma_f32 v[56:57], v[56:57], 0.5, v[60:61] op_sel_hi:[1,0,1]
	v_pk_fma_f32 v[54:55], v[54:55], 0.5, v[62:63] op_sel_hi:[1,0,1]
	v_add_f32_e32 v61, v56, v57
	v_add_f32_e32 v60, v54, v55
	v_add_f32_e32 v68, v118, v68
	v_add_f32_e32 v60, v60, v61
	v_add_f32_e32 v64, v68, v60
	v_mul_f32_e32 v60, v55, v55
	v_mul_f32_e32 v61, v57, v57
	v_add_f32_e32 v69, v69, v114
	v_fmac_f32_e32 v60, v54, v54
	v_fmac_f32_e32 v61, v56, v56
	v_add_f32_e32 v69, v119, v69
	v_add_f32_e32 v60, v60, v61
	v_add_f32_e32 v65, v69, v60
	v_sub_f32_e32 v61, v95, v163
	v_sub_f32_e32 v60, v94, v163
	v_sub_f32_e32 v63, v93, v163
	v_sub_f32_e32 v62, v92, v163
	v_pk_mul_f32 v[62:63], v[162:163], v[62:63] op_sel_hi:[0,1]
	v_pk_mul_f32 v[60:61], v[162:163], v[60:61] op_sel_hi:[0,1]
	v_pk_fma_f32 v[60:61], v[104:105], v[60:61], v[112:113]
	v_pk_fma_f32 v[62:63], v[102:103], v[62:63], v[110:111]
	v_pk_mul_f32 v[60:61], v[60:61], s[16:17] op_sel_hi:[1,0]
	v_pk_mul_f32 v[62:63], v[62:63], s[16:17] op_sel_hi:[1,0]
	v_pk_fma_f32 v[52:53], v[52:53], 0.5, v[60:61] op_sel_hi:[1,0,1]
	v_pk_fma_f32 v[50:51], v[50:51], 0.5, v[62:63] op_sel_hi:[1,0,1]
	v_add_f32_e32 v61, v52, v53
	v_add_f32_e32 v60, v50, v51
	v_add_f32_e32 v60, v60, v61
	v_mul_f32_e32 v61, v51, v51
	v_mul_f32_e32 v62, v53, v53
	s_nop 0
	s_nop 1
	v_bfe_u32 v69, v227, 4, 2
	v_sub_u32_e32 v68, 0, v69
	v_lshlrev_b32_e32 v68, 4, v68
	v_ashrrev_i32_e32 v69, 31, v68
	v_lshl_add_u64 v[68:69], v[76:77], 0, v[68:69]
	v_permlane16_swap_b32_e32 v54, v50
	v_permlane16_swap_b32_e32 v55, v51
	v_permlane16_swap_b32_e32 v56, v52
	v_permlane16_swap_b32_e32 v57, v53
	v_permlane32_swap_b32_e32 v54, v50
	v_permlane32_swap_b32_e32 v55, v51
	v_permlane32_swap_b32_e32 v56, v52
	v_permlane32_swap_b32_e32 v57, v53
	v_mov_b32_e32 v63, v54
	v_mov_b32_e32 v89, v55
	v_mov_b32_e32 v92, v56
	v_mov_b32_e32 v93, v57
	v_bfe_u32 v90, v227, 3, 1
	v_mul_i32_i24_e32 v90, 0xffff8040, v90
	v_ashrrev_i32_e32 v91, 31, v90
	v_lshl_add_u64 v[68:69], v[68:69], 0, v[90:91]
	v_mov_b32_e32 v90, 0x8000
	v_mov_b32_e32 v91, 0
	v_lshl_add_u64 v[90:91], v[68:69], 0, v[90:91]
	v_mov_b32_dpp v54, v50 row_ror:8 row_mask:0xf bank_mask:0xc
	v_mov_b32_dpp v55, v51 row_ror:8 row_mask:0xf bank_mask:0xc
	v_mov_b32_dpp v56, v52 row_ror:8 row_mask:0xf bank_mask:0xc
	v_mov_b32_dpp v57, v53 row_ror:8 row_mask:0xf bank_mask:0xc
	v_mov_b32_dpp v50, v63 row_ror:8 row_mask:0xf bank_mask:0x3
	v_mov_b32_dpp v51, v89 row_ror:8 row_mask:0xf bank_mask:0x3
	v_mov_b32_dpp v52, v92 row_ror:8 row_mask:0xf bank_mask:0x3
	v_mov_b32_dpp v53, v93 row_ror:8 row_mask:0xf bank_mask:0x3
	global_store_dwordx4 v[68:69], v[54:57], off offset:512 nt
	global_store_dwordx4 v[90:91], v[50:53], off offset:512 nt
	s_nop 1
	v_mov_b32_dpp v50, v54 row_ror:8 row_mask:0xf bank_mask:0x3
	v_mov_b32_dpp v51, v55 row_ror:8 row_mask:0xf bank_mask:0x3
	v_mov_b32_dpp v52, v56 row_ror:8 row_mask:0xf bank_mask:0x3
	v_mov_b32_dpp v53, v57 row_ror:8 row_mask:0xf bank_mask:0x3
	v_mov_b32_e32 v54, v63
	v_mov_b32_e32 v55, v89
	v_mov_b32_e32 v56, v92
	v_mov_b32_e32 v57, v93
	s_nop 1
	v_permlane32_swap_b32_e32 v54, v50
	v_permlane32_swap_b32_e32 v55, v51
	v_permlane32_swap_b32_e32 v56, v52
	v_permlane32_swap_b32_e32 v57, v53
	v_permlane16_swap_b32_e32 v54, v50
	v_permlane16_swap_b32_e32 v55, v51
	v_permlane16_swap_b32_e32 v56, v52
	v_permlane16_swap_b32_e32 v57, v53
	v_add_f32_e32 v60, v64, v60
	v_fmac_f32_e32 v61, v50, v50
	v_fmac_f32_e32 v62, v52, v52
	v_lshl_add_u64 v[76:77], v[58:59], 0, s[44:45]
	v_add_f32_e32 v61, v61, v62
	v_cvt_pk_bf16_f32 v54, v54, v55
	v_cvt_pk_bf16_f32 v55, v56, v57
	v_cvt_pk_bf16_f32 v56, v50, v51
	v_lshl_add_u64 v[50:51], v[76:77], 0, v[0:1]
	v_mov_b32_e32 v0, v60
	v_pk_add_f32 v[70:71], v[70:71], v[70:71] op_sel:[0,1] op_sel_hi:[1,0]
	v_pk_add_f32 v[72:73], v[72:73], v[72:73] op_sel:[0,1] op_sel_hi:[1,0]
	v_pk_add_f32 v[84:85], v[84:85], v[84:85] op_sel:[0,1] op_sel_hi:[1,0]
	v_add_f32_e32 v61, v65, v61
	v_cvt_pk_bf16_f32 v57, v52, v53
	v_permlane16_swap_b32_e32 v60, v0
	v_mov_b32_e32 v71, v70
	v_mov_b32_e32 v73, v72
	v_mov_b32_e32 v85, v84
	global_store_dwordx4 v[50:51], v[54:57], off
	v_add_f32_e32 v50, v60, v0
	v_mov_b32_e32 v0, v61
	v_permlane16_swap_b32_e32 v70, v71
	v_permlane16_swap_b32_e32 v72, v73
	v_permlane16_swap_b32_e32 v84, v85
	v_permlane16_swap_b32_e32 v61, v0
	v_add_f32_e32 v71, v70, v71
	v_add_f32_e32 v70, v72, v73
	v_add_f32_e32 v89, v84, v85
	v_add_f32_e32 v51, v61, v0
	v_mov_b32_e32 v73, v71
	v_mov_b32_e32 v72, v70
	v_mov_b32_e32 v91, v89
	v_mov_b32_e32 v90, v88
	v_mov_b32_e32 v85, v83
	v_mov_b32_e32 v84, v82
	v_mov_b32_e32 v52, v50
	v_mov_b32_e32 v53, v51
	v_permlane32_swap_b32_e32 v71, v73
	v_permlane32_swap_b32_e32 v70, v72
	v_permlane32_swap_b32_e32 v89, v91
	v_permlane32_swap_b32_e32 v88, v90
	v_permlane32_swap_b32_e32 v83, v85
	v_permlane32_swap_b32_e32 v82, v84
	v_permlane32_swap_b32_e32 v50, v52
	v_permlane32_swap_b32_e32 v51, v53
	s_and_saveexec_b64 s[24:25], s[40:41]
	s_cbranch_execz .LBB0_1713
	v_pk_add_f32 v[50:51], v[50:51], v[52:53]
	v_lshl_add_u64 v[52:53], s[8:9], 0, v[66:67]
	v_lshl_add_u64 v[52:53], s[38:39], 2, v[52:53]
	global_store_dwordx2 v[52:53], v[50:51], off
; __device__ __forceinline__ size_t blk_off(int r, int c, int K) { return (size_t)(r >> 8) * 256 * K + (size_t)(c >> 6) * (256 * 64) + (size_t)((r & 255) * 64 + (c & 63)); }
; __device__ __forceinline__ u32x4 pack8(const f32x4 a, const f32x4 b) { u32x4 w; w.x = cvt_pk_bf16(a[0], a[1]); w.y = cvt_pk_bf16(a[2], a[3]); w.z = cvt_pk_bf16(b[0], b[1]); w.w = cvt_pk_bf16(b[2], b[3]); return w; }
;     __device__ __forceinline__ void operator()(const f32x4 (&acc)[2][2][4][2], const pg8::Unit& u, int wr, int wc, int fr, int fq) const {
;     ...
;             for (int m = 0; m < 4; ++m) { const int row = row0 + ai * 128 + m * 16; const float mu = mu4[m], rs = rs4[m];
;                 f32x4 yv[2][2], gq[2][2], bq_[2][2];
; #pragma unroll
;                 for (int bj = 0; bj < 2; ++bj)
; #pragma unroll
;                     for (int n = 0; n < 2; ++n) { yv[bj][n] = *(const f32x4*)(Yin + (size_t)row * D_ + col0 + bj * 128 + 4 * n); gq[bj][n] = *(const f32x4*)(g + col0 + bj * 128 + 4 * n); bq_[bj][n] = *(const f32x4*)(b + col0 + bj * 128 + 4 * n); }
;                 asm volatile("" ::: "memory");
;                 float s1 = 0.f, s2 = 0.f;
; #pragma unroll
;                 for (int bj = 0; bj < 2; ++bj) { float* yp = Y + (size_t)row * D_ + col0 + bj * 128; f32x4 v[2];
; #pragma unroll
;                     for (int n = 0; n < 2; ++n) { v[n] = (((yv[bj][n] - mu) * rs) * gq[bj][n] + bq_[bj][n]) * ALPHA_ + acc[ai][bj][m][n] * sc;
;                         *(f32x4*)(yp + 4 * n) = v[n]; s1 += (v[n][0] + v[n][1]) + (v[n][2] + v[n][3]); s2 += (v[n][0] * v[n][0] + v[n][1] * v[n][1]) + (v[n][2] * v[n][2] + v[n][3] * v[n][3]); }
;                     *(u32x4*)(Yb + blk_off(row, col0 + bj * 128, D_)) = pack8(v[0], v[1]); }
.LBB0_1713:
	s_or_b64 exec, exec, s[24:25]
	v_pk_add_f32 v[50:51], v[70:71], v[72:73]
	s_mov_b32 s2, 0x3a800000
	v_pk_mul_f32 v[92:93], v[50:51], s[2:3] op_sel_hi:[1,0]
	s_mov_b32 s1, 0x800000
	v_fma_f32 v0, -v93, v93, v92
	v_max_f32_e32 v0, 0, v0
	v_add_f32_e32 v0, 0x3727c5ac, v0
	v_cmp_gt_f32_e32 vcc, s1, v0
	v_mul_f32_e32 v50, 0x4b800000, v0
	s_load_dwordx16 s[60:75], s[34:35], 0x38
	v_cndmask_b32_e32 v0, v0, v50, vcc
	v_rsq_f32_e32 v0, v0
	s_mov_b32 s2, 0x3fd744fd
	s_movk_i32 s1, 0x37c0
	v_mul_f32_e32 v50, 0x45800000, v0
	v_cndmask_b32_e32 v92, v0, v50, vcc
	v_lshlrev_b64 v[50:51], 12, v[96:97]
	s_waitcnt lgkmcnt(0)
	v_lshl_add_u64 v[50:51], s[74:75], 0, v[50:51]
	v_lshl_add_u64 v[94:95], v[152:153], 2, v[50:51]
	global_load_dwordx4 v[98:101], v[94:95], off offset:16
	global_load_dwordx4 v[102:105], v[94:95], off
	global_load_dwordx4 v[106:109], v[156:157], off offset:16
	global_load_dwordx4 v[110:113], v[156:157], off
	global_load_dwordx4 v[114:117], v[154:155], off offset:16
	global_load_dwordx4 v[118:121], v[154:155], off
	global_load_dwordx4 v[50:53], v[94:95], off offset:528
	global_load_dwordx4 v[70:73], v[94:95], off offset:512
	global_load_dwordx4 v[54:57], v[156:157], off offset:528
	global_load_dwordx4 v[62:65], v[156:157], off offset:512
	global_load_dwordx4 v[58:61], v[154:155], off offset:528
	global_load_dwordx4 v[66:69], v[154:155], off offset:512
	v_lshlrev_b32_e32 v0, 6, v96
	v_and_or_b32 v0, v0, s1, v196
	v_lshlrev_b32_e32 v0, 1, v0
	s_waitcnt vmcnt(10)
	v_sub_f32_e32 v97, v105, v93
	v_sub_f32_e32 v96, v104, v93
	v_sub_f32_e32 v103, v103, v93
	v_sub_f32_e32 v102, v102, v93
	v_pk_mul_f32 v[102:103], v[92:93], v[102:103] op_sel_hi:[0,1]
	v_pk_mul_f32 v[96:97], v[92:93], v[96:97] op_sel_hi:[0,1]
	s_waitcnt vmcnt(6)
	v_pk_fma_f32 v[96:97], v[112:113], v[96:97], v[120:121]
	v_pk_fma_f32 v[102:103], v[110:111], v[102:103], v[118:119]
	v_pk_mul_f32 v[96:97], v[96:97], s[2:3] op_sel_hi:[1,0]
	v_pk_mul_f32 v[102:103], v[102:103], s[2:3] op_sel_hi:[1,0]
	v_pk_fma_f32 v[104:105], v[48:49], 0.5, v[96:97] op_sel_hi:[1,0,1]
	v_pk_fma_f32 v[102:103], v[46:47], 0.5, v[102:103] op_sel_hi:[1,0,1]
	v_add_f32_e32 v47, v104, v105
	v_add_f32_e32 v46, v102, v103
	v_add_f32_e32 v46, v46, v47
	v_add_f32_e32 v110, 0, v46
	v_mul_f32_e32 v46, v103, v103
	v_mul_f32_e32 v47, v105, v105
	v_fmac_f32_e32 v46, v102, v102
	v_fmac_f32_e32 v47, v104, v104
	v_add_f32_e32 v111, v46, v47
	v_sub_f32_e32 v47, v101, v93
	v_sub_f32_e32 v46, v100, v93
	v_sub_f32_e32 v49, v99, v93
	v_sub_f32_e32 v48, v98, v93
	v_pk_mul_f32 v[48:49], v[92:93], v[48:49] op_sel_hi:[0,1]
	v_pk_mul_f32 v[46:47], v[92:93], v[46:47] op_sel_hi:[0,1]
	v_pk_fma_f32 v[46:47], v[108:109], v[46:47], v[116:117]
	v_pk_fma_f32 v[48:49], v[106:107], v[48:49], v[114:115]
	v_pk_mul_f32 v[46:47], v[46:47], s[2:3] op_sel_hi:[1,0]
	v_pk_mul_f32 v[48:49], v[48:49], s[2:3] op_sel_hi:[1,0]
	v_pk_fma_f32 v[98:99], v[44:45], 0.5, v[46:47] op_sel_hi:[1,0,1]
	v_pk_fma_f32 v[96:97], v[42:43], 0.5, v[48:49] op_sel_hi:[1,0,1]
	v_add_f32_e32 v43, v98, v99
	v_add_f32_e32 v42, v96, v97
	v_add_f32_e32 v42, v42, v43
	v_add_f32_e32 v47, v110, v42
	v_mul_f32_e32 v42, v97, v97
	v_mul_f32_e32 v43, v99, v99
	v_fmac_f32_e32 v42, v96, v96
	v_fmac_f32_e32 v43, v98, v98
	v_add_f32_e32 v42, v42, v43
	v_add_f32_e32 v46, v111, v42
	v_cvt_pk_bf16_f32 v42, v102, v103
	v_cvt_pk_bf16_f32 v43, v104, v105
	v_cvt_pk_bf16_f32 v44, v96, v97
	v_cvt_pk_bf16_f32 v45, v98, v99
	v_lshl_add_u64 v[48:49], v[78:79], 0, v[0:1]
	s_nop 0
	s_nop 1
	v_bfe_u32 v101, v227, 4, 2
	v_sub_u32_e32 v100, 0, v101
	v_lshlrev_b32_e32 v100, 4, v100
	v_ashrrev_i32_e32 v101, 31, v100
	v_lshl_add_u64 v[100:101], v[94:95], 0, v[100:101]
	v_permlane16_swap_b32_e32 v102, v96
	v_permlane16_swap_b32_e32 v103, v97
	v_permlane16_swap_b32_e32 v104, v98
	v_permlane16_swap_b32_e32 v105, v99
	v_permlane32_swap_b32_e32 v102, v96
	v_permlane32_swap_b32_e32 v103, v97
	v_permlane32_swap_b32_e32 v104, v98
	v_permlane32_swap_b32_e32 v105, v99
	v_mov_b32_e32 v108, v102
	v_mov_b32_e32 v109, v103
	v_mov_b32_e32 v110, v104
	v_mov_b32_e32 v111, v105
	v_bfe_u32 v106, v227, 3, 1
	v_mul_i32_i24_e32 v106, 0xffff8040, v106
	v_ashrrev_i32_e32 v107, 31, v106
	v_lshl_add_u64 v[100:101], v[100:101], 0, v[106:107]
	v_mov_b32_e32 v106, 0x8000
	v_mov_b32_e32 v107, 0
	v_lshl_add_u64 v[106:107], v[100:101], 0, v[106:107]
	v_mov_b32_dpp v102, v96 row_ror:8 row_mask:0xf bank_mask:0xc
	v_mov_b32_dpp v103, v97 row_ror:8 row_mask:0xf bank_mask:0xc
	v_mov_b32_dpp v104, v98 row_ror:8 row_mask:0xf bank_mask:0xc
	v_mov_b32_dpp v105, v99 row_ror:8 row_mask:0xf bank_mask:0xc
	v_mov_b32_dpp v96, v108 row_ror:8 row_mask:0xf bank_mask:0x3
	v_mov_b32_dpp v97, v109 row_ror:8 row_mask:0xf bank_mask:0x3
	v_mov_b32_dpp v98, v110 row_ror:8 row_mask:0xf bank_mask:0x3
	v_mov_b32_dpp v99, v111 row_ror:8 row_mask:0xf bank_mask:0x3
	global_store_dwordx4 v[100:101], v[102:105], off nt
	global_store_dwordx4 v[106:107], v[96:99], off nt
	s_nop 1
	global_store_dwordx4 v[48:49], v[42:45], off
	s_waitcnt vmcnt(7)
	s_nop 0
	v_sub_f32_e32 v43, v73, v93
	v_sub_f32_e32 v42, v72, v93
	v_sub_f32_e32 v45, v71, v93
	v_sub_f32_e32 v44, v70, v93
	v_pk_mul_f32 v[44:45], v[92:93], v[44:45] op_sel_hi:[0,1]
	v_pk_mul_f32 v[42:43], v[92:93], v[42:43] op_sel_hi:[0,1]
	s_waitcnt vmcnt(3)
; __device__ __forceinline__ float xsum16(float v) { const auto r = __builtin_amdgcn_permlane16_swap(__float_as_uint(v), __float_as_uint(v), false, false); return __uint_as_float(r[0]) + __uint_as_float(r[1]); }
; __device__ __forceinline__ float xsum32(float v) { const auto r = __builtin_amdgcn_permlane32_swap(__float_as_uint(v), __float_as_uint(v), false, false); return __uint_as_float(r[0]) + __uint_as_float(r[1]); }
; __device__ __forceinline__ size_t blk_off(int r, int c, int K) { return (size_t)(r >> 8) * 256 * K + (size_t)(c >> 6) * (256 * 64) + (size_t)((r & 255) * 64 + (c & 63)); }
; __device__ __forceinline__ u32x4 pack8(const f32x4 a, const f32x4 b) { u32x4 w; w.x = cvt_pk_bf16(a[0], a[1]); w.y = cvt_pk_bf16(a[2], a[3]); w.z = cvt_pk_bf16(b[0], b[1]); w.w = cvt_pk_bf16(b[2], b[3]); return w; }
;     __device__ __forceinline__ void operator()(const f32x4 (&acc)[2][2][4][2], const pg8::Unit& u, int wr, int wc, int fr, int fq) const {
;     ...
;                 for (int bj = 0; bj < 2; ++bj) { float* yp = Y + (size_t)row * D_ + col0 + bj * 128; f32x4 v[2];
; #pragma unroll
;                     for (int n = 0; n < 2; ++n) { v[n] = (((yv[bj][n] - mu) * rs) * gq[bj][n] + bq_[bj][n]) * ALPHA_ + acc[ai][bj][m][n] * sc;
;                         *(f32x4*)(yp + 4 * n) = v[n]; s1 += (v[n][0] + v[n][1]) + (v[n][2] + v[n][3]); s2 += (v[n][0] * v[n][0] + v[n][1] * v[n][1]) + (v[n][2] * v[n][2] + v[n][3] * v[n][3]); }
;                     *(u32x4*)(Yb + blk_off(row, col0 + bj * 128, D_)) = pack8(v[0], v[1]); }
;                 s1 = xsum32(xsum16(s1)); s2 = xsum32(xsum16(s2));
;                 if (fq == 0) *(f32x2*)(stn + (size_t)row * 32 + (u.pn * 4 + wc) * 2) = (f32x2){s1, s2}; asm volatile("" ::: "memory"); } }
	v_pk_fma_f32 v[42:43], v[64:65], v[42:43], v[68:69]
	v_pk_fma_f32 v[44:45], v[62:63], v[44:45], v[66:67]
	v_pk_mul_f32 v[42:43], v[42:43], s[2:3] op_sel_hi:[1,0]
	v_pk_mul_f32 v[44:45], v[44:45], s[2:3] op_sel_hi:[1,0]
	v_pk_fma_f32 v[40:41], v[40:41], 0.5, v[42:43] op_sel_hi:[1,0,1]
	v_pk_fma_f32 v[38:39], v[38:39], 0.5, v[44:45] op_sel_hi:[1,0,1]
	v_add_f32_e32 v43, v40, v41
	v_add_f32_e32 v42, v38, v39
	v_add_f32_e32 v42, v42, v43
	v_add_f32_e32 v47, v47, v42
	v_mul_f32_e32 v42, v39, v39
	v_mul_f32_e32 v43, v41, v41
	v_fmac_f32_e32 v42, v38, v38
	v_fmac_f32_e32 v43, v40, v40
	v_add_f32_e32 v42, v42, v43
	v_add_f32_e32 v46, v46, v42
	v_sub_f32_e32 v43, v53, v93
	v_sub_f32_e32 v42, v52, v93
	v_sub_f32_e32 v45, v51, v93
	v_sub_f32_e32 v44, v50, v93
	v_pk_mul_f32 v[44:45], v[92:93], v[44:45] op_sel_hi:[0,1]
	v_pk_mul_f32 v[42:43], v[92:93], v[42:43] op_sel_hi:[0,1]
	v_pk_fma_f32 v[42:43], v[56:57], v[42:43], v[60:61]
	v_pk_fma_f32 v[44:45], v[54:55], v[44:45], v[58:59]
	v_pk_mul_f32 v[42:43], v[42:43], s[2:3] op_sel_hi:[1,0]
	v_pk_mul_f32 v[44:45], v[44:45], s[2:3] op_sel_hi:[1,0]
	v_pk_fma_f32 v[36:37], v[36:37], 0.5, v[42:43] op_sel_hi:[1,0,1]
	v_pk_fma_f32 v[34:35], v[34:35], 0.5, v[44:45] op_sel_hi:[1,0,1]
	v_add_f32_e32 v43, v36, v37
	v_add_f32_e32 v42, v34, v35
	v_add_f32_e32 v42, v42, v43
	v_mul_f32_e32 v43, v35, v35
	v_mul_f32_e32 v44, v37, v37
	v_add_f32_e32 v42, v47, v42
	v_fmac_f32_e32 v43, v34, v34
	v_fmac_f32_e32 v44, v36, v36
	s_nop 0
	s_nop 1
	v_bfe_u32 v49, v227, 4, 2
	v_sub_u32_e32 v48, 0, v49
	v_lshlrev_b32_e32 v48, 4, v48
	v_ashrrev_i32_e32 v49, 31, v48
	v_lshl_add_u64 v[48:49], v[94:95], 0, v[48:49]
	v_permlane16_swap_b32_e32 v38, v34
	v_permlane16_swap_b32_e32 v39, v35
	v_permlane16_swap_b32_e32 v40, v36
	v_permlane16_swap_b32_e32 v41, v37
	v_permlane32_swap_b32_e32 v38, v34
	v_permlane32_swap_b32_e32 v39, v35
	v_permlane32_swap_b32_e32 v40, v36
	v_permlane32_swap_b32_e32 v41, v37
	v_mov_b32_e32 v45, v38
	v_mov_b32_e32 v52, v39
	v_mov_b32_e32 v53, v40
	v_mov_b32_e32 v54, v41
	v_bfe_u32 v50, v227, 3, 1
	v_mul_i32_i24_e32 v50, 0xffff8040, v50
	v_ashrrev_i32_e32 v51, 31, v50
	v_lshl_add_u64 v[48:49], v[48:49], 0, v[50:51]
	v_mov_b32_e32 v50, 0x8000
	v_mov_b32_e32 v51, 0
	v_lshl_add_u64 v[50:51], v[48:49], 0, v[50:51]
	v_mov_b32_dpp v38, v34 row_ror:8 row_mask:0xf bank_mask:0xc
	v_mov_b32_dpp v39, v35 row_ror:8 row_mask:0xf bank_mask:0xc
	v_mov_b32_dpp v40, v36 row_ror:8 row_mask:0xf bank_mask:0xc
	v_mov_b32_dpp v41, v37 row_ror:8 row_mask:0xf bank_mask:0xc
	v_mov_b32_dpp v34, v45 row_ror:8 row_mask:0xf bank_mask:0x3
	v_mov_b32_dpp v35, v52 row_ror:8 row_mask:0xf bank_mask:0x3
	v_mov_b32_dpp v36, v53 row_ror:8 row_mask:0xf bank_mask:0x3
	v_mov_b32_dpp v37, v54 row_ror:8 row_mask:0xf bank_mask:0x3
	global_store_dwordx4 v[48:49], v[38:41], off offset:512 nt
	global_store_dwordx4 v[50:51], v[34:37], off offset:512 nt
	s_nop 1
	v_mov_b32_dpp v34, v38 row_ror:8 row_mask:0xf bank_mask:0x3
	v_mov_b32_dpp v35, v39 row_ror:8 row_mask:0xf bank_mask:0x3
	v_mov_b32_dpp v36, v40 row_ror:8 row_mask:0xf bank_mask:0x3
	v_mov_b32_dpp v37, v41 row_ror:8 row_mask:0xf bank_mask:0x3
	v_mov_b32_e32 v38, v45
	v_mov_b32_e32 v39, v52
	v_mov_b32_e32 v40, v53
	v_mov_b32_e32 v41, v54
	s_nop 1
	v_permlane32_swap_b32_e32 v38, v34
	v_permlane32_swap_b32_e32 v39, v35
	v_permlane32_swap_b32_e32 v40, v36
	v_permlane32_swap_b32_e32 v41, v37
	v_permlane16_swap_b32_e32 v38, v34
	v_permlane16_swap_b32_e32 v39, v35
	v_permlane16_swap_b32_e32 v40, v36
	v_permlane16_swap_b32_e32 v41, v37
	v_add_f32_e32 v43, v43, v44
	v_cvt_pk_bf16_f32 v38, v38, v39
	v_cvt_pk_bf16_f32 v39, v40, v41
	v_cvt_pk_bf16_f32 v40, v34, v35
	v_lshl_add_u64 v[34:35], v[76:77], 0, v[0:1]
	v_mov_b32_e32 v0, v42
	v_add_f32_e32 v43, v46, v43
	v_cvt_pk_bf16_f32 v41, v36, v37
	v_permlane16_swap_b32_e32 v42, v0
	global_store_dwordx4 v[34:35], v[38:41], off
	v_add_f32_e32 v34, v42, v0
	v_mov_b32_e32 v0, v43
	s_nop 1
	v_permlane16_swap_b32_e32 v43, v0
	v_add_f32_e32 v35, v43, v0
	v_mov_b32_e32 v36, v34
	v_mov_b32_e32 v37, v35
	s_nop 0
	v_permlane32_swap_b32_e32 v34, v36
	v_permlane32_swap_b32_e32 v35, v37
	s_and_saveexec_b64 s[24:25], s[40:41]
	s_cbranch_execz .LBB0_1715
	v_pk_add_f32 v[34:35], v[34:35], v[36:37]
	v_lshl_add_u64 v[36:37], s[8:9], 0, v[86:87]
	v_lshl_add_u64 v[36:37], s[38:39], 2, v[36:37]
	global_store_dwordx2 v[36:37], v[34:35], off
; __device__ __forceinline__ size_t blk_off(int r, int c, int K) { return (size_t)(r >> 8) * 256 * K + (size_t)(c >> 6) * (256 * 64) + (size_t)((r & 255) * 64 + (c & 63)); }
; __device__ __forceinline__ u32x4 pack8(const f32x4 a, const f32x4 b) { u32x4 w; w.x = cvt_pk_bf16(a[0], a[1]); w.y = cvt_pk_bf16(a[2], a[3]); w.z = cvt_pk_bf16(b[0], b[1]); w.w = cvt_pk_bf16(b[2], b[3]); return w; }
;     __device__ __forceinline__ void operator()(const f32x4 (&acc)[2][2][4][2], const pg8::Unit& u, int wr, int wc, int fr, int fq) const {
;     ...
;             for (int m = 0; m < 4; ++m) { const int row = row0 + ai * 128 + m * 16; const float mu = mu4[m], rs = rs4[m];
;                 f32x4 yv[2][2], gq[2][2], bq_[2][2];
; #pragma unroll
;                 for (int bj = 0; bj < 2; ++bj)
; #pragma unroll
;                     for (int n = 0; n < 2; ++n) { yv[bj][n] = *(const f32x4*)(Yin + (size_t)row * D_ + col0 + bj * 128 + 4 * n); gq[bj][n] = *(const f32x4*)(g + col0 + bj * 128 + 4 * n); bq_[bj][n] = *(const f32x4*)(b + col0 + bj * 128 + 4 * n); }
;                 asm volatile("" ::: "memory");
;                 float s1 = 0.f, s2 = 0.f;
; #pragma unroll
;                 for (int bj = 0; bj < 2; ++bj) { float* yp = Y + (size_t)row * D_ + col0 + bj * 128; f32x4 v[2];
; #pragma unroll
;                     for (int n = 0; n < 2; ++n) { v[n] = (((yv[bj][n] - mu) * rs) * gq[bj][n] + bq_[bj][n]) * ALPHA_ + acc[ai][bj][m][n] * sc;
;                         *(f32x4*)(yp + 4 * n) = v[n]; s1 += (v[n][0] + v[n][1]) + (v[n][2] + v[n][3]); s2 += (v[n][0] * v[n][0] + v[n][1] * v[n][1]) + (v[n][2] * v[n][2] + v[n][3] * v[n][3]); }
;                     *(u32x4*)(Yb + blk_off(row, col0 + bj * 128, D_)) = pack8(v[0], v[1]); }
.LBB0_1715:
	s_or_b64 exec, exec, s[24:25]
	v_pk_add_f32 v[34:35], v[88:89], v[90:91]
	s_mov_b32 s2, 0x3a800000
	v_pk_mul_f32 v[58:59], v[34:35], s[2:3] op_sel_hi:[1,0]
	s_mov_b32 s1, 0x800000
	v_fma_f32 v0, -v59, v59, v58
	v_max_f32_e32 v0, 0, v0
	v_add_f32_e32 v0, 0x3727c5ac, v0
	v_cmp_gt_f32_e32 vcc, s1, v0
	v_mul_f32_e32 v34, 0x4b800000, v0
	s_load_dwordx16 s[60:75], s[34:35], 0x38
	v_cndmask_b32_e32 v0, v0, v34, vcc
	v_rsq_f32_e32 v0, v0
	s_mov_b32 s2, 0x3fd744fd
	s_movk_i32 s1, 0x3bc0
	v_mul_f32_e32 v34, 0x45800000, v0
	v_cndmask_b32_e32 v58, v0, v34, vcc
	v_lshlrev_b64 v[34:35], 12, v[80:81]
	s_waitcnt lgkmcnt(0)
	v_lshl_add_u64 v[34:35], s[74:75], 0, v[34:35]
	v_lshl_add_u64 v[60:61], v[152:153], 2, v[34:35]
	global_load_dwordx4 v[62:65], v[60:61], off offset:16
	global_load_dwordx4 v[66:69], v[60:61], off
	global_load_dwordx4 v[70:73], v[156:157], off offset:16
	global_load_dwordx4 v[86:89], v[156:157], off
	global_load_dwordx4 v[90:93], v[154:155], off offset:16
	global_load_dwordx4 v[94:97], v[154:155], off
	global_load_dwordx4 v[34:37], v[60:61], off offset:528
	global_load_dwordx4 v[54:57], v[60:61], off offset:512
	global_load_dwordx4 v[38:41], v[156:157], off offset:528
	global_load_dwordx4 v[46:49], v[156:157], off offset:512
	global_load_dwordx4 v[42:45], v[154:155], off offset:528
	global_load_dwordx4 v[50:53], v[154:155], off offset:512
	v_lshlrev_b32_e32 v0, 6, v80
	v_and_or_b32 v0, v0, s1, v196
	v_lshlrev_b32_e32 v0, 1, v0
	s_waitcnt vmcnt(10)
	v_sub_f32_e32 v69, v69, v59
	v_sub_f32_e32 v68, v68, v59
	v_sub_f32_e32 v67, v67, v59
	v_sub_f32_e32 v66, v66, v59
	v_pk_mul_f32 v[66:67], v[58:59], v[66:67] op_sel_hi:[0,1]
	v_pk_mul_f32 v[68:69], v[58:59], v[68:69] op_sel_hi:[0,1]
	s_waitcnt vmcnt(6)
	v_pk_fma_f32 v[68:69], v[88:89], v[68:69], v[96:97]
	v_pk_fma_f32 v[66:67], v[86:87], v[66:67], v[94:95]
	v_pk_mul_f32 v[68:69], v[68:69], s[2:3] op_sel_hi:[1,0]
	v_pk_mul_f32 v[66:67], v[66:67], s[2:3] op_sel_hi:[1,0]
	v_pk_fma_f32 v[68:69], v[32:33], 0.5, v[68:69] op_sel_hi:[1,0,1]
	v_pk_fma_f32 v[66:67], v[30:31], 0.5, v[66:67] op_sel_hi:[1,0,1]
	v_add_f32_e32 v31, v68, v69
	v_add_f32_e32 v30, v66, v67
	v_add_f32_e32 v30, v30, v31
	v_add_f32_e32 v86, 0, v30
	v_mul_f32_e32 v30, v67, v67
	v_mul_f32_e32 v31, v69, v69
	v_fmac_f32_e32 v30, v66, v66
	v_fmac_f32_e32 v31, v68, v68
	v_add_f32_e32 v87, v30, v31
	v_sub_f32_e32 v31, v65, v59
	v_sub_f32_e32 v30, v64, v59
	v_sub_f32_e32 v33, v63, v59
	v_sub_f32_e32 v32, v62, v59
	v_pk_mul_f32 v[32:33], v[58:59], v[32:33] op_sel_hi:[0,1]
	v_pk_mul_f32 v[30:31], v[58:59], v[30:31] op_sel_hi:[0,1]
	v_pk_fma_f32 v[30:31], v[72:73], v[30:31], v[92:93]
	v_pk_fma_f32 v[32:33], v[70:71], v[32:33], v[90:91]
	v_pk_mul_f32 v[30:31], v[30:31], s[2:3] op_sel_hi:[1,0]
	v_pk_mul_f32 v[32:33], v[32:33], s[2:3] op_sel_hi:[1,0]
	v_pk_fma_f32 v[64:65], v[28:29], 0.5, v[30:31] op_sel_hi:[1,0,1]
	v_pk_fma_f32 v[62:63], v[26:27], 0.5, v[32:33] op_sel_hi:[1,0,1]
	v_add_f32_e32 v27, v64, v65
	v_add_f32_e32 v26, v62, v63
	v_add_f32_e32 v26, v26, v27
	v_add_f32_e32 v31, v86, v26
	v_mul_f32_e32 v26, v63, v63
	v_mul_f32_e32 v27, v65, v65
	v_fmac_f32_e32 v26, v62, v62
	v_fmac_f32_e32 v27, v64, v64
	v_add_f32_e32 v26, v26, v27
	v_add_f32_e32 v30, v87, v26
	v_cvt_pk_bf16_f32 v26, v66, v67
	v_cvt_pk_bf16_f32 v27, v68, v69
	v_cvt_pk_bf16_f32 v28, v62, v63
	v_cvt_pk_bf16_f32 v29, v64, v65
	v_lshl_add_u64 v[32:33], v[78:79], 0, v[0:1]
	s_nop 0
	s_nop 1
	v_bfe_u32 v71, v227, 4, 2
	v_sub_u32_e32 v70, 0, v71
	v_lshlrev_b32_e32 v70, 4, v70
	v_ashrrev_i32_e32 v71, 31, v70
	v_lshl_add_u64 v[70:71], v[60:61], 0, v[70:71]
	v_permlane16_swap_b32_e32 v66, v62
	v_permlane16_swap_b32_e32 v67, v63
	v_permlane16_swap_b32_e32 v68, v64
	v_permlane16_swap_b32_e32 v69, v65
	v_permlane32_swap_b32_e32 v66, v62
	v_permlane32_swap_b32_e32 v67, v63
	v_permlane32_swap_b32_e32 v68, v64
	v_permlane32_swap_b32_e32 v69, v65
	v_mov_b32_e32 v86, v66
	v_mov_b32_e32 v87, v67
	v_mov_b32_e32 v88, v68
	v_mov_b32_e32 v89, v69
	v_bfe_u32 v72, v227, 3, 1
	v_mul_i32_i24_e32 v72, 0xffff8040, v72
	v_ashrrev_i32_e32 v73, 31, v72
	v_lshl_add_u64 v[70:71], v[70:71], 0, v[72:73]
	v_mov_b32_e32 v72, 0x8000
	v_mov_b32_e32 v73, 0
	v_lshl_add_u64 v[72:73], v[70:71], 0, v[72:73]
	v_mov_b32_dpp v66, v62 row_ror:8 row_mask:0xf bank_mask:0xc
	v_mov_b32_dpp v67, v63 row_ror:8 row_mask:0xf bank_mask:0xc
	v_mov_b32_dpp v68, v64 row_ror:8 row_mask:0xf bank_mask:0xc
	v_mov_b32_dpp v69, v65 row_ror:8 row_mask:0xf bank_mask:0xc
	v_mov_b32_dpp v62, v86 row_ror:8 row_mask:0xf bank_mask:0x3
	v_mov_b32_dpp v63, v87 row_ror:8 row_mask:0xf bank_mask:0x3
	v_mov_b32_dpp v64, v88 row_ror:8 row_mask:0xf bank_mask:0x3
	v_mov_b32_dpp v65, v89 row_ror:8 row_mask:0xf bank_mask:0x3
	global_store_dwordx4 v[70:71], v[66:69], off nt
	global_store_dwordx4 v[72:73], v[62:65], off nt
	s_nop 1
	global_store_dwordx4 v[32:33], v[26:29], off
	s_waitcnt vmcnt(7)
	s_nop 0
	v_sub_f32_e32 v27, v57, v59
	v_sub_f32_e32 v26, v56, v59
	v_sub_f32_e32 v29, v55, v59
	v_sub_f32_e32 v28, v54, v59
	v_pk_mul_f32 v[28:29], v[58:59], v[28:29] op_sel_hi:[0,1]
	v_pk_mul_f32 v[26:27], v[58:59], v[26:27] op_sel_hi:[0,1]
	s_waitcnt vmcnt(3)
; __device__ __forceinline__ float xsum16(float v) { const auto r = __builtin_amdgcn_permlane16_swap(__float_as_uint(v), __float_as_uint(v), false, false); return __uint_as_float(r[0]) + __uint_as_float(r[1]); }
; __device__ __forceinline__ float xsum32(float v) { const auto r = __builtin_amdgcn_permlane32_swap(__float_as_uint(v), __float_as_uint(v), false, false); return __uint_as_float(r[0]) + __uint_as_float(r[1]); }
; __device__ __forceinline__ size_t blk_off(int r, int c, int K) { return (size_t)(r >> 8) * 256 * K + (size_t)(c >> 6) * (256 * 64) + (size_t)((r & 255) * 64 + (c & 63)); }
; __device__ __forceinline__ u32x4 pack8(const f32x4 a, const f32x4 b) { u32x4 w; w.x = cvt_pk_bf16(a[0], a[1]); w.y = cvt_pk_bf16(a[2], a[3]); w.z = cvt_pk_bf16(b[0], b[1]); w.w = cvt_pk_bf16(b[2], b[3]); return w; }
;     __device__ __forceinline__ void operator()(const f32x4 (&acc)[2][2][4][2], const pg8::Unit& u, int wr, int wc, int fr, int fq) const {
;     ...
;                 for (int bj = 0; bj < 2; ++bj) { float* yp = Y + (size_t)row * D_ + col0 + bj * 128; f32x4 v[2];
; #pragma unroll
;                     for (int n = 0; n < 2; ++n) { v[n] = (((yv[bj][n] - mu) * rs) * gq[bj][n] + bq_[bj][n]) * ALPHA_ + acc[ai][bj][m][n] * sc;
;                         *(f32x4*)(yp + 4 * n) = v[n]; s1 += (v[n][0] + v[n][1]) + (v[n][2] + v[n][3]); s2 += (v[n][0] * v[n][0] + v[n][1] * v[n][1]) + (v[n][2] * v[n][2] + v[n][3] * v[n][3]); }
;                     *(u32x4*)(Yb + blk_off(row, col0 + bj * 128, D_)) = pack8(v[0], v[1]); }
;                 s1 = xsum32(xsum16(s1)); s2 = xsum32(xsum16(s2));
;                 if (fq == 0) *(f32x2*)(stn + (size_t)row * 32 + (u.pn * 4 + wc) * 2) = (f32x2){s1, s2}; asm volatile("" ::: "memory"); } }
	v_pk_fma_f32 v[26:27], v[48:49], v[26:27], v[52:53]
	v_pk_fma_f32 v[28:29], v[46:47], v[28:29], v[50:51]
	v_pk_mul_f32 v[26:27], v[26:27], s[2:3] op_sel_hi:[1,0]
	v_pk_mul_f32 v[28:29], v[28:29], s[2:3] op_sel_hi:[1,0]
	v_pk_fma_f32 v[24:25], v[24:25], 0.5, v[26:27] op_sel_hi:[1,0,1]
	v_pk_fma_f32 v[22:23], v[22:23], 0.5, v[28:29] op_sel_hi:[1,0,1]
	v_add_f32_e32 v27, v24, v25
	v_add_f32_e32 v26, v22, v23
	v_add_f32_e32 v26, v26, v27
	v_add_f32_e32 v31, v31, v26
	v_mul_f32_e32 v26, v23, v23
	v_mul_f32_e32 v27, v25, v25
	v_fmac_f32_e32 v26, v22, v22
	v_fmac_f32_e32 v27, v24, v24
	v_add_f32_e32 v26, v26, v27
	v_add_f32_e32 v30, v30, v26
	v_sub_f32_e32 v27, v37, v59
	v_sub_f32_e32 v26, v36, v59
	v_sub_f32_e32 v29, v35, v59
	v_sub_f32_e32 v28, v34, v59
	v_pk_mul_f32 v[28:29], v[58:59], v[28:29] op_sel_hi:[0,1]
	v_pk_mul_f32 v[26:27], v[58:59], v[26:27] op_sel_hi:[0,1]
	v_pk_fma_f32 v[26:27], v[40:41], v[26:27], v[44:45]
	v_pk_fma_f32 v[28:29], v[38:39], v[28:29], v[42:43]
	v_pk_mul_f32 v[26:27], v[26:27], s[2:3] op_sel_hi:[1,0]
	v_pk_mul_f32 v[28:29], v[28:29], s[2:3] op_sel_hi:[1,0]
	v_pk_fma_f32 v[20:21], v[20:21], 0.5, v[26:27] op_sel_hi:[1,0,1]
	v_pk_fma_f32 v[18:19], v[18:19], 0.5, v[28:29] op_sel_hi:[1,0,1]
	v_add_f32_e32 v27, v20, v21
	v_add_f32_e32 v26, v18, v19
	v_add_f32_e32 v26, v26, v27
	v_mul_f32_e32 v27, v19, v19
	v_mul_f32_e32 v28, v21, v21
	v_add_f32_e32 v26, v31, v26
	v_fmac_f32_e32 v27, v18, v18
	v_fmac_f32_e32 v28, v20, v20
	s_nop 0
	s_nop 1
	v_bfe_u32 v33, v227, 4, 2
	v_sub_u32_e32 v32, 0, v33
	v_lshlrev_b32_e32 v32, 4, v32
	v_ashrrev_i32_e32 v33, 31, v32
	v_lshl_add_u64 v[32:33], v[60:61], 0, v[32:33]
	v_permlane16_swap_b32_e32 v22, v18
	v_permlane16_swap_b32_e32 v23, v19
	v_permlane16_swap_b32_e32 v24, v20
	v_permlane16_swap_b32_e32 v25, v21
	v_permlane32_swap_b32_e32 v22, v18
	v_permlane32_swap_b32_e32 v23, v19
	v_permlane32_swap_b32_e32 v24, v20
	v_permlane32_swap_b32_e32 v25, v21
	v_mov_b32_e32 v29, v22
	v_mov_b32_e32 v36, v23
	v_mov_b32_e32 v37, v24
	v_mov_b32_e32 v38, v25
	v_bfe_u32 v34, v227, 3, 1
	v_mul_i32_i24_e32 v34, 0xffff8040, v34
	v_ashrrev_i32_e32 v35, 31, v34
	v_lshl_add_u64 v[32:33], v[32:33], 0, v[34:35]
	v_mov_b32_e32 v34, 0x8000
	v_mov_b32_e32 v35, 0
	v_lshl_add_u64 v[34:35], v[32:33], 0, v[34:35]
	v_mov_b32_dpp v22, v18 row_ror:8 row_mask:0xf bank_mask:0xc
	v_mov_b32_dpp v23, v19 row_ror:8 row_mask:0xf bank_mask:0xc
	v_mov_b32_dpp v24, v20 row_ror:8 row_mask:0xf bank_mask:0xc
	v_mov_b32_dpp v25, v21 row_ror:8 row_mask:0xf bank_mask:0xc
	v_mov_b32_dpp v18, v29 row_ror:8 row_mask:0xf bank_mask:0x3
	v_mov_b32_dpp v19, v36 row_ror:8 row_mask:0xf bank_mask:0x3
	v_mov_b32_dpp v20, v37 row_ror:8 row_mask:0xf bank_mask:0x3
	v_mov_b32_dpp v21, v38 row_ror:8 row_mask:0xf bank_mask:0x3
	global_store_dwordx4 v[32:33], v[22:25], off offset:512 nt
	global_store_dwordx4 v[34:35], v[18:21], off offset:512 nt
	s_nop 1
	v_mov_b32_dpp v18, v22 row_ror:8 row_mask:0xf bank_mask:0x3
	v_mov_b32_dpp v19, v23 row_ror:8 row_mask:0xf bank_mask:0x3
	v_mov_b32_dpp v20, v24 row_ror:8 row_mask:0xf bank_mask:0x3
	v_mov_b32_dpp v21, v25 row_ror:8 row_mask:0xf bank_mask:0x3
	v_mov_b32_e32 v22, v29
	v_mov_b32_e32 v23, v36
	v_mov_b32_e32 v24, v37
	v_mov_b32_e32 v25, v38
	s_nop 1
	v_permlane32_swap_b32_e32 v22, v18
	v_permlane32_swap_b32_e32 v23, v19
	v_permlane32_swap_b32_e32 v24, v20
	v_permlane32_swap_b32_e32 v25, v21
	v_permlane16_swap_b32_e32 v22, v18
	v_permlane16_swap_b32_e32 v23, v19
	v_permlane16_swap_b32_e32 v24, v20
	v_permlane16_swap_b32_e32 v25, v21
	v_add_f32_e32 v27, v27, v28
	v_cvt_pk_bf16_f32 v22, v22, v23
	v_cvt_pk_bf16_f32 v23, v24, v25
	v_cvt_pk_bf16_f32 v24, v18, v19
	v_lshl_add_u64 v[18:19], v[76:77], 0, v[0:1]
	v_mov_b32_e32 v0, v26
	v_add_f32_e32 v27, v30, v27
	v_cvt_pk_bf16_f32 v25, v20, v21
	v_permlane16_swap_b32_e32 v26, v0
	global_store_dwordx4 v[18:19], v[22:25], off
	v_add_f32_e32 v18, v26, v0
	v_mov_b32_e32 v0, v27
	s_nop 1
	v_permlane16_swap_b32_e32 v27, v0
	v_add_f32_e32 v19, v27, v0
	v_mov_b32_e32 v20, v18
	v_mov_b32_e32 v21, v19
	s_nop 0
	v_permlane32_swap_b32_e32 v18, v20
	v_permlane32_swap_b32_e32 v19, v21
	s_and_saveexec_b64 s[24:25], s[40:41]
	s_cbranch_execz .LBB0_1717
	v_pk_add_f32 v[18:19], v[18:19], v[20:21]
	v_lshlrev_b64 v[20:21], 7, v[80:81]
	v_lshl_add_u64 v[20:21], s[8:9], 0, v[20:21]
	v_lshl_add_u64 v[20:21], s[38:39], 2, v[20:21]
	global_store_dwordx2 v[20:21], v[18:19], off
; __device__ __forceinline__ size_t blk_off(int r, int c, int K) { return (size_t)(r >> 8) * 256 * K + (size_t)(c >> 6) * (256 * 64) + (size_t)((r & 255) * 64 + (c & 63)); }
; __device__ __forceinline__ u32x4 pack8(const f32x4 a, const f32x4 b) { u32x4 w; w.x = cvt_pk_bf16(a[0], a[1]); w.y = cvt_pk_bf16(a[2], a[3]); w.z = cvt_pk_bf16(b[0], b[1]); w.w = cvt_pk_bf16(b[2], b[3]); return w; }
;     __device__ __forceinline__ void operator()(const f32x4 (&acc)[2][2][4][2], const pg8::Unit& u, int wr, int wc, int fr, int fq) const {
;     ...
;             for (int m = 0; m < 4; ++m) { const int row = row0 + ai * 128 + m * 16; const float mu = mu4[m], rs = rs4[m];
;                 f32x4 yv[2][2], gq[2][2], bq_[2][2];
; #pragma unroll
;                 for (int bj = 0; bj < 2; ++bj)
; #pragma unroll
;                     for (int n = 0; n < 2; ++n) { yv[bj][n] = *(const f32x4*)(Yin + (size_t)row * D_ + col0 + bj * 128 + 4 * n); gq[bj][n] = *(const f32x4*)(g + col0 + bj * 128 + 4 * n); bq_[bj][n] = *(const f32x4*)(b + col0 + bj * 128 + 4 * n); }
;                 asm volatile("" ::: "memory");
;                 float s1 = 0.f, s2 = 0.f;
; #pragma unroll
;                 for (int bj = 0; bj < 2; ++bj) { float* yp = Y + (size_t)row * D_ + col0 + bj * 128; f32x4 v[2];
; #pragma unroll
;                     for (int n = 0; n < 2; ++n) { v[n] = (((yv[bj][n] - mu) * rs) * gq[bj][n] + bq_[bj][n]) * ALPHA_ + acc[ai][bj][m][n] * sc;
;                         *(f32x4*)(yp + 4 * n) = v[n]; s1 += (v[n][0] + v[n][1]) + (v[n][2] + v[n][3]); s2 += (v[n][0] * v[n][0] + v[n][1] * v[n][1]) + (v[n][2] * v[n][2] + v[n][3] * v[n][3]); }
;                     *(u32x4*)(Yb + blk_off(row, col0 + bj * 128, D_)) = pack8(v[0], v[1]); }
.LBB0_1717:
	s_or_b64 exec, exec, s[24:25]
	v_pk_add_f32 v[18:19], v[82:83], v[84:85]
	s_mov_b32 s2, 0x3a800000
	v_pk_mul_f32 v[42:43], v[18:19], s[2:3] op_sel_hi:[1,0]
	s_mov_b32 s1, 0x800000
	v_fma_f32 v0, -v43, v43, v42
	v_max_f32_e32 v0, 0, v0
	v_add_f32_e32 v0, 0x3727c5ac, v0
	v_cmp_gt_f32_e32 vcc, s1, v0
	v_mul_f32_e32 v18, 0x4b800000, v0
	s_load_dwordx16 s[60:75], s[34:35], 0x38
	v_cndmask_b32_e32 v0, v0, v18, vcc
	v_rsq_f32_e32 v0, v0
	s_mov_b32 s2, 0x3fd744fd
	s_movk_i32 s1, 0x3fc0
	v_mul_f32_e32 v18, 0x45800000, v0
	v_cndmask_b32_e32 v42, v0, v18, vcc
	v_lshlrev_b64 v[18:19], 12, v[74:75]
	s_waitcnt lgkmcnt(0)
	v_lshl_add_u64 v[18:19], s[74:75], 0, v[18:19]
	v_lshl_add_u64 v[44:45], v[152:153], 2, v[18:19]
	global_load_dwordx4 v[46:49], v[44:45], off offset:16
	global_load_dwordx4 v[50:53], v[44:45], off
	global_load_dwordx4 v[54:57], v[156:157], off offset:16
	global_load_dwordx4 v[58:61], v[156:157], off
	global_load_dwordx4 v[62:65], v[154:155], off offset:16
	global_load_dwordx4 v[66:69], v[154:155], off
	global_load_dwordx4 v[18:21], v[44:45], off offset:528
	global_load_dwordx4 v[38:41], v[44:45], off offset:512
	global_load_dwordx4 v[22:25], v[156:157], off offset:528
	global_load_dwordx4 v[30:33], v[156:157], off offset:512
	global_load_dwordx4 v[26:29], v[154:155], off offset:528
	global_load_dwordx4 v[34:37], v[154:155], off offset:512
	v_lshlrev_b32_e32 v0, 6, v74
	v_and_or_b32 v0, v0, s1, v196
	v_lshlrev_b32_e32 v0, 1, v0
	s_waitcnt vmcnt(10)
	v_sub_f32_e32 v53, v53, v43
	v_sub_f32_e32 v52, v52, v43
	v_sub_f32_e32 v51, v51, v43
	v_sub_f32_e32 v50, v50, v43
	v_pk_mul_f32 v[50:51], v[42:43], v[50:51] op_sel_hi:[0,1]
	v_pk_mul_f32 v[52:53], v[42:43], v[52:53] op_sel_hi:[0,1]
	s_waitcnt vmcnt(6)
	v_pk_fma_f32 v[52:53], v[60:61], v[52:53], v[68:69]
	v_pk_fma_f32 v[50:51], v[58:59], v[50:51], v[66:67]
	v_pk_mul_f32 v[52:53], v[52:53], s[2:3] op_sel_hi:[1,0]
	v_pk_mul_f32 v[50:51], v[50:51], s[2:3] op_sel_hi:[1,0]
	v_pk_fma_f32 v[52:53], v[16:17], 0.5, v[52:53] op_sel_hi:[1,0,1]
	v_pk_fma_f32 v[50:51], v[14:15], 0.5, v[50:51] op_sel_hi:[1,0,1]
	v_add_f32_e32 v15, v52, v53
	v_add_f32_e32 v14, v50, v51
	v_add_f32_e32 v14, v14, v15
	v_add_f32_e32 v58, 0, v14
	v_mul_f32_e32 v14, v51, v51
	v_mul_f32_e32 v15, v53, v53
	v_fmac_f32_e32 v14, v50, v50
	v_fmac_f32_e32 v15, v52, v52
	v_add_f32_e32 v59, v14, v15
	v_sub_f32_e32 v15, v49, v43
	v_sub_f32_e32 v14, v48, v43
	v_sub_f32_e32 v17, v47, v43
	v_sub_f32_e32 v16, v46, v43
	v_pk_mul_f32 v[16:17], v[42:43], v[16:17] op_sel_hi:[0,1]
	v_pk_mul_f32 v[14:15], v[42:43], v[14:15] op_sel_hi:[0,1]
	v_pk_fma_f32 v[14:15], v[56:57], v[14:15], v[64:65]
	v_pk_fma_f32 v[16:17], v[54:55], v[16:17], v[62:63]
	v_pk_mul_f32 v[14:15], v[14:15], s[2:3] op_sel_hi:[1,0]
	v_pk_mul_f32 v[16:17], v[16:17], s[2:3] op_sel_hi:[1,0]
	v_pk_fma_f32 v[48:49], v[12:13], 0.5, v[14:15] op_sel_hi:[1,0,1]
	v_pk_fma_f32 v[46:47], v[10:11], 0.5, v[16:17] op_sel_hi:[1,0,1]
	v_add_f32_e32 v11, v48, v49
	v_add_f32_e32 v10, v46, v47
	v_add_f32_e32 v10, v10, v11
	v_add_f32_e32 v15, v58, v10
	v_mul_f32_e32 v10, v47, v47
	v_mul_f32_e32 v11, v49, v49
	v_fmac_f32_e32 v10, v46, v46
	v_fmac_f32_e32 v11, v48, v48
	v_add_f32_e32 v10, v10, v11
	v_add_f32_e32 v14, v59, v10
	v_cvt_pk_bf16_f32 v10, v50, v51
	v_cvt_pk_bf16_f32 v11, v52, v53
	v_cvt_pk_bf16_f32 v12, v46, v47
	v_cvt_pk_bf16_f32 v13, v48, v49
	v_lshl_add_u64 v[16:17], v[78:79], 0, v[0:1]
	s_nop 0
	s_nop 1
	v_bfe_u32 v55, v227, 4, 2
	v_sub_u32_e32 v54, 0, v55
	v_lshlrev_b32_e32 v54, 4, v54
	v_ashrrev_i32_e32 v55, 31, v54
	v_lshl_add_u64 v[54:55], v[44:45], 0, v[54:55]
	v_permlane16_swap_b32_e32 v50, v46
	v_permlane16_swap_b32_e32 v51, v47
	v_permlane16_swap_b32_e32 v52, v48
	v_permlane16_swap_b32_e32 v53, v49
	v_permlane32_swap_b32_e32 v50, v46
	v_permlane32_swap_b32_e32 v51, v47
	v_permlane32_swap_b32_e32 v52, v48
	v_permlane32_swap_b32_e32 v53, v49
	v_mov_b32_e32 v58, v50
	v_mov_b32_e32 v59, v51
	v_mov_b32_e32 v60, v52
	v_mov_b32_e32 v61, v53
	v_bfe_u32 v56, v227, 3, 1
	v_mul_i32_i24_e32 v56, 0xffff8040, v56
	v_ashrrev_i32_e32 v57, 31, v56
	v_lshl_add_u64 v[54:55], v[54:55], 0, v[56:57]
	v_mov_b32_e32 v56, 0x8000
	v_mov_b32_e32 v57, 0
	v_lshl_add_u64 v[56:57], v[54:55], 0, v[56:57]
	v_mov_b32_dpp v50, v46 row_ror:8 row_mask:0xf bank_mask:0xc
	v_mov_b32_dpp v51, v47 row_ror:8 row_mask:0xf bank_mask:0xc
	v_mov_b32_dpp v52, v48 row_ror:8 row_mask:0xf bank_mask:0xc
	v_mov_b32_dpp v53, v49 row_ror:8 row_mask:0xf bank_mask:0xc
	v_mov_b32_dpp v46, v58 row_ror:8 row_mask:0xf bank_mask:0x3
	v_mov_b32_dpp v47, v59 row_ror:8 row_mask:0xf bank_mask:0x3
	v_mov_b32_dpp v48, v60 row_ror:8 row_mask:0xf bank_mask:0x3
	v_mov_b32_dpp v49, v61 row_ror:8 row_mask:0xf bank_mask:0x3
	global_store_dwordx4 v[54:55], v[50:53], off nt
	global_store_dwordx4 v[56:57], v[46:49], off nt
	s_nop 1
	global_store_dwordx4 v[16:17], v[10:13], off
	s_waitcnt vmcnt(7)
; __device__ __forceinline__ float xsum16(float v) { const auto r = __builtin_amdgcn_permlane16_swap(__float_as_uint(v), __float_as_uint(v), false, false); return __uint_as_float(r[0]) + __uint_as_float(r[1]); }
; __device__ __forceinline__ float xsum32(float v) { const auto r = __builtin_amdgcn_permlane32_swap(__float_as_uint(v), __float_as_uint(v), false, false); return __uint_as_float(r[0]) + __uint_as_float(r[1]); }
; __device__ __forceinline__ size_t blk_off(int r, int c, int K) { return (size_t)(r >> 8) * 256 * K + (size_t)(c >> 6) * (256 * 64) + (size_t)((r & 255) * 64 + (c & 63)); }
; __device__ __forceinline__ u32x4 pack8(const f32x4 a, const f32x4 b) { u32x4 w; w.x = cvt_pk_bf16(a[0], a[1]); w.y = cvt_pk_bf16(a[2], a[3]); w.z = cvt_pk_bf16(b[0], b[1]); w.w = cvt_pk_bf16(b[2], b[3]); return w; }
;     __device__ __forceinline__ void operator()(const f32x4 (&acc)[2][2][4][2], const pg8::Unit& u, int wr, int wc, int fr, int fq) const {
;     ...
;                 for (int bj = 0; bj < 2; ++bj) { float* yp = Y + (size_t)row * D_ + col0 + bj * 128; f32x4 v[2];
; #pragma unroll
;                     for (int n = 0; n < 2; ++n) { v[n] = (((yv[bj][n] - mu) * rs) * gq[bj][n] + bq_[bj][n]) * ALPHA_ + acc[ai][bj][m][n] * sc;
;                         *(f32x4*)(yp + 4 * n) = v[n]; s1 += (v[n][0] + v[n][1]) + (v[n][2] + v[n][3]); s2 += (v[n][0] * v[n][0] + v[n][1] * v[n][1]) + (v[n][2] * v[n][2] + v[n][3] * v[n][3]); }
;                     *(u32x4*)(Yb + blk_off(row, col0 + bj * 128, D_)) = pack8(v[0], v[1]); }
;                 s1 = xsum32(xsum16(s1)); s2 = xsum32(xsum16(s2));
;                 if (fq == 0) *(f32x2*)(stn + (size_t)row * 32 + (u.pn * 4 + wc) * 2) = (f32x2){s1, s2}; asm volatile("" ::: "memory"); } }
	s_nop 0
	v_sub_f32_e32 v11, v41, v43
	v_sub_f32_e32 v10, v40, v43
	v_sub_f32_e32 v13, v39, v43
	v_sub_f32_e32 v12, v38, v43
	v_pk_mul_f32 v[12:13], v[42:43], v[12:13] op_sel_hi:[0,1]
	v_pk_mul_f32 v[10:11], v[42:43], v[10:11] op_sel_hi:[0,1]
	s_waitcnt vmcnt(3)
	v_pk_fma_f32 v[10:11], v[32:33], v[10:11], v[36:37]
	v_pk_fma_f32 v[12:13], v[30:31], v[12:13], v[34:35]
	v_pk_mul_f32 v[10:11], v[10:11], s[2:3] op_sel_hi:[1,0]
	v_pk_mul_f32 v[12:13], v[12:13], s[2:3] op_sel_hi:[1,0]
	v_pk_fma_f32 v[8:9], v[8:9], 0.5, v[10:11] op_sel_hi:[1,0,1]
	v_pk_fma_f32 v[6:7], v[6:7], 0.5, v[12:13] op_sel_hi:[1,0,1]
	v_add_f32_e32 v11, v8, v9
	v_add_f32_e32 v10, v6, v7
	v_add_f32_e32 v10, v10, v11
	v_add_f32_e32 v15, v15, v10
	v_mul_f32_e32 v10, v7, v7
	v_mul_f32_e32 v11, v9, v9
	v_fmac_f32_e32 v10, v6, v6
	v_fmac_f32_e32 v11, v8, v8
	v_add_f32_e32 v10, v10, v11
	v_add_f32_e32 v14, v14, v10
	v_sub_f32_e32 v11, v21, v43
	v_sub_f32_e32 v10, v20, v43
	v_sub_f32_e32 v13, v19, v43
	v_sub_f32_e32 v12, v18, v43
	v_pk_mul_f32 v[12:13], v[42:43], v[12:13] op_sel_hi:[0,1]
	v_pk_mul_f32 v[10:11], v[42:43], v[10:11] op_sel_hi:[0,1]
	v_pk_fma_f32 v[10:11], v[24:25], v[10:11], v[28:29]
	v_pk_fma_f32 v[12:13], v[22:23], v[12:13], v[26:27]
	v_pk_mul_f32 v[10:11], v[10:11], s[2:3] op_sel_hi:[1,0]
	v_pk_mul_f32 v[12:13], v[12:13], s[2:3] op_sel_hi:[1,0]
	v_pk_fma_f32 v[4:5], v[4:5], 0.5, v[10:11] op_sel_hi:[1,0,1]
	v_pk_fma_f32 v[2:3], v[2:3], 0.5, v[12:13] op_sel_hi:[1,0,1]
	v_add_f32_e32 v11, v4, v5
	v_add_f32_e32 v10, v2, v3
	v_add_f32_e32 v10, v10, v11
	v_mul_f32_e32 v11, v3, v3
	v_mul_f32_e32 v12, v5, v5
	v_add_f32_e32 v10, v15, v10
	v_fmac_f32_e32 v11, v2, v2
	v_fmac_f32_e32 v12, v4, v4
	s_nop 0
	s_nop 1
	v_bfe_u32 v17, v227, 4, 2
	v_sub_u32_e32 v16, 0, v17
	v_lshlrev_b32_e32 v16, 4, v16
	v_ashrrev_i32_e32 v17, 31, v16
	v_lshl_add_u64 v[16:17], v[44:45], 0, v[16:17]
	v_permlane16_swap_b32_e32 v6, v2
	v_permlane16_swap_b32_e32 v7, v3
	v_permlane16_swap_b32_e32 v8, v4
	v_permlane16_swap_b32_e32 v9, v5
	v_permlane32_swap_b32_e32 v6, v2
	v_permlane32_swap_b32_e32 v7, v3
	v_permlane32_swap_b32_e32 v8, v4
	v_permlane32_swap_b32_e32 v9, v5
	v_mov_b32_e32 v13, v6
	v_mov_b32_e32 v20, v7
	v_mov_b32_e32 v21, v8
	v_mov_b32_e32 v22, v9
	v_bfe_u32 v18, v227, 3, 1
	v_mul_i32_i24_e32 v18, 0xffff8040, v18
	v_ashrrev_i32_e32 v19, 31, v18
	v_lshl_add_u64 v[16:17], v[16:17], 0, v[18:19]
	v_mov_b32_e32 v18, 0x8000
	v_mov_b32_e32 v19, 0
	v_lshl_add_u64 v[18:19], v[16:17], 0, v[18:19]
	v_mov_b32_dpp v6, v2 row_ror:8 row_mask:0xf bank_mask:0xc
	v_mov_b32_dpp v7, v3 row_ror:8 row_mask:0xf bank_mask:0xc
	v_mov_b32_dpp v8, v4 row_ror:8 row_mask:0xf bank_mask:0xc
	v_mov_b32_dpp v9, v5 row_ror:8 row_mask:0xf bank_mask:0xc
	v_mov_b32_dpp v2, v13 row_ror:8 row_mask:0xf bank_mask:0x3
	v_mov_b32_dpp v3, v20 row_ror:8 row_mask:0xf bank_mask:0x3
	v_mov_b32_dpp v4, v21 row_ror:8 row_mask:0xf bank_mask:0x3
	v_mov_b32_dpp v5, v22 row_ror:8 row_mask:0xf bank_mask:0x3
	global_store_dwordx4 v[16:17], v[6:9], off offset:512 nt
	global_store_dwordx4 v[18:19], v[2:5], off offset:512 nt
	s_nop 1
	v_mov_b32_dpp v2, v6 row_ror:8 row_mask:0xf bank_mask:0x3
	v_mov_b32_dpp v3, v7 row_ror:8 row_mask:0xf bank_mask:0x3
	v_mov_b32_dpp v4, v8 row_ror:8 row_mask:0xf bank_mask:0x3
	v_mov_b32_dpp v5, v9 row_ror:8 row_mask:0xf bank_mask:0x3
	v_mov_b32_e32 v6, v13
	v_mov_b32_e32 v7, v20
	v_mov_b32_e32 v8, v21
	v_mov_b32_e32 v9, v22
	s_nop 1
	v_permlane32_swap_b32_e32 v6, v2
	v_permlane32_swap_b32_e32 v7, v3
	v_permlane32_swap_b32_e32 v8, v4
	v_permlane32_swap_b32_e32 v9, v5
	v_permlane16_swap_b32_e32 v6, v2
	v_permlane16_swap_b32_e32 v7, v3
	v_permlane16_swap_b32_e32 v8, v4
	v_permlane16_swap_b32_e32 v9, v5
	v_add_f32_e32 v11, v11, v12
	v_cvt_pk_bf16_f32 v6, v6, v7
	v_cvt_pk_bf16_f32 v7, v8, v9
	v_cvt_pk_bf16_f32 v8, v2, v3
	v_lshl_add_u64 v[2:3], v[76:77], 0, v[0:1]
	v_mov_b32_e32 v0, v10
	v_add_f32_e32 v11, v14, v11
	v_cvt_pk_bf16_f32 v9, v4, v5
	v_permlane16_swap_b32_e32 v10, v0
	global_store_dwordx4 v[2:3], v[6:9], off
	v_add_f32_e32 v2, v10, v0
	v_mov_b32_e32 v0, v11
	s_nop 1
	v_permlane16_swap_b32_e32 v11, v0
	v_add_f32_e32 v3, v11, v0
	v_mov_b32_e32 v4, v2
	v_mov_b32_e32 v5, v3
	s_nop 0
	v_permlane32_swap_b32_e32 v2, v4
	v_permlane32_swap_b32_e32 v3, v5
	s_and_saveexec_b64 s[24:25], s[40:41]
	s_cbranch_execz .LBB0_1719
	v_pk_add_f32 v[2:3], v[2:3], v[4:5]
	v_lshlrev_b64 v[4:5], 7, v[74:75]
	v_lshl_add_u64 v[4:5], s[8:9], 0, v[4:5]
	v_lshl_add_u64 v[4:5], s[38:39], 2, v[4:5]
	global_store_dwordx2 v[4:5], v[2:3], off
